# combo9 plus permlane/DPP cross-lane reductions replacing ds_bpermute butterflies in LayerNorm statistics and diff-attention sub-norm
# baseline (speedup 1.0000x reference)
.LBB0_289:
	s_cmpk_gt_u32 s24, 0xff
	s_waitcnt lgkmcnt(0)
	s_barrier
	s_cbranch_scc1 .LBB0_280
	ds_read2st64_b32 v[10:11], v104 offset1:1
	ds_read2st64_b32 v[14:15], v104 offset0:16 offset1:17
	ds_read2st64_b32 v[20:21], v104 offset0:32 offset1:33
	ds_read2st64_b32 v[22:23], v104 offset0:48 offset1:49
	s_mov_b32 s0, 0x3727c5ac
	v_lshlrev_b32_e32 v178, 1, v162
	s_waitcnt lgkmcnt(3)
	v_mov_b32_e32 v8, v10
	s_waitcnt lgkmcnt(2)
	v_mov_b32_e32 v9, v14
	v_mov_b32_e32 v14, v11
	v_pk_fma_f32 v[12:13], s[6:7], v[8:9], v[92:93] neg_lo:[1,0,0] neg_hi:[1,0,0]
	s_waitcnt lgkmcnt(1)
	v_mov_b32_e32 v8, v20
	s_waitcnt lgkmcnt(0)
	v_mov_b32_e32 v9, v22
	v_pk_fma_f32 v[14:15], s[6:7], v[14:15], v[96:97] neg_lo:[1,0,0] neg_hi:[1,0,0]
	v_mov_b32_e32 v22, v21
	v_pk_mul_f32 v[16:17], v[12:13], v[12:13]
	v_pk_fma_f32 v[8:9], s[6:7], v[8:9], v[94:95] neg_lo:[1,0,0] neg_hi:[1,0,0]
	v_pk_mul_f32 v[28:29], v[14:15], v[14:15]
	v_pk_fma_f32 v[10:11], s[6:7], v[22:23], v[98:99] neg_lo:[1,0,0] neg_hi:[1,0,0]
	v_pk_mul_f32 v[24:25], v[8:9], v[8:9]
	v_pk_mul_f32 v[20:21], v[10:11], v[10:11]
	v_mov_b32_e32 v22, v28
	v_mov_b32_e32 v23, v16
	v_mov_b32_e32 v16, v29
	v_pk_add_f32 v[16:17], v[22:23], v[16:17]
	v_mov_b32_e32 v22, v20
	v_mov_b32_e32 v23, v24
	v_pk_add_f32 v[16:17], v[16:17], v[22:23]
	v_mov_b32_e32 v24, v21
	v_pk_add_f32 v[16:17], v[16:17], v[24:25]
	ds_read2st64_b32 v[24:25], v104 offset0:2 offset1:3
	ds_read2st64_b32 v[28:29], v104 offset0:18 offset1:19
	ds_read2st64_b32 v[32:33], v104 offset0:34 offset1:35
	ds_read2st64_b32 v[46:47], v104 offset0:50 offset1:51
	s_waitcnt lgkmcnt(4)
	s_nop 1
	v_add_f32_dpp v16, v16, v16 quad_perm:[1,0,3,2] row_mask:0xf bank_mask:0xf
	v_add_f32_dpp v17, v17, v17 quad_perm:[1,0,3,2] row_mask:0xf bank_mask:0xf
	s_waitcnt lgkmcnt(0)
	s_nop 1
	v_add_f32_dpp v16, v16, v16 quad_perm:[2,3,0,1] row_mask:0xf bank_mask:0xf
	v_add_f32_dpp v17, v17, v17 quad_perm:[2,3,0,1] row_mask:0xf bank_mask:0xf
	s_waitcnt lgkmcnt(0)
	s_nop 1
	v_add_f32_dpp v16, v16, v16 row_half_mirror row_mask:0xf bank_mask:0xf
	v_add_f32_dpp v17, v17, v17 row_half_mirror row_mask:0xf bank_mask:0xf
	s_waitcnt lgkmcnt(0)
	s_nop 1
	v_add_f32_dpp v16, v16, v16 row_mirror row_mask:0xf bank_mask:0xf
	v_add_f32_dpp v17, v17, v17 row_mirror row_mask:0xf bank_mask:0xf
	s_waitcnt lgkmcnt(0)
	v_mov_b32_e32 v20, v16
	v_mov_b32_e32 v21, v17
	s_nop 1
	v_permlane16_swap_b32_e32 v20, v16
	v_permlane16_swap_b32_e32 v21, v17
	v_add_f32_e32 v16, v16, v20
	v_add_f32_e32 v17, v17, v21
	v_mov_b64_e32 v[20:21], s[0:1]
	v_pk_fma_f32 v[16:17], v[16:17], s[42:43], v[20:21] op_sel_hi:[1,0,0]
	s_lshl_b32 s0, s23, 14
	v_mul_f32_e32 v22, 0x4b800000, v17
	v_cmp_gt_f32_e64 s[4:5], s41, v17
	v_cmp_gt_f32_e32 vcc, s41, v16
	s_add_i32 s0, s0, 0
	v_cndmask_b32_e64 v17, v17, v22, s[4:5]
	v_rsq_f32_e32 v17, v17
	s_nop 0
	v_mul_f32_e32 v22, 0x45800000, v17
	v_cndmask_b32_e64 v17, v17, v22, s[4:5]
	v_mul_f32_e32 v92, v171, v17
	v_mul_f32_e32 v17, 0x4b800000, v16
	v_cndmask_b32_e32 v16, v16, v17, vcc
	v_rsq_f32_e32 v16, v16
	v_mul_f32_e32 v12, v12, v92
	s_waitcnt vmcnt(3)
	v_mul_f32_e32 v12, v103, v12
	v_mul_f32_e32 v17, 0x45800000, v16
	v_cndmask_b32_e32 v16, v16, v17, vcc
	v_mul_f32_e32 v93, v171, v16
	v_mov_b32_e32 v16, v24
	v_mov_b32_e32 v17, v28
	v_mov_b32_e32 v28, v25
	v_pk_fma_f32 v[22:23], s[6:7], v[16:17], v[90:91] neg_lo:[1,0,0] neg_hi:[1,0,0]
	v_mov_b32_e32 v16, v32
	v_mov_b32_e32 v17, v46
	v_pk_fma_f32 v[24:25], s[6:7], v[28:29], v[88:89] neg_lo:[1,0,0] neg_hi:[1,0,0]
	v_mov_b32_e32 v46, v33
	v_pk_mul_f32 v[30:31], v[22:23], v[22:23]
	v_pk_fma_f32 v[16:17], s[6:7], v[16:17], v[18:19] neg_lo:[1,0,0] neg_hi:[1,0,0]
	v_pk_mul_f32 v[28:29], v[24:25], v[24:25]
	v_pk_fma_f32 v[18:19], s[6:7], v[46:47], v[86:87] neg_lo:[1,0,0] neg_hi:[1,0,0]
	v_pk_mul_f32 v[48:49], v[16:17], v[16:17]
	v_pk_mul_f32 v[32:33], v[18:19], v[18:19]
	v_mov_b32_e32 v46, v28
	v_mov_b32_e32 v47, v30
	v_mov_b32_e32 v30, v29
	v_pk_add_f32 v[28:29], v[46:47], v[30:31]
	v_mov_b32_e32 v30, v32
	v_mov_b32_e32 v31, v48
	v_pk_add_f32 v[28:29], v[28:29], v[30:31]
	v_mov_b32_e32 v48, v33
	v_pk_add_f32 v[28:29], v[28:29], v[48:49]
	s_waitcnt lgkmcnt(0)
	s_nop 1
	v_add_f32_dpp v28, v28, v28 quad_perm:[1,0,3,2] row_mask:0xf bank_mask:0xf
	v_add_f32_dpp v29, v29, v29 quad_perm:[1,0,3,2] row_mask:0xf bank_mask:0xf
	s_waitcnt lgkmcnt(0)
	s_nop 1
	v_add_f32_dpp v28, v28, v28 quad_perm:[2,3,0,1] row_mask:0xf bank_mask:0xf
	v_add_f32_dpp v29, v29, v29 quad_perm:[2,3,0,1] row_mask:0xf bank_mask:0xf
	s_waitcnt lgkmcnt(0)
	s_nop 1
	v_add_f32_dpp v28, v28, v28 row_half_mirror row_mask:0xf bank_mask:0xf
	v_add_f32_dpp v29, v29, v29 row_half_mirror row_mask:0xf bank_mask:0xf
	s_waitcnt lgkmcnt(0)
	s_nop 1
	v_add_f32_dpp v28, v28, v28 row_mirror row_mask:0xf bank_mask:0xf
	v_add_f32_dpp v29, v29, v29 row_mirror row_mask:0xf bank_mask:0xf
	s_waitcnt lgkmcnt(0)
	v_mov_b32_e32 v30, v28
	v_mov_b32_e32 v31, v29
	s_nop 1
	v_permlane16_swap_b32_e32 v30, v28
	v_permlane16_swap_b32_e32 v31, v29
	v_add_f32_e32 v28, v28, v30
	v_add_f32_e32 v29, v29, v31
	s_nop 0
	v_pk_fma_f32 v[28:29], v[28:29], s[42:43], v[20:21] op_sel_hi:[1,0,0]
	s_nop 0
	v_mul_f32_e32 v30, 0x4b800000, v29
	v_cmp_gt_f32_e64 s[4:5], s41, v29
	v_cmp_gt_f32_e32 vcc, s41, v28
	s_nop 0
	v_cndmask_b32_e64 v29, v29, v30, s[4:5]
	v_rsq_f32_e32 v29, v29
	s_nop 0
	v_mul_f32_e32 v30, 0x45800000, v29
	v_cndmask_b32_e64 v29, v29, v30, s[4:5]
	v_mul_f32_e32 v86, v171, v29
	v_mul_f32_e32 v29, 0x4b800000, v28
	v_cndmask_b32_e32 v28, v28, v29, vcc
	v_rsq_f32_e32 v28, v28
	ds_read2st64_b32 v[30:31], v104 offset0:4 offset1:5
	ds_read2st64_b32 v[46:47], v104 offset0:20 offset1:21
	ds_read2st64_b32 v[58:59], v104 offset0:36 offset1:37
	ds_read2st64_b32 v[60:61], v104 offset0:52 offset1:53
	v_mul_f32_e32 v29, 0x45800000, v28
	v_cndmask_b32_e32 v28, v28, v29, vcc
	v_mul_f32_e32 v87, v171, v28
	s_waitcnt lgkmcnt(3)
	v_mov_b32_e32 v28, v30
	s_waitcnt lgkmcnt(2)
	v_mov_b32_e32 v29, v46
	v_pk_fma_f32 v[32:33], s[6:7], v[28:29], v[84:85] neg_lo:[1,0,0] neg_hi:[1,0,0]
	s_waitcnt lgkmcnt(1)
	v_mov_b32_e32 v28, v58
	s_waitcnt lgkmcnt(0)
	v_mov_b32_e32 v29, v60
	v_mov_b32_e32 v46, v31
	v_pk_fma_f32 v[28:29], s[6:7], v[28:29], v[34:35] neg_lo:[1,0,0] neg_hi:[1,0,0]
	v_pk_fma_f32 v[34:35], s[6:7], v[46:47], v[82:83] neg_lo:[1,0,0] neg_hi:[1,0,0]
	v_mov_b32_e32 v60, v59
	v_pk_mul_f32 v[48:49], v[32:33], v[32:33]
	v_pk_mul_f32 v[46:47], v[34:35], v[34:35]
	v_pk_fma_f32 v[30:31], s[6:7], v[60:61], v[80:81] neg_lo:[1,0,0] neg_hi:[1,0,0]
	v_pk_mul_f32 v[62:63], v[28:29], v[28:29]
	v_pk_mul_f32 v[58:59], v[30:31], v[30:31]
	v_mov_b32_e32 v60, v46
	v_mov_b32_e32 v61, v48
	v_mov_b32_e32 v48, v47
	v_pk_add_f32 v[46:47], v[60:61], v[48:49]
	v_mov_b32_e32 v48, v58
	v_mov_b32_e32 v49, v62
	v_pk_add_f32 v[46:47], v[46:47], v[48:49]
	v_mov_b32_e32 v62, v59
	v_pk_add_f32 v[46:47], v[46:47], v[62:63]
	ds_read2st64_b32 v[58:59], v104 offset0:6 offset1:7
	ds_read2st64_b32 v[60:61], v104 offset0:22 offset1:23
	s_waitcnt lgkmcnt(2)
	s_nop 1
	v_add_f32_dpp v46, v46, v46 quad_perm:[1,0,3,2] row_mask:0xf bank_mask:0xf
	v_add_f32_dpp v47, v47, v47 quad_perm:[1,0,3,2] row_mask:0xf bank_mask:0xf
	s_waitcnt lgkmcnt(0)
	s_nop 1
	v_add_f32_dpp v46, v46, v46 quad_perm:[2,3,0,1] row_mask:0xf bank_mask:0xf
	v_add_f32_dpp v47, v47, v47 quad_perm:[2,3,0,1] row_mask:0xf bank_mask:0xf
	s_waitcnt lgkmcnt(0)
	s_nop 1
	v_add_f32_dpp v46, v46, v46 row_half_mirror row_mask:0xf bank_mask:0xf
	v_add_f32_dpp v47, v47, v47 row_half_mirror row_mask:0xf bank_mask:0xf
	s_waitcnt lgkmcnt(0)
	s_nop 1
	v_add_f32_dpp v46, v46, v46 row_mirror row_mask:0xf bank_mask:0xf
	v_add_f32_dpp v47, v47, v47 row_mirror row_mask:0xf bank_mask:0xf
	s_waitcnt lgkmcnt(0)
	v_mov_b32_e32 v48, v46
	v_mov_b32_e32 v49, v47
	s_nop 1
	v_permlane16_swap_b32_e32 v48, v46
	v_permlane16_swap_b32_e32 v49, v47
	v_add_f32_e32 v46, v46, v48
	v_add_f32_e32 v47, v47, v49
	s_nop 0
	v_pk_fma_f32 v[46:47], v[46:47], s[42:43], v[20:21] op_sel_hi:[1,0,0]
	s_nop 0
	v_mul_f32_e32 v48, 0x4b800000, v47
	v_cmp_gt_f32_e64 s[4:5], s41, v47
	v_cmp_gt_f32_e32 vcc, s41, v46
	s_nop 0
	v_cndmask_b32_e64 v47, v47, v48, s[4:5]
	v_rsq_f32_e32 v47, v47
	s_nop 0
	v_mul_f32_e32 v48, 0x45800000, v47
	v_cndmask_b32_e64 v47, v47, v48, s[4:5]
	v_mul_f32_e32 v80, v171, v47
	v_mul_f32_e32 v47, 0x4b800000, v46
	v_cndmask_b32_e32 v46, v46, v47, vcc
	v_rsq_f32_e32 v46, v46
	s_nop 0
	v_mul_f32_e32 v47, 0x45800000, v46
	v_cndmask_b32_e32 v46, v46, v47, vcc
	v_mul_f32_e32 v81, v171, v46
	v_mov_b32_e32 v46, v58
	v_mov_b32_e32 v47, v60
	v_pk_fma_f32 v[46:47], s[6:7], v[46:47], v[78:79] neg_lo:[1,0,0] neg_hi:[1,0,0]
	ds_read2st64_b32 v[64:65], v104 offset0:38 offset1:39
	ds_read2st64_b32 v[78:79], v104 offset0:54 offset1:55
	v_mov_b32_e32 v60, v59
	v_pk_fma_f32 v[60:61], s[6:7], v[60:61], v[74:75] neg_lo:[1,0,0] neg_hi:[1,0,0]
	v_pk_mul_f32 v[62:63], v[46:47], v[46:47]
	s_waitcnt lgkmcnt(1)
	v_mov_b32_e32 v48, v64
	s_waitcnt lgkmcnt(0)
	v_mov_b32_e32 v49, v78
	v_mov_b32_e32 v78, v65
	v_pk_fma_f32 v[48:49], s[6:7], v[48:49], v[76:77] neg_lo:[1,0,0] neg_hi:[1,0,0]
	v_pk_mul_f32 v[74:75], v[60:61], v[60:61]
	v_pk_fma_f32 v[58:59], s[6:7], v[78:79], v[72:73] neg_lo:[1,0,0] neg_hi:[1,0,0]
	v_pk_mul_f32 v[76:77], v[48:49], v[48:49]
	v_pk_mul_f32 v[64:65], v[58:59], v[58:59]
	v_mov_b32_e32 v72, v74
	v_mov_b32_e32 v73, v62
	v_mov_b32_e32 v62, v75
	v_pk_add_f32 v[62:63], v[72:73], v[62:63]
	v_mov_b32_e32 v72, v64
	v_mov_b32_e32 v73, v76
	v_pk_add_f32 v[62:63], v[62:63], v[72:73]
	v_mov_b32_e32 v76, v65
	v_pk_add_f32 v[62:63], v[62:63], v[76:77]
	ds_read2st64_b32 v[72:73], v104 offset0:8 offset1:9
	ds_read2st64_b32 v[74:75], v104 offset0:24 offset1:25
	ds_read2st64_b32 v[76:77], v104 offset0:40 offset1:41
	ds_read2st64_b32 v[82:83], v104 offset0:56 offset1:57
	s_waitcnt lgkmcnt(4)
	s_nop 1
	v_add_f32_dpp v62, v62, v62 quad_perm:[1,0,3,2] row_mask:0xf bank_mask:0xf
	v_add_f32_dpp v63, v63, v63 quad_perm:[1,0,3,2] row_mask:0xf bank_mask:0xf
	s_waitcnt lgkmcnt(0)
	s_nop 1
	v_add_f32_dpp v62, v62, v62 quad_perm:[2,3,0,1] row_mask:0xf bank_mask:0xf
	v_add_f32_dpp v63, v63, v63 quad_perm:[2,3,0,1] row_mask:0xf bank_mask:0xf
	s_waitcnt lgkmcnt(0)
	s_nop 1
	v_add_f32_dpp v62, v62, v62 row_half_mirror row_mask:0xf bank_mask:0xf
	v_add_f32_dpp v63, v63, v63 row_half_mirror row_mask:0xf bank_mask:0xf
	s_waitcnt lgkmcnt(0)
	s_nop 1
	v_add_f32_dpp v62, v62, v62 row_mirror row_mask:0xf bank_mask:0xf
	v_add_f32_dpp v63, v63, v63 row_mirror row_mask:0xf bank_mask:0xf
	s_waitcnt lgkmcnt(0)
	v_mov_b32_e32 v64, v62
	v_mov_b32_e32 v65, v63
	s_nop 1
	v_permlane16_swap_b32_e32 v64, v62
	v_permlane16_swap_b32_e32 v65, v63
	v_add_f32_e32 v62, v62, v64
	v_add_f32_e32 v63, v63, v65
	s_nop 0
	v_pk_fma_f32 v[62:63], v[62:63], s[42:43], v[20:21] op_sel_hi:[1,0,0]
	s_nop 0
	v_mul_f32_e32 v64, 0x4b800000, v63
	v_cmp_gt_f32_e64 s[4:5], s41, v63
	v_cmp_gt_f32_e32 vcc, s41, v62
	s_nop 0
	v_cndmask_b32_e64 v63, v63, v64, s[4:5]
	v_rsq_f32_e32 v63, v63
	s_nop 0
	v_mul_f32_e32 v64, 0x45800000, v63
	v_cndmask_b32_e64 v63, v63, v64, s[4:5]
	v_mul_f32_e32 v78, v171, v63
	v_mul_f32_e32 v63, 0x4b800000, v62
	v_cndmask_b32_e32 v62, v62, v63, vcc
	v_rsq_f32_e32 v62, v62
	s_nop 0
	v_mul_f32_e32 v63, 0x45800000, v62
	v_cndmask_b32_e32 v62, v62, v63, vcc
	v_mul_f32_e32 v79, v171, v62
	v_mov_b32_e32 v62, v72
	v_mov_b32_e32 v63, v74
	v_pk_fma_f32 v[64:65], s[6:7], v[62:63], v[70:71] neg_lo:[1,0,0] neg_hi:[1,0,0]
	v_mov_b32_e32 v62, v76
	v_mov_b32_e32 v63, v82
	v_mov_b32_e32 v74, v73
	v_pk_fma_f32 v[62:63], s[6:7], v[62:63], v[66:67] neg_lo:[1,0,0] neg_hi:[1,0,0]
	v_pk_fma_f32 v[66:67], s[6:7], v[74:75], v[68:69] neg_lo:[1,0,0] neg_hi:[1,0,0]
	v_mov_b32_e32 v82, v77
	v_pk_mul_f32 v[70:71], v[64:65], v[64:65]
	v_pk_mul_f32 v[68:69], v[66:67], v[66:67]
	v_pk_fma_f32 v[56:57], s[6:7], v[82:83], v[56:57] neg_lo:[1,0,0] neg_hi:[1,0,0]
	v_pk_mul_f32 v[84:85], v[62:63], v[62:63]
	v_pk_mul_f32 v[72:73], v[56:57], v[56:57]
	v_mov_b32_e32 v74, v68
	v_mov_b32_e32 v75, v70
	v_mov_b32_e32 v70, v69
	v_pk_add_f32 v[68:69], v[74:75], v[70:71]
	v_mov_b32_e32 v70, v72
	v_mov_b32_e32 v71, v84
	v_pk_add_f32 v[68:69], v[68:69], v[70:71]
	v_mov_b32_e32 v84, v73
	v_pk_add_f32 v[68:69], v[68:69], v[84:85]
	s_waitcnt lgkmcnt(0)
	s_nop 1
	v_add_f32_dpp v68, v68, v68 quad_perm:[1,0,3,2] row_mask:0xf bank_mask:0xf
	v_add_f32_dpp v69, v69, v69 quad_perm:[1,0,3,2] row_mask:0xf bank_mask:0xf
	s_waitcnt lgkmcnt(0)
	s_nop 1
	v_add_f32_dpp v68, v68, v68 quad_perm:[2,3,0,1] row_mask:0xf bank_mask:0xf
	v_add_f32_dpp v69, v69, v69 quad_perm:[2,3,0,1] row_mask:0xf bank_mask:0xf
	s_waitcnt lgkmcnt(0)
	s_nop 1
	v_add_f32_dpp v68, v68, v68 row_half_mirror row_mask:0xf bank_mask:0xf
	v_add_f32_dpp v69, v69, v69 row_half_mirror row_mask:0xf bank_mask:0xf
	s_waitcnt lgkmcnt(0)
	s_nop 1
	v_add_f32_dpp v68, v68, v68 row_mirror row_mask:0xf bank_mask:0xf
	v_add_f32_dpp v69, v69, v69 row_mirror row_mask:0xf bank_mask:0xf
	s_waitcnt lgkmcnt(0)
	v_mov_b32_e32 v70, v68
	v_mov_b32_e32 v71, v69
	s_nop 1
	v_permlane16_swap_b32_e32 v70, v68
	v_permlane16_swap_b32_e32 v71, v69
	v_add_f32_e32 v68, v68, v70
	v_add_f32_e32 v69, v69, v71
	s_nop 0
	v_pk_fma_f32 v[68:69], v[68:69], s[42:43], v[20:21] op_sel_hi:[1,0,0]
	s_nop 0
	v_mul_f32_e32 v70, 0x4b800000, v69
	v_cmp_gt_f32_e64 s[4:5], s41, v69
	v_cmp_gt_f32_e32 vcc, s41, v68
	s_nop 0
	v_cndmask_b32_e64 v69, v69, v70, s[4:5]
	v_rsq_f32_e32 v69, v69
	s_nop 0
	v_mul_f32_e32 v70, 0x45800000, v69
	v_cndmask_b32_e64 v69, v69, v70, s[4:5]
	v_mul_f32_e32 v82, v171, v69
	v_mul_f32_e32 v69, 0x4b800000, v68
	v_cndmask_b32_e32 v68, v68, v69, vcc
	v_rsq_f32_e32 v68, v68
	s_nop 0
	v_mul_f32_e32 v69, 0x45800000, v68
	v_cndmask_b32_e32 v68, v68, v69, vcc
	v_mul_f32_e32 v83, v171, v68
	ds_read2st64_b32 v[68:69], v104 offset0:10 offset1:11
	ds_read2st64_b32 v[70:71], v104 offset0:26 offset1:27
	ds_read2st64_b32 v[74:75], v104 offset0:42 offset1:43
	ds_read2st64_b32 v[76:77], v104 offset0:58 offset1:59
	s_waitcnt lgkmcnt(3)
	v_mov_b32_e32 v72, v68
	s_waitcnt lgkmcnt(2)
	v_mov_b32_e32 v73, v70
	v_mov_b32_e32 v70, v69
	v_pk_fma_f32 v[54:55], s[6:7], v[72:73], v[54:55] neg_lo:[1,0,0] neg_hi:[1,0,0]
	s_waitcnt lgkmcnt(1)
	v_mov_b32_e32 v84, v74
	s_waitcnt lgkmcnt(0)
	v_mov_b32_e32 v85, v76
	v_pk_fma_f32 v[52:53], s[6:7], v[70:71], v[52:53] neg_lo:[1,0,0] neg_hi:[1,0,0]
	v_mov_b32_e32 v76, v75
	v_pk_mul_f32 v[72:73], v[54:55], v[54:55]
	v_pk_fma_f32 v[50:51], s[6:7], v[84:85], v[50:51] neg_lo:[1,0,0] neg_hi:[1,0,0]
	v_pk_mul_f32 v[68:69], v[52:53], v[52:53]
	v_pk_fma_f32 v[44:45], s[6:7], v[76:77], v[44:45] neg_lo:[1,0,0] neg_hi:[1,0,0]
	v_pk_mul_f32 v[84:85], v[50:51], v[50:51]
	v_pk_mul_f32 v[70:71], v[44:45], v[44:45]
	v_mov_b32_e32 v74, v68
	v_mov_b32_e32 v75, v72
	v_mov_b32_e32 v72, v69
	v_pk_add_f32 v[68:69], v[74:75], v[72:73]
	v_mov_b32_e32 v72, v70
	v_mov_b32_e32 v73, v84
	v_pk_add_f32 v[68:69], v[68:69], v[72:73]
	v_mov_b32_e32 v84, v71
	v_pk_add_f32 v[68:69], v[68:69], v[84:85]
	s_waitcnt lgkmcnt(0)
	s_nop 1
	v_add_f32_dpp v68, v68, v68 quad_perm:[1,0,3,2] row_mask:0xf bank_mask:0xf
	v_add_f32_dpp v69, v69, v69 quad_perm:[1,0,3,2] row_mask:0xf bank_mask:0xf
	s_waitcnt lgkmcnt(0)
	s_nop 1
	v_add_f32_dpp v68, v68, v68 quad_perm:[2,3,0,1] row_mask:0xf bank_mask:0xf
	v_add_f32_dpp v69, v69, v69 quad_perm:[2,3,0,1] row_mask:0xf bank_mask:0xf
	s_waitcnt lgkmcnt(0)
	s_nop 1
	v_add_f32_dpp v68, v68, v68 row_half_mirror row_mask:0xf bank_mask:0xf
	v_add_f32_dpp v69, v69, v69 row_half_mirror row_mask:0xf bank_mask:0xf
	s_waitcnt lgkmcnt(0)
	s_nop 1
	v_add_f32_dpp v68, v68, v68 row_mirror row_mask:0xf bank_mask:0xf
	v_add_f32_dpp v69, v69, v69 row_mirror row_mask:0xf bank_mask:0xf
	s_waitcnt lgkmcnt(0)
	v_mov_b32_e32 v70, v68
	v_mov_b32_e32 v71, v69
	s_nop 1
	v_permlane16_swap_b32_e32 v70, v68
	v_permlane16_swap_b32_e32 v71, v69
	v_add_f32_e32 v68, v68, v70
	v_add_f32_e32 v69, v69, v71
	s_nop 0
	v_pk_fma_f32 v[68:69], v[68:69], s[42:43], v[20:21] op_sel_hi:[1,0,0]
	s_nop 0
	v_mul_f32_e32 v70, 0x4b800000, v69
	v_cmp_gt_f32_e64 s[4:5], s41, v69
	v_cmp_gt_f32_e32 vcc, s41, v68
	s_nop 0
	v_cndmask_b32_e64 v69, v69, v70, s[4:5]
	v_rsq_f32_e32 v69, v69
	s_nop 0
	v_mul_f32_e32 v70, 0x45800000, v69
	v_cndmask_b32_e64 v69, v69, v70, s[4:5]
	v_mul_f32_e32 v84, v171, v69
	v_mul_f32_e32 v69, 0x4b800000, v68
	v_cndmask_b32_e32 v68, v68, v69, vcc
	v_rsq_f32_e32 v68, v68
	s_nop 0
	v_mul_f32_e32 v69, 0x45800000, v68
	v_cndmask_b32_e32 v68, v68, v69, vcc
	v_mul_f32_e32 v85, v171, v68
	ds_read2st64_b32 v[68:69], v104 offset0:12 offset1:13
	ds_read2st64_b32 v[70:71], v104 offset0:28 offset1:29
	ds_read2st64_b32 v[74:75], v104 offset0:44 offset1:45
	ds_read2st64_b32 v[76:77], v104 offset0:60 offset1:61
	s_waitcnt lgkmcnt(3)
	v_mov_b32_e32 v72, v68
	s_waitcnt lgkmcnt(2)
	v_mov_b32_e32 v73, v70
	v_mov_b32_e32 v70, v69
	v_pk_fma_f32 v[42:43], s[6:7], v[72:73], v[42:43] neg_lo:[1,0,0] neg_hi:[1,0,0]
	s_waitcnt lgkmcnt(1)
	v_mov_b32_e32 v88, v74
	s_waitcnt lgkmcnt(0)
	v_mov_b32_e32 v89, v76
	v_pk_fma_f32 v[40:41], s[6:7], v[70:71], v[40:41] neg_lo:[1,0,0] neg_hi:[1,0,0]
	v_mov_b32_e32 v76, v75
	v_pk_mul_f32 v[72:73], v[42:43], v[42:43]
	v_pk_fma_f32 v[38:39], s[6:7], v[88:89], v[38:39] neg_lo:[1,0,0] neg_hi:[1,0,0]
	v_pk_mul_f32 v[68:69], v[40:41], v[40:41]
	v_pk_fma_f32 v[36:37], s[6:7], v[76:77], v[36:37] neg_lo:[1,0,0] neg_hi:[1,0,0]
	v_pk_mul_f32 v[88:89], v[38:39], v[38:39]
	v_pk_mul_f32 v[70:71], v[36:37], v[36:37]
	v_mov_b32_e32 v74, v68
	v_mov_b32_e32 v75, v72
	v_mov_b32_e32 v72, v69
	v_pk_add_f32 v[68:69], v[74:75], v[72:73]
	v_mov_b32_e32 v72, v70
	v_mov_b32_e32 v73, v88
	v_pk_add_f32 v[68:69], v[68:69], v[72:73]
	v_mov_b32_e32 v88, v71
	v_pk_add_f32 v[68:69], v[68:69], v[88:89]
	s_waitcnt lgkmcnt(0)
	s_nop 1
	v_add_f32_dpp v68, v68, v68 quad_perm:[1,0,3,2] row_mask:0xf bank_mask:0xf
	v_add_f32_dpp v69, v69, v69 quad_perm:[1,0,3,2] row_mask:0xf bank_mask:0xf
	s_waitcnt lgkmcnt(0)
	s_nop 1
	v_add_f32_dpp v68, v68, v68 quad_perm:[2,3,0,1] row_mask:0xf bank_mask:0xf
	v_add_f32_dpp v69, v69, v69 quad_perm:[2,3,0,1] row_mask:0xf bank_mask:0xf
	s_waitcnt lgkmcnt(0)
	s_nop 1
	v_add_f32_dpp v68, v68, v68 row_half_mirror row_mask:0xf bank_mask:0xf
	v_add_f32_dpp v69, v69, v69 row_half_mirror row_mask:0xf bank_mask:0xf
	s_waitcnt lgkmcnt(0)
	s_nop 1
	v_add_f32_dpp v68, v68, v68 row_mirror row_mask:0xf bank_mask:0xf
	v_add_f32_dpp v69, v69, v69 row_mirror row_mask:0xf bank_mask:0xf
	s_waitcnt lgkmcnt(0)
	v_mov_b32_e32 v70, v68
	v_mov_b32_e32 v71, v69
	s_nop 1
	v_permlane16_swap_b32_e32 v70, v68
	v_permlane16_swap_b32_e32 v71, v69
	v_add_f32_e32 v68, v68, v70
	v_add_f32_e32 v69, v69, v71
	s_nop 0
	v_pk_fma_f32 v[68:69], v[68:69], s[42:43], v[20:21] op_sel_hi:[1,0,0]
	s_nop 0
	v_mul_f32_e32 v70, 0x4b800000, v69
	v_cmp_gt_f32_e64 s[4:5], s41, v69
	v_cmp_gt_f32_e32 vcc, s41, v68
	s_nop 0
	v_cndmask_b32_e64 v69, v69, v70, s[4:5]
	v_rsq_f32_e32 v69, v69
	s_nop 0
	v_mul_f32_e32 v70, 0x45800000, v69
	v_cndmask_b32_e64 v69, v69, v70, s[4:5]
	v_mul_f32_e32 v88, v171, v69
	v_mul_f32_e32 v69, 0x4b800000, v68
	v_cndmask_b32_e32 v68, v68, v69, vcc
	v_rsq_f32_e32 v68, v68
	s_nop 0
	v_mul_f32_e32 v69, 0x45800000, v68
	v_cndmask_b32_e32 v68, v68, v69, vcc
	v_mul_f32_e32 v89, v171, v68
	ds_read2st64_b32 v[68:69], v104 offset0:14 offset1:15
	ds_read2st64_b32 v[72:73], v104 offset0:30 offset1:31
	ds_read2st64_b32 v[74:75], v104 offset0:46 offset1:47
	ds_read2st64_b32 v[76:77], v104 offset0:62 offset1:63
	s_waitcnt lgkmcnt(0)
	s_waitcnt lgkmcnt(3)
	v_mov_b32_e32 v70, v68
	s_waitcnt lgkmcnt(2)
	v_mov_b32_e32 v71, v72
	v_mov_b32_e32 v72, v69
	v_pk_fma_f32 v[26:27], s[6:7], v[70:71], v[26:27] neg_lo:[1,0,0] neg_hi:[1,0,0]
	s_waitcnt lgkmcnt(1)
	v_mov_b32_e32 v90, v74
	s_waitcnt lgkmcnt(0)
	v_mov_b32_e32 v91, v76
	v_pk_fma_f32 v[4:5], s[6:7], v[72:73], v[4:5] neg_lo:[1,0,0] neg_hi:[1,0,0]
	v_mov_b32_e32 v76, v75
	v_pk_mul_f32 v[70:71], v[26:27], v[26:27]
	v_pk_fma_f32 v[6:7], s[6:7], v[90:91], v[6:7] neg_lo:[1,0,0] neg_hi:[1,0,0]
	v_pk_mul_f32 v[68:69], v[4:5], v[4:5]
	v_pk_fma_f32 v[2:3], s[6:7], v[76:77], v[2:3] neg_lo:[1,0,0] neg_hi:[1,0,0]
	v_pk_mul_f32 v[90:91], v[6:7], v[6:7]
	v_pk_mul_f32 v[72:73], v[2:3], v[2:3]
	v_mov_b32_e32 v74, v68
	v_mov_b32_e32 v75, v70
	v_mov_b32_e32 v70, v69
	v_pk_add_f32 v[68:69], v[74:75], v[70:71]
	v_mov_b32_e32 v70, v72
	v_mov_b32_e32 v71, v90
	v_pk_add_f32 v[68:69], v[68:69], v[70:71]
	v_mov_b32_e32 v90, v73
	v_pk_add_f32 v[68:69], v[68:69], v[90:91]
	s_waitcnt lgkmcnt(0)
	s_nop 1
	v_add_f32_dpp v68, v68, v68 quad_perm:[1,0,3,2] row_mask:0xf bank_mask:0xf
	v_add_f32_dpp v69, v69, v69 quad_perm:[1,0,3,2] row_mask:0xf bank_mask:0xf
	s_waitcnt lgkmcnt(0)
	s_nop 1
	v_add_f32_dpp v68, v68, v68 quad_perm:[2,3,0,1] row_mask:0xf bank_mask:0xf
	v_add_f32_dpp v69, v69, v69 quad_perm:[2,3,0,1] row_mask:0xf bank_mask:0xf
	s_waitcnt lgkmcnt(0)
	s_nop 1
	v_add_f32_dpp v68, v68, v68 row_half_mirror row_mask:0xf bank_mask:0xf
	v_add_f32_dpp v69, v69, v69 row_half_mirror row_mask:0xf bank_mask:0xf
	s_waitcnt lgkmcnt(0)
	s_nop 1
	v_add_f32_dpp v68, v68, v68 row_mirror row_mask:0xf bank_mask:0xf
	v_add_f32_dpp v69, v69, v69 row_mirror row_mask:0xf bank_mask:0xf
	s_waitcnt lgkmcnt(0)
	v_mov_b32_e32 v70, v68
	v_mov_b32_e32 v71, v69
	s_nop 1
	v_permlane16_swap_b32_e32 v70, v68
	v_permlane16_swap_b32_e32 v71, v69
	v_add_f32_e32 v68, v68, v70
	v_add_f32_e32 v69, v69, v71
	s_nop 0
	v_pk_fma_f32 v[20:21], v[68:69], s[42:43], v[20:21] op_sel_hi:[1,0,0]
	v_lshlrev_b32_e32 v69, 1, v164
	v_mul_f32_e32 v68, 0x4b800000, v21
	v_cmp_gt_f32_e64 s[4:5], s41, v21
	v_cmp_gt_f32_e32 vcc, s41, v20
	s_nop 0
	v_cndmask_b32_e64 v21, v21, v68, s[4:5]
	v_rsq_f32_e32 v21, v21
	s_nop 0
	v_mul_f32_e32 v68, 0x45800000, v21
	v_cndmask_b32_e64 v21, v21, v68, s[4:5]
	v_mul_f32_e32 v68, 0x4b800000, v20
	v_cndmask_b32_e32 v20, v20, v68, vcc
	v_rsq_f32_e32 v20, v20
	v_mul_f32_e32 v21, v171, v21
	s_lshl_b64 s[4:5], s[18:19], 11
	s_add_u32 s1, s9, s4
	v_mul_f32_e32 v68, 0x45800000, v20
	v_cndmask_b32_e32 v20, v20, v68, vcc
	v_lshlrev_b32_e32 v68, 10, v173
	v_add3_u32 v68, s0, v68, v69
	v_bfe_u32 v69, v12, 16, 1
	v_add3_u32 v12, v12, v69, s97
	ds_write_b16_d16_hi v68, v12
	v_mul_f32_e32 v12, v14, v93
	v_mul_f32_e32 v12, v103, v12
	v_bfe_u32 v14, v12, 16, 1
	v_add3_u32 v12, v12, v14, s97
	ds_write_b16_d16_hi v68, v12 offset:256
	v_mul_f32_e32 v12, v22, v86
	v_mul_f32_e32 v12, v103, v12
	v_bfe_u32 v14, v12, 16, 1
	v_add3_u32 v12, v12, v14, s97
	ds_write_b16_d16_hi v68, v12 offset:512
	v_mul_f32_e32 v12, v24, v87
	v_mul_f32_e32 v12, v103, v12
	v_bfe_u32 v14, v12, 16, 1
	v_add3_u32 v12, v12, v14, s97
	ds_write_b16_d16_hi v68, v12 offset:768
	v_mul_f32_e32 v12, v32, v80
	v_mul_f32_e32 v12, v103, v12
	v_bfe_u32 v14, v12, 16, 1
	v_add3_u32 v12, v12, v14, s97
	ds_write_b16_d16_hi v68, v12 offset:2048
	v_mul_f32_e32 v12, v34, v81
	v_mul_f32_e32 v12, v103, v12
	v_bfe_u32 v14, v12, 16, 1
	v_add3_u32 v12, v12, v14, s97
	ds_write_b16_d16_hi v68, v12 offset:2304
	v_mul_f32_e32 v12, v46, v78
	v_mul_f32_e32 v12, v103, v12
	v_bfe_u32 v14, v12, 16, 1
	v_add3_u32 v12, v12, v14, s97
	ds_write_b16_d16_hi v68, v12 offset:2560
	v_mul_f32_e32 v12, v60, v79
	v_mul_f32_e32 v12, v103, v12
	v_bfe_u32 v14, v12, 16, 1
	v_add3_u32 v12, v12, v14, s97
	ds_write_b16_d16_hi v68, v12 offset:2816
	v_mul_f32_e32 v12, v64, v82
	v_mul_f32_e32 v12, v103, v12
	v_bfe_u32 v14, v12, 16, 1
	v_add3_u32 v12, v12, v14, s97
	ds_write_b16_d16_hi v68, v12 offset:4096
	v_mul_f32_e32 v12, v66, v83
	v_mul_f32_e32 v12, v103, v12
	v_bfe_u32 v14, v12, 16, 1
	v_add3_u32 v12, v12, v14, s97
	ds_write_b16_d16_hi v68, v12 offset:4352
	v_mul_f32_e32 v12, v54, v84
	v_mul_f32_e32 v12, v103, v12
	v_bfe_u32 v14, v12, 16, 1
	v_add3_u32 v12, v12, v14, s97
	ds_write_b16_d16_hi v68, v12 offset:4608
	v_mul_f32_e32 v12, v52, v85
	v_mul_f32_e32 v12, v103, v12
	v_bfe_u32 v14, v12, 16, 1
	v_add3_u32 v12, v12, v14, s97
	ds_write_b16_d16_hi v68, v12 offset:4864
	v_mul_f32_e32 v12, v42, v88
	v_mul_f32_e32 v12, v103, v12
	v_bfe_u32 v14, v12, 16, 1
	v_add3_u32 v12, v12, v14, s97
	ds_write_b16_d16_hi v68, v12 offset:6144
	v_mul_f32_e32 v12, v40, v89
	v_mul_f32_e32 v12, v103, v12
	v_bfe_u32 v14, v12, 16, 1
	v_add3_u32 v12, v12, v14, s97
	ds_write_b16_d16_hi v68, v12 offset:6400
	v_mul_f32_e32 v12, v26, v21
	v_mul_f32_e32 v20, v171, v20
	v_mul_f32_e32 v12, v103, v12
	v_bfe_u32 v14, v12, 16, 1
	v_mul_f32_e32 v4, v4, v20
	v_add3_u32 v12, v12, v14, s97
	v_mul_f32_e32 v4, v103, v4
	ds_write_b16_d16_hi v68, v12 offset:6656
	v_bfe_u32 v12, v4, 16, 1
	v_add3_u32 v4, v4, v12, s97
	ds_write_b16_d16_hi v68, v4 offset:6912
	v_mul_f32_e32 v4, v13, v92
	s_waitcnt vmcnt(2)
	v_mul_f32_e32 v4, v102, v4
	v_bfe_u32 v12, v4, 16, 1
	v_add3_u32 v4, v4, v12, s97
	ds_write_b16_d16_hi v68, v4 offset:64
	v_mul_f32_e32 v4, v15, v93
	v_mul_f32_e32 v4, v102, v4
	v_bfe_u32 v12, v4, 16, 1
	v_add3_u32 v4, v4, v12, s97
	ds_write_b16_d16_hi v68, v4 offset:320
	v_mul_f32_e32 v4, v23, v86
	v_mul_f32_e32 v4, v102, v4
	v_bfe_u32 v12, v4, 16, 1
	v_add3_u32 v4, v4, v12, s97
	ds_write_b16_d16_hi v68, v4 offset:576
	v_mul_f32_e32 v4, v25, v87
	v_mul_f32_e32 v4, v102, v4
	v_bfe_u32 v12, v4, 16, 1
	v_add3_u32 v4, v4, v12, s97
	ds_write_b16_d16_hi v68, v4 offset:832
	v_mul_f32_e32 v4, v33, v80
	v_mul_f32_e32 v4, v102, v4
	v_bfe_u32 v12, v4, 16, 1
	v_add3_u32 v4, v4, v12, s97
	ds_write_b16_d16_hi v68, v4 offset:2112
	v_mul_f32_e32 v4, v35, v81
	v_mul_f32_e32 v4, v102, v4
	v_bfe_u32 v12, v4, 16, 1
	v_add3_u32 v4, v4, v12, s97
	ds_write_b16_d16_hi v68, v4 offset:2368
	v_mul_f32_e32 v4, v47, v78
	v_mul_f32_e32 v4, v102, v4
	v_bfe_u32 v12, v4, 16, 1
	v_add3_u32 v4, v4, v12, s97
	ds_write_b16_d16_hi v68, v4 offset:2624
	v_mul_f32_e32 v4, v61, v79
	v_mul_f32_e32 v4, v102, v4
	v_bfe_u32 v12, v4, 16, 1
	v_add3_u32 v4, v4, v12, s97
	ds_write_b16_d16_hi v68, v4 offset:2880
	v_mul_f32_e32 v4, v65, v82
	v_mul_f32_e32 v4, v102, v4
	v_bfe_u32 v12, v4, 16, 1
	v_add3_u32 v4, v4, v12, s97
	ds_write_b16_d16_hi v68, v4 offset:4160
	v_mul_f32_e32 v4, v67, v83
	v_mul_f32_e32 v4, v102, v4
	v_bfe_u32 v12, v4, 16, 1
	v_add3_u32 v4, v4, v12, s97
	ds_write_b16_d16_hi v68, v4 offset:4416
	v_mul_f32_e32 v4, v55, v84
	v_mul_f32_e32 v4, v102, v4
	v_bfe_u32 v12, v4, 16, 1
	v_add3_u32 v4, v4, v12, s97
	ds_write_b16_d16_hi v68, v4 offset:4672
	v_mul_f32_e32 v4, v53, v85
	v_mul_f32_e32 v4, v102, v4
	v_bfe_u32 v12, v4, 16, 1
	v_add3_u32 v4, v4, v12, s97
	ds_write_b16_d16_hi v68, v4 offset:4928
	v_mul_f32_e32 v4, v43, v88
	v_mul_f32_e32 v4, v102, v4
	v_bfe_u32 v12, v4, 16, 1
	v_add3_u32 v4, v4, v12, s97
	ds_write_b16_d16_hi v68, v4 offset:6208
	v_mul_f32_e32 v4, v41, v89
	v_mul_f32_e32 v4, v102, v4
	v_bfe_u32 v12, v4, 16, 1
	v_add3_u32 v4, v4, v12, s97
	ds_write_b16_d16_hi v68, v4 offset:6464
	v_mul_f32_e32 v4, v27, v21
	v_mul_f32_e32 v4, v102, v4
	v_bfe_u32 v12, v4, 16, 1
	v_add3_u32 v4, v4, v12, s97
	ds_write_b16_d16_hi v68, v4 offset:6720
	v_mul_f32_e32 v4, v5, v20
	v_mul_f32_e32 v4, v102, v4
	v_bfe_u32 v5, v4, 16, 1
	v_add3_u32 v4, v4, v5, s97
	ds_write_b16_d16_hi v68, v4 offset:6976
	v_mul_f32_e32 v4, v8, v92
	s_waitcnt vmcnt(1)
	v_mul_f32_e32 v4, v101, v4
	v_bfe_u32 v5, v4, 16, 1
	v_add3_u32 v4, v4, v5, s97
	ds_write_b16_d16_hi v68, v4 offset:128
	v_mul_f32_e32 v4, v10, v93
	v_mul_f32_e32 v4, v101, v4
	v_bfe_u32 v5, v4, 16, 1
	v_add3_u32 v4, v4, v5, s97
	ds_write_b16_d16_hi v68, v4 offset:384
	v_mul_f32_e32 v4, v16, v86
	v_mul_f32_e32 v4, v101, v4
	v_bfe_u32 v5, v4, 16, 1
	v_add3_u32 v4, v4, v5, s97
	ds_write_b16_d16_hi v68, v4 offset:640
	v_mul_f32_e32 v4, v18, v87
	v_mul_f32_e32 v4, v101, v4
	v_bfe_u32 v5, v4, 16, 1
	v_add3_u32 v4, v4, v5, s97
	ds_write_b16_d16_hi v68, v4 offset:896
	v_mul_f32_e32 v4, v28, v80
	v_mul_f32_e32 v4, v101, v4
	v_bfe_u32 v5, v4, 16, 1
	v_add3_u32 v4, v4, v5, s97
	ds_write_b16_d16_hi v68, v4 offset:2176
	v_mul_f32_e32 v4, v30, v81
	v_mul_f32_e32 v4, v101, v4
	v_bfe_u32 v5, v4, 16, 1
	v_add3_u32 v4, v4, v5, s97
	ds_write_b16_d16_hi v68, v4 offset:2432
	v_mul_f32_e32 v4, v48, v78
	v_mul_f32_e32 v4, v101, v4
	v_bfe_u32 v5, v4, 16, 1
	v_add3_u32 v4, v4, v5, s97
	ds_write_b16_d16_hi v68, v4 offset:2688
	v_mul_f32_e32 v4, v58, v79
	v_mul_f32_e32 v4, v101, v4
	v_bfe_u32 v5, v4, 16, 1
	v_add3_u32 v4, v4, v5, s97
	ds_write_b16_d16_hi v68, v4 offset:2944
	v_mul_f32_e32 v4, v62, v82
	v_mul_f32_e32 v4, v101, v4
	v_bfe_u32 v5, v4, 16, 1
	v_add3_u32 v4, v4, v5, s97
	ds_write_b16_d16_hi v68, v4 offset:4224
	v_mul_f32_e32 v4, v56, v83
	v_mul_f32_e32 v4, v101, v4
	v_bfe_u32 v5, v4, 16, 1
	v_add3_u32 v4, v4, v5, s97
	ds_write_b16_d16_hi v68, v4 offset:4480
	v_mul_f32_e32 v4, v50, v84
	v_mul_f32_e32 v4, v101, v4
	v_bfe_u32 v5, v4, 16, 1
	v_add3_u32 v4, v4, v5, s97
	ds_write_b16_d16_hi v68, v4 offset:4736
	v_mul_f32_e32 v4, v44, v85
	v_mul_f32_e32 v4, v101, v4
	v_bfe_u32 v5, v4, 16, 1
	v_add3_u32 v4, v4, v5, s97
	ds_write_b16_d16_hi v68, v4 offset:4992
	v_mul_f32_e32 v4, v38, v88
	v_mul_f32_e32 v4, v101, v4
	v_bfe_u32 v5, v4, 16, 1
	v_add3_u32 v4, v4, v5, s97
	ds_write_b16_d16_hi v68, v4 offset:6272
	v_mul_f32_e32 v4, v36, v89
	v_mul_f32_e32 v4, v101, v4
	v_bfe_u32 v5, v4, 16, 1
	v_add3_u32 v4, v4, v5, s97
	ds_write_b16_d16_hi v68, v4 offset:6528
	v_mul_f32_e32 v4, v6, v21
	v_mul_f32_e32 v4, v101, v4
	v_bfe_u32 v5, v4, 16, 1
	v_mul_f32_e32 v2, v2, v20
	v_add3_u32 v4, v4, v5, s97
	v_mul_f32_e32 v2, v101, v2
	ds_write_b16_d16_hi v68, v4 offset:6784
	v_bfe_u32 v4, v2, 16, 1
	v_add3_u32 v2, v2, v4, s97
	ds_write_b16_d16_hi v68, v2 offset:7040
	v_mul_f32_e32 v2, v9, v92
	s_waitcnt vmcnt(0)
	v_mul_f32_e32 v2, v100, v2
	v_bfe_u32 v4, v2, 16, 1
	v_add3_u32 v2, v2, v4, s97
	ds_write_b16_d16_hi v68, v2 offset:192
	v_mul_f32_e32 v2, v11, v93
	v_mul_f32_e32 v2, v100, v2
	v_bfe_u32 v4, v2, 16, 1
	v_add3_u32 v2, v2, v4, s97
	ds_write_b16_d16_hi v68, v2 offset:448
	v_mul_f32_e32 v2, v17, v86
	v_mul_f32_e32 v2, v100, v2
	v_bfe_u32 v4, v2, 16, 1
	v_add3_u32 v2, v2, v4, s97
	ds_write_b16_d16_hi v68, v2 offset:704
	v_mul_f32_e32 v2, v19, v87
	v_mul_f32_e32 v2, v100, v2
	v_bfe_u32 v4, v2, 16, 1
	v_add3_u32 v2, v2, v4, s97
	ds_write_b16_d16_hi v68, v2 offset:960
	v_mul_f32_e32 v2, v29, v80
	v_mul_f32_e32 v2, v100, v2
	v_bfe_u32 v4, v2, 16, 1
	v_add3_u32 v2, v2, v4, s97
	ds_write_b16_d16_hi v68, v2 offset:2240
	v_mul_f32_e32 v2, v31, v81
	v_mul_f32_e32 v2, v100, v2
	v_bfe_u32 v4, v2, 16, 1
	v_add3_u32 v2, v2, v4, s97
	ds_write_b16_d16_hi v68, v2 offset:2496
	v_mul_f32_e32 v2, v49, v78
	v_mul_f32_e32 v2, v100, v2
	v_bfe_u32 v4, v2, 16, 1
	v_add3_u32 v2, v2, v4, s97
	ds_write_b16_d16_hi v68, v2 offset:2752
	v_mul_f32_e32 v2, v59, v79
	v_mul_f32_e32 v2, v100, v2
	v_bfe_u32 v4, v2, 16, 1
	v_add3_u32 v2, v2, v4, s97
	ds_write_b16_d16_hi v68, v2 offset:3008
	v_mul_f32_e32 v2, v63, v82
	v_mul_f32_e32 v2, v100, v2
	v_bfe_u32 v4, v2, 16, 1
	v_add3_u32 v2, v2, v4, s97
	ds_write_b16_d16_hi v68, v2 offset:4288
	v_mul_f32_e32 v2, v57, v83
	v_mul_f32_e32 v2, v100, v2
	v_bfe_u32 v4, v2, 16, 1
	v_add3_u32 v2, v2, v4, s97
	ds_write_b16_d16_hi v68, v2 offset:4544
	v_mul_f32_e32 v2, v51, v84
	v_mul_f32_e32 v2, v100, v2
	v_bfe_u32 v4, v2, 16, 1
	v_add3_u32 v2, v2, v4, s97
	ds_write_b16_d16_hi v68, v2 offset:4800
	v_mul_f32_e32 v2, v45, v85
	v_mul_f32_e32 v2, v100, v2
	v_bfe_u32 v4, v2, 16, 1
	v_add3_u32 v2, v2, v4, s97
	ds_write_b16_d16_hi v68, v2 offset:5056
	v_mul_f32_e32 v2, v39, v88
	v_mul_f32_e32 v2, v100, v2
	v_bfe_u32 v4, v2, 16, 1
	v_add3_u32 v2, v2, v4, s97
	ds_write_b16_d16_hi v68, v2 offset:6336
	v_mul_f32_e32 v2, v37, v89
	v_mul_f32_e32 v2, v100, v2
	v_bfe_u32 v4, v2, 16, 1
	v_add3_u32 v2, v2, v4, s97
	ds_write_b16_d16_hi v68, v2 offset:6592
	v_mul_f32_e32 v2, v7, v21
	v_mul_f32_e32 v2, v100, v2
	v_bfe_u32 v4, v2, 16, 1
	v_add3_u32 v2, v2, v4, s97
	ds_write_b16_d16_hi v68, v2 offset:6848
	v_mul_f32_e32 v2, v3, v20
	v_mul_f32_e32 v2, v100, v2
	v_bfe_u32 v3, v2, 16, 1
	v_add3_u32 v2, v2, v3, s97
	ds_write_b16_d16_hi v68, v2 offset:7104
	v_lshrrev_b32_e32 v10, 4, v172
	v_add_u32_e32 v11, s0, v178
	s_waitcnt lgkmcnt(0)
	v_lshl_add_u32 v2, v10, 8, v11
	s_addc_u32 s5, s16, s5
	s_lshl_b32 s4, s22, 1
	ds_read_b128 v[2:5], v2
	s_add_u32 s4, s1, s4
	s_addc_u32 s5, s5, 0
	v_lshl_add_u64 v[6:7], s[4:5], 0, v[178:179]
	v_lshlrev_b32_e32 v178, 11, v10
	v_lshl_add_u64 v[8:9], v[6:7], 0, v[178:179]
	s_waitcnt lgkmcnt(0)
	global_store_dwordx4 v[8:9], v[2:5], off sc1
	v_or_b32_e32 v8, 4, v10
	v_lshlrev_b32_e32 v178, 11, v8
	v_lshl_add_u32 v2, v8, 8, v11
	ds_read_b128 v[2:5], v2
	v_lshl_add_u64 v[8:9], v[6:7], 0, v[178:179]
	s_waitcnt lgkmcnt(0)
	global_store_dwordx4 v[8:9], v[2:5], off sc1
	v_or_b32_e32 v8, 8, v10
	s_nop 0
	v_lshl_add_u32 v2, v8, 8, v11
	ds_read_b128 v[2:5], v2
	v_lshlrev_b32_e32 v178, 11, v8
	v_lshl_add_u64 v[8:9], v[6:7], 0, v[178:179]
	s_waitcnt lgkmcnt(0)
	global_store_dwordx4 v[8:9], v[2:5], off sc1
	v_or_b32_e32 v8, 12, v10
	s_nop 0
	v_lshl_add_u32 v2, v8, 8, v11
	ds_read_b128 v[2:5], v2
	v_lshlrev_b32_e32 v178, 11, v8
	v_lshl_add_u64 v[8:9], v[6:7], 0, v[178:179]
	s_waitcnt lgkmcnt(0)
	global_store_dwordx4 v[8:9], v[2:5], off sc1
	v_or_b32_e32 v8, 16, v10
	s_nop 0
	v_lshl_add_u32 v2, v8, 8, v11
	ds_read_b128 v[2:5], v2
	v_lshlrev_b32_e32 v178, 11, v8
	v_lshl_add_u64 v[8:9], v[6:7], 0, v[178:179]
	s_waitcnt lgkmcnt(0)
	global_store_dwordx4 v[8:9], v[2:5], off sc1
	v_or_b32_e32 v8, 20, v10
	s_nop 0
	v_lshl_add_u32 v2, v8, 8, v11
	ds_read_b128 v[2:5], v2
	v_lshlrev_b32_e32 v178, 11, v8
	v_lshl_add_u64 v[8:9], v[6:7], 0, v[178:179]
	s_waitcnt lgkmcnt(0)
	global_store_dwordx4 v[8:9], v[2:5], off sc1
	v_or_b32_e32 v8, 24, v10
	s_nop 0
	v_lshl_add_u32 v2, v8, 8, v11
	ds_read_b128 v[2:5], v2
	v_lshlrev_b32_e32 v178, 11, v8
	v_lshl_add_u64 v[8:9], v[6:7], 0, v[178:179]
	s_waitcnt lgkmcnt(0)
	global_store_dwordx4 v[8:9], v[2:5], off sc1
	v_or_b32_e32 v8, 28, v10
	s_nop 0
	v_lshl_add_u32 v2, v8, 8, v11
	ds_read_b128 v[2:5], v2
	v_lshlrev_b32_e32 v178, 11, v8
	v_lshl_add_u64 v[6:7], v[6:7], 0, v[178:179]
	s_waitcnt lgkmcnt(0)
	global_store_dwordx4 v[6:7], v[2:5], off sc1
	s_branch .LBB0_280

.LBB0_764:
	s_add_u32 s0, s74, s24
	s_addc_u32 s1, s75, s25
	v_lshrrev_b32_e32 v130, 1, v166
	s_add_u32 s24, s0, 0x9c00000
	v_and_b32_e32 v130, 24, v130
	s_addc_u32 s25, s1, 0
	s_lshl_b32 s0, s8, 8
	v_lshl_or_b32 v130, s95, 5, v130
	v_lshl_or_b32 v131, s95, 6, v144
	s_lshl_b32 s34, s11, 8
	v_or_b32_e32 v130, s0, v130
	v_or_b32_e32 v162, s0, v131
	s_add_i32 s0, s34, s29
	v_or_b32_e32 v132, s0, v167
	v_ashrrev_i32_e32 v133, 31, v132
	v_lshlrev_b64 v[138:139], 11, v[132:133]
	v_ashrrev_i32_e32 v163, 31, v162
	v_lshl_add_u64 v[134:135], s[18:19], 0, v[138:139]
	v_lshl_add_u64 v[134:135], v[134:135], 0, v[162:163]
	s_barrier
	v_ashrrev_i32_e32 v131, 31, v130
	v_mov_b64_e32 v[248:249], v[134:135]
	v_lshl_add_u64 v[138:139], s[24:25], 0, v[138:139]
	v_lshlrev_b64 v[164:165], 1, v[130:131]
	v_lshl_add_u64 v[142:143], v[138:139], 0, v[164:165]
	v_mov_b64_e32 v[250:251], v[142:143]
	v_mov_b64_e32 v[212:213], v[248:249]
	global_load_dwordx4 v[212:215], v[212:213], off
	v_mov_b64_e32 v[216:217], v[250:251]
	global_load_dwordx4 v[216:219], v[216:217], off
	v_mov_b64_e32 v[220:221], v[250:251]
	global_load_dwordx4 v[220:223], v[220:221], off offset:256
	s_mov_b32 s98, 0x8000
	s_mov_b32 s99, 0
	v_lshl_add_u64 v[224:225], v[248:249], 0, s[98:99]
	global_load_dwordx4 v[224:227], v[224:225], off
	s_mov_b32 s98, 0x8000
	s_mov_b32 s99, 0
	v_lshl_add_u64 v[228:229], v[250:251], 0, s[98:99]
	global_load_dwordx4 v[228:231], v[228:229], off
	s_mov_b32 s98, 0x8000
	s_mov_b32 s99, 0
	v_lshl_add_u64 v[232:233], v[250:251], 0, s[98:99]
	global_load_dwordx4 v[232:235], v[232:233], off offset:256
	s_mov_b32 s98, 0x10000
	s_mov_b32 s99, 0
	v_lshl_add_u64 v[236:237], v[248:249], 0, s[98:99]
	global_load_dwordx4 v[236:239], v[236:237], off
	s_mov_b32 s98, 0x10000
	s_mov_b32 s99, 0
	v_lshl_add_u64 v[240:241], v[250:251], 0, s[98:99]
	global_load_dwordx4 v[240:243], v[240:241], off
	s_mov_b32 s98, 0x10000
	s_mov_b32 s99, 0
	v_lshl_add_u64 v[244:245], v[250:251], 0, s[98:99]
	global_load_dwordx4 v[244:247], v[244:245], off offset:256
	s_waitcnt vmcnt(0)
	v_mov_b64_e32 v[134:135], v[212:213]
	v_mov_b64_e32 v[136:137], v[214:215]
	v_mov_b64_e32 v[138:139], v[216:217]
	v_mov_b64_e32 v[140:141], v[218:219]
	s_mov_b32 s0, 0x3a000000
	v_and_b32_e32 v171, 64, v205
	v_xor_b32_e32 v170, 16, v205
	v_add_u32_e32 v171, 64, v171
	v_cmp_lt_i32_e32 vcc, v170, v171
	v_xor_b32_e32 v172, 32, v205
	v_and_b32_e32 v169, 63, v166
	v_cndmask_b32_e32 v170, v205, v170, vcc
	v_cmp_lt_i32_e32 vcc, v172, v171
	v_lshlrev_b32_e32 v170, 2, v170
	s_waitcnt vmcnt(0)
	v_cvt_pk_f32_fp8_sdwa v[146:147], v134 src0_sel:WORD_1
	v_cvt_pk_f32_fp8_e32 v[144:145], v134
	v_cvt_pk_f32_fp8_e32 v[148:149], v135
	v_cvt_pk_f32_fp8_sdwa v[134:135], v135 src0_sel:WORD_1
	v_lshlrev_b32_e32 v150, 16, v138
	v_and_b32_e32 v151, 0xffff0000, v138
	v_lshlrev_b32_e32 v138, 16, v139
	v_and_b32_e32 v139, 0xffff0000, v139
	v_pk_fma_f32 v[138:139], v[146:147], s[0:1], v[138:139] op_sel_hi:[1,0,1]
	v_lshlrev_b32_e32 v146, 16, v140
	v_and_b32_e32 v147, 0xffff0000, v140
	v_lshlrev_b32_e32 v140, 16, v141
	v_and_b32_e32 v141, 0xffff0000, v141
	v_pk_fma_f32 v[134:135], v[134:135], s[0:1], v[140:141] op_sel_hi:[1,0,1]
	v_pk_fma_f32 v[16:17], v[138:139], s[86:87], v[16:17] op_sel_hi:[1,0,1]
	s_waitcnt vmcnt(0)
	v_mov_b64_e32 v[138:139], v[220:221]
	v_mov_b64_e32 v[140:141], v[222:223]
	v_pk_fma_f32 v[12:13], v[134:135], s[86:87], v[12:13] op_sel_hi:[1,0,1]
	v_cvt_pk_f32_fp8_e32 v[134:135], v136
	v_pk_fma_f32 v[146:147], v[148:149], s[0:1], v[146:147] op_sel_hi:[1,0,1]
	v_cvt_pk_f32_fp8_sdwa v[142:143], v136 src0_sel:WORD_1
	v_pk_fma_f32 v[144:145], v[144:145], s[0:1], v[150:151] op_sel_hi:[1,0,1]
	v_pk_fma_f32 v[10:11], v[146:147], s[86:87], v[10:11] op_sel_hi:[1,0,1]
	v_pk_fma_f32 v[14:15], v[144:145], s[86:87], v[14:15] op_sel_hi:[1,0,1]
	v_cvt_pk_f32_fp8_e32 v[144:145], v137
	v_cvt_pk_f32_fp8_sdwa v[136:137], v137 src0_sel:WORD_1
	v_cndmask_b32_e32 v171, v205, v172, vcc
	v_lshlrev_b32_e32 v171, 2, v171
	v_cmp_gt_u32_e32 vcc, 16, v169
	s_waitcnt vmcnt(0)
	v_lshlrev_b32_e32 v146, 16, v138
	v_and_b32_e32 v147, 0xffff0000, v138
	v_pk_fma_f32 v[134:135], v[134:135], s[0:1], v[146:147] op_sel_hi:[1,0,1]
	v_lshlrev_b32_e32 v138, 16, v139
	v_and_b32_e32 v139, 0xffff0000, v139
	v_pk_fma_f32 v[22:23], v[134:135], s[86:87], v[22:23] op_sel_hi:[1,0,1]
	v_or_b32_e32 v134, 16, v132
	v_pk_fma_f32 v[138:139], v[142:143], s[0:1], v[138:139] op_sel_hi:[1,0,1]
	v_ashrrev_i32_e32 v135, 31, v134
	v_lshlrev_b32_e32 v142, 16, v140
	v_and_b32_e32 v143, 0xffff0000, v140
	v_lshlrev_b32_e32 v140, 16, v141
	v_and_b32_e32 v141, 0xffff0000, v141
	v_pk_fma_f32 v[24:25], v[138:139], s[86:87], v[24:25] op_sel_hi:[1,0,1]
	v_lshlrev_b64 v[138:139], 11, v[134:135]
	v_pk_fma_f32 v[142:143], v[144:145], s[0:1], v[142:143] op_sel_hi:[1,0,1]
	v_pk_fma_f32 v[136:137], v[136:137], s[0:1], v[140:141] op_sel_hi:[1,0,1]
	v_lshl_add_u64 v[134:135], s[18:19], 0, v[138:139]
	v_pk_fma_f32 v[20:21], v[136:137], s[86:87], v[20:21] op_sel_hi:[1,0,1]
	v_pk_fma_f32 v[18:19], v[142:143], s[86:87], v[18:19] op_sel_hi:[1,0,1]
	v_lshl_add_u64 v[134:135], v[134:135], 0, v[162:163]
	s_waitcnt vmcnt(0)
	v_mov_b64_e32 v[134:135], v[224:225]
	v_mov_b64_e32 v[136:137], v[226:227]
	v_lshl_add_u64 v[138:139], s[24:25], 0, v[138:139]
	v_lshl_add_u64 v[142:143], v[138:139], 0, v[164:165]
	s_waitcnt vmcnt(0)
	v_mov_b64_e32 v[138:139], v[228:229]
	v_mov_b64_e32 v[140:141], v[230:231]
	v_mov_b32_e32 v172, v15
	v_mov_b32_e32 v173, v16
	v_mov_b32_e32 v174, v14
	v_mov_b32_e32 v175, v17
	v_pk_add_f32 v[172:173], v[172:173], v[174:175]
	v_mov_b32_e32 v174, v11
	v_mov_b32_e32 v175, v12
	v_mov_b32_e32 v176, v10
	v_mov_b32_e32 v177, v13
	v_pk_add_f32 v[174:175], v[174:175], v[176:177]
	v_add_f32_e32 v172, v172, v173
	v_pk_add_f32 v[174:175], v[174:175], v[174:175] op_sel_hi:[0,1]
	v_add_f32_e32 v173, 0, v172
	v_add_f32_e32 v177, v22, v23
	v_add_f32_e32 v197, v24, v25
	v_mov_b32_e32 v176, v18
	v_mov_b32_e32 v196, v19
	v_mov_b32_e32 v174, v20
	v_mov_b32_e32 v172, v21
	v_pk_add_f32 v[176:177], v[176:177], v[196:197]
	v_pk_add_f32 v[172:173], v[174:175], v[172:173]
	s_waitcnt vmcnt(1)
	v_cvt_pk_f32_fp8_sdwa v[146:147], v134 src0_sel:WORD_1
	v_cvt_pk_f32_fp8_e32 v[144:145], v134
	v_cvt_pk_f32_fp8_e32 v[148:149], v135
	v_cvt_pk_f32_fp8_sdwa v[134:135], v135 src0_sel:WORD_1
	s_waitcnt vmcnt(0)
	v_lshlrev_b32_e32 v150, 16, v138
	v_and_b32_e32 v151, 0xffff0000, v138
	v_lshlrev_b32_e32 v138, 16, v139
	v_and_b32_e32 v139, 0xffff0000, v139
	v_pk_fma_f32 v[138:139], v[146:147], s[0:1], v[138:139] op_sel_hi:[1,0,1]
	v_lshlrev_b32_e32 v146, 16, v140
	v_and_b32_e32 v147, 0xffff0000, v140
	v_lshlrev_b32_e32 v140, 16, v141
	v_and_b32_e32 v141, 0xffff0000, v141
	v_pk_fma_f32 v[134:135], v[134:135], s[0:1], v[140:141] op_sel_hi:[1,0,1]
	v_pk_fma_f32 v[40:41], v[138:139], s[86:87], v[40:41] op_sel_hi:[1,0,1]
	s_waitcnt vmcnt(0)
	v_mov_b64_e32 v[138:139], v[232:233]
	v_mov_b64_e32 v[140:141], v[234:235]
	v_pk_fma_f32 v[36:37], v[134:135], s[86:87], v[36:37] op_sel_hi:[1,0,1]
	v_cvt_pk_f32_fp8_e32 v[134:135], v136
	v_pk_fma_f32 v[146:147], v[148:149], s[0:1], v[146:147] op_sel_hi:[1,0,1]
	v_cvt_pk_f32_fp8_sdwa v[142:143], v136 src0_sel:WORD_1
	v_pk_fma_f32 v[144:145], v[144:145], s[0:1], v[150:151] op_sel_hi:[1,0,1]
	v_pk_fma_f32 v[34:35], v[146:147], s[86:87], v[34:35] op_sel_hi:[1,0,1]
	v_pk_fma_f32 v[38:39], v[144:145], s[86:87], v[38:39] op_sel_hi:[1,0,1]
	v_cvt_pk_f32_fp8_e32 v[144:145], v137
	v_cvt_pk_f32_fp8_sdwa v[136:137], v137 src0_sel:WORD_1
	v_pk_add_f32 v[172:173], v[176:177], v[172:173]
	s_waitcnt vmcnt(0)
	v_lshlrev_b32_e32 v146, 16, v138
	v_and_b32_e32 v147, 0xffff0000, v138
	v_pk_fma_f32 v[134:135], v[134:135], s[0:1], v[146:147] op_sel_hi:[1,0,1]
	v_lshlrev_b32_e32 v138, 16, v139
	v_and_b32_e32 v139, 0xffff0000, v139
	v_pk_fma_f32 v[46:47], v[134:135], s[86:87], v[46:47] op_sel_hi:[1,0,1]
	v_or_b32_e32 v134, 32, v132
	v_pk_fma_f32 v[138:139], v[142:143], s[0:1], v[138:139] op_sel_hi:[1,0,1]
	v_ashrrev_i32_e32 v135, 31, v134
	v_lshlrev_b32_e32 v142, 16, v140
	v_and_b32_e32 v143, 0xffff0000, v140
	v_lshlrev_b32_e32 v140, 16, v141
	v_and_b32_e32 v141, 0xffff0000, v141
	v_pk_fma_f32 v[48:49], v[138:139], s[86:87], v[48:49] op_sel_hi:[1,0,1]
	v_lshlrev_b64 v[138:139], 11, v[134:135]
	v_pk_fma_f32 v[142:143], v[144:145], s[0:1], v[142:143] op_sel_hi:[1,0,1]
	v_pk_fma_f32 v[136:137], v[136:137], s[0:1], v[140:141] op_sel_hi:[1,0,1]
	v_lshl_add_u64 v[134:135], s[18:19], 0, v[138:139]
	v_pk_fma_f32 v[44:45], v[136:137], s[86:87], v[44:45] op_sel_hi:[1,0,1]
	v_pk_fma_f32 v[42:43], v[142:143], s[86:87], v[42:43] op_sel_hi:[1,0,1]
	v_lshl_add_u64 v[134:135], v[134:135], 0, v[162:163]
	s_waitcnt vmcnt(0)
	v_mov_b64_e32 v[134:135], v[236:237]
	v_mov_b64_e32 v[136:137], v[238:239]
	v_lshl_add_u64 v[138:139], s[24:25], 0, v[138:139]
	v_lshl_add_u64 v[142:143], v[138:139], 0, v[164:165]
	s_waitcnt vmcnt(0)
	v_mov_b64_e32 v[138:139], v[240:241]
	v_mov_b64_e32 v[140:141], v[242:243]
	v_add_f32_e32 v172, v172, v173
	v_mov_b32_e32 v173, v172
	s_nop 1
	v_permlane16_swap_b32_e32 v173, v172
	s_waitcnt lgkmcnt(0)
	v_add_f32_e32 v172, v172, v173
	v_mov_b32_e32 v173, v172
	s_nop 1
	v_permlane32_swap_b32_e32 v173, v172
	s_waitcnt lgkmcnt(0)
	v_add_f32_e32 v172, v172, v173
	v_fmamk_f32 v174, v172, 0xbc800000, v17
	v_fmamk_f32 v176, v172, 0xbc800000, v15
	v_fmamk_f32 v173, v172, 0xbc800000, v16
	v_fmamk_f32 v175, v172, 0xbc800000, v14
	v_mul_f32_e32 v176, v176, v176
	v_mul_f32_e32 v174, v174, v174
	v_fmac_f32_e32 v176, v175, v175
	v_fmac_f32_e32 v174, v173, v173
	v_fmamk_f32 v175, v172, 0xbc800000, v13
	v_fmamk_f32 v177, v172, 0xbc800000, v11
	v_add_f32_e32 v173, v176, v174
	v_fmamk_f32 v174, v172, 0xbc800000, v12
	v_fmamk_f32 v176, v172, 0xbc800000, v10
	v_mul_f32_e32 v177, v177, v177
	v_mul_f32_e32 v175, v175, v175
	v_fmac_f32_e32 v177, v176, v176
	v_fmac_f32_e32 v175, v174, v174
	v_add_f32_e32 v174, v177, v175
	v_fmamk_f32 v175, v172, 0xbc800000, v25
	v_fmamk_f32 v177, v172, 0xbc800000, v23
	v_add_f32_e32 v173, v173, v174
	v_fmamk_f32 v174, v172, 0xbc800000, v24
	v_fmamk_f32 v176, v172, 0xbc800000, v22
	v_mul_f32_e32 v177, v177, v177
	v_mul_f32_e32 v175, v175, v175
	v_fmac_f32_e32 v177, v176, v176
	v_fmac_f32_e32 v175, v174, v174
	v_add_f32_e32 v174, v177, v175
	v_fmamk_f32 v175, v172, 0xbc800000, v21
	v_fmamk_f32 v177, v172, 0xbc800000, v19
	v_add_f32_e32 v173, v174, v173
	v_fmamk_f32 v174, v172, 0xbc800000, v20
	v_fmamk_f32 v176, v172, 0xbc800000, v18
	v_mul_f32_e32 v177, v177, v177
	v_mul_f32_e32 v175, v175, v175
	v_fmac_f32_e32 v177, v176, v176
	v_fmac_f32_e32 v175, v174, v174
	v_add_f32_e32 v174, v177, v175
	v_add_f32_e32 v173, v174, v173
	v_mov_b32_e32 v174, v173
	s_nop 1
	v_permlane16_swap_b32_e32 v174, v173
	s_waitcnt lgkmcnt(0)
	v_add_f32_e32 v173, v173, v174
	v_mov_b32_e32 v174, v173
	s_nop 1
	v_permlane32_swap_b32_e32 v174, v173
	s_waitcnt vmcnt(1)
	v_cvt_pk_f32_fp8_sdwa v[146:147], v134 src0_sel:WORD_1
	v_cvt_pk_f32_fp8_e32 v[144:145], v134
	v_cvt_pk_f32_fp8_e32 v[148:149], v135
	v_cvt_pk_f32_fp8_sdwa v[134:135], v135 src0_sel:WORD_1
	s_waitcnt vmcnt(0)
	v_lshlrev_b32_e32 v150, 16, v138
	v_and_b32_e32 v151, 0xffff0000, v138
	v_lshlrev_b32_e32 v138, 16, v139
	v_and_b32_e32 v139, 0xffff0000, v139
	v_pk_fma_f32 v[138:139], v[146:147], s[0:1], v[138:139] op_sel_hi:[1,0,1]
	v_lshlrev_b32_e32 v146, 16, v140
	v_and_b32_e32 v147, 0xffff0000, v140
	v_lshlrev_b32_e32 v140, 16, v141
	v_and_b32_e32 v141, 0xffff0000, v141
	v_pk_fma_f32 v[134:135], v[134:135], s[0:1], v[140:141] op_sel_hi:[1,0,1]
	v_pk_fma_f32 v[64:65], v[138:139], s[86:87], v[64:65] op_sel_hi:[1,0,1]
	s_waitcnt vmcnt(0)
	v_mov_b64_e32 v[138:139], v[244:245]
	v_mov_b64_e32 v[140:141], v[246:247]
	s_mov_b32 s98, 0x18000
	s_mov_b32 s99, 0
	v_lshl_add_u64 v[212:213], v[248:249], 0, s[98:99]
	global_load_dwordx4 v[212:215], v[212:213], off
	s_mov_b32 s98, 0x18000
	s_mov_b32 s99, 0
	v_lshl_add_u64 v[216:217], v[250:251], 0, s[98:99]
	global_load_dwordx4 v[216:219], v[216:217], off
	s_mov_b32 s98, 0x18000
	s_mov_b32 s99, 0
	v_lshl_add_u64 v[220:221], v[250:251], 0, s[98:99]
	global_load_dwordx4 v[220:223], v[220:221], off offset:256
	s_mov_b32 s98, 0x40000
	s_mov_b32 s99, 0
	v_lshl_add_u64 v[224:225], v[248:249], 0, s[98:99]
	global_load_dwordx4 v[224:227], v[224:225], off
	s_mov_b32 s98, 0x40000
	s_mov_b32 s99, 0
	v_lshl_add_u64 v[228:229], v[250:251], 0, s[98:99]
	global_load_dwordx4 v[228:231], v[228:229], off
	s_mov_b32 s98, 0x40000
	s_mov_b32 s99, 0
	v_lshl_add_u64 v[232:233], v[250:251], 0, s[98:99]
	global_load_dwordx4 v[232:235], v[232:233], off offset:256
	s_mov_b32 s98, 0x48000
	s_mov_b32 s99, 0
	v_lshl_add_u64 v[236:237], v[248:249], 0, s[98:99]
	global_load_dwordx4 v[236:239], v[236:237], off
	s_mov_b32 s98, 0x48000
	s_mov_b32 s99, 0
	v_lshl_add_u64 v[240:241], v[250:251], 0, s[98:99]
	global_load_dwordx4 v[240:243], v[240:241], off
	s_mov_b32 s98, 0x48000
	s_mov_b32 s99, 0
	v_lshl_add_u64 v[244:245], v[250:251], 0, s[98:99]
	global_load_dwordx4 v[244:247], v[244:245], off offset:256
	v_pk_fma_f32 v[60:61], v[134:135], s[86:87], v[60:61] op_sel_hi:[1,0,1]
	v_cvt_pk_f32_fp8_e32 v[134:135], v136
	v_pk_fma_f32 v[146:147], v[148:149], s[0:1], v[146:147] op_sel_hi:[1,0,1]
	v_cvt_pk_f32_fp8_sdwa v[142:143], v136 src0_sel:WORD_1
	v_pk_fma_f32 v[144:145], v[144:145], s[0:1], v[150:151] op_sel_hi:[1,0,1]
	v_pk_fma_f32 v[58:59], v[146:147], s[86:87], v[58:59] op_sel_hi:[1,0,1]
	v_pk_fma_f32 v[62:63], v[144:145], s[86:87], v[62:63] op_sel_hi:[1,0,1]
	v_cvt_pk_f32_fp8_e32 v[144:145], v137
	v_cvt_pk_f32_fp8_sdwa v[136:137], v137 src0_sel:WORD_1
	s_waitcnt vmcnt(0)
	v_lshlrev_b32_e32 v146, 16, v138
	v_and_b32_e32 v147, 0xffff0000, v138
	v_pk_fma_f32 v[134:135], v[134:135], s[0:1], v[146:147] op_sel_hi:[1,0,1]
	v_lshlrev_b32_e32 v138, 16, v139
	v_and_b32_e32 v139, 0xffff0000, v139
	v_pk_fma_f32 v[70:71], v[134:135], s[86:87], v[70:71] op_sel_hi:[1,0,1]
	v_or_b32_e32 v134, 48, v132
	v_pk_fma_f32 v[138:139], v[142:143], s[0:1], v[138:139] op_sel_hi:[1,0,1]
	v_ashrrev_i32_e32 v135, 31, v134
	v_lshlrev_b32_e32 v142, 16, v140
	v_and_b32_e32 v143, 0xffff0000, v140
	v_lshlrev_b32_e32 v140, 16, v141
	v_and_b32_e32 v141, 0xffff0000, v141
	v_pk_fma_f32 v[72:73], v[138:139], s[86:87], v[72:73] op_sel_hi:[1,0,1]
	v_lshlrev_b64 v[138:139], 11, v[134:135]
	v_pk_fma_f32 v[142:143], v[144:145], s[0:1], v[142:143] op_sel_hi:[1,0,1]
	v_pk_fma_f32 v[136:137], v[136:137], s[0:1], v[140:141] op_sel_hi:[1,0,1]
	v_lshl_add_u64 v[134:135], s[18:19], 0, v[138:139]
	v_pk_fma_f32 v[68:69], v[136:137], s[86:87], v[68:69] op_sel_hi:[1,0,1]
	v_pk_fma_f32 v[66:67], v[142:143], s[86:87], v[66:67] op_sel_hi:[1,0,1]
	v_lshl_add_u64 v[134:135], v[134:135], 0, v[162:163]
	s_waitcnt vmcnt(0)
	v_mov_b64_e32 v[134:135], v[212:213]
	v_mov_b64_e32 v[136:137], v[214:215]
	v_lshl_add_u64 v[138:139], s[24:25], 0, v[138:139]
	v_lshl_add_u64 v[142:143], v[138:139], 0, v[164:165]
	s_waitcnt vmcnt(0)
	v_mov_b64_e32 v[138:139], v[216:217]
	v_mov_b64_e32 v[140:141], v[218:219]
	s_waitcnt vmcnt(1)
	v_cvt_pk_f32_fp8_sdwa v[146:147], v134 src0_sel:WORD_1
	v_cvt_pk_f32_fp8_e32 v[144:145], v134
	v_cvt_pk_f32_fp8_e32 v[148:149], v135
	v_cvt_pk_f32_fp8_sdwa v[134:135], v135 src0_sel:WORD_1
	s_waitcnt vmcnt(0)
	v_lshlrev_b32_e32 v150, 16, v138
	v_and_b32_e32 v151, 0xffff0000, v138
	v_lshlrev_b32_e32 v138, 16, v139
	v_and_b32_e32 v139, 0xffff0000, v139
	v_pk_fma_f32 v[138:139], v[146:147], s[0:1], v[138:139] op_sel_hi:[1,0,1]
	v_lshlrev_b32_e32 v146, 16, v140
	v_and_b32_e32 v147, 0xffff0000, v140
	v_lshlrev_b32_e32 v140, 16, v141
	v_and_b32_e32 v141, 0xffff0000, v141
	v_pk_fma_f32 v[134:135], v[134:135], s[0:1], v[140:141] op_sel_hi:[1,0,1]
	v_pk_fma_f32 v[88:89], v[138:139], s[86:87], v[88:89] op_sel_hi:[1,0,1]
	s_waitcnt vmcnt(0)
	v_mov_b64_e32 v[138:139], v[220:221]
	v_mov_b64_e32 v[140:141], v[222:223]
	v_pk_fma_f32 v[84:85], v[134:135], s[86:87], v[84:85] op_sel_hi:[1,0,1]
	v_cvt_pk_f32_fp8_e32 v[134:135], v136
	v_pk_fma_f32 v[146:147], v[148:149], s[0:1], v[146:147] op_sel_hi:[1,0,1]
	v_cvt_pk_f32_fp8_sdwa v[142:143], v136 src0_sel:WORD_1
	v_pk_fma_f32 v[144:145], v[144:145], s[0:1], v[150:151] op_sel_hi:[1,0,1]
	v_pk_fma_f32 v[82:83], v[146:147], s[86:87], v[82:83] op_sel_hi:[1,0,1]
	v_pk_fma_f32 v[86:87], v[144:145], s[86:87], v[86:87] op_sel_hi:[1,0,1]
	v_cvt_pk_f32_fp8_e32 v[144:145], v137
	v_cvt_pk_f32_fp8_sdwa v[136:137], v137 src0_sel:WORD_1
	s_waitcnt vmcnt(0)
	v_lshlrev_b32_e32 v146, 16, v138
	v_and_b32_e32 v147, 0xffff0000, v138
	v_pk_fma_f32 v[134:135], v[134:135], s[0:1], v[146:147] op_sel_hi:[1,0,1]
	v_lshlrev_b32_e32 v138, 16, v139
	v_and_b32_e32 v139, 0xffff0000, v139
	v_pk_fma_f32 v[94:95], v[134:135], s[86:87], v[94:95] op_sel_hi:[1,0,1]
	v_add_u32_e32 v134, 0x80, v132
	v_pk_fma_f32 v[138:139], v[142:143], s[0:1], v[138:139] op_sel_hi:[1,0,1]
	v_ashrrev_i32_e32 v135, 31, v134
	v_lshlrev_b32_e32 v142, 16, v140
	v_and_b32_e32 v143, 0xffff0000, v140
	v_lshlrev_b32_e32 v140, 16, v141
	v_and_b32_e32 v141, 0xffff0000, v141
	v_pk_fma_f32 v[96:97], v[138:139], s[86:87], v[96:97] op_sel_hi:[1,0,1]
	v_lshlrev_b64 v[138:139], 11, v[134:135]
	v_pk_fma_f32 v[142:143], v[144:145], s[0:1], v[142:143] op_sel_hi:[1,0,1]
	v_pk_fma_f32 v[136:137], v[136:137], s[0:1], v[140:141] op_sel_hi:[1,0,1]
	v_lshl_add_u64 v[134:135], s[18:19], 0, v[138:139]
	v_pk_fma_f32 v[92:93], v[136:137], s[86:87], v[92:93] op_sel_hi:[1,0,1]
	v_pk_fma_f32 v[90:91], v[142:143], s[86:87], v[90:91] op_sel_hi:[1,0,1]
	v_lshl_add_u64 v[134:135], v[134:135], 0, v[162:163]
	s_waitcnt vmcnt(0)
	v_mov_b64_e32 v[134:135], v[224:225]
	v_mov_b64_e32 v[136:137], v[226:227]
	v_lshl_add_u64 v[138:139], s[24:25], 0, v[138:139]
	v_lshl_add_u64 v[142:143], v[138:139], 0, v[164:165]
	s_waitcnt vmcnt(0)
	v_mov_b64_e32 v[138:139], v[228:229]
	v_mov_b64_e32 v[140:141], v[230:231]
	s_waitcnt vmcnt(1)
	v_cvt_pk_f32_fp8_sdwa v[146:147], v134 src0_sel:WORD_1
	v_cvt_pk_f32_fp8_e32 v[144:145], v134
	v_cvt_pk_f32_fp8_e32 v[148:149], v135
	v_cvt_pk_f32_fp8_sdwa v[134:135], v135 src0_sel:WORD_1
	s_waitcnt vmcnt(0)
	v_lshlrev_b32_e32 v150, 16, v138
	v_and_b32_e32 v151, 0xffff0000, v138
	v_lshlrev_b32_e32 v138, 16, v139
	v_and_b32_e32 v139, 0xffff0000, v139
	v_pk_fma_f32 v[138:139], v[146:147], s[0:1], v[138:139] op_sel_hi:[1,0,1]
	v_lshlrev_b32_e32 v146, 16, v140
	v_and_b32_e32 v147, 0xffff0000, v140
	v_lshlrev_b32_e32 v140, 16, v141
	v_and_b32_e32 v141, 0xffff0000, v141
	v_pk_fma_f32 v[134:135], v[134:135], s[0:1], v[140:141] op_sel_hi:[1,0,1]
	v_pk_fma_f32 v[120:121], v[138:139], s[86:87], v[120:121] op_sel_hi:[1,0,1]
	s_waitcnt vmcnt(0)
	v_mov_b64_e32 v[138:139], v[232:233]
	v_mov_b64_e32 v[140:141], v[234:235]
	v_pk_fma_f32 v[116:117], v[134:135], s[86:87], v[116:117] op_sel_hi:[1,0,1]
	v_cvt_pk_f32_fp8_e32 v[134:135], v136
	v_pk_fma_f32 v[146:147], v[148:149], s[0:1], v[146:147] op_sel_hi:[1,0,1]
	v_cvt_pk_f32_fp8_sdwa v[142:143], v136 src0_sel:WORD_1
	v_pk_fma_f32 v[144:145], v[144:145], s[0:1], v[150:151] op_sel_hi:[1,0,1]
	v_pk_fma_f32 v[114:115], v[146:147], s[86:87], v[114:115] op_sel_hi:[1,0,1]
	v_pk_fma_f32 v[118:119], v[144:145], s[86:87], v[118:119] op_sel_hi:[1,0,1]
	v_cvt_pk_f32_fp8_e32 v[144:145], v137
	v_cvt_pk_f32_fp8_sdwa v[136:137], v137 src0_sel:WORD_1
	s_waitcnt vmcnt(0)
	v_lshlrev_b32_e32 v146, 16, v138
	v_and_b32_e32 v147, 0xffff0000, v138
	v_pk_fma_f32 v[134:135], v[134:135], s[0:1], v[146:147] op_sel_hi:[1,0,1]
	v_lshlrev_b32_e32 v138, 16, v139
	v_and_b32_e32 v139, 0xffff0000, v139
	v_pk_fma_f32 v[126:127], v[134:135], s[86:87], v[126:127] op_sel_hi:[1,0,1]
	v_add_u32_e32 v134, 0x90, v132
	v_pk_fma_f32 v[138:139], v[142:143], s[0:1], v[138:139] op_sel_hi:[1,0,1]
	v_ashrrev_i32_e32 v135, 31, v134
	v_lshlrev_b32_e32 v142, 16, v140
	v_and_b32_e32 v143, 0xffff0000, v140
	v_lshlrev_b32_e32 v140, 16, v141
	v_and_b32_e32 v141, 0xffff0000, v141
	v_pk_fma_f32 v[128:129], v[138:139], s[86:87], v[128:129] op_sel_hi:[1,0,1]
	v_lshlrev_b64 v[138:139], 11, v[134:135]
	v_pk_fma_f32 v[142:143], v[144:145], s[0:1], v[142:143] op_sel_hi:[1,0,1]
	v_pk_fma_f32 v[136:137], v[136:137], s[0:1], v[140:141] op_sel_hi:[1,0,1]
	v_lshl_add_u64 v[134:135], s[18:19], 0, v[138:139]
	v_pk_fma_f32 v[124:125], v[136:137], s[86:87], v[124:125] op_sel_hi:[1,0,1]
	v_pk_fma_f32 v[122:123], v[142:143], s[86:87], v[122:123] op_sel_hi:[1,0,1]
	v_lshl_add_u64 v[134:135], v[134:135], 0, v[162:163]
	s_waitcnt vmcnt(0)
	v_mov_b64_e32 v[134:135], v[236:237]
	v_mov_b64_e32 v[136:137], v[238:239]
	v_lshl_add_u64 v[138:139], s[24:25], 0, v[138:139]
	v_lshl_add_u64 v[142:143], v[138:139], 0, v[164:165]
	s_waitcnt vmcnt(0)
	v_mov_b64_e32 v[138:139], v[240:241]
	v_mov_b64_e32 v[140:141], v[242:243]
	s_waitcnt vmcnt(1)
	v_cvt_pk_f32_fp8_sdwa v[146:147], v134 src0_sel:WORD_1
	v_cvt_pk_f32_fp8_e32 v[144:145], v134
	v_cvt_pk_f32_fp8_e32 v[148:149], v135
	v_cvt_pk_f32_fp8_sdwa v[134:135], v135 src0_sel:WORD_1
	s_waitcnt vmcnt(0)
	v_lshlrev_b32_e32 v150, 16, v138
	v_and_b32_e32 v151, 0xffff0000, v138
	v_lshlrev_b32_e32 v138, 16, v139
	v_and_b32_e32 v139, 0xffff0000, v139
	v_pk_fma_f32 v[138:139], v[146:147], s[0:1], v[138:139] op_sel_hi:[1,0,1]
	v_lshlrev_b32_e32 v146, 16, v140
	v_and_b32_e32 v147, 0xffff0000, v140
	v_lshlrev_b32_e32 v140, 16, v141
	v_and_b32_e32 v141, 0xffff0000, v141
	v_pk_fma_f32 v[134:135], v[134:135], s[0:1], v[140:141] op_sel_hi:[1,0,1]
	v_pk_fma_f32 v[112:113], v[138:139], s[86:87], v[112:113] op_sel_hi:[1,0,1]
	s_waitcnt vmcnt(0)
	v_mov_b64_e32 v[138:139], v[244:245]
	v_mov_b64_e32 v[140:141], v[246:247]
	s_mov_b32 s98, 0x50000
	s_mov_b32 s99, 0
	v_lshl_add_u64 v[212:213], v[248:249], 0, s[98:99]
	global_load_dwordx4 v[212:215], v[212:213], off
	s_mov_b32 s98, 0x50000
	s_mov_b32 s99, 0
	v_lshl_add_u64 v[216:217], v[250:251], 0, s[98:99]
	global_load_dwordx4 v[216:219], v[216:217], off
	s_mov_b32 s98, 0x50000
	s_mov_b32 s99, 0
	v_lshl_add_u64 v[220:221], v[250:251], 0, s[98:99]
	global_load_dwordx4 v[220:223], v[220:221], off offset:256
	s_mov_b32 s98, 0x58000
	s_mov_b32 s99, 0
	v_lshl_add_u64 v[224:225], v[248:249], 0, s[98:99]
	global_load_dwordx4 v[224:227], v[224:225], off
	s_mov_b32 s98, 0x58000
	s_mov_b32 s99, 0
	v_lshl_add_u64 v[228:229], v[250:251], 0, s[98:99]
	global_load_dwordx4 v[228:231], v[228:229], off
	s_mov_b32 s98, 0x58000
	s_mov_b32 s99, 0
	v_lshl_add_u64 v[232:233], v[250:251], 0, s[98:99]
	global_load_dwordx4 v[232:235], v[232:233], off offset:256
	v_pk_fma_f32 v[108:109], v[134:135], s[86:87], v[108:109] op_sel_hi:[1,0,1]
	v_cvt_pk_f32_fp8_e32 v[134:135], v136
	v_pk_fma_f32 v[146:147], v[148:149], s[0:1], v[146:147] op_sel_hi:[1,0,1]
	v_cvt_pk_f32_fp8_sdwa v[142:143], v136 src0_sel:WORD_1
	v_pk_fma_f32 v[144:145], v[144:145], s[0:1], v[150:151] op_sel_hi:[1,0,1]
	v_pk_fma_f32 v[106:107], v[146:147], s[86:87], v[106:107] op_sel_hi:[1,0,1]
	v_pk_fma_f32 v[110:111], v[144:145], s[86:87], v[110:111] op_sel_hi:[1,0,1]
	v_cvt_pk_f32_fp8_e32 v[144:145], v137
	v_cvt_pk_f32_fp8_sdwa v[136:137], v137 src0_sel:WORD_1
	s_waitcnt vmcnt(0)
	v_lshlrev_b32_e32 v146, 16, v138
	v_and_b32_e32 v147, 0xffff0000, v138
	v_pk_fma_f32 v[134:135], v[134:135], s[0:1], v[146:147] op_sel_hi:[1,0,1]
	v_lshlrev_b32_e32 v138, 16, v139
	v_and_b32_e32 v139, 0xffff0000, v139
	v_pk_fma_f32 v[102:103], v[134:135], s[86:87], v[102:103] op_sel_hi:[1,0,1]
	v_add_u32_e32 v134, 0xa0, v132
	v_pk_fma_f32 v[138:139], v[142:143], s[0:1], v[138:139] op_sel_hi:[1,0,1]
	v_ashrrev_i32_e32 v135, 31, v134
	v_lshlrev_b32_e32 v142, 16, v140
	v_and_b32_e32 v143, 0xffff0000, v140
	v_lshlrev_b32_e32 v140, 16, v141
	v_and_b32_e32 v141, 0xffff0000, v141
	v_pk_fma_f32 v[104:105], v[138:139], s[86:87], v[104:105] op_sel_hi:[1,0,1]
	v_lshlrev_b64 v[138:139], 11, v[134:135]
	v_pk_fma_f32 v[142:143], v[144:145], s[0:1], v[142:143] op_sel_hi:[1,0,1]
	v_pk_fma_f32 v[136:137], v[136:137], s[0:1], v[140:141] op_sel_hi:[1,0,1]
	v_lshl_add_u64 v[134:135], s[18:19], 0, v[138:139]
	v_pk_fma_f32 v[100:101], v[136:137], s[86:87], v[100:101] op_sel_hi:[1,0,1]
	v_pk_fma_f32 v[98:99], v[142:143], s[86:87], v[98:99] op_sel_hi:[1,0,1]
	v_lshl_add_u64 v[134:135], v[134:135], 0, v[162:163]
	s_waitcnt vmcnt(0)
	v_mov_b64_e32 v[134:135], v[212:213]
	v_mov_b64_e32 v[136:137], v[214:215]
	v_lshl_add_u64 v[138:139], s[24:25], 0, v[138:139]
	v_lshl_add_u64 v[142:143], v[138:139], 0, v[164:165]
	s_waitcnt vmcnt(0)
	v_mov_b64_e32 v[138:139], v[216:217]
	v_mov_b64_e32 v[140:141], v[218:219]
	v_add_u32_e32 v132, 0xb0, v132
	v_ashrrev_i32_e32 v133, 31, v132
	s_waitcnt vmcnt(1)
	v_cvt_pk_f32_fp8_sdwa v[146:147], v134 src0_sel:WORD_1
	v_cvt_pk_f32_fp8_e32 v[144:145], v134
	v_cvt_pk_f32_fp8_e32 v[148:149], v135
	v_cvt_pk_f32_fp8_sdwa v[134:135], v135 src0_sel:WORD_1
	s_waitcnt vmcnt(0)
	v_lshlrev_b32_e32 v150, 16, v138
	v_and_b32_e32 v151, 0xffff0000, v138
	v_lshlrev_b32_e32 v138, 16, v139
	v_and_b32_e32 v139, 0xffff0000, v139
	v_pk_fma_f32 v[138:139], v[146:147], s[0:1], v[138:139] op_sel_hi:[1,0,1]
	v_lshlrev_b32_e32 v146, 16, v140
	v_and_b32_e32 v147, 0xffff0000, v140
	v_lshlrev_b32_e32 v140, 16, v141
	v_and_b32_e32 v141, 0xffff0000, v141
	v_pk_fma_f32 v[134:135], v[134:135], s[0:1], v[140:141] op_sel_hi:[1,0,1]
	v_pk_fma_f32 v[80:81], v[138:139], s[86:87], v[80:81] op_sel_hi:[1,0,1]
	s_waitcnt vmcnt(0)
	v_mov_b64_e32 v[138:139], v[220:221]
	v_mov_b64_e32 v[140:141], v[222:223]
	v_pk_fma_f32 v[144:145], v[144:145], s[0:1], v[150:151] op_sel_hi:[1,0,1]
	v_cvt_pk_f32_fp8_sdwa v[142:143], v136 src0_sel:WORD_1
	v_pk_fma_f32 v[78:79], v[144:145], s[86:87], v[78:79] op_sel_hi:[1,0,1]
	v_pk_fma_f32 v[76:77], v[134:135], s[86:87], v[76:77] op_sel_hi:[1,0,1]
	v_cvt_pk_f32_fp8_e32 v[134:135], v136
	v_cvt_pk_f32_fp8_e32 v[144:145], v137
	v_cvt_pk_f32_fp8_sdwa v[136:137], v137 src0_sel:WORD_1
	v_pk_fma_f32 v[146:147], v[148:149], s[0:1], v[146:147] op_sel_hi:[1,0,1]
	s_nop 0
	v_pk_fma_f32 v[74:75], v[146:147], s[86:87], v[74:75] op_sel_hi:[1,0,1]
	s_waitcnt vmcnt(0)
	v_lshlrev_b32_e32 v146, 16, v138
	v_and_b32_e32 v147, 0xffff0000, v138
	v_lshlrev_b32_e32 v138, 16, v139
	v_and_b32_e32 v139, 0xffff0000, v139
	v_pk_fma_f32 v[138:139], v[142:143], s[0:1], v[138:139] op_sel_hi:[1,0,1]
	v_lshlrev_b32_e32 v142, 16, v140
	v_and_b32_e32 v143, 0xffff0000, v140
	v_lshlrev_b32_e32 v140, 16, v141
	v_and_b32_e32 v141, 0xffff0000, v141
	v_pk_fma_f32 v[136:137], v[136:137], s[0:1], v[140:141] op_sel_hi:[1,0,1]
	v_pk_fma_f32 v[134:135], v[134:135], s[0:1], v[146:147] op_sel_hi:[1,0,1]
	v_pk_fma_f32 v[52:53], v[136:137], s[86:87], v[52:53] op_sel_hi:[1,0,1]
	v_lshlrev_b64 v[136:137], 11, v[132:133]
	v_pk_fma_f32 v[142:143], v[144:145], s[0:1], v[142:143] op_sel_hi:[1,0,1]
	v_lshl_add_u64 v[132:133], s[18:19], 0, v[136:137]
	v_pk_fma_f32 v[56:57], v[138:139], s[86:87], v[56:57] op_sel_hi:[1,0,1]
	v_pk_fma_f32 v[54:55], v[134:135], s[86:87], v[54:55] op_sel_hi:[1,0,1]
	v_pk_fma_f32 v[50:51], v[142:143], s[86:87], v[50:51] op_sel_hi:[1,0,1]
	v_lshl_add_u64 v[132:133], v[132:133], 0, v[162:163]
	s_waitcnt vmcnt(0)
	v_mov_b64_e32 v[132:133], v[224:225]
	v_mov_b64_e32 v[134:135], v[226:227]
	v_lshl_add_u64 v[136:137], s[24:25], 0, v[136:137]
	v_lshl_add_u64 v[140:141], v[136:137], 0, v[164:165]
	s_waitcnt vmcnt(0)
	v_mov_b64_e32 v[136:137], v[228:229]
	v_mov_b64_e32 v[138:139], v[230:231]
	s_waitcnt vmcnt(1)
	v_cvt_pk_f32_fp8_sdwa v[144:145], v132 src0_sel:WORD_1
	v_cvt_pk_f32_fp8_e32 v[142:143], v132
	v_cvt_pk_f32_fp8_e32 v[146:147], v133
	v_cvt_pk_f32_fp8_sdwa v[132:133], v133 src0_sel:WORD_1
	s_waitcnt vmcnt(0)
	v_lshlrev_b32_e32 v148, 16, v136
	v_and_b32_e32 v149, 0xffff0000, v136
	v_lshlrev_b32_e32 v136, 16, v137
	v_and_b32_e32 v137, 0xffff0000, v137
	v_pk_fma_f32 v[136:137], v[144:145], s[0:1], v[136:137] op_sel_hi:[1,0,1]
	v_lshlrev_b32_e32 v144, 16, v138
	v_and_b32_e32 v145, 0xffff0000, v138
	v_lshlrev_b32_e32 v138, 16, v139
	v_and_b32_e32 v139, 0xffff0000, v139
	v_pk_fma_f32 v[132:133], v[132:133], s[0:1], v[138:139] op_sel_hi:[1,0,1]
	v_pk_fma_f32 v[32:33], v[136:137], s[86:87], v[32:33] op_sel_hi:[1,0,1]
	s_waitcnt vmcnt(0)
	v_mov_b64_e32 v[136:137], v[232:233]
	v_mov_b64_e32 v[138:139], v[234:235]
	v_pk_fma_f32 v[142:143], v[142:143], s[0:1], v[148:149] op_sel_hi:[1,0,1]
	v_cvt_pk_f32_fp8_sdwa v[140:141], v134 src0_sel:WORD_1
	v_pk_fma_f32 v[30:31], v[142:143], s[86:87], v[30:31] op_sel_hi:[1,0,1]
	v_pk_fma_f32 v[28:29], v[132:133], s[86:87], v[28:29] op_sel_hi:[1,0,1]
	v_cvt_pk_f32_fp8_e32 v[132:133], v134
	v_cvt_pk_f32_fp8_e32 v[142:143], v135
	v_cvt_pk_f32_fp8_sdwa v[134:135], v135 src0_sel:WORD_1
	v_pk_fma_f32 v[144:145], v[146:147], s[0:1], v[144:145] op_sel_hi:[1,0,1]
	s_nop 0
	v_pk_fma_f32 v[26:27], v[144:145], s[86:87], v[26:27] op_sel_hi:[1,0,1]
	s_waitcnt vmcnt(0)
	v_lshlrev_b32_e32 v144, 16, v136
	v_and_b32_e32 v145, 0xffff0000, v136
	v_lshlrev_b32_e32 v136, 16, v137
	v_and_b32_e32 v137, 0xffff0000, v137
	v_pk_fma_f32 v[136:137], v[140:141], s[0:1], v[136:137] op_sel_hi:[1,0,1]
	v_lshlrev_b32_e32 v140, 16, v138
	v_and_b32_e32 v141, 0xffff0000, v138
	v_lshlrev_b32_e32 v138, 16, v139
	v_and_b32_e32 v139, 0xffff0000, v139
	v_pk_fma_f32 v[132:133], v[132:133], s[0:1], v[144:145] op_sel_hi:[1,0,1]
	v_pk_fma_f32 v[140:141], v[142:143], s[0:1], v[140:141] op_sel_hi:[1,0,1]
	v_pk_fma_f32 v[138:139], v[134:135], s[0:1], v[138:139] op_sel_hi:[1,0,1]
	v_readlane_b32 s0, v255, 18
	v_pk_fma_f32 v[134:135], v[132:133], s[86:87], v[6:7] op_sel_hi:[1,0,1]
	v_lshlrev_b64 v[6:7], 2, v[130:131]
	v_readlane_b32 s1, v255, 19
	v_pk_fma_f32 v[136:137], v[136:137], s[86:87], v[8:9] op_sel_hi:[1,0,1]
	v_pk_fma_f32 v[4:5], v[138:139], s[86:87], v[4:5] op_sel_hi:[1,0,1]
	v_lshl_add_u64 v[130:131], s[0:1], 0, v[6:7]
	v_readlane_b32 s0, v255, 27
	v_readlane_b32 s1, v255, 28
	v_pk_fma_f32 v[2:3], v[140:141], s[86:87], v[2:3] op_sel_hi:[1,0,1]
	s_nop 0
	v_lshl_add_u64 v[142:143], s[0:1], 0, v[6:7]
	global_load_dwordx4 v[146:149], v[130:131], off offset:16
	global_load_dwordx4 v[154:157], v[130:131], off
	global_load_dwordx4 v[150:153], v[142:143], off offset:16
	global_load_dwordx4 v[158:161], v[142:143], off
	global_load_dwordx4 v[6:9], v[130:131], off offset:528
	global_load_dwordx4 v[138:141], v[130:131], off offset:512
	s_nop 0
	global_load_dwordx4 v[130:133], v[142:143], off offset:528
	s_nop 0
	global_load_dwordx4 v[142:145], v[142:143], off offset:512
	s_lshl_b32 s0, s95, 3
	s_add_i32 s4, s0, 0
	s_and_saveexec_b64 s[0:1], vcc
	v_readlane_b32 s13, v255, 29
	s_cbranch_execz .LBB0_766
	s_lshl_b32 s5, s10, 11
	s_add_i32 s5, s4, s5
	v_mul_f32_e32 v172, 0x3c800000, v172
	v_lshl_add_u32 v175, v167, 5, s5
	s_waitcnt lgkmcnt(0)
	v_add_f32_e32 v173, v173, v174
	ds_write_b64 v175, v[172:173]
.LBB0_766:
	s_or_b64 exec, exec, s[0:1]
	v_mov_b32_e32 v172, v39
	v_mov_b32_e32 v173, v40
	s_waitcnt lgkmcnt(0)
	v_mov_b32_e32 v174, v38
	v_mov_b32_e32 v175, v41
	v_pk_add_f32 v[172:173], v[172:173], v[174:175]
	v_mov_b32_e32 v174, v35
	v_mov_b32_e32 v175, v36
	v_mov_b32_e32 v176, v34
	v_mov_b32_e32 v177, v37
	v_pk_add_f32 v[174:175], v[174:175], v[176:177]
	v_add_f32_e32 v172, v172, v173
	v_pk_add_f32 v[174:175], v[174:175], v[174:175] op_sel_hi:[0,1]
	v_add_f32_e32 v173, 0, v172
	v_add_f32_e32 v177, v46, v47
	v_add_f32_e32 v197, v48, v49
	v_mov_b32_e32 v176, v42
	v_mov_b32_e32 v196, v43
	v_mov_b32_e32 v174, v44
	v_mov_b32_e32 v172, v45
	v_pk_add_f32 v[176:177], v[176:177], v[196:197]
	v_pk_add_f32 v[172:173], v[174:175], v[172:173]
	s_nop 0
	v_pk_add_f32 v[172:173], v[176:177], v[172:173]
	s_nop 0
	v_add_f32_e32 v172, v172, v173
	v_mov_b32_e32 v173, v172
	s_nop 1
	v_permlane16_swap_b32_e32 v173, v172
	s_waitcnt lgkmcnt(0)
	v_add_f32_e32 v172, v172, v173
	v_mov_b32_e32 v173, v172
	s_nop 1
	v_permlane32_swap_b32_e32 v173, v172
	s_waitcnt lgkmcnt(0)
	v_add_f32_e32 v172, v172, v173
	v_fmamk_f32 v174, v172, 0xbc800000, v41
	v_fmamk_f32 v176, v172, 0xbc800000, v39
	v_fmamk_f32 v173, v172, 0xbc800000, v40
	v_fmamk_f32 v175, v172, 0xbc800000, v38
	v_mul_f32_e32 v176, v176, v176
	v_mul_f32_e32 v174, v174, v174
	v_fmac_f32_e32 v176, v175, v175
	v_fmac_f32_e32 v174, v173, v173
	v_fmamk_f32 v175, v172, 0xbc800000, v37
	v_fmamk_f32 v177, v172, 0xbc800000, v35
	v_add_f32_e32 v173, v176, v174
	v_fmamk_f32 v174, v172, 0xbc800000, v36
	v_fmamk_f32 v176, v172, 0xbc800000, v34
	v_mul_f32_e32 v177, v177, v177
	v_mul_f32_e32 v175, v175, v175
	v_fmac_f32_e32 v177, v176, v176
	v_fmac_f32_e32 v175, v174, v174
	v_add_f32_e32 v174, v177, v175
	v_fmamk_f32 v175, v172, 0xbc800000, v49
	v_fmamk_f32 v177, v172, 0xbc800000, v47
	v_add_f32_e32 v173, v173, v174
	v_fmamk_f32 v174, v172, 0xbc800000, v48
	v_fmamk_f32 v176, v172, 0xbc800000, v46
	v_mul_f32_e32 v177, v177, v177
	v_mul_f32_e32 v175, v175, v175
	v_fmac_f32_e32 v177, v176, v176
	v_fmac_f32_e32 v175, v174, v174
	v_add_f32_e32 v174, v177, v175
	v_fmamk_f32 v175, v172, 0xbc800000, v45
	v_fmamk_f32 v177, v172, 0xbc800000, v43
	v_add_f32_e32 v173, v174, v173
	v_fmamk_f32 v174, v172, 0xbc800000, v44
	v_fmamk_f32 v176, v172, 0xbc800000, v42
	v_mul_f32_e32 v177, v177, v177
	v_mul_f32_e32 v175, v175, v175
	v_fmac_f32_e32 v177, v176, v176
	v_fmac_f32_e32 v175, v174, v174
	v_add_f32_e32 v174, v177, v175
	v_add_f32_e32 v173, v174, v173
	v_mov_b32_e32 v174, v173
	s_nop 1
	v_permlane16_swap_b32_e32 v174, v173
	s_waitcnt lgkmcnt(0)
	v_add_f32_e32 v173, v173, v174
	v_mov_b32_e32 v174, v173
	s_nop 1
	v_permlane32_swap_b32_e32 v174, v173
	s_and_saveexec_b64 s[0:1], vcc
	s_cbranch_execz .LBB0_768
	s_lshl_b32 s5, s10, 11
	s_add_i32 s5, s4, s5
	v_mul_f32_e32 v172, 0x3c800000, v172
	v_lshl_add_u32 v175, v167, 5, s5
	s_waitcnt lgkmcnt(0)
	v_add_f32_e32 v173, v173, v174
	ds_write_b64 v175, v[172:173] offset:512
.LBB0_768:
	s_or_b64 exec, exec, s[0:1]
	v_mov_b32_e32 v172, v63
	v_mov_b32_e32 v173, v64
	s_waitcnt lgkmcnt(0)
	v_mov_b32_e32 v174, v62
	v_mov_b32_e32 v175, v65
	v_pk_add_f32 v[172:173], v[172:173], v[174:175]
	v_mov_b32_e32 v174, v59
	v_mov_b32_e32 v175, v60
	v_mov_b32_e32 v176, v58
	v_mov_b32_e32 v177, v61
	v_pk_add_f32 v[174:175], v[174:175], v[176:177]
	v_add_f32_e32 v172, v172, v173
	v_pk_add_f32 v[174:175], v[174:175], v[174:175] op_sel_hi:[0,1]
	v_add_f32_e32 v173, 0, v172
	v_add_f32_e32 v177, v70, v71
	v_add_f32_e32 v197, v72, v73
	v_mov_b32_e32 v176, v66
	v_mov_b32_e32 v196, v67
	v_mov_b32_e32 v174, v68
	v_mov_b32_e32 v172, v69
	v_pk_add_f32 v[176:177], v[176:177], v[196:197]
	v_pk_add_f32 v[172:173], v[174:175], v[172:173]
	s_nop 0
	v_pk_add_f32 v[172:173], v[176:177], v[172:173]
	s_nop 0
	v_add_f32_e32 v172, v172, v173
	v_mov_b32_e32 v173, v172
	s_nop 1
	v_permlane16_swap_b32_e32 v173, v172
	s_waitcnt lgkmcnt(0)
	v_add_f32_e32 v172, v172, v173
	v_mov_b32_e32 v173, v172
	s_nop 1
	v_permlane32_swap_b32_e32 v173, v172
	s_waitcnt lgkmcnt(0)
	v_add_f32_e32 v172, v172, v173
	v_fmamk_f32 v174, v172, 0xbc800000, v65
	v_fmamk_f32 v176, v172, 0xbc800000, v63
	v_fmamk_f32 v173, v172, 0xbc800000, v64
	v_fmamk_f32 v175, v172, 0xbc800000, v62
	v_mul_f32_e32 v176, v176, v176
	v_mul_f32_e32 v174, v174, v174
	v_fmac_f32_e32 v176, v175, v175
	v_fmac_f32_e32 v174, v173, v173
	v_fmamk_f32 v175, v172, 0xbc800000, v61
	v_fmamk_f32 v177, v172, 0xbc800000, v59
	v_add_f32_e32 v173, v176, v174
	v_fmamk_f32 v174, v172, 0xbc800000, v60
	v_fmamk_f32 v176, v172, 0xbc800000, v58
	v_mul_f32_e32 v177, v177, v177
	v_mul_f32_e32 v175, v175, v175
	v_fmac_f32_e32 v177, v176, v176
	v_fmac_f32_e32 v175, v174, v174
	v_add_f32_e32 v174, v177, v175
	v_fmamk_f32 v175, v172, 0xbc800000, v73
	v_fmamk_f32 v177, v172, 0xbc800000, v71
	v_add_f32_e32 v173, v173, v174
	v_fmamk_f32 v174, v172, 0xbc800000, v72
	v_fmamk_f32 v176, v172, 0xbc800000, v70
	v_mul_f32_e32 v177, v177, v177
	v_mul_f32_e32 v175, v175, v175
	v_fmac_f32_e32 v177, v176, v176
	v_fmac_f32_e32 v175, v174, v174
	v_add_f32_e32 v174, v177, v175
	v_fmamk_f32 v175, v172, 0xbc800000, v69
	v_fmamk_f32 v177, v172, 0xbc800000, v67
	v_add_f32_e32 v173, v174, v173
	v_fmamk_f32 v174, v172, 0xbc800000, v68
	v_fmamk_f32 v176, v172, 0xbc800000, v66
	v_mul_f32_e32 v177, v177, v177
	v_mul_f32_e32 v175, v175, v175
	v_fmac_f32_e32 v177, v176, v176
	v_fmac_f32_e32 v175, v174, v174
	v_add_f32_e32 v174, v177, v175
	v_add_f32_e32 v173, v174, v173
	v_mov_b32_e32 v174, v173
	s_nop 1
	v_permlane16_swap_b32_e32 v174, v173
	s_waitcnt lgkmcnt(0)
	v_add_f32_e32 v173, v173, v174
	v_mov_b32_e32 v174, v173
	s_nop 1
	v_permlane32_swap_b32_e32 v174, v173
	s_and_saveexec_b64 s[0:1], vcc
	s_cbranch_execz .LBB0_770
	s_lshl_b32 s5, s10, 11
	s_add_i32 s5, s4, s5
	v_mul_f32_e32 v172, 0x3c800000, v172
	v_lshl_add_u32 v175, v167, 5, s5
	s_waitcnt lgkmcnt(0)
	v_add_f32_e32 v173, v173, v174
	ds_write_b64 v175, v[172:173] offset:1024
.LBB0_770:
	s_or_b64 exec, exec, s[0:1]
	v_mov_b32_e32 v172, v87
	v_mov_b32_e32 v173, v88
	s_waitcnt lgkmcnt(0)
	v_mov_b32_e32 v174, v86
	v_mov_b32_e32 v175, v89
	v_pk_add_f32 v[172:173], v[172:173], v[174:175]
	v_mov_b32_e32 v174, v83
	v_mov_b32_e32 v175, v84
	v_mov_b32_e32 v176, v82
	v_mov_b32_e32 v177, v85
	v_pk_add_f32 v[174:175], v[174:175], v[176:177]
	v_add_f32_e32 v172, v172, v173
	v_pk_add_f32 v[174:175], v[174:175], v[174:175] op_sel_hi:[0,1]
	v_add_f32_e32 v173, 0, v172
	v_add_f32_e32 v177, v94, v95
	v_add_f32_e32 v197, v96, v97
	v_mov_b32_e32 v176, v90
	v_mov_b32_e32 v196, v91
	v_mov_b32_e32 v174, v92
	v_mov_b32_e32 v172, v93
	v_pk_add_f32 v[176:177], v[176:177], v[196:197]
	v_pk_add_f32 v[172:173], v[174:175], v[172:173]
	s_nop 0
	v_pk_add_f32 v[172:173], v[176:177], v[172:173]
	s_nop 0
	v_add_f32_e32 v172, v172, v173
	v_mov_b32_e32 v173, v172
	s_nop 1
	v_permlane16_swap_b32_e32 v173, v172
	s_waitcnt lgkmcnt(0)
	v_add_f32_e32 v172, v172, v173
	v_mov_b32_e32 v173, v172
	s_nop 1
	v_permlane32_swap_b32_e32 v173, v172
	s_waitcnt lgkmcnt(0)
	v_add_f32_e32 v172, v172, v173
	v_fmamk_f32 v174, v172, 0xbc800000, v89
	v_fmamk_f32 v176, v172, 0xbc800000, v87
	v_fmamk_f32 v173, v172, 0xbc800000, v88
	v_fmamk_f32 v175, v172, 0xbc800000, v86
	v_mul_f32_e32 v176, v176, v176
	v_mul_f32_e32 v174, v174, v174
	v_fmac_f32_e32 v176, v175, v175
	v_fmac_f32_e32 v174, v173, v173
	v_fmamk_f32 v175, v172, 0xbc800000, v85
	v_fmamk_f32 v177, v172, 0xbc800000, v83
	v_add_f32_e32 v173, v176, v174
	v_fmamk_f32 v174, v172, 0xbc800000, v84
	v_fmamk_f32 v176, v172, 0xbc800000, v82
	v_mul_f32_e32 v177, v177, v177
	v_mul_f32_e32 v175, v175, v175
	v_fmac_f32_e32 v177, v176, v176
	v_fmac_f32_e32 v175, v174, v174
	v_add_f32_e32 v174, v177, v175
	v_fmamk_f32 v175, v172, 0xbc800000, v97
	v_fmamk_f32 v177, v172, 0xbc800000, v95
	v_add_f32_e32 v173, v173, v174
	v_fmamk_f32 v174, v172, 0xbc800000, v96
	v_fmamk_f32 v176, v172, 0xbc800000, v94
	v_mul_f32_e32 v177, v177, v177
	v_mul_f32_e32 v175, v175, v175
	v_fmac_f32_e32 v177, v176, v176
	v_fmac_f32_e32 v175, v174, v174
	v_add_f32_e32 v174, v177, v175
	v_fmamk_f32 v175, v172, 0xbc800000, v93
	v_fmamk_f32 v177, v172, 0xbc800000, v91
	v_add_f32_e32 v173, v174, v173
	v_fmamk_f32 v174, v172, 0xbc800000, v92
	v_fmamk_f32 v176, v172, 0xbc800000, v90
	v_mul_f32_e32 v177, v177, v177
	v_mul_f32_e32 v175, v175, v175
	v_fmac_f32_e32 v177, v176, v176
	v_fmac_f32_e32 v175, v174, v174
	v_add_f32_e32 v174, v177, v175
	v_add_f32_e32 v173, v174, v173
	v_mov_b32_e32 v174, v173
	s_nop 1
	v_permlane16_swap_b32_e32 v174, v173
	s_waitcnt lgkmcnt(0)
	v_add_f32_e32 v173, v173, v174
	v_mov_b32_e32 v174, v173
	s_nop 1
	v_permlane32_swap_b32_e32 v174, v173
	s_and_saveexec_b64 s[0:1], vcc
	s_cbranch_execz .LBB0_772
	s_lshl_b32 s5, s10, 11
	s_add_i32 s5, s4, s5
	v_mul_f32_e32 v172, 0x3c800000, v172
	v_lshl_add_u32 v175, v167, 5, s5
	s_waitcnt lgkmcnt(0)
	v_add_f32_e32 v173, v173, v174
	ds_write_b64 v175, v[172:173] offset:1536
.LBB0_772:
	s_or_b64 exec, exec, s[0:1]
	v_mov_b32_e32 v172, v119
	v_mov_b32_e32 v173, v120
	s_waitcnt lgkmcnt(0)
	v_mov_b32_e32 v174, v118
	v_mov_b32_e32 v175, v121
	v_pk_add_f32 v[172:173], v[172:173], v[174:175]
	v_mov_b32_e32 v174, v115
	v_mov_b32_e32 v175, v116
	v_mov_b32_e32 v176, v114
	v_mov_b32_e32 v177, v117
	v_pk_add_f32 v[174:175], v[174:175], v[176:177]
	v_add_f32_e32 v172, v172, v173
	v_pk_add_f32 v[174:175], v[174:175], v[174:175] op_sel_hi:[0,1]
	v_add_f32_e32 v173, 0, v172
	v_add_f32_e32 v177, v126, v127
	v_add_f32_e32 v197, v128, v129
	v_mov_b32_e32 v176, v122
	v_mov_b32_e32 v196, v123
	v_mov_b32_e32 v174, v124
	v_mov_b32_e32 v172, v125
	v_pk_add_f32 v[176:177], v[176:177], v[196:197]
	v_pk_add_f32 v[172:173], v[174:175], v[172:173]
	s_nop 0
	v_pk_add_f32 v[172:173], v[176:177], v[172:173]
	s_nop 0
	v_add_f32_e32 v172, v172, v173
	v_mov_b32_e32 v173, v172
	s_nop 1
	v_permlane16_swap_b32_e32 v173, v172
	s_waitcnt lgkmcnt(0)
	v_add_f32_e32 v172, v172, v173
	v_mov_b32_e32 v173, v172
	s_nop 1
	v_permlane32_swap_b32_e32 v173, v172
	s_waitcnt lgkmcnt(0)
	v_add_f32_e32 v172, v172, v173
	v_fmamk_f32 v174, v172, 0xbc800000, v121
	v_fmamk_f32 v176, v172, 0xbc800000, v119
	v_fmamk_f32 v173, v172, 0xbc800000, v120
	v_fmamk_f32 v175, v172, 0xbc800000, v118
	v_mul_f32_e32 v176, v176, v176
	v_mul_f32_e32 v174, v174, v174
	v_fmac_f32_e32 v176, v175, v175
	v_fmac_f32_e32 v174, v173, v173
	v_fmamk_f32 v175, v172, 0xbc800000, v117
	v_fmamk_f32 v177, v172, 0xbc800000, v115
	v_add_f32_e32 v173, v176, v174
	v_fmamk_f32 v174, v172, 0xbc800000, v116
	v_fmamk_f32 v176, v172, 0xbc800000, v114
	v_mul_f32_e32 v177, v177, v177
	v_mul_f32_e32 v175, v175, v175
	v_fmac_f32_e32 v177, v176, v176
	v_fmac_f32_e32 v175, v174, v174
	v_add_f32_e32 v174, v177, v175
	v_fmamk_f32 v175, v172, 0xbc800000, v129
	v_fmamk_f32 v177, v172, 0xbc800000, v127
	v_add_f32_e32 v173, v173, v174
	v_fmamk_f32 v174, v172, 0xbc800000, v128
	v_fmamk_f32 v176, v172, 0xbc800000, v126
	v_mul_f32_e32 v177, v177, v177
	v_mul_f32_e32 v175, v175, v175
	v_fmac_f32_e32 v177, v176, v176
	v_fmac_f32_e32 v175, v174, v174
	v_add_f32_e32 v174, v177, v175
	v_fmamk_f32 v175, v172, 0xbc800000, v125
	v_fmamk_f32 v177, v172, 0xbc800000, v123
	v_add_f32_e32 v173, v174, v173
	v_fmamk_f32 v174, v172, 0xbc800000, v124
	v_fmamk_f32 v176, v172, 0xbc800000, v122
	v_mul_f32_e32 v177, v177, v177
	v_mul_f32_e32 v175, v175, v175
	v_fmac_f32_e32 v177, v176, v176
	v_fmac_f32_e32 v175, v174, v174
	v_add_f32_e32 v174, v177, v175
	v_add_f32_e32 v173, v174, v173
	v_mov_b32_e32 v174, v173
	s_nop 1
	v_permlane16_swap_b32_e32 v174, v173
	s_waitcnt lgkmcnt(0)
	v_add_f32_e32 v173, v173, v174
	v_mov_b32_e32 v174, v173
	s_nop 1
	v_permlane32_swap_b32_e32 v174, v173
	s_and_saveexec_b64 s[0:1], vcc
	s_cbranch_execz .LBB0_774
	s_lshl_b32 s5, s10, 11
	s_add_i32 s5, s4, s5
	v_mul_f32_e32 v172, 0x3c800000, v172
	v_lshl_add_u32 v175, v167, 5, s5
	s_waitcnt lgkmcnt(0)
	v_add_f32_e32 v173, v173, v174
	ds_write_b64 v175, v[172:173] offset:4096
.LBB0_774:
	s_or_b64 exec, exec, s[0:1]
	v_mov_b32_e32 v172, v111
	v_mov_b32_e32 v173, v112
	s_waitcnt lgkmcnt(0)
	v_mov_b32_e32 v174, v110
	v_mov_b32_e32 v175, v113
	v_pk_add_f32 v[172:173], v[172:173], v[174:175]
	v_mov_b32_e32 v174, v107
	v_mov_b32_e32 v175, v108
	v_mov_b32_e32 v176, v106
	v_mov_b32_e32 v177, v109
	v_pk_add_f32 v[174:175], v[174:175], v[176:177]
	v_add_f32_e32 v172, v172, v173
	v_pk_add_f32 v[174:175], v[174:175], v[174:175] op_sel_hi:[0,1]
	v_add_f32_e32 v173, 0, v172
	v_add_f32_e32 v177, v102, v103
	v_add_f32_e32 v197, v104, v105
	v_mov_b32_e32 v176, v98
	v_mov_b32_e32 v196, v99
	v_mov_b32_e32 v174, v100
	v_mov_b32_e32 v172, v101
	v_pk_add_f32 v[176:177], v[176:177], v[196:197]
	v_pk_add_f32 v[172:173], v[174:175], v[172:173]
	s_nop 0
	v_pk_add_f32 v[172:173], v[176:177], v[172:173]
	s_nop 0
	v_add_f32_e32 v172, v172, v173
	v_mov_b32_e32 v173, v172
	s_nop 1
	v_permlane16_swap_b32_e32 v173, v172
	s_waitcnt lgkmcnt(0)
	v_add_f32_e32 v172, v172, v173
	v_mov_b32_e32 v173, v172
	s_nop 1
	v_permlane32_swap_b32_e32 v173, v172
	s_waitcnt lgkmcnt(0)
	v_add_f32_e32 v172, v172, v173
	v_fmamk_f32 v174, v172, 0xbc800000, v113
	v_fmamk_f32 v176, v172, 0xbc800000, v111
	v_fmamk_f32 v173, v172, 0xbc800000, v112
	v_fmamk_f32 v175, v172, 0xbc800000, v110
	v_mul_f32_e32 v176, v176, v176
	v_mul_f32_e32 v174, v174, v174
	v_fmac_f32_e32 v176, v175, v175
	v_fmac_f32_e32 v174, v173, v173
	v_fmamk_f32 v175, v172, 0xbc800000, v109
	v_fmamk_f32 v177, v172, 0xbc800000, v107
	v_add_f32_e32 v173, v176, v174
	v_fmamk_f32 v174, v172, 0xbc800000, v108
	v_fmamk_f32 v176, v172, 0xbc800000, v106
	v_mul_f32_e32 v177, v177, v177
	v_mul_f32_e32 v175, v175, v175
	v_fmac_f32_e32 v177, v176, v176
	v_fmac_f32_e32 v175, v174, v174
	v_add_f32_e32 v174, v177, v175
	v_fmamk_f32 v175, v172, 0xbc800000, v105
	v_fmamk_f32 v177, v172, 0xbc800000, v103
	v_add_f32_e32 v173, v173, v174
	v_fmamk_f32 v174, v172, 0xbc800000, v104
	v_fmamk_f32 v176, v172, 0xbc800000, v102
	v_mul_f32_e32 v177, v177, v177
	v_mul_f32_e32 v175, v175, v175
	v_fmac_f32_e32 v177, v176, v176
	v_fmac_f32_e32 v175, v174, v174
	v_add_f32_e32 v174, v177, v175
	v_fmamk_f32 v175, v172, 0xbc800000, v101
	v_fmamk_f32 v177, v172, 0xbc800000, v99
	v_add_f32_e32 v173, v174, v173
	v_fmamk_f32 v174, v172, 0xbc800000, v100
	v_fmamk_f32 v176, v172, 0xbc800000, v98
	v_mul_f32_e32 v177, v177, v177
	v_mul_f32_e32 v175, v175, v175
	v_fmac_f32_e32 v177, v176, v176
	v_fmac_f32_e32 v175, v174, v174
	v_add_f32_e32 v174, v177, v175
	v_add_f32_e32 v173, v174, v173
	v_mov_b32_e32 v174, v173
	s_nop 1
	v_permlane16_swap_b32_e32 v174, v173
	s_waitcnt lgkmcnt(0)
	v_add_f32_e32 v173, v173, v174
	v_mov_b32_e32 v174, v173
	s_nop 1
	v_permlane32_swap_b32_e32 v174, v173
	s_and_saveexec_b64 s[0:1], vcc
	s_cbranch_execz .LBB0_776
	s_lshl_b32 s5, s10, 11
	s_add_i32 s5, s4, s5
	v_mul_f32_e32 v172, 0x3c800000, v172
	v_lshl_add_u32 v175, v167, 5, s5
	s_waitcnt lgkmcnt(0)
	v_add_f32_e32 v173, v173, v174
	ds_write_b64 v175, v[172:173] offset:4608
.LBB0_776:
	s_or_b64 exec, exec, s[0:1]
	v_mov_b32_e32 v172, v79
	v_mov_b32_e32 v173, v80
	s_waitcnt lgkmcnt(0)
	v_mov_b32_e32 v174, v78
	v_mov_b32_e32 v175, v81
	v_pk_add_f32 v[172:173], v[172:173], v[174:175]
	v_mov_b32_e32 v174, v75
	v_mov_b32_e32 v175, v76
	v_mov_b32_e32 v176, v74
	v_mov_b32_e32 v177, v77
	v_pk_add_f32 v[174:175], v[174:175], v[176:177]
	v_add_f32_e32 v172, v172, v173
	v_pk_add_f32 v[174:175], v[174:175], v[174:175] op_sel_hi:[0,1]
	v_add_f32_e32 v173, 0, v172
	v_add_f32_e32 v177, v54, v55
	v_add_f32_e32 v197, v56, v57
	v_mov_b32_e32 v176, v50
	v_mov_b32_e32 v196, v51
	v_mov_b32_e32 v174, v52
	v_mov_b32_e32 v172, v53
	v_pk_add_f32 v[176:177], v[176:177], v[196:197]
	v_pk_add_f32 v[172:173], v[174:175], v[172:173]
	s_nop 0
	v_pk_add_f32 v[172:173], v[176:177], v[172:173]
	s_nop 0
	v_add_f32_e32 v172, v172, v173
	v_mov_b32_e32 v173, v172
	s_nop 1
	v_permlane16_swap_b32_e32 v173, v172
	s_waitcnt lgkmcnt(0)
	v_add_f32_e32 v172, v172, v173
	v_mov_b32_e32 v173, v172
	s_nop 1
	v_permlane32_swap_b32_e32 v173, v172
	s_waitcnt lgkmcnt(0)
	v_add_f32_e32 v172, v172, v173
	v_fmamk_f32 v174, v172, 0xbc800000, v81
	v_fmamk_f32 v176, v172, 0xbc800000, v79
	v_fmamk_f32 v173, v172, 0xbc800000, v80
	v_fmamk_f32 v175, v172, 0xbc800000, v78
	v_mul_f32_e32 v176, v176, v176
	v_mul_f32_e32 v174, v174, v174
	v_fmac_f32_e32 v176, v175, v175
	v_fmac_f32_e32 v174, v173, v173
	v_fmamk_f32 v175, v172, 0xbc800000, v77
	v_fmamk_f32 v177, v172, 0xbc800000, v75
	v_add_f32_e32 v173, v176, v174
	v_fmamk_f32 v174, v172, 0xbc800000, v76
	v_fmamk_f32 v176, v172, 0xbc800000, v74
	v_mul_f32_e32 v177, v177, v177
	v_mul_f32_e32 v175, v175, v175
	v_fmac_f32_e32 v177, v176, v176
	v_fmac_f32_e32 v175, v174, v174
	v_add_f32_e32 v174, v177, v175
	v_fmamk_f32 v175, v172, 0xbc800000, v57
	v_fmamk_f32 v177, v172, 0xbc800000, v55
	v_add_f32_e32 v173, v173, v174
	v_fmamk_f32 v174, v172, 0xbc800000, v56
	v_fmamk_f32 v176, v172, 0xbc800000, v54
	v_mul_f32_e32 v177, v177, v177
	v_mul_f32_e32 v175, v175, v175
	v_fmac_f32_e32 v177, v176, v176
	v_fmac_f32_e32 v175, v174, v174
	v_add_f32_e32 v174, v177, v175
	v_fmamk_f32 v175, v172, 0xbc800000, v53
	v_fmamk_f32 v177, v172, 0xbc800000, v51
	v_add_f32_e32 v173, v174, v173
	v_fmamk_f32 v174, v172, 0xbc800000, v52
	v_fmamk_f32 v176, v172, 0xbc800000, v50
	v_mul_f32_e32 v177, v177, v177
	v_mul_f32_e32 v175, v175, v175
	v_fmac_f32_e32 v177, v176, v176
	v_fmac_f32_e32 v175, v174, v174
	v_add_f32_e32 v174, v177, v175
	v_add_f32_e32 v173, v174, v173
	v_mov_b32_e32 v174, v173
	s_nop 1
	v_permlane16_swap_b32_e32 v174, v173
	s_waitcnt lgkmcnt(0)
	v_add_f32_e32 v173, v173, v174
	v_mov_b32_e32 v174, v173
	s_nop 1
	v_permlane32_swap_b32_e32 v174, v173
	s_and_saveexec_b64 s[0:1], vcc
	s_cbranch_execz .LBB0_778
	s_lshl_b32 s5, s10, 11
	s_add_i32 s5, s4, s5
	v_mul_f32_e32 v172, 0x3c800000, v172
	v_lshl_add_u32 v175, v167, 5, s5
	s_waitcnt lgkmcnt(0)
	v_add_f32_e32 v173, v173, v174
	ds_write_b64 v175, v[172:173] offset:5120
.LBB0_778:
	s_or_b64 exec, exec, s[0:1]
	v_mov_b32_e32 v172, v31
	v_mov_b32_e32 v173, v32
	s_waitcnt lgkmcnt(0)
	v_mov_b32_e32 v174, v30
	v_mov_b32_e32 v175, v33
	v_pk_add_f32 v[172:173], v[172:173], v[174:175]
	v_mov_b32_e32 v174, v27
	v_mov_b32_e32 v175, v28
	v_mov_b32_e32 v176, v26
	v_mov_b32_e32 v177, v29
	v_pk_add_f32 v[174:175], v[174:175], v[176:177]
	v_add_f32_e32 v172, v172, v173
	v_pk_add_f32 v[174:175], v[174:175], v[174:175] op_sel_hi:[0,1]
	v_add_f32_e32 v173, 0, v172
	v_add_f32_e32 v177, v134, v135
	v_add_f32_e32 v197, v136, v137
	v_mov_b32_e32 v176, v2
	v_mov_b32_e32 v196, v3
	v_mov_b32_e32 v174, v4
	v_mov_b32_e32 v172, v5
	v_pk_add_f32 v[176:177], v[176:177], v[196:197]
	v_pk_add_f32 v[172:173], v[174:175], v[172:173]
	s_nop 0
	v_pk_add_f32 v[172:173], v[176:177], v[172:173]
	s_nop 0
	v_add_f32_e32 v172, v172, v173
	v_mov_b32_e32 v173, v172
	s_nop 1
	v_permlane16_swap_b32_e32 v173, v172
	s_waitcnt lgkmcnt(0)
	v_add_f32_e32 v172, v172, v173
	v_mov_b32_e32 v173, v172
	s_nop 1
	v_permlane32_swap_b32_e32 v173, v172
	s_waitcnt lgkmcnt(0)
	v_add_f32_e32 v172, v172, v173
	v_fmamk_f32 v174, v172, 0xbc800000, v33
	v_fmamk_f32 v176, v172, 0xbc800000, v31
	v_fmamk_f32 v173, v172, 0xbc800000, v32
	v_fmamk_f32 v175, v172, 0xbc800000, v30
	v_mul_f32_e32 v176, v176, v176
	v_mul_f32_e32 v174, v174, v174
	v_fmac_f32_e32 v176, v175, v175
	v_fmac_f32_e32 v174, v173, v173
	v_fmamk_f32 v175, v172, 0xbc800000, v29
	v_fmamk_f32 v177, v172, 0xbc800000, v27
	v_add_f32_e32 v173, v176, v174
	v_fmamk_f32 v174, v172, 0xbc800000, v28
	v_fmamk_f32 v176, v172, 0xbc800000, v26
	v_mul_f32_e32 v177, v177, v177
	v_mul_f32_e32 v175, v175, v175
	v_fmac_f32_e32 v177, v176, v176
	v_fmac_f32_e32 v175, v174, v174
	v_add_f32_e32 v174, v177, v175
	v_fmamk_f32 v175, v172, 0xbc800000, v137
	v_fmamk_f32 v177, v172, 0xbc800000, v135
	v_add_f32_e32 v173, v173, v174
	v_fmamk_f32 v174, v172, 0xbc800000, v136
	v_fmamk_f32 v176, v172, 0xbc800000, v134
	v_mul_f32_e32 v177, v177, v177
	v_mul_f32_e32 v175, v175, v175
	v_fmac_f32_e32 v177, v176, v176
	v_fmac_f32_e32 v175, v174, v174
	v_add_f32_e32 v174, v177, v175
	v_fmamk_f32 v175, v172, 0xbc800000, v5
	v_fmamk_f32 v177, v172, 0xbc800000, v3
	v_add_f32_e32 v173, v174, v173
	v_fmamk_f32 v174, v172, 0xbc800000, v4
	v_fmamk_f32 v176, v172, 0xbc800000, v2
	v_mul_f32_e32 v177, v177, v177
	v_mul_f32_e32 v175, v175, v175
	v_fmac_f32_e32 v177, v176, v176
	v_fmac_f32_e32 v175, v174, v174
	v_add_f32_e32 v174, v177, v175
	v_add_f32_e32 v173, v174, v173
	v_mov_b32_e32 v170, v173
	s_nop 1
	v_permlane16_swap_b32_e32 v170, v173
	s_waitcnt lgkmcnt(0)
	v_add_f32_e32 v170, v173, v170
	v_mov_b32_e32 v171, v170
	s_nop 1
	v_permlane32_swap_b32_e32 v171, v170
	s_and_saveexec_b64 s[0:1], vcc
	s_cbranch_execz .LBB0_780
	s_lshl_b32 s5, s10, 11
	s_add_i32 s4, s4, s5
	v_mul_f32_e32 v172, 0x3c800000, v172
	v_lshl_add_u32 v167, v167, 5, s4
	s_waitcnt lgkmcnt(0)
	v_add_f32_e32 v173, v170, v171
	ds_write_b64 v167, v[172:173] offset:5632

.LBB0_825:
	s_lshl_b64 s[0:1], s[34:35], 2
	v_readlane_b32 s60, v253, 6
	v_readlane_b32 s61, v253, 7
	s_add_u32 s0, s60, s0
	s_addc_u32 s1, s61, s1
	v_lshrrev_b32_e32 v130, 1, v170
	s_lshl_b32 s12, s82, 8
	v_and_b32_e32 v130, 24, v130
	s_add_i32 s4, s12, s41
	s_lshl_b32 s28, s8, 8
	v_lshl_or_b32 v130, s10, 5, v130
	v_or_b32_e32 v166, s4, v171
	v_or_b32_e32 v162, s28, v130
	v_ashrrev_i32_e32 v167, 31, v166
	v_ashrrev_i32_e32 v163, 31, v162
	v_lshlrev_b64 v[130:131], 12, v[166:167]
	v_lshl_add_u64 v[130:131], s[0:1], 0, v[130:131]
	v_lshlrev_b64 v[164:165], 2, v[162:163]
	v_lshl_add_u64 v[142:143], v[130:131], 0, v[164:165]
	s_barrier
	global_load_dwordx4 v[130:133], v[142:143], off
	global_load_dwordx4 v[134:137], v[142:143], off offset:16
	global_load_dwordx4 v[138:141], v[142:143], off offset:512
	s_nop 0
	global_load_dwordx4 v[142:145], v[142:143], off offset:528
	v_or_b32_e32 v146, 16, v166
	v_ashrrev_i32_e32 v147, 31, v146
	v_lshlrev_b64 v[146:147], 12, v[146:147]
	v_lshl_add_u64 v[146:147], s[0:1], 0, v[146:147]
	v_lshl_add_u64 v[172:173], v[146:147], 0, v[164:165]
	v_readlane_b32 s62, v253, 8
	v_readlane_b32 s63, v253, 9
	v_readlane_b32 s64, v253, 10
	v_readlane_b32 s65, v253, 11
	v_readlane_b32 s66, v253, 12
	v_readlane_b32 s67, v253, 13
	v_readlane_b32 s68, v253, 14
	v_readlane_b32 s69, v253, 15
	v_readlane_b32 s70, v253, 16
	v_readlane_b32 s71, v253, 17
	v_readlane_b32 s72, v253, 18
	v_readlane_b32 s73, v253, 19
	v_readlane_b32 s74, v253, 20
	v_readlane_b32 s75, v253, 21
	s_waitcnt vmcnt(0)
	v_pk_fma_f32 v[160:161], v[132:133], s[86:87], v[128:129] op_sel_hi:[1,0,1]
	v_pk_fma_f32 v[158:159], v[130:131], s[86:87], v[126:127] op_sel_hi:[1,0,1]
	v_pk_fma_f32 v[156:157], v[136:137], s[86:87], v[124:125] op_sel_hi:[1,0,1]
	v_pk_fma_f32 v[154:155], v[134:135], s[86:87], v[122:123] op_sel_hi:[1,0,1]
	v_pk_fma_f32 v[152:153], v[140:141], s[86:87], v[120:121] op_sel_hi:[1,0,1]
	v_pk_fma_f32 v[150:151], v[138:139], s[86:87], v[118:119] op_sel_hi:[1,0,1]
	v_pk_fma_f32 v[148:149], v[144:145], s[86:87], v[116:117] op_sel_hi:[1,0,1]
	v_pk_fma_f32 v[146:147], v[142:143], s[86:87], v[114:115] op_sel_hi:[1,0,1]
	v_or_b32_e32 v130, 32, v166
	global_load_dwordx4 v[114:117], v[172:173], off
	global_load_dwordx4 v[118:121], v[172:173], off offset:16
	global_load_dwordx4 v[122:125], v[172:173], off offset:512
	global_load_dwordx4 v[126:129], v[172:173], off offset:528
	v_ashrrev_i32_e32 v131, 31, v130
	v_lshlrev_b64 v[130:131], 12, v[130:131]
	v_lshl_add_u64 v[130:131], s[0:1], 0, v[130:131]
	v_lshl_add_u64 v[172:173], v[130:131], 0, v[164:165]
	v_add_f32_e32 v177, v152, v153
	v_mov_b32_e32 v176, v147
	s_waitcnt vmcnt(3)
	v_pk_fma_f32 v[144:145], v[116:117], s[86:87], v[112:113] op_sel_hi:[1,0,1]
	v_pk_fma_f32 v[142:143], v[114:115], s[86:87], v[110:111] op_sel_hi:[1,0,1]
	s_waitcnt vmcnt(2)
	v_pk_fma_f32 v[140:141], v[120:121], s[86:87], v[108:109] op_sel_hi:[1,0,1]
	v_pk_fma_f32 v[138:139], v[118:119], s[86:87], v[106:107] op_sel_hi:[1,0,1]
	s_waitcnt vmcnt(1)
	v_pk_fma_f32 v[136:137], v[124:125], s[86:87], v[104:105] op_sel_hi:[1,0,1]
	v_pk_fma_f32 v[134:135], v[122:123], s[86:87], v[102:103] op_sel_hi:[1,0,1]
	s_waitcnt vmcnt(0)
	v_pk_fma_f32 v[132:133], v[128:129], s[86:87], v[100:101] op_sel_hi:[1,0,1]
	v_pk_fma_f32 v[130:131], v[126:127], s[86:87], v[98:99] op_sel_hi:[1,0,1]
	v_or_b32_e32 v114, 48, v166
	global_load_dwordx4 v[98:101], v[172:173], off
	global_load_dwordx4 v[102:105], v[172:173], off offset:16
	global_load_dwordx4 v[106:109], v[172:173], off offset:512
	global_load_dwordx4 v[110:113], v[172:173], off offset:528
	v_ashrrev_i32_e32 v115, 31, v114
	v_lshlrev_b64 v[114:115], 12, v[114:115]
	v_lshl_add_u64 v[114:115], s[0:1], 0, v[114:115]
	v_lshl_add_u64 v[172:173], v[114:115], 0, v[164:165]
	s_waitcnt vmcnt(3)
	v_pk_fma_f32 v[128:129], v[100:101], s[86:87], v[96:97] op_sel_hi:[1,0,1]
	v_pk_fma_f32 v[126:127], v[98:99], s[86:87], v[94:95] op_sel_hi:[1,0,1]
	s_waitcnt vmcnt(2)
	v_pk_fma_f32 v[124:125], v[104:105], s[86:87], v[92:93] op_sel_hi:[1,0,1]
	v_pk_fma_f32 v[122:123], v[102:103], s[86:87], v[90:91] op_sel_hi:[1,0,1]
	s_waitcnt vmcnt(1)
	v_pk_fma_f32 v[120:121], v[108:109], s[86:87], v[88:89] op_sel_hi:[1,0,1]
	v_pk_fma_f32 v[118:119], v[106:107], s[86:87], v[86:87] op_sel_hi:[1,0,1]
	s_waitcnt vmcnt(0)
	v_pk_fma_f32 v[116:117], v[112:113], s[86:87], v[84:85] op_sel_hi:[1,0,1]
	v_pk_fma_f32 v[114:115], v[110:111], s[86:87], v[82:83] op_sel_hi:[1,0,1]
	v_add_u32_e32 v98, 0x80, v166
	global_load_dwordx4 v[82:85], v[172:173], off
	global_load_dwordx4 v[86:89], v[172:173], off offset:16
	global_load_dwordx4 v[90:93], v[172:173], off offset:512
	global_load_dwordx4 v[94:97], v[172:173], off offset:528
	v_ashrrev_i32_e32 v99, 31, v98
	v_lshlrev_b64 v[98:99], 12, v[98:99]
	v_lshl_add_u64 v[98:99], s[0:1], 0, v[98:99]
	v_lshl_add_u64 v[172:173], v[98:99], 0, v[164:165]
	s_waitcnt vmcnt(3)
	v_pk_fma_f32 v[112:113], v[84:85], s[86:87], v[80:81] op_sel_hi:[1,0,1]
	v_pk_fma_f32 v[110:111], v[82:83], s[86:87], v[78:79] op_sel_hi:[1,0,1]
	s_waitcnt vmcnt(2)
	v_pk_fma_f32 v[108:109], v[88:89], s[86:87], v[76:77] op_sel_hi:[1,0,1]
	v_pk_fma_f32 v[106:107], v[86:87], s[86:87], v[74:75] op_sel_hi:[1,0,1]
	s_waitcnt vmcnt(1)
	v_pk_fma_f32 v[104:105], v[92:93], s[86:87], v[72:73] op_sel_hi:[1,0,1]
	v_pk_fma_f32 v[102:103], v[90:91], s[86:87], v[70:71] op_sel_hi:[1,0,1]
	s_waitcnt vmcnt(0)
	v_pk_fma_f32 v[100:101], v[96:97], s[86:87], v[68:69] op_sel_hi:[1,0,1]
	v_pk_fma_f32 v[98:99], v[94:95], s[86:87], v[66:67] op_sel_hi:[1,0,1]
	v_add_u32_e32 v82, 0x90, v166
	global_load_dwordx4 v[66:69], v[172:173], off
	global_load_dwordx4 v[70:73], v[172:173], off offset:16
	global_load_dwordx4 v[74:77], v[172:173], off offset:512
	global_load_dwordx4 v[78:81], v[172:173], off offset:528
	v_ashrrev_i32_e32 v83, 31, v82
	v_lshlrev_b64 v[82:83], 12, v[82:83]
	v_lshl_add_u64 v[82:83], s[0:1], 0, v[82:83]
	v_lshl_add_u64 v[172:173], v[82:83], 0, v[164:165]
	s_waitcnt vmcnt(3)
	v_pk_fma_f32 v[96:97], v[68:69], s[86:87], v[64:65] op_sel_hi:[1,0,1]
	v_pk_fma_f32 v[94:95], v[66:67], s[86:87], v[62:63] op_sel_hi:[1,0,1]
	s_waitcnt vmcnt(2)
	v_pk_fma_f32 v[92:93], v[72:73], s[86:87], v[60:61] op_sel_hi:[1,0,1]
	v_pk_fma_f32 v[90:91], v[70:71], s[86:87], v[58:59] op_sel_hi:[1,0,1]
	s_waitcnt vmcnt(1)
	v_pk_fma_f32 v[88:89], v[76:77], s[86:87], v[56:57] op_sel_hi:[1,0,1]
	v_pk_fma_f32 v[86:87], v[74:75], s[86:87], v[54:55] op_sel_hi:[1,0,1]
	s_waitcnt vmcnt(0)
	v_pk_fma_f32 v[84:85], v[80:81], s[86:87], v[52:53] op_sel_hi:[1,0,1]
	v_pk_fma_f32 v[82:83], v[78:79], s[86:87], v[50:51] op_sel_hi:[1,0,1]
	v_add_u32_e32 v66, 0xa0, v166
	global_load_dwordx4 v[50:53], v[172:173], off
	global_load_dwordx4 v[54:57], v[172:173], off offset:16
	global_load_dwordx4 v[58:61], v[172:173], off offset:512
	global_load_dwordx4 v[62:65], v[172:173], off offset:528
	v_ashrrev_i32_e32 v67, 31, v66
	v_lshlrev_b64 v[66:67], 12, v[66:67]
	v_lshl_add_u64 v[66:67], s[0:1], 0, v[66:67]
	v_lshl_add_u64 v[172:173], v[66:67], 0, v[164:165]
	s_waitcnt vmcnt(3)
	v_pk_fma_f32 v[80:81], v[52:53], s[86:87], v[48:49] op_sel_hi:[1,0,1]
	v_pk_fma_f32 v[78:79], v[50:51], s[86:87], v[46:47] op_sel_hi:[1,0,1]
	s_waitcnt vmcnt(2)
	v_pk_fma_f32 v[76:77], v[56:57], s[86:87], v[44:45] op_sel_hi:[1,0,1]
	v_pk_fma_f32 v[74:75], v[54:55], s[86:87], v[42:43] op_sel_hi:[1,0,1]
	s_waitcnt vmcnt(1)
	v_pk_fma_f32 v[72:73], v[60:61], s[86:87], v[40:41] op_sel_hi:[1,0,1]
	v_pk_fma_f32 v[70:71], v[58:59], s[86:87], v[38:39] op_sel_hi:[1,0,1]
	s_waitcnt vmcnt(0)
	v_pk_fma_f32 v[68:69], v[64:65], s[86:87], v[36:37] op_sel_hi:[1,0,1]
	v_pk_fma_f32 v[66:67], v[62:63], s[86:87], v[34:35] op_sel_hi:[1,0,1]
	v_add_u32_e32 v50, 0xb0, v166
	global_load_dwordx4 v[34:37], v[172:173], off
	global_load_dwordx4 v[38:41], v[172:173], off offset:16
	global_load_dwordx4 v[42:45], v[172:173], off offset:512
	global_load_dwordx4 v[46:49], v[172:173], off offset:528
	v_ashrrev_i32_e32 v51, 31, v50
	v_lshlrev_b64 v[50:51], 12, v[50:51]
	v_lshl_add_u64 v[50:51], s[0:1], 0, v[50:51]
	v_lshl_add_u64 v[50:51], v[50:51], 0, v[164:165]
	v_readlane_b32 s0, v255, 18
	v_readlane_b32 s1, v255, 19
	s_waitcnt vmcnt(3)
	v_pk_fma_f32 v[64:65], v[36:37], s[86:87], v[32:33] op_sel_hi:[1,0,1]
	v_pk_fma_f32 v[62:63], v[34:35], s[86:87], v[30:31] op_sel_hi:[1,0,1]
	s_waitcnt vmcnt(2)
	v_pk_fma_f32 v[60:61], v[40:41], s[86:87], v[28:29] op_sel_hi:[1,0,1]
	v_pk_fma_f32 v[58:59], v[38:39], s[86:87], v[26:27] op_sel_hi:[1,0,1]
	s_waitcnt vmcnt(1)
	v_pk_fma_f32 v[32:33], v[44:45], s[86:87], v[24:25] op_sel_hi:[1,0,1]
	v_pk_fma_f32 v[30:31], v[42:43], s[86:87], v[22:23] op_sel_hi:[1,0,1]
	s_waitcnt vmcnt(0)
	v_pk_fma_f32 v[28:29], v[48:49], s[86:87], v[20:21] op_sel_hi:[1,0,1]
	v_pk_fma_f32 v[26:27], v[46:47], s[86:87], v[18:19] op_sel_hi:[1,0,1]
	v_and_b32_e32 v39, 64, v205
	global_load_dwordx4 v[18:21], v[50:51], off
	global_load_dwordx4 v[22:25], v[50:51], off offset:16
	global_load_dwordx4 v[34:37], v[50:51], off offset:512
	global_load_dwordx4 v[42:45], v[50:51], off offset:528
	v_xor_b32_e32 v38, 16, v205
	v_add_u32_e32 v167, 64, v39
	v_cmp_lt_i32_e32 vcc, v38, v167
	v_lshl_add_u64 v[172:173], s[0:1], 0, v[164:165]
	v_readlane_b32 s0, v255, 27
	v_cndmask_b32_e32 v38, v205, v38, vcc
	v_lshlrev_b32_e32 v166, 2, v38
	v_mov_b32_e32 v38, v159
	v_mov_b32_e32 v39, v160
	v_mov_b32_e32 v40, v158
	v_mov_b32_e32 v41, v161
	v_readlane_b32 s1, v255, 28
	v_pk_add_f32 v[174:175], v[38:39], v[40:41]
	s_waitcnt vmcnt(3)
	v_pk_fma_f32 v[48:49], v[20:21], s[86:87], v[16:17] op_sel_hi:[1,0,1]
	v_pk_fma_f32 v[46:47], v[18:19], s[86:87], v[14:15] op_sel_hi:[1,0,1]
	s_waitcnt vmcnt(2)
	v_pk_fma_f32 v[40:41], v[24:25], s[86:87], v[12:13] op_sel_hi:[1,0,1]
	v_pk_fma_f32 v[38:39], v[22:23], s[86:87], v[10:11] op_sel_hi:[1,0,1]
	s_waitcnt vmcnt(1)
	v_pk_fma_f32 v[16:17], v[36:37], s[86:87], v[8:9] op_sel_hi:[1,0,1]
	v_pk_fma_f32 v[14:15], v[34:35], s[86:87], v[6:7] op_sel_hi:[1,0,1]
	s_waitcnt vmcnt(0)
	v_pk_fma_f32 v[8:9], v[44:45], s[86:87], v[4:5] op_sel_hi:[1,0,1]
	v_pk_fma_f32 v[6:7], v[42:43], s[86:87], v[2:3] op_sel_hi:[1,0,1]
	v_lshl_add_u64 v[164:165], s[0:1], 0, v[164:165]
	global_load_dwordx4 v[34:37], v[172:173], off offset:16
	global_load_dwordx4 v[50:53], v[172:173], off
	global_load_dwordx4 v[42:45], v[164:165], off offset:16
	global_load_dwordx4 v[54:57], v[164:165], off
	global_load_dwordx4 v[2:5], v[172:173], off offset:528
	global_load_dwordx4 v[18:21], v[172:173], off offset:512
	global_load_dwordx4 v[10:13], v[164:165], off offset:528
	global_load_dwordx4 v[22:25], v[164:165], off offset:512
	v_add_f32_e32 v164, v174, v175
	v_mov_b32_e32 v172, v155
	v_mov_b32_e32 v173, v156
	v_mov_b32_e32 v174, v154
	v_mov_b32_e32 v175, v157
	v_pk_add_f32 v[172:173], v[172:173], v[174:175]
	v_add_f32_e32 v165, 0, v164
	v_pk_add_f32 v[172:173], v[172:173], v[172:173] op_sel_hi:[0,1]
	v_add_f32_e32 v175, v150, v151
	v_mov_b32_e32 v174, v146
	v_mov_b32_e32 v172, v148
	v_mov_b32_e32 v164, v149
	v_pk_add_f32 v[174:175], v[174:175], v[176:177]
	v_pk_add_f32 v[164:165], v[172:173], v[164:165]
	s_lshl_b32 s0, s10, 3
	v_pk_add_f32 v[164:165], v[174:175], v[164:165]
	s_add_i32 s4, s0, 0
	v_add_f32_e32 v165, v164, v165
	v_mov_b32_e32 v172, v165
	s_nop 1
	v_permlane16_swap_b32_e32 v172, v165
	v_xor_b32_e32 v164, 32, v205
	v_cmp_lt_i32_e32 vcc, v164, v167
	s_waitcnt lgkmcnt(0)
	v_add_f32_e32 v165, v165, v172
	v_cndmask_b32_e32 v164, v205, v164, vcc
	v_lshlrev_b32_e32 v164, 2, v164
	v_mov_b32_e32 v167, v165
	s_nop 1
	v_permlane32_swap_b32_e32 v167, v165
	s_waitcnt lgkmcnt(0)
	v_add_f32_e32 v165, v165, v167
	v_fmamk_f32 v172, v165, 0xbc800000, v161
	v_fmamk_f32 v174, v165, 0xbc800000, v159
	v_fmamk_f32 v167, v165, 0xbc800000, v160
	v_fmamk_f32 v173, v165, 0xbc800000, v158
	v_mul_f32_e32 v174, v174, v174
	v_mul_f32_e32 v172, v172, v172
	v_fmac_f32_e32 v174, v173, v173
	v_fmac_f32_e32 v172, v167, v167
	v_fmamk_f32 v173, v165, 0xbc800000, v157
	v_fmamk_f32 v175, v165, 0xbc800000, v155
	v_add_f32_e32 v167, v174, v172
	v_fmamk_f32 v172, v165, 0xbc800000, v156
	v_fmamk_f32 v174, v165, 0xbc800000, v154
	v_mul_f32_e32 v175, v175, v175
	v_mul_f32_e32 v173, v173, v173
	v_fmac_f32_e32 v175, v174, v174
	v_fmac_f32_e32 v173, v172, v172
	v_add_f32_e32 v172, v175, v173
	v_fmamk_f32 v173, v165, 0xbc800000, v153
	v_fmamk_f32 v175, v165, 0xbc800000, v151
	v_add_f32_e32 v167, v167, v172
	v_fmamk_f32 v172, v165, 0xbc800000, v152
	v_fmamk_f32 v174, v165, 0xbc800000, v150
	v_mul_f32_e32 v175, v175, v175
	v_mul_f32_e32 v173, v173, v173
	v_fmac_f32_e32 v175, v174, v174
	v_fmac_f32_e32 v173, v172, v172
	v_add_f32_e32 v172, v175, v173
	v_fmamk_f32 v173, v165, 0xbc800000, v149
	v_fmamk_f32 v175, v165, 0xbc800000, v147
	v_add_f32_e32 v167, v172, v167
	v_fmamk_f32 v172, v165, 0xbc800000, v148
	v_fmamk_f32 v174, v165, 0xbc800000, v146
	v_mul_f32_e32 v175, v175, v175
	v_mul_f32_e32 v173, v173, v173
	v_fmac_f32_e32 v175, v174, v174
	v_fmac_f32_e32 v173, v172, v172
	v_add_f32_e32 v172, v175, v173
	v_add_f32_e32 v167, v172, v167
	v_mov_b32_e32 v172, v167
	s_nop 1
	v_permlane16_swap_b32_e32 v172, v167
	s_waitcnt lgkmcnt(0)
	v_add_f32_e32 v172, v167, v172
	v_mov_b32_e32 v173, v172
	s_nop 1
	v_permlane32_swap_b32_e32 v173, v172
	v_and_b32_e32 v167, 63, v170
	v_cmp_gt_u32_e32 vcc, 16, v167
	s_and_saveexec_b64 s[0:1], vcc
	v_readlane_b32 s62, v255, 10
	v_readlane_b32 s84, v255, 12
	v_readlane_b32 s63, v255, 11
	v_readlane_b32 s85, v255, 13
	s_movk_i32 s89, 0x60
	s_cbranch_execz .LBB0_827
	s_lshl_b32 s5, s13, 11
	s_add_i32 s5, s4, s5
	v_mul_f32_e32 v174, 0x3c800000, v165
	v_lshl_add_u32 v165, v171, 5, s5
	s_waitcnt lgkmcnt(0)
	v_add_f32_e32 v175, v172, v173
	ds_write_b64 v165, v[174:175]
.LBB0_827:
	s_or_b64 exec, exec, s[0:1]
	v_mov_b32_e32 v172, v143
	s_waitcnt lgkmcnt(0)
	v_mov_b32_e32 v173, v144
	v_mov_b32_e32 v174, v142
	v_mov_b32_e32 v175, v145
	v_pk_add_f32 v[172:173], v[172:173], v[174:175]
	v_mov_b32_e32 v174, v139
	v_mov_b32_e32 v175, v140
	v_mov_b32_e32 v176, v138
	v_mov_b32_e32 v177, v141
	v_pk_add_f32 v[174:175], v[174:175], v[176:177]
	v_add_f32_e32 v165, v172, v173
	v_pk_add_f32 v[174:175], v[174:175], v[174:175] op_sel_hi:[0,1]
	v_add_f32_e32 v173, 0, v165
	v_add_f32_e32 v177, v134, v135
	v_add_f32_e32 v197, v136, v137
	v_mov_b32_e32 v176, v130
	v_mov_b32_e32 v196, v131
	v_mov_b32_e32 v174, v132
	v_mov_b32_e32 v172, v133
	v_pk_add_f32 v[176:177], v[176:177], v[196:197]
	v_pk_add_f32 v[172:173], v[174:175], v[172:173]
	s_nop 0
	v_pk_add_f32 v[172:173], v[176:177], v[172:173]
	s_nop 0
	v_add_f32_e32 v165, v172, v173
	v_mov_b32_e32 v172, v165
	s_nop 1
	v_permlane16_swap_b32_e32 v172, v165
	s_waitcnt lgkmcnt(0)
	v_add_f32_e32 v165, v165, v172
	v_mov_b32_e32 v172, v165
	s_nop 1
	v_permlane32_swap_b32_e32 v172, v165
	s_waitcnt lgkmcnt(0)
	v_add_f32_e32 v165, v165, v172
	v_fmamk_f32 v173, v165, 0xbc800000, v145
	v_fmamk_f32 v175, v165, 0xbc800000, v143
	v_fmamk_f32 v172, v165, 0xbc800000, v144
	v_fmamk_f32 v174, v165, 0xbc800000, v142
	v_mul_f32_e32 v175, v175, v175
	v_mul_f32_e32 v173, v173, v173
	v_fmac_f32_e32 v175, v174, v174
	v_fmac_f32_e32 v173, v172, v172
	v_fmamk_f32 v174, v165, 0xbc800000, v141
	v_fmamk_f32 v176, v165, 0xbc800000, v139
	v_add_f32_e32 v172, v175, v173
	v_fmamk_f32 v173, v165, 0xbc800000, v140
	v_fmamk_f32 v175, v165, 0xbc800000, v138
	v_mul_f32_e32 v176, v176, v176
	v_mul_f32_e32 v174, v174, v174
	v_fmac_f32_e32 v176, v175, v175
	v_fmac_f32_e32 v174, v173, v173
	v_add_f32_e32 v173, v176, v174
	v_fmamk_f32 v174, v165, 0xbc800000, v137
	v_fmamk_f32 v176, v165, 0xbc800000, v135
	v_add_f32_e32 v172, v172, v173
	v_fmamk_f32 v173, v165, 0xbc800000, v136
	v_fmamk_f32 v175, v165, 0xbc800000, v134
	v_mul_f32_e32 v176, v176, v176
	v_mul_f32_e32 v174, v174, v174
	v_fmac_f32_e32 v176, v175, v175
	v_fmac_f32_e32 v174, v173, v173
	v_add_f32_e32 v173, v176, v174
	v_fmamk_f32 v174, v165, 0xbc800000, v133
	v_fmamk_f32 v176, v165, 0xbc800000, v131
	v_add_f32_e32 v172, v173, v172
	v_fmamk_f32 v173, v165, 0xbc800000, v132
	v_fmamk_f32 v175, v165, 0xbc800000, v130
	v_mul_f32_e32 v176, v176, v176
	v_mul_f32_e32 v174, v174, v174
	v_fmac_f32_e32 v176, v175, v175
	v_fmac_f32_e32 v174, v173, v173
	v_add_f32_e32 v173, v176, v174
	v_add_f32_e32 v172, v173, v172
	v_mov_b32_e32 v173, v172
	s_nop 1
	v_permlane16_swap_b32_e32 v173, v172
	s_waitcnt lgkmcnt(0)
	v_add_f32_e32 v172, v172, v173
	v_mov_b32_e32 v173, v172
	s_nop 1
	v_permlane32_swap_b32_e32 v173, v172
	s_and_saveexec_b64 s[0:1], vcc
	s_cbranch_execz .LBB0_829
	s_lshl_b32 s5, s13, 11
	s_add_i32 s5, s4, s5
	v_mul_f32_e32 v174, 0x3c800000, v165
	v_lshl_add_u32 v165, v171, 5, s5
	s_waitcnt lgkmcnt(0)
	v_add_f32_e32 v175, v172, v173
	ds_write_b64 v165, v[174:175] offset:512
.LBB0_829:
	s_or_b64 exec, exec, s[0:1]
	v_mov_b32_e32 v172, v127
	s_waitcnt lgkmcnt(0)
	v_mov_b32_e32 v173, v128
	v_mov_b32_e32 v174, v126
	v_mov_b32_e32 v175, v129
	v_pk_add_f32 v[172:173], v[172:173], v[174:175]
	v_mov_b32_e32 v174, v123
	v_mov_b32_e32 v175, v124
	v_mov_b32_e32 v176, v122
	v_mov_b32_e32 v177, v125
	v_pk_add_f32 v[174:175], v[174:175], v[176:177]
	v_add_f32_e32 v165, v172, v173
	v_pk_add_f32 v[174:175], v[174:175], v[174:175] op_sel_hi:[0,1]
	v_add_f32_e32 v173, 0, v165
	v_add_f32_e32 v177, v118, v119
	v_add_f32_e32 v197, v120, v121
	v_mov_b32_e32 v176, v114
	v_mov_b32_e32 v196, v115
	v_mov_b32_e32 v174, v116
	v_mov_b32_e32 v172, v117
	v_pk_add_f32 v[176:177], v[176:177], v[196:197]
	v_pk_add_f32 v[172:173], v[174:175], v[172:173]
	s_nop 0
	v_pk_add_f32 v[172:173], v[176:177], v[172:173]
	s_nop 0
	v_add_f32_e32 v165, v172, v173
	v_mov_b32_e32 v172, v165
	s_nop 1
	v_permlane16_swap_b32_e32 v172, v165
	s_waitcnt lgkmcnt(0)
	v_add_f32_e32 v165, v165, v172
	v_mov_b32_e32 v172, v165
	s_nop 1
	v_permlane32_swap_b32_e32 v172, v165
	s_waitcnt lgkmcnt(0)
	v_add_f32_e32 v165, v165, v172
	v_fmamk_f32 v173, v165, 0xbc800000, v129
	v_fmamk_f32 v175, v165, 0xbc800000, v127
	v_fmamk_f32 v172, v165, 0xbc800000, v128
	v_fmamk_f32 v174, v165, 0xbc800000, v126
	v_mul_f32_e32 v175, v175, v175
	v_mul_f32_e32 v173, v173, v173
	v_fmac_f32_e32 v175, v174, v174
	v_fmac_f32_e32 v173, v172, v172
	v_fmamk_f32 v174, v165, 0xbc800000, v125
	v_fmamk_f32 v176, v165, 0xbc800000, v123
	v_add_f32_e32 v172, v175, v173
	v_fmamk_f32 v173, v165, 0xbc800000, v124
	v_fmamk_f32 v175, v165, 0xbc800000, v122
	v_mul_f32_e32 v176, v176, v176
	v_mul_f32_e32 v174, v174, v174
	v_fmac_f32_e32 v176, v175, v175
	v_fmac_f32_e32 v174, v173, v173
	v_add_f32_e32 v173, v176, v174
	v_fmamk_f32 v174, v165, 0xbc800000, v121
	v_fmamk_f32 v176, v165, 0xbc800000, v119
	v_add_f32_e32 v172, v172, v173
	v_fmamk_f32 v173, v165, 0xbc800000, v120
	v_fmamk_f32 v175, v165, 0xbc800000, v118
	v_mul_f32_e32 v176, v176, v176
	v_mul_f32_e32 v174, v174, v174
	v_fmac_f32_e32 v176, v175, v175
	v_fmac_f32_e32 v174, v173, v173
	v_add_f32_e32 v173, v176, v174
	v_fmamk_f32 v174, v165, 0xbc800000, v117
	v_fmamk_f32 v176, v165, 0xbc800000, v115
	v_add_f32_e32 v172, v173, v172
	v_fmamk_f32 v173, v165, 0xbc800000, v116
	v_fmamk_f32 v175, v165, 0xbc800000, v114
	v_mul_f32_e32 v176, v176, v176
	v_mul_f32_e32 v174, v174, v174
	v_fmac_f32_e32 v176, v175, v175
	v_fmac_f32_e32 v174, v173, v173
	v_add_f32_e32 v173, v176, v174
	v_add_f32_e32 v172, v173, v172
	v_mov_b32_e32 v173, v172
	s_nop 1
	v_permlane16_swap_b32_e32 v173, v172
	s_waitcnt lgkmcnt(0)
	v_add_f32_e32 v172, v172, v173
	v_mov_b32_e32 v173, v172
	s_nop 1
	v_permlane32_swap_b32_e32 v173, v172
	s_and_saveexec_b64 s[0:1], vcc
	s_mov_b64 s[74:75], s[50:51]
	s_mov_b64 s[72:73], s[48:49]
	s_mov_b64 s[70:71], s[46:47]
	s_mov_b64 s[68:69], s[44:45]
	s_mov_b32 s67, s17
	s_mov_b64 s[34:35], s[14:15]
	s_mov_b32 s20, s16
	s_cbranch_execz .LBB0_831
	s_lshl_b32 s5, s13, 11
	s_add_i32 s5, s4, s5
	v_mul_f32_e32 v174, 0x3c800000, v165
	v_lshl_add_u32 v165, v171, 5, s5
	s_waitcnt lgkmcnt(0)
	v_add_f32_e32 v175, v172, v173
	ds_write_b64 v165, v[174:175] offset:1024
.LBB0_831:
	s_or_b64 exec, exec, s[0:1]
	v_mov_b32_e32 v172, v111
	s_waitcnt lgkmcnt(0)
	v_mov_b32_e32 v173, v112
	v_mov_b32_e32 v174, v110
	v_mov_b32_e32 v175, v113
	v_pk_add_f32 v[172:173], v[172:173], v[174:175]
	v_mov_b32_e32 v174, v107
	v_mov_b32_e32 v175, v108
	v_mov_b32_e32 v176, v106
	v_mov_b32_e32 v177, v109
	v_pk_add_f32 v[174:175], v[174:175], v[176:177]
	v_add_f32_e32 v165, v172, v173
	v_pk_add_f32 v[174:175], v[174:175], v[174:175] op_sel_hi:[0,1]
	v_add_f32_e32 v173, 0, v165
	v_add_f32_e32 v177, v102, v103
	v_add_f32_e32 v197, v104, v105
	v_mov_b32_e32 v176, v98
	v_mov_b32_e32 v196, v99
	v_mov_b32_e32 v174, v100
	v_mov_b32_e32 v172, v101
	v_pk_add_f32 v[176:177], v[176:177], v[196:197]
	v_pk_add_f32 v[172:173], v[174:175], v[172:173]
	s_nop 0
	v_pk_add_f32 v[172:173], v[176:177], v[172:173]
	s_nop 0
	v_add_f32_e32 v165, v172, v173
	v_mov_b32_e32 v172, v165
	s_nop 1
	v_permlane16_swap_b32_e32 v172, v165
	s_waitcnt lgkmcnt(0)
	v_add_f32_e32 v165, v165, v172
	v_mov_b32_e32 v172, v165
	s_nop 1
	v_permlane32_swap_b32_e32 v172, v165
	s_waitcnt lgkmcnt(0)
	v_add_f32_e32 v165, v165, v172
	v_fmamk_f32 v173, v165, 0xbc800000, v113
	v_fmamk_f32 v175, v165, 0xbc800000, v111
	v_fmamk_f32 v172, v165, 0xbc800000, v112
	v_fmamk_f32 v174, v165, 0xbc800000, v110
	v_mul_f32_e32 v175, v175, v175
	v_mul_f32_e32 v173, v173, v173
	v_fmac_f32_e32 v175, v174, v174
	v_fmac_f32_e32 v173, v172, v172
	v_fmamk_f32 v174, v165, 0xbc800000, v109
	v_fmamk_f32 v176, v165, 0xbc800000, v107
	v_add_f32_e32 v172, v175, v173
	v_fmamk_f32 v173, v165, 0xbc800000, v108
	v_fmamk_f32 v175, v165, 0xbc800000, v106
	v_mul_f32_e32 v176, v176, v176
	v_mul_f32_e32 v174, v174, v174
	v_fmac_f32_e32 v176, v175, v175
	v_fmac_f32_e32 v174, v173, v173
	v_add_f32_e32 v173, v176, v174
	v_fmamk_f32 v174, v165, 0xbc800000, v105
	v_fmamk_f32 v176, v165, 0xbc800000, v103
	v_add_f32_e32 v172, v172, v173
	v_fmamk_f32 v173, v165, 0xbc800000, v104
	v_fmamk_f32 v175, v165, 0xbc800000, v102
	v_mul_f32_e32 v176, v176, v176
	v_mul_f32_e32 v174, v174, v174
	v_fmac_f32_e32 v176, v175, v175
	v_fmac_f32_e32 v174, v173, v173
	v_add_f32_e32 v173, v176, v174
	v_fmamk_f32 v174, v165, 0xbc800000, v101
	v_fmamk_f32 v176, v165, 0xbc800000, v99
	v_add_f32_e32 v172, v173, v172
	v_fmamk_f32 v173, v165, 0xbc800000, v100
	v_fmamk_f32 v175, v165, 0xbc800000, v98
	v_mul_f32_e32 v176, v176, v176
	v_mul_f32_e32 v174, v174, v174
	v_fmac_f32_e32 v176, v175, v175
	v_fmac_f32_e32 v174, v173, v173
	v_add_f32_e32 v173, v176, v174
	v_add_f32_e32 v172, v173, v172
	v_mov_b32_e32 v173, v172
	s_nop 1
	v_permlane16_swap_b32_e32 v173, v172
	s_waitcnt lgkmcnt(0)
	v_add_f32_e32 v172, v172, v173
	v_mov_b32_e32 v173, v172
	s_nop 1
	v_permlane32_swap_b32_e32 v173, v172
	s_and_saveexec_b64 s[0:1], vcc
	s_cbranch_execz .LBB0_833
	s_lshl_b32 s5, s13, 11
	s_add_i32 s5, s4, s5
	v_mul_f32_e32 v174, 0x3c800000, v165
	v_lshl_add_u32 v165, v171, 5, s5
	s_waitcnt lgkmcnt(0)
	v_add_f32_e32 v175, v172, v173
	ds_write_b64 v165, v[174:175] offset:1536
.LBB0_833:
	s_or_b64 exec, exec, s[0:1]
	v_mov_b32_e32 v172, v95
	s_waitcnt lgkmcnt(0)
	v_mov_b32_e32 v173, v96
	v_mov_b32_e32 v174, v94
	v_mov_b32_e32 v175, v97
	v_pk_add_f32 v[172:173], v[172:173], v[174:175]
	v_mov_b32_e32 v174, v91
	v_mov_b32_e32 v175, v92
	v_mov_b32_e32 v176, v90
	v_mov_b32_e32 v177, v93
	v_pk_add_f32 v[174:175], v[174:175], v[176:177]
	v_add_f32_e32 v165, v172, v173
	v_pk_add_f32 v[174:175], v[174:175], v[174:175] op_sel_hi:[0,1]
	v_add_f32_e32 v173, 0, v165
	v_add_f32_e32 v177, v86, v87
	v_add_f32_e32 v197, v88, v89
	v_mov_b32_e32 v176, v82
	v_mov_b32_e32 v196, v83
	v_mov_b32_e32 v174, v84
	v_mov_b32_e32 v172, v85
	v_pk_add_f32 v[176:177], v[176:177], v[196:197]
	v_pk_add_f32 v[172:173], v[174:175], v[172:173]
	s_nop 0
	v_pk_add_f32 v[172:173], v[176:177], v[172:173]
	s_nop 0
	v_add_f32_e32 v165, v172, v173
	v_mov_b32_e32 v172, v165
	s_nop 1
	v_permlane16_swap_b32_e32 v172, v165
	s_waitcnt lgkmcnt(0)
	v_add_f32_e32 v165, v165, v172
	v_mov_b32_e32 v172, v165
	s_nop 1
	v_permlane32_swap_b32_e32 v172, v165
	s_waitcnt lgkmcnt(0)
	v_add_f32_e32 v165, v165, v172
	v_fmamk_f32 v173, v165, 0xbc800000, v97
	v_fmamk_f32 v175, v165, 0xbc800000, v95
	v_fmamk_f32 v172, v165, 0xbc800000, v96
	v_fmamk_f32 v174, v165, 0xbc800000, v94
	v_mul_f32_e32 v175, v175, v175
	v_mul_f32_e32 v173, v173, v173
	v_fmac_f32_e32 v175, v174, v174
	v_fmac_f32_e32 v173, v172, v172
	v_fmamk_f32 v174, v165, 0xbc800000, v93
	v_fmamk_f32 v176, v165, 0xbc800000, v91
	v_add_f32_e32 v172, v175, v173
	v_fmamk_f32 v173, v165, 0xbc800000, v92
	v_fmamk_f32 v175, v165, 0xbc800000, v90
	v_mul_f32_e32 v176, v176, v176
	v_mul_f32_e32 v174, v174, v174
	v_fmac_f32_e32 v176, v175, v175
	v_fmac_f32_e32 v174, v173, v173
	v_add_f32_e32 v173, v176, v174
	v_fmamk_f32 v174, v165, 0xbc800000, v89
	v_fmamk_f32 v176, v165, 0xbc800000, v87
	v_add_f32_e32 v172, v172, v173
	v_fmamk_f32 v173, v165, 0xbc800000, v88
	v_fmamk_f32 v175, v165, 0xbc800000, v86
	v_mul_f32_e32 v176, v176, v176
	v_mul_f32_e32 v174, v174, v174
	v_fmac_f32_e32 v176, v175, v175
	v_fmac_f32_e32 v174, v173, v173
	v_add_f32_e32 v173, v176, v174
	v_fmamk_f32 v174, v165, 0xbc800000, v85
	v_fmamk_f32 v176, v165, 0xbc800000, v83
	v_add_f32_e32 v172, v173, v172
	v_fmamk_f32 v173, v165, 0xbc800000, v84
	v_fmamk_f32 v175, v165, 0xbc800000, v82
	v_mul_f32_e32 v176, v176, v176
	v_mul_f32_e32 v174, v174, v174
	v_fmac_f32_e32 v176, v175, v175
	v_fmac_f32_e32 v174, v173, v173
	v_add_f32_e32 v173, v176, v174
	v_add_f32_e32 v172, v173, v172
	v_mov_b32_e32 v173, v172
	s_nop 1
	v_permlane16_swap_b32_e32 v173, v172
	s_waitcnt lgkmcnt(0)
	v_add_f32_e32 v172, v172, v173
	v_mov_b32_e32 v173, v172
	s_nop 1
	v_permlane32_swap_b32_e32 v173, v172
	s_and_saveexec_b64 s[0:1], vcc
	s_cbranch_execz .LBB0_835
	s_lshl_b32 s5, s13, 11
	s_add_i32 s5, s4, s5
	v_mul_f32_e32 v174, 0x3c800000, v165
	v_lshl_add_u32 v165, v171, 5, s5
	s_waitcnt lgkmcnt(0)
	v_add_f32_e32 v175, v172, v173
	ds_write_b64 v165, v[174:175] offset:4096
.LBB0_835:
	s_or_b64 exec, exec, s[0:1]
	v_mov_b32_e32 v172, v79
	s_waitcnt lgkmcnt(0)
	v_mov_b32_e32 v173, v80
	v_mov_b32_e32 v174, v78
	v_mov_b32_e32 v175, v81
	v_pk_add_f32 v[172:173], v[172:173], v[174:175]
	v_mov_b32_e32 v174, v75
	v_mov_b32_e32 v175, v76
	v_mov_b32_e32 v176, v74
	v_mov_b32_e32 v177, v77
	v_pk_add_f32 v[174:175], v[174:175], v[176:177]
	v_add_f32_e32 v165, v172, v173
	v_pk_add_f32 v[174:175], v[174:175], v[174:175] op_sel_hi:[0,1]
	v_add_f32_e32 v173, 0, v165
	v_add_f32_e32 v177, v70, v71
	v_add_f32_e32 v197, v72, v73
	v_mov_b32_e32 v176, v66
	v_mov_b32_e32 v196, v67
	v_mov_b32_e32 v174, v68
	v_mov_b32_e32 v172, v69
	v_pk_add_f32 v[176:177], v[176:177], v[196:197]
	v_pk_add_f32 v[172:173], v[174:175], v[172:173]
	s_nop 0
	v_pk_add_f32 v[172:173], v[176:177], v[172:173]
	s_nop 0
	v_add_f32_e32 v165, v172, v173
	v_mov_b32_e32 v172, v165
	s_nop 1
	v_permlane16_swap_b32_e32 v172, v165
	s_waitcnt lgkmcnt(0)
	v_add_f32_e32 v165, v165, v172
	v_mov_b32_e32 v172, v165
	s_nop 1
	v_permlane32_swap_b32_e32 v172, v165
	s_waitcnt lgkmcnt(0)
	v_add_f32_e32 v165, v165, v172
	v_fmamk_f32 v173, v165, 0xbc800000, v81
	v_fmamk_f32 v175, v165, 0xbc800000, v79
	v_fmamk_f32 v172, v165, 0xbc800000, v80
	v_fmamk_f32 v174, v165, 0xbc800000, v78
	v_mul_f32_e32 v175, v175, v175
	v_mul_f32_e32 v173, v173, v173
	v_fmac_f32_e32 v175, v174, v174
	v_fmac_f32_e32 v173, v172, v172
	v_fmamk_f32 v174, v165, 0xbc800000, v77
	v_fmamk_f32 v176, v165, 0xbc800000, v75
	v_add_f32_e32 v172, v175, v173
	v_fmamk_f32 v173, v165, 0xbc800000, v76
	v_fmamk_f32 v175, v165, 0xbc800000, v74
	v_mul_f32_e32 v176, v176, v176
	v_mul_f32_e32 v174, v174, v174
	v_fmac_f32_e32 v176, v175, v175
	v_fmac_f32_e32 v174, v173, v173
	v_add_f32_e32 v173, v176, v174
	v_fmamk_f32 v174, v165, 0xbc800000, v73
	v_fmamk_f32 v176, v165, 0xbc800000, v71
	v_add_f32_e32 v172, v172, v173
	v_fmamk_f32 v173, v165, 0xbc800000, v72
	v_fmamk_f32 v175, v165, 0xbc800000, v70
	v_mul_f32_e32 v176, v176, v176
	v_mul_f32_e32 v174, v174, v174
	v_fmac_f32_e32 v176, v175, v175
	v_fmac_f32_e32 v174, v173, v173
	v_add_f32_e32 v173, v176, v174
	v_fmamk_f32 v174, v165, 0xbc800000, v69
	v_fmamk_f32 v176, v165, 0xbc800000, v67
	v_add_f32_e32 v172, v173, v172
	v_fmamk_f32 v173, v165, 0xbc800000, v68
	v_fmamk_f32 v175, v165, 0xbc800000, v66
	v_mul_f32_e32 v176, v176, v176
	v_mul_f32_e32 v174, v174, v174
	v_fmac_f32_e32 v176, v175, v175
	v_fmac_f32_e32 v174, v173, v173
	v_add_f32_e32 v173, v176, v174
	v_add_f32_e32 v172, v173, v172
	v_mov_b32_e32 v173, v172
	s_nop 1
	v_permlane16_swap_b32_e32 v173, v172
	s_waitcnt lgkmcnt(0)
	v_add_f32_e32 v172, v172, v173
	v_mov_b32_e32 v173, v172
	s_nop 1
	v_permlane32_swap_b32_e32 v173, v172
	s_and_saveexec_b64 s[0:1], vcc
	s_cbranch_execz .LBB0_837
	s_lshl_b32 s5, s13, 11
	s_add_i32 s5, s4, s5
	v_mul_f32_e32 v174, 0x3c800000, v165
	v_lshl_add_u32 v165, v171, 5, s5
	s_waitcnt lgkmcnt(0)
	v_add_f32_e32 v175, v172, v173
	ds_write_b64 v165, v[174:175] offset:4608
.LBB0_837:
	s_or_b64 exec, exec, s[0:1]
	v_mov_b32_e32 v172, v63
	s_waitcnt lgkmcnt(0)
	v_mov_b32_e32 v173, v64
	v_mov_b32_e32 v174, v62
	v_mov_b32_e32 v175, v65
	v_pk_add_f32 v[172:173], v[172:173], v[174:175]
	v_mov_b32_e32 v174, v59
	v_mov_b32_e32 v175, v60
	v_mov_b32_e32 v176, v58
	v_mov_b32_e32 v177, v61
	v_pk_add_f32 v[174:175], v[174:175], v[176:177]
	v_add_f32_e32 v165, v172, v173
	v_pk_add_f32 v[174:175], v[174:175], v[174:175] op_sel_hi:[0,1]
	v_add_f32_e32 v173, 0, v165
	v_add_f32_e32 v177, v30, v31
	v_add_f32_e32 v197, v32, v33
	v_mov_b32_e32 v176, v26
	v_mov_b32_e32 v196, v27
	v_mov_b32_e32 v174, v28
	v_mov_b32_e32 v172, v29
	v_pk_add_f32 v[176:177], v[176:177], v[196:197]
	v_pk_add_f32 v[172:173], v[174:175], v[172:173]
	s_nop 0
	v_pk_add_f32 v[172:173], v[176:177], v[172:173]
	s_nop 0
	v_add_f32_e32 v165, v172, v173
	v_mov_b32_e32 v172, v165
	s_nop 1
	v_permlane16_swap_b32_e32 v172, v165
	s_waitcnt lgkmcnt(0)
	v_add_f32_e32 v165, v165, v172
	v_mov_b32_e32 v172, v165
	s_nop 1
	v_permlane32_swap_b32_e32 v172, v165
	s_waitcnt lgkmcnt(0)
	v_add_f32_e32 v165, v165, v172
	v_fmamk_f32 v173, v165, 0xbc800000, v65
	v_fmamk_f32 v175, v165, 0xbc800000, v63
	v_fmamk_f32 v172, v165, 0xbc800000, v64
	v_fmamk_f32 v174, v165, 0xbc800000, v62
	v_mul_f32_e32 v175, v175, v175
	v_mul_f32_e32 v173, v173, v173
	v_fmac_f32_e32 v175, v174, v174
	v_fmac_f32_e32 v173, v172, v172
	v_fmamk_f32 v174, v165, 0xbc800000, v61
	v_fmamk_f32 v176, v165, 0xbc800000, v59
	v_add_f32_e32 v172, v175, v173
	v_fmamk_f32 v173, v165, 0xbc800000, v60
	v_fmamk_f32 v175, v165, 0xbc800000, v58
	v_mul_f32_e32 v176, v176, v176
	v_mul_f32_e32 v174, v174, v174
	v_fmac_f32_e32 v176, v175, v175
	v_fmac_f32_e32 v174, v173, v173
	v_add_f32_e32 v173, v176, v174
	v_fmamk_f32 v174, v165, 0xbc800000, v33
	v_fmamk_f32 v176, v165, 0xbc800000, v31
	v_add_f32_e32 v172, v172, v173
	v_fmamk_f32 v173, v165, 0xbc800000, v32
	v_fmamk_f32 v175, v165, 0xbc800000, v30
	v_mul_f32_e32 v176, v176, v176
	v_mul_f32_e32 v174, v174, v174
	v_fmac_f32_e32 v176, v175, v175
	v_fmac_f32_e32 v174, v173, v173
	v_add_f32_e32 v173, v176, v174
	v_fmamk_f32 v174, v165, 0xbc800000, v29
	v_fmamk_f32 v176, v165, 0xbc800000, v27
	v_add_f32_e32 v172, v173, v172
	v_fmamk_f32 v173, v165, 0xbc800000, v28
	v_fmamk_f32 v175, v165, 0xbc800000, v26
	v_mul_f32_e32 v176, v176, v176
	v_mul_f32_e32 v174, v174, v174
	v_fmac_f32_e32 v176, v175, v175
	v_fmac_f32_e32 v174, v173, v173
	v_add_f32_e32 v173, v176, v174
	v_add_f32_e32 v172, v173, v172
	v_mov_b32_e32 v173, v172
	s_nop 1
	v_permlane16_swap_b32_e32 v173, v172
	s_waitcnt lgkmcnt(0)
	v_add_f32_e32 v172, v172, v173
	v_mov_b32_e32 v173, v172
	s_nop 1
	v_permlane32_swap_b32_e32 v173, v172
	s_and_saveexec_b64 s[0:1], vcc
	s_cbranch_execz .LBB0_839
	s_lshl_b32 s5, s13, 11
	s_add_i32 s5, s4, s5
	v_mul_f32_e32 v174, 0x3c800000, v165
	v_lshl_add_u32 v165, v171, 5, s5
	s_waitcnt lgkmcnt(0)
	v_add_f32_e32 v175, v172, v173
	ds_write_b64 v165, v[174:175] offset:5120
.LBB0_839:
	s_or_b64 exec, exec, s[0:1]
	v_mov_b32_e32 v172, v47
	s_waitcnt lgkmcnt(0)
	v_mov_b32_e32 v173, v48
	v_mov_b32_e32 v174, v46
	v_mov_b32_e32 v175, v49
	v_pk_add_f32 v[172:173], v[172:173], v[174:175]
	v_mov_b32_e32 v174, v39
	v_mov_b32_e32 v175, v40
	v_mov_b32_e32 v176, v38
	v_mov_b32_e32 v177, v41
	v_pk_add_f32 v[174:175], v[174:175], v[176:177]
	v_add_f32_e32 v165, v172, v173
	v_pk_add_f32 v[174:175], v[174:175], v[174:175] op_sel_hi:[0,1]
	v_add_f32_e32 v173, 0, v165
	v_add_f32_e32 v177, v14, v15
	v_add_f32_e32 v197, v16, v17
	v_mov_b32_e32 v176, v6
	v_mov_b32_e32 v196, v7
	v_mov_b32_e32 v174, v8
	v_mov_b32_e32 v172, v9
	v_pk_add_f32 v[176:177], v[176:177], v[196:197]
	v_pk_add_f32 v[172:173], v[174:175], v[172:173]
	s_nop 0
	v_pk_add_f32 v[172:173], v[176:177], v[172:173]
	s_nop 0
	v_add_f32_e32 v165, v172, v173
	v_mov_b32_e32 v172, v165
	s_nop 1
	v_permlane16_swap_b32_e32 v172, v165
	s_waitcnt lgkmcnt(0)
	v_add_f32_e32 v165, v165, v172
	v_mov_b32_e32 v172, v165
	s_nop 1
	v_permlane32_swap_b32_e32 v172, v165
	s_waitcnt lgkmcnt(0)
	v_add_f32_e32 v165, v165, v172
	v_fmamk_f32 v173, v165, 0xbc800000, v49
	v_fmamk_f32 v175, v165, 0xbc800000, v47
	v_fmamk_f32 v172, v165, 0xbc800000, v48
	v_fmamk_f32 v174, v165, 0xbc800000, v46
	v_mul_f32_e32 v175, v175, v175
	v_mul_f32_e32 v173, v173, v173
	v_fmac_f32_e32 v175, v174, v174
	v_fmac_f32_e32 v173, v172, v172
	v_fmamk_f32 v174, v165, 0xbc800000, v41
	v_fmamk_f32 v176, v165, 0xbc800000, v39
	v_add_f32_e32 v172, v175, v173
	v_fmamk_f32 v173, v165, 0xbc800000, v40
	v_fmamk_f32 v175, v165, 0xbc800000, v38
	v_mul_f32_e32 v176, v176, v176
	v_mul_f32_e32 v174, v174, v174
	v_fmac_f32_e32 v176, v175, v175
	v_fmac_f32_e32 v174, v173, v173
	v_add_f32_e32 v173, v176, v174
	v_fmamk_f32 v174, v165, 0xbc800000, v17
	v_fmamk_f32 v176, v165, 0xbc800000, v15
	v_add_f32_e32 v172, v172, v173
	v_fmamk_f32 v173, v165, 0xbc800000, v16
	v_fmamk_f32 v175, v165, 0xbc800000, v14
	v_mul_f32_e32 v176, v176, v176
	v_mul_f32_e32 v174, v174, v174
	v_fmac_f32_e32 v176, v175, v175
	v_fmac_f32_e32 v174, v173, v173
	v_add_f32_e32 v173, v176, v174
	v_fmamk_f32 v174, v165, 0xbc800000, v9
	v_fmamk_f32 v176, v165, 0xbc800000, v7
	v_add_f32_e32 v172, v173, v172
	v_fmamk_f32 v173, v165, 0xbc800000, v8
	v_fmamk_f32 v175, v165, 0xbc800000, v6
	v_mul_f32_e32 v176, v176, v176
	v_mul_f32_e32 v174, v174, v174
	v_fmac_f32_e32 v176, v175, v175
	v_fmac_f32_e32 v174, v173, v173
	v_add_f32_e32 v173, v176, v174
	v_add_f32_e32 v172, v173, v172
	v_mov_b32_e32 v166, v172
	s_nop 1
	v_permlane16_swap_b32_e32 v166, v172
	s_waitcnt lgkmcnt(0)
	v_add_f32_e32 v166, v172, v166
	v_mov_b32_e32 v164, v166
	s_nop 1
	v_permlane32_swap_b32_e32 v164, v166
	s_and_saveexec_b64 s[0:1], vcc
	s_cbranch_execz .LBB0_841
	s_lshl_b32 s5, s13, 11
	s_add_i32 s4, s4, s5
	v_mul_f32_e32 v172, 0x3c800000, v165
	v_lshl_add_u32 v165, v171, 5, s4
	s_waitcnt lgkmcnt(0)
	v_add_f32_e32 v173, v166, v164
	ds_write_b64 v165, v[172:173] offset:5632

.LBB0_1026:
	s_add_u32 s4, s74, s88
	v_lshrrev_b32_e32 v130, 1, v166
	s_addc_u32 s5, s75, s89
	v_and_b32_e32 v130, 24, v130
	s_add_u32 s88, s4, 0x9c00000
	s_addc_u32 s89, s5, 0
	s_lshl_b32 s4, s0, 8
	v_lshl_or_b32 v130, s1, 5, v130
	v_lshl_or_b32 v131, s1, 6, v144
	s_lshl_b32 s11, s10, 8
	v_or_b32_e32 v130, s4, v130
	v_or_b32_e32 v162, s4, v131
	s_add_i32 s4, s11, s96
	v_or_b32_e32 v132, s4, v167
	v_ashrrev_i32_e32 v133, 31, v132
	v_lshlrev_b64 v[138:139], 11, v[132:133]
	v_ashrrev_i32_e32 v163, 31, v162
	v_lshl_add_u64 v[134:135], s[92:93], 0, v[138:139]
	v_lshl_add_u64 v[134:135], v[134:135], 0, v[162:163]
	s_barrier
	v_ashrrev_i32_e32 v131, 31, v130
	v_mov_b64_e32 v[248:249], v[134:135]
	v_lshl_add_u64 v[138:139], s[88:89], 0, v[138:139]
	v_lshlrev_b64 v[164:165], 1, v[130:131]
	v_lshl_add_u64 v[142:143], v[138:139], 0, v[164:165]
	v_mov_b64_e32 v[250:251], v[142:143]
	v_mov_b64_e32 v[212:213], v[248:249]
	global_load_dwordx4 v[212:215], v[212:213], off
	v_mov_b64_e32 v[216:217], v[250:251]
	global_load_dwordx4 v[216:219], v[216:217], off
	v_mov_b64_e32 v[220:221], v[250:251]
	global_load_dwordx4 v[220:223], v[220:221], off offset:256
	s_mov_b32 s98, 0x8000
	s_mov_b32 s99, 0
	v_lshl_add_u64 v[224:225], v[248:249], 0, s[98:99]
	global_load_dwordx4 v[224:227], v[224:225], off
	s_mov_b32 s98, 0x8000
	s_mov_b32 s99, 0
	v_lshl_add_u64 v[228:229], v[250:251], 0, s[98:99]
	global_load_dwordx4 v[228:231], v[228:229], off
	s_mov_b32 s98, 0x8000
	s_mov_b32 s99, 0
	v_lshl_add_u64 v[232:233], v[250:251], 0, s[98:99]
	global_load_dwordx4 v[232:235], v[232:233], off offset:256
	s_mov_b32 s98, 0x10000
	s_mov_b32 s99, 0
	v_lshl_add_u64 v[236:237], v[248:249], 0, s[98:99]
	global_load_dwordx4 v[236:239], v[236:237], off
	s_mov_b32 s98, 0x10000
	s_mov_b32 s99, 0
	v_lshl_add_u64 v[240:241], v[250:251], 0, s[98:99]
	global_load_dwordx4 v[240:243], v[240:241], off
	s_mov_b32 s98, 0x10000
	s_mov_b32 s99, 0
	v_lshl_add_u64 v[244:245], v[250:251], 0, s[98:99]
	global_load_dwordx4 v[244:247], v[244:245], off offset:256
	s_waitcnt vmcnt(0)
	v_mov_b64_e32 v[134:135], v[212:213]
	v_mov_b64_e32 v[136:137], v[214:215]
	v_mov_b64_e32 v[138:139], v[216:217]
	v_mov_b64_e32 v[140:141], v[218:219]
	s_mov_b32 s4, 0x3a000000
	v_readlane_b32 s6, v255, 27
	v_lshlrev_b64 v[130:131], 2, v[130:131]
	v_readlane_b32 s7, v255, 28
	v_and_b32_e32 v171, 64, v205
	v_xor_b32_e32 v170, 16, v205
	v_add_u32_e32 v171, 64, v171
	v_xor_b32_e32 v172, 32, v205
	v_and_b32_e32 v169, 63, v166
	s_lshl_b32 s1, s1, 3
	s_add_i32 s1, s1, 0
	s_waitcnt vmcnt(0)
	v_cvt_pk_f32_fp8_sdwa v[146:147], v134 src0_sel:WORD_1
	v_cvt_pk_f32_fp8_e32 v[144:145], v134
	v_cvt_pk_f32_fp8_e32 v[148:149], v135
	v_cvt_pk_f32_fp8_sdwa v[134:135], v135 src0_sel:WORD_1
	v_lshlrev_b32_e32 v150, 16, v138
	v_and_b32_e32 v151, 0xffff0000, v138
	v_lshlrev_b32_e32 v138, 16, v139
	v_and_b32_e32 v139, 0xffff0000, v139
	v_pk_fma_f32 v[138:139], v[146:147], s[4:5], v[138:139] op_sel_hi:[1,0,1]
	v_lshlrev_b32_e32 v146, 16, v140
	v_and_b32_e32 v147, 0xffff0000, v140
	v_lshlrev_b32_e32 v140, 16, v141
	v_and_b32_e32 v141, 0xffff0000, v141
	v_pk_fma_f32 v[134:135], v[134:135], s[4:5], v[140:141] op_sel_hi:[1,0,1]
	v_pk_fma_f32 v[8:9], v[138:139], s[86:87], v[8:9] op_sel_hi:[1,0,1]
	s_waitcnt vmcnt(0)
	v_mov_b64_e32 v[138:139], v[220:221]
	v_mov_b64_e32 v[140:141], v[222:223]
	v_pk_fma_f32 v[4:5], v[134:135], s[86:87], v[4:5] op_sel_hi:[1,0,1]
	v_cvt_pk_f32_fp8_e32 v[134:135], v136
	v_pk_fma_f32 v[146:147], v[148:149], s[4:5], v[146:147] op_sel_hi:[1,0,1]
	v_cvt_pk_f32_fp8_sdwa v[142:143], v136 src0_sel:WORD_1
	v_pk_fma_f32 v[144:145], v[144:145], s[4:5], v[150:151] op_sel_hi:[1,0,1]
	v_pk_fma_f32 v[2:3], v[146:147], s[86:87], v[2:3] op_sel_hi:[1,0,1]
	v_pk_fma_f32 v[6:7], v[144:145], s[86:87], v[6:7] op_sel_hi:[1,0,1]
	v_cvt_pk_f32_fp8_e32 v[144:145], v137
	v_cvt_pk_f32_fp8_sdwa v[136:137], v137 src0_sel:WORD_1
	s_waitcnt vmcnt(0)
	v_lshlrev_b32_e32 v146, 16, v138
	v_and_b32_e32 v147, 0xffff0000, v138
	v_pk_fma_f32 v[134:135], v[134:135], s[4:5], v[146:147] op_sel_hi:[1,0,1]
	v_lshlrev_b32_e32 v138, 16, v139
	v_and_b32_e32 v139, 0xffff0000, v139
	v_pk_fma_f32 v[14:15], v[134:135], s[86:87], v[14:15] op_sel_hi:[1,0,1]
	v_or_b32_e32 v134, 16, v132
	v_pk_fma_f32 v[138:139], v[142:143], s[4:5], v[138:139] op_sel_hi:[1,0,1]
	v_ashrrev_i32_e32 v135, 31, v134
	v_lshlrev_b32_e32 v142, 16, v140
	v_and_b32_e32 v143, 0xffff0000, v140
	v_lshlrev_b32_e32 v140, 16, v141
	v_and_b32_e32 v141, 0xffff0000, v141
	v_pk_fma_f32 v[16:17], v[138:139], s[86:87], v[16:17] op_sel_hi:[1,0,1]
	v_lshlrev_b64 v[138:139], 11, v[134:135]
	v_pk_fma_f32 v[142:143], v[144:145], s[4:5], v[142:143] op_sel_hi:[1,0,1]
	v_pk_fma_f32 v[136:137], v[136:137], s[4:5], v[140:141] op_sel_hi:[1,0,1]
	v_lshl_add_u64 v[134:135], s[92:93], 0, v[138:139]
	v_pk_fma_f32 v[12:13], v[136:137], s[86:87], v[12:13] op_sel_hi:[1,0,1]
	v_pk_fma_f32 v[10:11], v[142:143], s[86:87], v[10:11] op_sel_hi:[1,0,1]
	v_lshl_add_u64 v[134:135], v[134:135], 0, v[162:163]
	s_waitcnt vmcnt(0)
	v_mov_b64_e32 v[134:135], v[224:225]
	v_mov_b64_e32 v[136:137], v[226:227]
	v_lshl_add_u64 v[138:139], s[88:89], 0, v[138:139]
	v_lshl_add_u64 v[142:143], v[138:139], 0, v[164:165]
	s_waitcnt vmcnt(0)
	v_mov_b64_e32 v[138:139], v[228:229]
	v_mov_b64_e32 v[140:141], v[230:231]
	v_mov_b32_e32 v173, v8
	v_mov_b32_e32 v174, v6
	v_mov_b32_e32 v175, v9
	v_mov_b32_e32 v176, v2
	v_mov_b32_e32 v177, v5
	v_add_f32_e32 v197, v16, v17
	v_mov_b32_e32 v196, v11
	s_waitcnt vmcnt(1)
	v_cvt_pk_f32_fp8_sdwa v[146:147], v134 src0_sel:WORD_1
	v_cvt_pk_f32_fp8_e32 v[144:145], v134
	v_cvt_pk_f32_fp8_e32 v[148:149], v135
	v_cvt_pk_f32_fp8_sdwa v[134:135], v135 src0_sel:WORD_1
	s_waitcnt vmcnt(0)
	v_lshlrev_b32_e32 v150, 16, v138
	v_and_b32_e32 v151, 0xffff0000, v138
	v_lshlrev_b32_e32 v138, 16, v139
	v_and_b32_e32 v139, 0xffff0000, v139
	v_pk_fma_f32 v[138:139], v[146:147], s[4:5], v[138:139] op_sel_hi:[1,0,1]
	v_lshlrev_b32_e32 v146, 16, v140
	v_and_b32_e32 v147, 0xffff0000, v140
	v_lshlrev_b32_e32 v140, 16, v141
	v_and_b32_e32 v141, 0xffff0000, v141
	v_pk_fma_f32 v[134:135], v[134:135], s[4:5], v[140:141] op_sel_hi:[1,0,1]
	v_pk_fma_f32 v[32:33], v[138:139], s[86:87], v[32:33] op_sel_hi:[1,0,1]
	s_waitcnt vmcnt(0)
	v_mov_b64_e32 v[138:139], v[232:233]
	v_mov_b64_e32 v[140:141], v[234:235]
	v_pk_fma_f32 v[28:29], v[134:135], s[86:87], v[28:29] op_sel_hi:[1,0,1]
	v_cvt_pk_f32_fp8_e32 v[134:135], v136
	v_pk_fma_f32 v[146:147], v[148:149], s[4:5], v[146:147] op_sel_hi:[1,0,1]
	v_cvt_pk_f32_fp8_sdwa v[142:143], v136 src0_sel:WORD_1
	v_pk_fma_f32 v[144:145], v[144:145], s[4:5], v[150:151] op_sel_hi:[1,0,1]
	v_pk_fma_f32 v[26:27], v[146:147], s[86:87], v[26:27] op_sel_hi:[1,0,1]
	v_pk_fma_f32 v[30:31], v[144:145], s[86:87], v[30:31] op_sel_hi:[1,0,1]
	v_cvt_pk_f32_fp8_e32 v[144:145], v137
	v_cvt_pk_f32_fp8_sdwa v[136:137], v137 src0_sel:WORD_1
	s_waitcnt vmcnt(0)
	v_lshlrev_b32_e32 v146, 16, v138
	v_and_b32_e32 v147, 0xffff0000, v138
	v_pk_fma_f32 v[134:135], v[134:135], s[4:5], v[146:147] op_sel_hi:[1,0,1]
	v_lshlrev_b32_e32 v138, 16, v139
	v_and_b32_e32 v139, 0xffff0000, v139
	v_pk_fma_f32 v[46:47], v[134:135], s[86:87], v[46:47] op_sel_hi:[1,0,1]
	v_or_b32_e32 v134, 32, v132
	v_pk_fma_f32 v[138:139], v[142:143], s[4:5], v[138:139] op_sel_hi:[1,0,1]
	v_ashrrev_i32_e32 v135, 31, v134
	v_lshlrev_b32_e32 v142, 16, v140
	v_and_b32_e32 v143, 0xffff0000, v140
	v_lshlrev_b32_e32 v140, 16, v141
	v_and_b32_e32 v141, 0xffff0000, v141
	v_pk_fma_f32 v[48:49], v[138:139], s[86:87], v[48:49] op_sel_hi:[1,0,1]
	v_lshlrev_b64 v[138:139], 11, v[134:135]
	v_pk_fma_f32 v[142:143], v[144:145], s[4:5], v[142:143] op_sel_hi:[1,0,1]
	v_pk_fma_f32 v[136:137], v[136:137], s[4:5], v[140:141] op_sel_hi:[1,0,1]
	v_lshl_add_u64 v[134:135], s[92:93], 0, v[138:139]
	v_pk_fma_f32 v[44:45], v[136:137], s[86:87], v[44:45] op_sel_hi:[1,0,1]
	v_pk_fma_f32 v[42:43], v[142:143], s[86:87], v[42:43] op_sel_hi:[1,0,1]
	v_lshl_add_u64 v[134:135], v[134:135], 0, v[162:163]
	s_waitcnt vmcnt(0)
	v_mov_b64_e32 v[134:135], v[236:237]
	v_mov_b64_e32 v[136:137], v[238:239]
	v_lshl_add_u64 v[138:139], s[88:89], 0, v[138:139]
	v_lshl_add_u64 v[142:143], v[138:139], 0, v[164:165]
	s_waitcnt vmcnt(0)
	v_mov_b64_e32 v[138:139], v[240:241]
	v_mov_b64_e32 v[140:141], v[242:243]
	s_waitcnt vmcnt(1)
	v_cvt_pk_f32_fp8_sdwa v[146:147], v134 src0_sel:WORD_1
	v_cvt_pk_f32_fp8_e32 v[144:145], v134
	v_cvt_pk_f32_fp8_e32 v[148:149], v135
	v_cvt_pk_f32_fp8_sdwa v[134:135], v135 src0_sel:WORD_1
	s_waitcnt vmcnt(0)
	v_lshlrev_b32_e32 v150, 16, v138
	v_and_b32_e32 v151, 0xffff0000, v138
	v_lshlrev_b32_e32 v138, 16, v139
	v_and_b32_e32 v139, 0xffff0000, v139
	v_pk_fma_f32 v[138:139], v[146:147], s[4:5], v[138:139] op_sel_hi:[1,0,1]
	v_lshlrev_b32_e32 v146, 16, v140
	v_and_b32_e32 v147, 0xffff0000, v140
	v_lshlrev_b32_e32 v140, 16, v141
	v_and_b32_e32 v141, 0xffff0000, v141
	v_pk_fma_f32 v[134:135], v[134:135], s[4:5], v[140:141] op_sel_hi:[1,0,1]
	v_pk_fma_f32 v[60:61], v[138:139], s[86:87], v[60:61] op_sel_hi:[1,0,1]
	s_waitcnt vmcnt(0)
	v_mov_b64_e32 v[138:139], v[244:245]
	v_mov_b64_e32 v[140:141], v[246:247]
	s_mov_b32 s98, 0x18000
	s_mov_b32 s99, 0
	v_lshl_add_u64 v[212:213], v[248:249], 0, s[98:99]
	global_load_dwordx4 v[212:215], v[212:213], off
	s_mov_b32 s98, 0x18000
	s_mov_b32 s99, 0
	v_lshl_add_u64 v[216:217], v[250:251], 0, s[98:99]
	global_load_dwordx4 v[216:219], v[216:217], off
	s_mov_b32 s98, 0x18000
	s_mov_b32 s99, 0
	v_lshl_add_u64 v[220:221], v[250:251], 0, s[98:99]
	global_load_dwordx4 v[220:223], v[220:221], off offset:256
	s_mov_b32 s98, 0x40000
	s_mov_b32 s99, 0
	v_lshl_add_u64 v[224:225], v[248:249], 0, s[98:99]
	global_load_dwordx4 v[224:227], v[224:225], off
	s_mov_b32 s98, 0x40000
	s_mov_b32 s99, 0
	v_lshl_add_u64 v[228:229], v[250:251], 0, s[98:99]
	global_load_dwordx4 v[228:231], v[228:229], off
	s_mov_b32 s98, 0x40000
	s_mov_b32 s99, 0
	v_lshl_add_u64 v[232:233], v[250:251], 0, s[98:99]
	global_load_dwordx4 v[232:235], v[232:233], off offset:256
	s_mov_b32 s98, 0x48000
	s_mov_b32 s99, 0
	v_lshl_add_u64 v[236:237], v[248:249], 0, s[98:99]
	global_load_dwordx4 v[236:239], v[236:237], off
	s_mov_b32 s98, 0x48000
	s_mov_b32 s99, 0
	v_lshl_add_u64 v[240:241], v[250:251], 0, s[98:99]
	global_load_dwordx4 v[240:243], v[240:241], off
	s_mov_b32 s98, 0x48000
	s_mov_b32 s99, 0
	v_lshl_add_u64 v[244:245], v[250:251], 0, s[98:99]
	global_load_dwordx4 v[244:247], v[244:245], off offset:256
	v_pk_fma_f32 v[52:53], v[134:135], s[86:87], v[52:53] op_sel_hi:[1,0,1]
	v_cvt_pk_f32_fp8_e32 v[134:135], v136
	v_pk_fma_f32 v[146:147], v[148:149], s[4:5], v[146:147] op_sel_hi:[1,0,1]
	v_cvt_pk_f32_fp8_sdwa v[142:143], v136 src0_sel:WORD_1
	v_pk_fma_f32 v[144:145], v[144:145], s[4:5], v[150:151] op_sel_hi:[1,0,1]
	v_pk_fma_f32 v[50:51], v[146:147], s[86:87], v[50:51] op_sel_hi:[1,0,1]
	v_pk_fma_f32 v[58:59], v[144:145], s[86:87], v[58:59] op_sel_hi:[1,0,1]
	v_cvt_pk_f32_fp8_e32 v[144:145], v137
	v_cvt_pk_f32_fp8_sdwa v[136:137], v137 src0_sel:WORD_1
	s_waitcnt vmcnt(0)
	v_lshlrev_b32_e32 v146, 16, v138
	v_and_b32_e32 v147, 0xffff0000, v138
	v_pk_fma_f32 v[134:135], v[134:135], s[4:5], v[146:147] op_sel_hi:[1,0,1]
	v_lshlrev_b32_e32 v138, 16, v139
	v_and_b32_e32 v139, 0xffff0000, v139
	v_pk_fma_f32 v[70:71], v[134:135], s[86:87], v[70:71] op_sel_hi:[1,0,1]
	v_or_b32_e32 v134, 48, v132
	v_pk_fma_f32 v[138:139], v[142:143], s[4:5], v[138:139] op_sel_hi:[1,0,1]
	v_ashrrev_i32_e32 v135, 31, v134
	v_lshlrev_b32_e32 v142, 16, v140
	v_and_b32_e32 v143, 0xffff0000, v140
	v_lshlrev_b32_e32 v140, 16, v141
	v_and_b32_e32 v141, 0xffff0000, v141
	v_pk_fma_f32 v[72:73], v[138:139], s[86:87], v[72:73] op_sel_hi:[1,0,1]
	v_lshlrev_b64 v[138:139], 11, v[134:135]
	v_pk_fma_f32 v[142:143], v[144:145], s[4:5], v[142:143] op_sel_hi:[1,0,1]
	v_pk_fma_f32 v[136:137], v[136:137], s[4:5], v[140:141] op_sel_hi:[1,0,1]
	v_lshl_add_u64 v[134:135], s[92:93], 0, v[138:139]
	v_pk_fma_f32 v[68:69], v[136:137], s[86:87], v[68:69] op_sel_hi:[1,0,1]
	v_pk_fma_f32 v[66:67], v[142:143], s[86:87], v[66:67] op_sel_hi:[1,0,1]
	v_lshl_add_u64 v[134:135], v[134:135], 0, v[162:163]
	s_waitcnt vmcnt(0)
	v_mov_b64_e32 v[134:135], v[212:213]
	v_mov_b64_e32 v[136:137], v[214:215]
	v_lshl_add_u64 v[138:139], s[88:89], 0, v[138:139]
	v_lshl_add_u64 v[142:143], v[138:139], 0, v[164:165]
	s_waitcnt vmcnt(0)
	v_mov_b64_e32 v[138:139], v[216:217]
	v_mov_b64_e32 v[140:141], v[218:219]
	s_waitcnt vmcnt(1)
	v_cvt_pk_f32_fp8_sdwa v[146:147], v134 src0_sel:WORD_1
	v_cvt_pk_f32_fp8_e32 v[144:145], v134
	v_cvt_pk_f32_fp8_e32 v[148:149], v135
	v_cvt_pk_f32_fp8_sdwa v[134:135], v135 src0_sel:WORD_1
	s_waitcnt vmcnt(0)
	v_lshlrev_b32_e32 v150, 16, v138
	v_and_b32_e32 v151, 0xffff0000, v138
	v_lshlrev_b32_e32 v138, 16, v139
	v_and_b32_e32 v139, 0xffff0000, v139
	v_pk_fma_f32 v[138:139], v[146:147], s[4:5], v[138:139] op_sel_hi:[1,0,1]
	v_lshlrev_b32_e32 v146, 16, v140
	v_and_b32_e32 v147, 0xffff0000, v140
	v_lshlrev_b32_e32 v140, 16, v141
	v_and_b32_e32 v141, 0xffff0000, v141
	v_pk_fma_f32 v[134:135], v[134:135], s[4:5], v[140:141] op_sel_hi:[1,0,1]
	v_pk_fma_f32 v[88:89], v[138:139], s[86:87], v[88:89] op_sel_hi:[1,0,1]
	s_waitcnt vmcnt(0)
	v_mov_b64_e32 v[138:139], v[220:221]
	v_mov_b64_e32 v[140:141], v[222:223]
	v_pk_fma_f32 v[84:85], v[134:135], s[86:87], v[84:85] op_sel_hi:[1,0,1]
	v_cvt_pk_f32_fp8_e32 v[134:135], v136
	v_pk_fma_f32 v[146:147], v[148:149], s[4:5], v[146:147] op_sel_hi:[1,0,1]
	v_cvt_pk_f32_fp8_sdwa v[142:143], v136 src0_sel:WORD_1
	v_pk_fma_f32 v[144:145], v[144:145], s[4:5], v[150:151] op_sel_hi:[1,0,1]
	v_pk_fma_f32 v[82:83], v[146:147], s[86:87], v[82:83] op_sel_hi:[1,0,1]
	v_pk_fma_f32 v[86:87], v[144:145], s[86:87], v[86:87] op_sel_hi:[1,0,1]
	v_cvt_pk_f32_fp8_e32 v[144:145], v137
	v_cvt_pk_f32_fp8_sdwa v[136:137], v137 src0_sel:WORD_1
	s_waitcnt vmcnt(0)
	v_lshlrev_b32_e32 v146, 16, v138
	v_and_b32_e32 v147, 0xffff0000, v138
	v_pk_fma_f32 v[134:135], v[134:135], s[4:5], v[146:147] op_sel_hi:[1,0,1]
	v_lshlrev_b32_e32 v138, 16, v139
	v_and_b32_e32 v139, 0xffff0000, v139
	v_pk_fma_f32 v[94:95], v[134:135], s[86:87], v[94:95] op_sel_hi:[1,0,1]
	v_add_u32_e32 v134, 0x80, v132
	v_pk_fma_f32 v[138:139], v[142:143], s[4:5], v[138:139] op_sel_hi:[1,0,1]
	v_ashrrev_i32_e32 v135, 31, v134
	v_lshlrev_b32_e32 v142, 16, v140
	v_and_b32_e32 v143, 0xffff0000, v140
	v_lshlrev_b32_e32 v140, 16, v141
	v_and_b32_e32 v141, 0xffff0000, v141
	v_pk_fma_f32 v[96:97], v[138:139], s[86:87], v[96:97] op_sel_hi:[1,0,1]
	v_lshlrev_b64 v[138:139], 11, v[134:135]
	v_pk_fma_f32 v[142:143], v[144:145], s[4:5], v[142:143] op_sel_hi:[1,0,1]
	v_pk_fma_f32 v[136:137], v[136:137], s[4:5], v[140:141] op_sel_hi:[1,0,1]
	v_lshl_add_u64 v[134:135], s[92:93], 0, v[138:139]
	v_pk_fma_f32 v[92:93], v[136:137], s[86:87], v[92:93] op_sel_hi:[1,0,1]
	v_pk_fma_f32 v[90:91], v[142:143], s[86:87], v[90:91] op_sel_hi:[1,0,1]
	v_lshl_add_u64 v[134:135], v[134:135], 0, v[162:163]
	s_waitcnt vmcnt(0)
	v_mov_b64_e32 v[134:135], v[224:225]
	v_mov_b64_e32 v[136:137], v[226:227]
	v_lshl_add_u64 v[138:139], s[88:89], 0, v[138:139]
	v_lshl_add_u64 v[142:143], v[138:139], 0, v[164:165]
	s_waitcnt vmcnt(0)
	v_mov_b64_e32 v[138:139], v[228:229]
	v_mov_b64_e32 v[140:141], v[230:231]
	s_waitcnt vmcnt(1)
	v_cvt_pk_f32_fp8_sdwa v[146:147], v134 src0_sel:WORD_1
	v_cvt_pk_f32_fp8_e32 v[144:145], v134
	v_cvt_pk_f32_fp8_e32 v[148:149], v135
	v_cvt_pk_f32_fp8_sdwa v[134:135], v135 src0_sel:WORD_1
	s_waitcnt vmcnt(0)
	v_lshlrev_b32_e32 v150, 16, v138
	v_and_b32_e32 v151, 0xffff0000, v138
	v_lshlrev_b32_e32 v138, 16, v139
	v_and_b32_e32 v139, 0xffff0000, v139
	v_pk_fma_f32 v[138:139], v[146:147], s[4:5], v[138:139] op_sel_hi:[1,0,1]
	v_lshlrev_b32_e32 v146, 16, v140
	v_and_b32_e32 v147, 0xffff0000, v140
	v_lshlrev_b32_e32 v140, 16, v141
	v_and_b32_e32 v141, 0xffff0000, v141
	v_pk_fma_f32 v[134:135], v[134:135], s[4:5], v[140:141] op_sel_hi:[1,0,1]
	v_pk_fma_f32 v[112:113], v[138:139], s[86:87], v[112:113] op_sel_hi:[1,0,1]
	s_waitcnt vmcnt(0)
	v_mov_b64_e32 v[138:139], v[232:233]
	v_mov_b64_e32 v[140:141], v[234:235]
	v_pk_fma_f32 v[108:109], v[134:135], s[86:87], v[108:109] op_sel_hi:[1,0,1]
	v_cvt_pk_f32_fp8_e32 v[134:135], v136
	v_pk_fma_f32 v[146:147], v[148:149], s[4:5], v[146:147] op_sel_hi:[1,0,1]
	v_cvt_pk_f32_fp8_sdwa v[142:143], v136 src0_sel:WORD_1
	v_pk_fma_f32 v[144:145], v[144:145], s[4:5], v[150:151] op_sel_hi:[1,0,1]
	v_pk_fma_f32 v[106:107], v[146:147], s[86:87], v[106:107] op_sel_hi:[1,0,1]
	v_pk_fma_f32 v[110:111], v[144:145], s[86:87], v[110:111] op_sel_hi:[1,0,1]
	v_cvt_pk_f32_fp8_e32 v[144:145], v137
	v_cvt_pk_f32_fp8_sdwa v[136:137], v137 src0_sel:WORD_1
	s_waitcnt vmcnt(0)
	v_lshlrev_b32_e32 v146, 16, v138
	v_and_b32_e32 v147, 0xffff0000, v138
	v_pk_fma_f32 v[134:135], v[134:135], s[4:5], v[146:147] op_sel_hi:[1,0,1]
	v_lshlrev_b32_e32 v138, 16, v139
	v_and_b32_e32 v139, 0xffff0000, v139
	v_pk_fma_f32 v[118:119], v[134:135], s[86:87], v[118:119] op_sel_hi:[1,0,1]
	v_add_u32_e32 v134, 0x90, v132
	v_pk_fma_f32 v[138:139], v[142:143], s[4:5], v[138:139] op_sel_hi:[1,0,1]
	v_ashrrev_i32_e32 v135, 31, v134
	v_lshlrev_b32_e32 v142, 16, v140
	v_and_b32_e32 v143, 0xffff0000, v140
	v_lshlrev_b32_e32 v140, 16, v141
	v_and_b32_e32 v141, 0xffff0000, v141
	v_pk_fma_f32 v[120:121], v[138:139], s[86:87], v[120:121] op_sel_hi:[1,0,1]
	v_lshlrev_b64 v[138:139], 11, v[134:135]
	v_pk_fma_f32 v[142:143], v[144:145], s[4:5], v[142:143] op_sel_hi:[1,0,1]
	v_pk_fma_f32 v[136:137], v[136:137], s[4:5], v[140:141] op_sel_hi:[1,0,1]
	v_lshl_add_u64 v[134:135], s[92:93], 0, v[138:139]
	v_pk_fma_f32 v[116:117], v[136:137], s[86:87], v[116:117] op_sel_hi:[1,0,1]
	v_pk_fma_f32 v[114:115], v[142:143], s[86:87], v[114:115] op_sel_hi:[1,0,1]
	v_lshl_add_u64 v[134:135], v[134:135], 0, v[162:163]
	s_waitcnt vmcnt(0)
	v_mov_b64_e32 v[134:135], v[236:237]
	v_mov_b64_e32 v[136:137], v[238:239]
	v_lshl_add_u64 v[138:139], s[88:89], 0, v[138:139]
	v_lshl_add_u64 v[142:143], v[138:139], 0, v[164:165]
	s_waitcnt vmcnt(0)
	v_mov_b64_e32 v[138:139], v[240:241]
	v_mov_b64_e32 v[140:141], v[242:243]
	s_waitcnt vmcnt(1)
	v_cvt_pk_f32_fp8_sdwa v[146:147], v134 src0_sel:WORD_1
	v_cvt_pk_f32_fp8_e32 v[144:145], v134
	v_cvt_pk_f32_fp8_e32 v[148:149], v135
	v_cvt_pk_f32_fp8_sdwa v[134:135], v135 src0_sel:WORD_1
	s_waitcnt vmcnt(0)
	v_lshlrev_b32_e32 v150, 16, v138
	v_and_b32_e32 v151, 0xffff0000, v138
	v_lshlrev_b32_e32 v138, 16, v139
	v_and_b32_e32 v139, 0xffff0000, v139
	v_pk_fma_f32 v[138:139], v[146:147], s[4:5], v[138:139] op_sel_hi:[1,0,1]
	v_lshlrev_b32_e32 v146, 16, v140
	v_and_b32_e32 v147, 0xffff0000, v140
	v_lshlrev_b32_e32 v140, 16, v141
	v_and_b32_e32 v141, 0xffff0000, v141
	v_pk_fma_f32 v[134:135], v[134:135], s[4:5], v[140:141] op_sel_hi:[1,0,1]
	v_pk_fma_f32 v[128:129], v[138:139], s[86:87], v[128:129] op_sel_hi:[1,0,1]
	s_waitcnt vmcnt(0)
	v_mov_b64_e32 v[138:139], v[244:245]
	v_mov_b64_e32 v[140:141], v[246:247]
	s_mov_b32 s98, 0x50000
	s_mov_b32 s99, 0
	v_lshl_add_u64 v[212:213], v[248:249], 0, s[98:99]
	global_load_dwordx4 v[212:215], v[212:213], off
	s_mov_b32 s98, 0x50000
	s_mov_b32 s99, 0
	v_lshl_add_u64 v[216:217], v[250:251], 0, s[98:99]
	global_load_dwordx4 v[216:219], v[216:217], off
	s_mov_b32 s98, 0x50000
	s_mov_b32 s99, 0
	v_lshl_add_u64 v[220:221], v[250:251], 0, s[98:99]
	global_load_dwordx4 v[220:223], v[220:221], off offset:256
	s_mov_b32 s98, 0x58000
	s_mov_b32 s99, 0
	v_lshl_add_u64 v[224:225], v[248:249], 0, s[98:99]
	global_load_dwordx4 v[224:227], v[224:225], off
	s_mov_b32 s98, 0x58000
	s_mov_b32 s99, 0
	v_lshl_add_u64 v[228:229], v[250:251], 0, s[98:99]
	global_load_dwordx4 v[228:231], v[228:229], off
	s_mov_b32 s98, 0x58000
	s_mov_b32 s99, 0
	v_lshl_add_u64 v[232:233], v[250:251], 0, s[98:99]
	global_load_dwordx4 v[232:235], v[232:233], off offset:256
	v_pk_fma_f32 v[124:125], v[134:135], s[86:87], v[124:125] op_sel_hi:[1,0,1]
	v_cvt_pk_f32_fp8_e32 v[134:135], v136
	v_pk_fma_f32 v[146:147], v[148:149], s[4:5], v[146:147] op_sel_hi:[1,0,1]
	v_cvt_pk_f32_fp8_sdwa v[142:143], v136 src0_sel:WORD_1
	v_pk_fma_f32 v[144:145], v[144:145], s[4:5], v[150:151] op_sel_hi:[1,0,1]
	v_pk_fma_f32 v[122:123], v[146:147], s[86:87], v[122:123] op_sel_hi:[1,0,1]
	v_pk_fma_f32 v[126:127], v[144:145], s[86:87], v[126:127] op_sel_hi:[1,0,1]
	v_cvt_pk_f32_fp8_e32 v[144:145], v137
	v_cvt_pk_f32_fp8_sdwa v[136:137], v137 src0_sel:WORD_1
	s_waitcnt vmcnt(0)
	v_lshlrev_b32_e32 v146, 16, v138
	v_and_b32_e32 v147, 0xffff0000, v138
	v_pk_fma_f32 v[134:135], v[134:135], s[4:5], v[146:147] op_sel_hi:[1,0,1]
	v_lshlrev_b32_e32 v138, 16, v139
	v_and_b32_e32 v139, 0xffff0000, v139
	v_pk_fma_f32 v[102:103], v[134:135], s[86:87], v[102:103] op_sel_hi:[1,0,1]
	v_add_u32_e32 v134, 0xa0, v132
	v_pk_fma_f32 v[138:139], v[142:143], s[4:5], v[138:139] op_sel_hi:[1,0,1]
	v_ashrrev_i32_e32 v135, 31, v134
	v_lshlrev_b32_e32 v142, 16, v140
	v_and_b32_e32 v143, 0xffff0000, v140
	v_lshlrev_b32_e32 v140, 16, v141
	v_and_b32_e32 v141, 0xffff0000, v141
	v_pk_fma_f32 v[104:105], v[138:139], s[86:87], v[104:105] op_sel_hi:[1,0,1]
	v_lshlrev_b64 v[138:139], 11, v[134:135]
	v_pk_fma_f32 v[142:143], v[144:145], s[4:5], v[142:143] op_sel_hi:[1,0,1]
	v_pk_fma_f32 v[136:137], v[136:137], s[4:5], v[140:141] op_sel_hi:[1,0,1]
	v_lshl_add_u64 v[134:135], s[92:93], 0, v[138:139]
	v_pk_fma_f32 v[100:101], v[136:137], s[86:87], v[100:101] op_sel_hi:[1,0,1]
	v_pk_fma_f32 v[98:99], v[142:143], s[86:87], v[98:99] op_sel_hi:[1,0,1]
	v_lshl_add_u64 v[134:135], v[134:135], 0, v[162:163]
	s_waitcnt vmcnt(0)
	v_mov_b64_e32 v[134:135], v[212:213]
	v_mov_b64_e32 v[136:137], v[214:215]
	v_lshl_add_u64 v[138:139], s[88:89], 0, v[138:139]
	v_lshl_add_u64 v[142:143], v[138:139], 0, v[164:165]
	s_waitcnt vmcnt(0)
	v_mov_b64_e32 v[138:139], v[216:217]
	v_mov_b64_e32 v[140:141], v[218:219]
	v_add_u32_e32 v132, 0xb0, v132
	v_ashrrev_i32_e32 v133, 31, v132
	s_waitcnt vmcnt(1)
	v_cvt_pk_f32_fp8_sdwa v[146:147], v134 src0_sel:WORD_1
	v_cvt_pk_f32_fp8_e32 v[144:145], v134
	v_cvt_pk_f32_fp8_e32 v[148:149], v135
	v_cvt_pk_f32_fp8_sdwa v[134:135], v135 src0_sel:WORD_1
	s_waitcnt vmcnt(0)
	v_lshlrev_b32_e32 v150, 16, v138
	v_and_b32_e32 v151, 0xffff0000, v138
	v_lshlrev_b32_e32 v138, 16, v139
	v_and_b32_e32 v139, 0xffff0000, v139
	v_pk_fma_f32 v[138:139], v[146:147], s[4:5], v[138:139] op_sel_hi:[1,0,1]
	v_lshlrev_b32_e32 v146, 16, v140
	v_and_b32_e32 v147, 0xffff0000, v140
	v_lshlrev_b32_e32 v140, 16, v141
	v_and_b32_e32 v141, 0xffff0000, v141
	v_pk_fma_f32 v[134:135], v[134:135], s[4:5], v[140:141] op_sel_hi:[1,0,1]
	v_pk_fma_f32 v[80:81], v[138:139], s[86:87], v[80:81] op_sel_hi:[1,0,1]
	s_waitcnt vmcnt(0)
	v_mov_b64_e32 v[138:139], v[220:221]
	v_mov_b64_e32 v[140:141], v[222:223]
	v_pk_fma_f32 v[144:145], v[144:145], s[4:5], v[150:151] op_sel_hi:[1,0,1]
	v_cvt_pk_f32_fp8_sdwa v[142:143], v136 src0_sel:WORD_1
	v_pk_fma_f32 v[78:79], v[144:145], s[86:87], v[78:79] op_sel_hi:[1,0,1]
	v_pk_fma_f32 v[76:77], v[134:135], s[86:87], v[76:77] op_sel_hi:[1,0,1]
	v_cvt_pk_f32_fp8_e32 v[134:135], v136
	v_cvt_pk_f32_fp8_e32 v[144:145], v137
	v_cvt_pk_f32_fp8_sdwa v[136:137], v137 src0_sel:WORD_1
	v_pk_fma_f32 v[146:147], v[148:149], s[4:5], v[146:147] op_sel_hi:[1,0,1]
	s_nop 0
	v_pk_fma_f32 v[74:75], v[146:147], s[86:87], v[74:75] op_sel_hi:[1,0,1]
	s_waitcnt vmcnt(0)
	v_lshlrev_b32_e32 v146, 16, v138
	v_and_b32_e32 v147, 0xffff0000, v138
	v_lshlrev_b32_e32 v138, 16, v139
	v_and_b32_e32 v139, 0xffff0000, v139
	v_pk_fma_f32 v[138:139], v[142:143], s[4:5], v[138:139] op_sel_hi:[1,0,1]
	v_lshlrev_b32_e32 v142, 16, v140
	v_and_b32_e32 v143, 0xffff0000, v140
	v_lshlrev_b32_e32 v140, 16, v141
	v_and_b32_e32 v141, 0xffff0000, v141
	v_pk_fma_f32 v[136:137], v[136:137], s[4:5], v[140:141] op_sel_hi:[1,0,1]
	v_pk_fma_f32 v[134:135], v[134:135], s[4:5], v[146:147] op_sel_hi:[1,0,1]
	v_pk_fma_f32 v[56:57], v[136:137], s[86:87], v[56:57] op_sel_hi:[1,0,1]
	v_lshlrev_b64 v[136:137], 11, v[132:133]
	v_pk_fma_f32 v[142:143], v[144:145], s[4:5], v[142:143] op_sel_hi:[1,0,1]
	v_lshl_add_u64 v[132:133], s[92:93], 0, v[136:137]
	v_pk_fma_f32 v[64:65], v[138:139], s[86:87], v[64:65] op_sel_hi:[1,0,1]
	v_pk_fma_f32 v[62:63], v[134:135], s[86:87], v[62:63] op_sel_hi:[1,0,1]
	v_pk_fma_f32 v[54:55], v[142:143], s[86:87], v[54:55] op_sel_hi:[1,0,1]
	v_lshl_add_u64 v[132:133], v[132:133], 0, v[162:163]
	s_waitcnt vmcnt(0)
	v_mov_b64_e32 v[132:133], v[224:225]
	v_mov_b64_e32 v[134:135], v[226:227]
	v_lshl_add_u64 v[136:137], s[88:89], 0, v[136:137]
	v_lshl_add_u64 v[140:141], v[136:137], 0, v[164:165]
	s_waitcnt vmcnt(0)
	v_mov_b64_e32 v[136:137], v[228:229]
	v_mov_b64_e32 v[138:139], v[230:231]
	s_waitcnt vmcnt(1)
	v_cvt_pk_f32_fp8_sdwa v[144:145], v132 src0_sel:WORD_1
	v_cvt_pk_f32_fp8_e32 v[142:143], v132
	v_cvt_pk_f32_fp8_e32 v[146:147], v133
	v_cvt_pk_f32_fp8_sdwa v[132:133], v133 src0_sel:WORD_1
	s_waitcnt vmcnt(0)
	v_lshlrev_b32_e32 v148, 16, v136
	v_and_b32_e32 v149, 0xffff0000, v136
	v_lshlrev_b32_e32 v136, 16, v137
	v_and_b32_e32 v137, 0xffff0000, v137
	v_pk_fma_f32 v[136:137], v[144:145], s[4:5], v[136:137] op_sel_hi:[1,0,1]
	v_lshlrev_b32_e32 v144, 16, v138
	v_and_b32_e32 v145, 0xffff0000, v138
	v_lshlrev_b32_e32 v138, 16, v139
	v_and_b32_e32 v139, 0xffff0000, v139
	v_pk_fma_f32 v[132:133], v[132:133], s[4:5], v[138:139] op_sel_hi:[1,0,1]
	v_pk_fma_f32 v[40:41], v[136:137], s[86:87], v[40:41] op_sel_hi:[1,0,1]
	s_waitcnt vmcnt(0)
	v_mov_b64_e32 v[136:137], v[232:233]
	v_mov_b64_e32 v[138:139], v[234:235]
	v_pk_fma_f32 v[142:143], v[142:143], s[4:5], v[148:149] op_sel_hi:[1,0,1]
	v_cvt_pk_f32_fp8_sdwa v[140:141], v134 src0_sel:WORD_1
	v_pk_fma_f32 v[38:39], v[142:143], s[86:87], v[38:39] op_sel_hi:[1,0,1]
	v_pk_fma_f32 v[36:37], v[132:133], s[86:87], v[36:37] op_sel_hi:[1,0,1]
	v_cvt_pk_f32_fp8_e32 v[132:133], v134
	v_cvt_pk_f32_fp8_e32 v[142:143], v135
	v_cvt_pk_f32_fp8_sdwa v[134:135], v135 src0_sel:WORD_1
	v_pk_fma_f32 v[144:145], v[146:147], s[4:5], v[144:145] op_sel_hi:[1,0,1]
	s_nop 0
	v_pk_fma_f32 v[34:35], v[144:145], s[86:87], v[34:35] op_sel_hi:[1,0,1]
	s_waitcnt vmcnt(0)
	v_lshlrev_b32_e32 v144, 16, v136
	v_and_b32_e32 v145, 0xffff0000, v136
	v_lshlrev_b32_e32 v136, 16, v137
	v_and_b32_e32 v137, 0xffff0000, v137
	v_pk_fma_f32 v[136:137], v[140:141], s[4:5], v[136:137] op_sel_hi:[1,0,1]
	v_lshlrev_b32_e32 v140, 16, v138
	v_and_b32_e32 v141, 0xffff0000, v138
	v_lshlrev_b32_e32 v138, 16, v139
	v_and_b32_e32 v139, 0xffff0000, v139
	v_pk_fma_f32 v[132:133], v[132:133], s[4:5], v[144:145] op_sel_hi:[1,0,1]
	v_pk_fma_f32 v[140:141], v[142:143], s[4:5], v[140:141] op_sel_hi:[1,0,1]
	v_pk_fma_f32 v[134:135], v[134:135], s[4:5], v[138:139] op_sel_hi:[1,0,1]
	v_readlane_b32 s4, v255, 18
	v_readlane_b32 s5, v255, 19
	v_pk_fma_f32 v[22:23], v[132:133], s[86:87], v[22:23] op_sel_hi:[1,0,1]
	v_pk_fma_f32 v[20:21], v[134:135], s[86:87], v[20:21] op_sel_hi:[1,0,1]
	v_lshl_add_u64 v[132:133], s[4:5], 0, v[130:131]
	s_mov_b64 s[4:5], 0x1000
	v_lshl_add_u64 v[130:131], s[6:7], 0, v[130:131]
	v_lshl_add_u64 v[134:135], v[132:133], 0, s[4:5]
	v_lshl_add_u64 v[142:143], v[130:131], 0, s[4:5]
	s_movk_i32 s4, 0x1000
	v_add_co_u32_e32 v132, vcc, s4, v132
	v_pk_fma_f32 v[24:25], v[136:137], s[86:87], v[24:25] op_sel_hi:[1,0,1]
	s_nop 0
	v_addc_co_u32_e32 v133, vcc, 0, v133, vcc
	v_add_co_u32_e32 v130, vcc, s4, v130
	v_pk_fma_f32 v[18:19], v[140:141], s[86:87], v[18:19] op_sel_hi:[1,0,1]
	s_nop 0
	v_addc_co_u32_e32 v131, vcc, 0, v131, vcc
	global_load_dwordx4 v[154:157], v[132:133], off
	global_load_dwordx4 v[146:149], v[134:135], off offset:16
	global_load_dwordx4 v[158:161], v[130:131], off
	global_load_dwordx4 v[150:153], v[142:143], off offset:16
	s_nop 0
	global_load_dwordx4 v[130:133], v[134:135], off offset:528
	global_load_dwordx4 v[138:141], v[134:135], off offset:512
	s_nop 0
	global_load_dwordx4 v[134:137], v[142:143], off offset:528
	s_nop 0
	global_load_dwordx4 v[142:145], v[142:143], off offset:512
	v_cmp_lt_i32_e32 vcc, v170, v171
	s_nop 1
	v_cndmask_b32_e32 v170, v205, v170, vcc
	v_cmp_lt_i32_e32 vcc, v172, v171
	v_lshlrev_b32_e32 v170, 2, v170
	s_nop 0
	v_cndmask_b32_e32 v171, v205, v172, vcc
	v_mov_b32_e32 v172, v7
	v_pk_add_f32 v[172:173], v[172:173], v[174:175]
	v_mov_b32_e32 v174, v3
	v_mov_b32_e32 v175, v4
	v_pk_add_f32 v[174:175], v[174:175], v[176:177]
	v_add_f32_e32 v172, v172, v173
	v_pk_add_f32 v[174:175], v[174:175], v[174:175] op_sel_hi:[0,1]
	v_add_f32_e32 v173, 0, v172
	v_add_f32_e32 v177, v14, v15
	v_mov_b32_e32 v176, v10
	v_mov_b32_e32 v174, v12
	v_mov_b32_e32 v172, v13
	v_pk_add_f32 v[176:177], v[176:177], v[196:197]
	v_pk_add_f32 v[172:173], v[174:175], v[172:173]
	v_lshlrev_b32_e32 v171, 2, v171
	v_pk_add_f32 v[172:173], v[176:177], v[172:173]
	v_cmp_gt_u32_e32 vcc, 16, v169
	v_add_f32_e32 v172, v172, v173
	v_mov_b32_e32 v173, v172
	s_nop 1
	v_permlane16_swap_b32_e32 v173, v172
	s_waitcnt lgkmcnt(0)
	v_add_f32_e32 v172, v172, v173
	v_mov_b32_e32 v173, v172
	s_nop 1
	v_permlane32_swap_b32_e32 v173, v172
	s_waitcnt lgkmcnt(0)
	v_add_f32_e32 v172, v172, v173
	v_fmamk_f32 v174, v172, 0xbc800000, v9
	v_fmamk_f32 v176, v172, 0xbc800000, v7
	v_fmamk_f32 v173, v172, 0xbc800000, v8
	v_fmamk_f32 v175, v172, 0xbc800000, v6
	v_mul_f32_e32 v176, v176, v176
	v_mul_f32_e32 v174, v174, v174
	v_fmac_f32_e32 v176, v175, v175
	v_fmac_f32_e32 v174, v173, v173
	v_fmamk_f32 v175, v172, 0xbc800000, v5
	v_fmamk_f32 v177, v172, 0xbc800000, v3
	v_add_f32_e32 v173, v176, v174
	v_fmamk_f32 v174, v172, 0xbc800000, v4
	v_fmamk_f32 v176, v172, 0xbc800000, v2
	v_mul_f32_e32 v177, v177, v177
	v_mul_f32_e32 v175, v175, v175
	v_fmac_f32_e32 v177, v176, v176
	v_fmac_f32_e32 v175, v174, v174
	v_add_f32_e32 v174, v177, v175
	v_fmamk_f32 v175, v172, 0xbc800000, v17
	v_fmamk_f32 v177, v172, 0xbc800000, v15
	v_add_f32_e32 v173, v173, v174
	v_fmamk_f32 v174, v172, 0xbc800000, v16
	v_fmamk_f32 v176, v172, 0xbc800000, v14
	v_mul_f32_e32 v177, v177, v177
	v_mul_f32_e32 v175, v175, v175
	v_fmac_f32_e32 v177, v176, v176
	v_fmac_f32_e32 v175, v174, v174
	v_add_f32_e32 v174, v177, v175
	v_fmamk_f32 v175, v172, 0xbc800000, v13
	v_fmamk_f32 v177, v172, 0xbc800000, v11
	v_add_f32_e32 v173, v174, v173
	v_fmamk_f32 v174, v172, 0xbc800000, v12
	v_fmamk_f32 v176, v172, 0xbc800000, v10
	v_mul_f32_e32 v177, v177, v177
	v_mul_f32_e32 v175, v175, v175
	v_fmac_f32_e32 v177, v176, v176
	v_fmac_f32_e32 v175, v174, v174
	v_add_f32_e32 v174, v177, v175
	v_add_f32_e32 v173, v174, v173
	v_mov_b32_e32 v174, v173
	s_nop 1
	v_permlane16_swap_b32_e32 v174, v173
	s_waitcnt lgkmcnt(0)
	v_add_f32_e32 v173, v173, v174
	v_mov_b32_e32 v174, v173
	s_nop 1
	v_permlane32_swap_b32_e32 v174, v173
	s_and_saveexec_b64 s[4:5], vcc
	v_readlane_b32 s62, v255, 10
	v_readlane_b32 s84, v255, 12
	v_readlane_b32 s28, v255, 14
	v_readlane_b32 s63, v255, 11
	v_readlane_b32 s85, v255, 13
	v_readlane_b32 s29, v255, 15
	s_mov_b32 s94, s67
	s_cbranch_execz .LBB0_1028
	s_lshl_b32 s6, s12, 11
	s_add_i32 s6, s1, s6
	v_mul_f32_e32 v172, 0x3c800000, v172
	v_lshl_add_u32 v175, v167, 5, s6
	s_waitcnt lgkmcnt(0)
	v_add_f32_e32 v173, v173, v174
	ds_write_b64 v175, v[172:173]
.LBB0_1028:
	s_or_b64 exec, exec, s[4:5]
	v_mov_b32_e32 v172, v31
	v_mov_b32_e32 v173, v32
	s_waitcnt lgkmcnt(0)
	v_mov_b32_e32 v174, v30
	v_mov_b32_e32 v175, v33
	v_pk_add_f32 v[172:173], v[172:173], v[174:175]
	v_mov_b32_e32 v174, v27
	v_mov_b32_e32 v175, v28
	v_mov_b32_e32 v176, v26
	v_mov_b32_e32 v177, v29
	v_pk_add_f32 v[174:175], v[174:175], v[176:177]
	v_add_f32_e32 v172, v172, v173
	v_pk_add_f32 v[174:175], v[174:175], v[174:175] op_sel_hi:[0,1]
	v_add_f32_e32 v173, 0, v172
	v_add_f32_e32 v177, v46, v47
	v_add_f32_e32 v197, v48, v49
	v_mov_b32_e32 v176, v42
	v_mov_b32_e32 v196, v43
	v_mov_b32_e32 v174, v44
	v_mov_b32_e32 v172, v45
	v_pk_add_f32 v[176:177], v[176:177], v[196:197]
	v_pk_add_f32 v[172:173], v[174:175], v[172:173]
	s_nop 0
	v_pk_add_f32 v[172:173], v[176:177], v[172:173]
	s_nop 0
	v_add_f32_e32 v172, v172, v173
	v_mov_b32_e32 v173, v172
	s_nop 1
	v_permlane16_swap_b32_e32 v173, v172
	s_waitcnt lgkmcnt(0)
	v_add_f32_e32 v172, v172, v173
	v_mov_b32_e32 v173, v172
	s_nop 1
	v_permlane32_swap_b32_e32 v173, v172
	s_waitcnt lgkmcnt(0)
	v_add_f32_e32 v172, v172, v173
	v_fmamk_f32 v174, v172, 0xbc800000, v33
	v_fmamk_f32 v176, v172, 0xbc800000, v31
	v_fmamk_f32 v173, v172, 0xbc800000, v32
	v_fmamk_f32 v175, v172, 0xbc800000, v30
	v_mul_f32_e32 v176, v176, v176
	v_mul_f32_e32 v174, v174, v174
	v_fmac_f32_e32 v176, v175, v175
	v_fmac_f32_e32 v174, v173, v173
	v_fmamk_f32 v175, v172, 0xbc800000, v29
	v_fmamk_f32 v177, v172, 0xbc800000, v27
	v_add_f32_e32 v173, v176, v174
	v_fmamk_f32 v174, v172, 0xbc800000, v28
	v_fmamk_f32 v176, v172, 0xbc800000, v26
	v_mul_f32_e32 v177, v177, v177
	v_mul_f32_e32 v175, v175, v175
	v_fmac_f32_e32 v177, v176, v176
	v_fmac_f32_e32 v175, v174, v174
	v_add_f32_e32 v174, v177, v175
	v_fmamk_f32 v175, v172, 0xbc800000, v49
	v_fmamk_f32 v177, v172, 0xbc800000, v47
	v_add_f32_e32 v173, v173, v174
	v_fmamk_f32 v174, v172, 0xbc800000, v48
	v_fmamk_f32 v176, v172, 0xbc800000, v46
	v_mul_f32_e32 v177, v177, v177
	v_mul_f32_e32 v175, v175, v175
	v_fmac_f32_e32 v177, v176, v176
	v_fmac_f32_e32 v175, v174, v174
	v_add_f32_e32 v174, v177, v175
	v_fmamk_f32 v175, v172, 0xbc800000, v45
	v_fmamk_f32 v177, v172, 0xbc800000, v43
	v_add_f32_e32 v173, v174, v173
	v_fmamk_f32 v174, v172, 0xbc800000, v44
	v_fmamk_f32 v176, v172, 0xbc800000, v42
	v_mul_f32_e32 v177, v177, v177
	v_mul_f32_e32 v175, v175, v175
	v_fmac_f32_e32 v177, v176, v176
	v_fmac_f32_e32 v175, v174, v174
	v_add_f32_e32 v174, v177, v175
	v_add_f32_e32 v173, v174, v173
	v_mov_b32_e32 v174, v173
	s_nop 1
	v_permlane16_swap_b32_e32 v174, v173
	s_waitcnt lgkmcnt(0)
	v_add_f32_e32 v173, v173, v174
	v_mov_b32_e32 v174, v173
	s_nop 1
	v_permlane32_swap_b32_e32 v174, v173
	s_and_saveexec_b64 s[4:5], vcc
	s_movk_i32 s96, 0x80
	s_mov_b32 s67, s66
	s_cbranch_execz .LBB0_1030
	s_lshl_b32 s6, s12, 11
	s_add_i32 s6, s1, s6
	v_mul_f32_e32 v172, 0x3c800000, v172
	v_lshl_add_u32 v175, v167, 5, s6
	s_waitcnt lgkmcnt(0)
	v_add_f32_e32 v173, v173, v174
	ds_write_b64 v175, v[172:173] offset:512
.LBB0_1030:
	s_or_b64 exec, exec, s[4:5]
	v_mov_b32_e32 v172, v59
	v_mov_b32_e32 v173, v60
	s_waitcnt lgkmcnt(0)
	v_mov_b32_e32 v174, v58
	v_mov_b32_e32 v175, v61
	v_pk_add_f32 v[172:173], v[172:173], v[174:175]
	v_mov_b32_e32 v174, v51
	v_mov_b32_e32 v175, v52
	v_mov_b32_e32 v176, v50
	v_mov_b32_e32 v177, v53
	v_pk_add_f32 v[174:175], v[174:175], v[176:177]
	v_add_f32_e32 v172, v172, v173
	v_pk_add_f32 v[174:175], v[174:175], v[174:175] op_sel_hi:[0,1]
	v_add_f32_e32 v173, 0, v172
	v_add_f32_e32 v177, v70, v71
	v_add_f32_e32 v197, v72, v73
	v_mov_b32_e32 v176, v66
	v_mov_b32_e32 v196, v67
	v_mov_b32_e32 v174, v68
	v_mov_b32_e32 v172, v69
	v_pk_add_f32 v[176:177], v[176:177], v[196:197]
	v_pk_add_f32 v[172:173], v[174:175], v[172:173]
	s_nop 0
	v_pk_add_f32 v[172:173], v[176:177], v[172:173]
	s_nop 0
	v_add_f32_e32 v172, v172, v173
	v_mov_b32_e32 v173, v172
	s_nop 1
	v_permlane16_swap_b32_e32 v173, v172
	s_waitcnt lgkmcnt(0)
	v_add_f32_e32 v172, v172, v173
	v_mov_b32_e32 v173, v172
	s_nop 1
	v_permlane32_swap_b32_e32 v173, v172
	s_waitcnt lgkmcnt(0)
	v_add_f32_e32 v172, v172, v173
	v_fmamk_f32 v174, v172, 0xbc800000, v61
	v_fmamk_f32 v176, v172, 0xbc800000, v59
	v_fmamk_f32 v173, v172, 0xbc800000, v60
	v_fmamk_f32 v175, v172, 0xbc800000, v58
	v_mul_f32_e32 v176, v176, v176
	v_mul_f32_e32 v174, v174, v174
	v_fmac_f32_e32 v176, v175, v175
	v_fmac_f32_e32 v174, v173, v173
	v_fmamk_f32 v175, v172, 0xbc800000, v53
	v_fmamk_f32 v177, v172, 0xbc800000, v51
	v_add_f32_e32 v173, v176, v174
	v_fmamk_f32 v174, v172, 0xbc800000, v52
	v_fmamk_f32 v176, v172, 0xbc800000, v50
	v_mul_f32_e32 v177, v177, v177
	v_mul_f32_e32 v175, v175, v175
	v_fmac_f32_e32 v177, v176, v176
	v_fmac_f32_e32 v175, v174, v174
	v_add_f32_e32 v174, v177, v175
	v_fmamk_f32 v175, v172, 0xbc800000, v73
	v_fmamk_f32 v177, v172, 0xbc800000, v71
	v_add_f32_e32 v173, v173, v174
	v_fmamk_f32 v174, v172, 0xbc800000, v72
	v_fmamk_f32 v176, v172, 0xbc800000, v70
	v_mul_f32_e32 v177, v177, v177
	v_mul_f32_e32 v175, v175, v175
	v_fmac_f32_e32 v177, v176, v176
	v_fmac_f32_e32 v175, v174, v174
	v_add_f32_e32 v174, v177, v175
	v_fmamk_f32 v175, v172, 0xbc800000, v69
	v_fmamk_f32 v177, v172, 0xbc800000, v67
	v_add_f32_e32 v173, v174, v173
	v_fmamk_f32 v174, v172, 0xbc800000, v68
	v_fmamk_f32 v176, v172, 0xbc800000, v66
	v_mul_f32_e32 v177, v177, v177
	v_mul_f32_e32 v175, v175, v175
	v_fmac_f32_e32 v177, v176, v176
	v_fmac_f32_e32 v175, v174, v174
	v_add_f32_e32 v174, v177, v175
	v_add_f32_e32 v173, v174, v173
	v_mov_b32_e32 v174, v173
	s_nop 1
	v_permlane16_swap_b32_e32 v174, v173
	s_waitcnt lgkmcnt(0)
	v_add_f32_e32 v173, v173, v174
	v_mov_b32_e32 v174, v173
	s_nop 1
	v_permlane32_swap_b32_e32 v174, v173
	s_and_saveexec_b64 s[4:5], vcc
	s_cbranch_execz .LBB0_1032
	s_lshl_b32 s6, s12, 11
	s_add_i32 s6, s1, s6
	v_mul_f32_e32 v172, 0x3c800000, v172
	v_lshl_add_u32 v175, v167, 5, s6
	s_waitcnt lgkmcnt(0)
	v_add_f32_e32 v173, v173, v174
	ds_write_b64 v175, v[172:173] offset:1024
.LBB0_1032:
	s_or_b64 exec, exec, s[4:5]
	v_mov_b32_e32 v172, v87
	v_mov_b32_e32 v173, v88
	s_waitcnt lgkmcnt(0)
	v_mov_b32_e32 v174, v86
	v_mov_b32_e32 v175, v89
	v_pk_add_f32 v[172:173], v[172:173], v[174:175]
	v_mov_b32_e32 v174, v83
	v_mov_b32_e32 v175, v84
	v_mov_b32_e32 v176, v82
	v_mov_b32_e32 v177, v85
	v_pk_add_f32 v[174:175], v[174:175], v[176:177]
	v_add_f32_e32 v172, v172, v173
	v_pk_add_f32 v[174:175], v[174:175], v[174:175] op_sel_hi:[0,1]
	v_add_f32_e32 v173, 0, v172
	v_add_f32_e32 v177, v94, v95
	v_add_f32_e32 v197, v96, v97
	v_mov_b32_e32 v176, v90
	v_mov_b32_e32 v196, v91
	v_mov_b32_e32 v174, v92
	v_mov_b32_e32 v172, v93
	v_pk_add_f32 v[176:177], v[176:177], v[196:197]
	v_pk_add_f32 v[172:173], v[174:175], v[172:173]
	s_nop 0
	v_pk_add_f32 v[172:173], v[176:177], v[172:173]
	s_nop 0
	v_add_f32_e32 v172, v172, v173
	v_mov_b32_e32 v173, v172
	s_nop 1
	v_permlane16_swap_b32_e32 v173, v172
	s_waitcnt lgkmcnt(0)
	v_add_f32_e32 v172, v172, v173
	v_mov_b32_e32 v173, v172
	s_nop 1
	v_permlane32_swap_b32_e32 v173, v172
	s_waitcnt lgkmcnt(0)
	v_add_f32_e32 v172, v172, v173
	v_fmamk_f32 v174, v172, 0xbc800000, v89
	v_fmamk_f32 v176, v172, 0xbc800000, v87
	v_fmamk_f32 v173, v172, 0xbc800000, v88
	v_fmamk_f32 v175, v172, 0xbc800000, v86
	v_mul_f32_e32 v176, v176, v176
	v_mul_f32_e32 v174, v174, v174
	v_fmac_f32_e32 v176, v175, v175
	v_fmac_f32_e32 v174, v173, v173
	v_fmamk_f32 v175, v172, 0xbc800000, v85
	v_fmamk_f32 v177, v172, 0xbc800000, v83
	v_add_f32_e32 v173, v176, v174
	v_fmamk_f32 v174, v172, 0xbc800000, v84
	v_fmamk_f32 v176, v172, 0xbc800000, v82
	v_mul_f32_e32 v177, v177, v177
	v_mul_f32_e32 v175, v175, v175
	v_fmac_f32_e32 v177, v176, v176
	v_fmac_f32_e32 v175, v174, v174
	v_add_f32_e32 v174, v177, v175
	v_fmamk_f32 v175, v172, 0xbc800000, v97
	v_fmamk_f32 v177, v172, 0xbc800000, v95
	v_add_f32_e32 v173, v173, v174
	v_fmamk_f32 v174, v172, 0xbc800000, v96
	v_fmamk_f32 v176, v172, 0xbc800000, v94
	v_mul_f32_e32 v177, v177, v177
	v_mul_f32_e32 v175, v175, v175
	v_fmac_f32_e32 v177, v176, v176
	v_fmac_f32_e32 v175, v174, v174
	v_add_f32_e32 v174, v177, v175
	v_fmamk_f32 v175, v172, 0xbc800000, v93
	v_fmamk_f32 v177, v172, 0xbc800000, v91
	v_add_f32_e32 v173, v174, v173
	v_fmamk_f32 v174, v172, 0xbc800000, v92
	v_fmamk_f32 v176, v172, 0xbc800000, v90
	v_mul_f32_e32 v177, v177, v177
	v_mul_f32_e32 v175, v175, v175
	v_fmac_f32_e32 v177, v176, v176
	v_fmac_f32_e32 v175, v174, v174
	v_add_f32_e32 v174, v177, v175
	v_add_f32_e32 v173, v174, v173
	v_mov_b32_e32 v174, v173
	s_nop 1
	v_permlane16_swap_b32_e32 v174, v173
	s_waitcnt lgkmcnt(0)
	v_add_f32_e32 v173, v173, v174
	v_mov_b32_e32 v174, v173
	s_nop 1
	v_permlane32_swap_b32_e32 v174, v173
	s_and_saveexec_b64 s[4:5], vcc
	s_cbranch_execz .LBB0_1034
	s_lshl_b32 s6, s12, 11
	s_add_i32 s6, s1, s6
	v_mul_f32_e32 v172, 0x3c800000, v172
	v_lshl_add_u32 v175, v167, 5, s6
	s_waitcnt lgkmcnt(0)
	v_add_f32_e32 v173, v173, v174
	ds_write_b64 v175, v[172:173] offset:1536
.LBB0_1034:
	s_or_b64 exec, exec, s[4:5]
	v_mov_b32_e32 v172, v111
	v_mov_b32_e32 v173, v112
	s_waitcnt lgkmcnt(0)
	v_mov_b32_e32 v174, v110
	v_mov_b32_e32 v175, v113
	v_pk_add_f32 v[172:173], v[172:173], v[174:175]
	v_mov_b32_e32 v174, v107
	v_mov_b32_e32 v175, v108
	v_mov_b32_e32 v176, v106
	v_mov_b32_e32 v177, v109
	v_pk_add_f32 v[174:175], v[174:175], v[176:177]
	v_add_f32_e32 v172, v172, v173
	v_pk_add_f32 v[174:175], v[174:175], v[174:175] op_sel_hi:[0,1]
	v_add_f32_e32 v173, 0, v172
	v_add_f32_e32 v177, v118, v119
	v_add_f32_e32 v197, v120, v121
	v_mov_b32_e32 v176, v114
	v_mov_b32_e32 v196, v115
	v_mov_b32_e32 v174, v116
	v_mov_b32_e32 v172, v117
	v_pk_add_f32 v[176:177], v[176:177], v[196:197]
	v_pk_add_f32 v[172:173], v[174:175], v[172:173]
	s_nop 0
	v_pk_add_f32 v[172:173], v[176:177], v[172:173]
	s_nop 0
	v_add_f32_e32 v172, v172, v173
	v_mov_b32_e32 v173, v172
	s_nop 1
	v_permlane16_swap_b32_e32 v173, v172
	s_waitcnt lgkmcnt(0)
	v_add_f32_e32 v172, v172, v173
	v_mov_b32_e32 v173, v172
	s_nop 1
	v_permlane32_swap_b32_e32 v173, v172
	s_waitcnt lgkmcnt(0)
	v_add_f32_e32 v172, v172, v173
	v_fmamk_f32 v174, v172, 0xbc800000, v113
	v_fmamk_f32 v176, v172, 0xbc800000, v111
	v_fmamk_f32 v173, v172, 0xbc800000, v112
	v_fmamk_f32 v175, v172, 0xbc800000, v110
	v_mul_f32_e32 v176, v176, v176
	v_mul_f32_e32 v174, v174, v174
	v_fmac_f32_e32 v176, v175, v175
	v_fmac_f32_e32 v174, v173, v173
	v_fmamk_f32 v175, v172, 0xbc800000, v109
	v_fmamk_f32 v177, v172, 0xbc800000, v107
	v_add_f32_e32 v173, v176, v174
	v_fmamk_f32 v174, v172, 0xbc800000, v108
	v_fmamk_f32 v176, v172, 0xbc800000, v106
	v_mul_f32_e32 v177, v177, v177
	v_mul_f32_e32 v175, v175, v175
	v_fmac_f32_e32 v177, v176, v176
	v_fmac_f32_e32 v175, v174, v174
	v_add_f32_e32 v174, v177, v175
	v_fmamk_f32 v175, v172, 0xbc800000, v121
	v_fmamk_f32 v177, v172, 0xbc800000, v119
	v_add_f32_e32 v173, v173, v174
	v_fmamk_f32 v174, v172, 0xbc800000, v120
	v_fmamk_f32 v176, v172, 0xbc800000, v118
	v_mul_f32_e32 v177, v177, v177
	v_mul_f32_e32 v175, v175, v175
	v_fmac_f32_e32 v177, v176, v176
	v_fmac_f32_e32 v175, v174, v174
	v_add_f32_e32 v174, v177, v175
	v_fmamk_f32 v175, v172, 0xbc800000, v117
	v_fmamk_f32 v177, v172, 0xbc800000, v115
	v_add_f32_e32 v173, v174, v173
	v_fmamk_f32 v174, v172, 0xbc800000, v116
	v_fmamk_f32 v176, v172, 0xbc800000, v114
	v_mul_f32_e32 v177, v177, v177
	v_mul_f32_e32 v175, v175, v175
	v_fmac_f32_e32 v177, v176, v176
	v_fmac_f32_e32 v175, v174, v174
	v_add_f32_e32 v174, v177, v175
	v_add_f32_e32 v173, v174, v173
	v_mov_b32_e32 v174, v173
	s_nop 1
	v_permlane16_swap_b32_e32 v174, v173
	s_waitcnt lgkmcnt(0)
	v_add_f32_e32 v173, v173, v174
	v_mov_b32_e32 v174, v173
	s_nop 1
	v_permlane32_swap_b32_e32 v174, v173
	s_and_saveexec_b64 s[4:5], vcc
	s_cbranch_execz .LBB0_1036
	s_lshl_b32 s6, s12, 11
	s_add_i32 s6, s1, s6
	v_mul_f32_e32 v172, 0x3c800000, v172
	v_lshl_add_u32 v175, v167, 5, s6
	s_waitcnt lgkmcnt(0)
	v_add_f32_e32 v173, v173, v174
	ds_write_b64 v175, v[172:173] offset:4096
.LBB0_1036:
	s_or_b64 exec, exec, s[4:5]
	v_mov_b32_e32 v172, v127
	v_mov_b32_e32 v173, v128
	s_waitcnt lgkmcnt(0)
	v_mov_b32_e32 v174, v126
	v_mov_b32_e32 v175, v129
	v_pk_add_f32 v[172:173], v[172:173], v[174:175]
	v_mov_b32_e32 v174, v123
	v_mov_b32_e32 v175, v124
	v_mov_b32_e32 v176, v122
	v_mov_b32_e32 v177, v125
	v_pk_add_f32 v[174:175], v[174:175], v[176:177]
	v_add_f32_e32 v172, v172, v173
	v_pk_add_f32 v[174:175], v[174:175], v[174:175] op_sel_hi:[0,1]
	v_add_f32_e32 v173, 0, v172
	v_add_f32_e32 v177, v102, v103
	v_add_f32_e32 v197, v104, v105
	v_mov_b32_e32 v176, v98
	v_mov_b32_e32 v196, v99
	v_mov_b32_e32 v174, v100
	v_mov_b32_e32 v172, v101
	v_pk_add_f32 v[176:177], v[176:177], v[196:197]
	v_pk_add_f32 v[172:173], v[174:175], v[172:173]
	s_nop 0
	v_pk_add_f32 v[172:173], v[176:177], v[172:173]
	s_nop 0
	v_add_f32_e32 v172, v172, v173
	v_mov_b32_e32 v173, v172
	s_nop 1
	v_permlane16_swap_b32_e32 v173, v172
	s_waitcnt lgkmcnt(0)
	v_add_f32_e32 v172, v172, v173
	v_mov_b32_e32 v173, v172
	s_nop 1
	v_permlane32_swap_b32_e32 v173, v172
	s_waitcnt lgkmcnt(0)
	v_add_f32_e32 v172, v172, v173
	v_fmamk_f32 v174, v172, 0xbc800000, v129
	v_fmamk_f32 v176, v172, 0xbc800000, v127
	v_fmamk_f32 v173, v172, 0xbc800000, v128
	v_fmamk_f32 v175, v172, 0xbc800000, v126
	v_mul_f32_e32 v176, v176, v176
	v_mul_f32_e32 v174, v174, v174
	v_fmac_f32_e32 v176, v175, v175
	v_fmac_f32_e32 v174, v173, v173
	v_fmamk_f32 v175, v172, 0xbc800000, v125
	v_fmamk_f32 v177, v172, 0xbc800000, v123
	v_add_f32_e32 v173, v176, v174
	v_fmamk_f32 v174, v172, 0xbc800000, v124
	v_fmamk_f32 v176, v172, 0xbc800000, v122
	v_mul_f32_e32 v177, v177, v177
	v_mul_f32_e32 v175, v175, v175
	v_fmac_f32_e32 v177, v176, v176
	v_fmac_f32_e32 v175, v174, v174
	v_add_f32_e32 v174, v177, v175
	v_fmamk_f32 v175, v172, 0xbc800000, v105
	v_fmamk_f32 v177, v172, 0xbc800000, v103
	v_add_f32_e32 v173, v173, v174
	v_fmamk_f32 v174, v172, 0xbc800000, v104
	v_fmamk_f32 v176, v172, 0xbc800000, v102
	v_mul_f32_e32 v177, v177, v177
	v_mul_f32_e32 v175, v175, v175
	v_fmac_f32_e32 v177, v176, v176
	v_fmac_f32_e32 v175, v174, v174
	v_add_f32_e32 v174, v177, v175
	v_fmamk_f32 v175, v172, 0xbc800000, v101
	v_fmamk_f32 v177, v172, 0xbc800000, v99
	v_add_f32_e32 v173, v174, v173
	v_fmamk_f32 v174, v172, 0xbc800000, v100
	v_fmamk_f32 v176, v172, 0xbc800000, v98
	v_mul_f32_e32 v177, v177, v177
	v_mul_f32_e32 v175, v175, v175
	v_fmac_f32_e32 v177, v176, v176
	v_fmac_f32_e32 v175, v174, v174
	v_add_f32_e32 v174, v177, v175
	v_add_f32_e32 v173, v174, v173
	v_mov_b32_e32 v174, v173
	s_nop 1
	v_permlane16_swap_b32_e32 v174, v173
	s_waitcnt lgkmcnt(0)
	v_add_f32_e32 v173, v173, v174
	v_mov_b32_e32 v174, v173
	s_nop 1
	v_permlane32_swap_b32_e32 v174, v173
	s_and_saveexec_b64 s[4:5], vcc
	s_cbranch_execz .LBB0_1038
	s_lshl_b32 s6, s12, 11
	s_add_i32 s6, s1, s6
	v_mul_f32_e32 v172, 0x3c800000, v172
	v_lshl_add_u32 v175, v167, 5, s6
	s_waitcnt lgkmcnt(0)
	v_add_f32_e32 v173, v173, v174
	ds_write_b64 v175, v[172:173] offset:4608
.LBB0_1038:
	s_or_b64 exec, exec, s[4:5]
	v_mov_b32_e32 v172, v79
	v_mov_b32_e32 v173, v80
	s_waitcnt lgkmcnt(0)
	v_mov_b32_e32 v174, v78
	v_mov_b32_e32 v175, v81
	v_pk_add_f32 v[172:173], v[172:173], v[174:175]
	v_mov_b32_e32 v174, v75
	v_mov_b32_e32 v175, v76
	v_mov_b32_e32 v176, v74
	v_mov_b32_e32 v177, v77
	v_pk_add_f32 v[174:175], v[174:175], v[176:177]
	v_add_f32_e32 v172, v172, v173
	v_pk_add_f32 v[174:175], v[174:175], v[174:175] op_sel_hi:[0,1]
	v_add_f32_e32 v173, 0, v172
	v_add_f32_e32 v177, v62, v63
	v_add_f32_e32 v197, v64, v65
	v_mov_b32_e32 v176, v54
	v_mov_b32_e32 v196, v55
	v_mov_b32_e32 v174, v56
	v_mov_b32_e32 v172, v57
	v_pk_add_f32 v[176:177], v[176:177], v[196:197]
	v_pk_add_f32 v[172:173], v[174:175], v[172:173]
	s_nop 0
	v_pk_add_f32 v[172:173], v[176:177], v[172:173]
	s_nop 0
	v_add_f32_e32 v172, v172, v173
	v_mov_b32_e32 v173, v172
	s_nop 1
	v_permlane16_swap_b32_e32 v173, v172
	s_waitcnt lgkmcnt(0)
	v_add_f32_e32 v172, v172, v173
	v_mov_b32_e32 v173, v172
	s_nop 1
	v_permlane32_swap_b32_e32 v173, v172
	s_waitcnt lgkmcnt(0)
	v_add_f32_e32 v172, v172, v173
	v_fmamk_f32 v174, v172, 0xbc800000, v81
	v_fmamk_f32 v176, v172, 0xbc800000, v79
	v_fmamk_f32 v173, v172, 0xbc800000, v80
	v_fmamk_f32 v175, v172, 0xbc800000, v78
	v_mul_f32_e32 v176, v176, v176
	v_mul_f32_e32 v174, v174, v174
	v_fmac_f32_e32 v176, v175, v175
	v_fmac_f32_e32 v174, v173, v173
	v_fmamk_f32 v175, v172, 0xbc800000, v77
	v_fmamk_f32 v177, v172, 0xbc800000, v75
	v_add_f32_e32 v173, v176, v174
	v_fmamk_f32 v174, v172, 0xbc800000, v76
	v_fmamk_f32 v176, v172, 0xbc800000, v74
	v_mul_f32_e32 v177, v177, v177
	v_mul_f32_e32 v175, v175, v175
	v_fmac_f32_e32 v177, v176, v176
	v_fmac_f32_e32 v175, v174, v174
	v_add_f32_e32 v174, v177, v175
	v_fmamk_f32 v175, v172, 0xbc800000, v65
	v_fmamk_f32 v177, v172, 0xbc800000, v63
	v_add_f32_e32 v173, v173, v174
	v_fmamk_f32 v174, v172, 0xbc800000, v64
	v_fmamk_f32 v176, v172, 0xbc800000, v62
	v_mul_f32_e32 v177, v177, v177
	v_mul_f32_e32 v175, v175, v175
	v_fmac_f32_e32 v177, v176, v176
	v_fmac_f32_e32 v175, v174, v174
	v_add_f32_e32 v174, v177, v175
	v_fmamk_f32 v175, v172, 0xbc800000, v57
	v_fmamk_f32 v177, v172, 0xbc800000, v55
	v_add_f32_e32 v173, v174, v173
	v_fmamk_f32 v174, v172, 0xbc800000, v56
	v_fmamk_f32 v176, v172, 0xbc800000, v54
	v_mul_f32_e32 v177, v177, v177
	v_mul_f32_e32 v175, v175, v175
	v_fmac_f32_e32 v177, v176, v176
	v_fmac_f32_e32 v175, v174, v174
	v_add_f32_e32 v174, v177, v175
	v_add_f32_e32 v173, v174, v173
	v_mov_b32_e32 v174, v173
	s_nop 1
	v_permlane16_swap_b32_e32 v174, v173
	s_waitcnt lgkmcnt(0)
	v_add_f32_e32 v173, v173, v174
	v_mov_b32_e32 v174, v173
	s_nop 1
	v_permlane32_swap_b32_e32 v174, v173
	s_and_saveexec_b64 s[4:5], vcc
	s_cbranch_execz .LBB0_1040
	s_lshl_b32 s6, s12, 11
	s_add_i32 s6, s1, s6
	v_mul_f32_e32 v172, 0x3c800000, v172
	v_lshl_add_u32 v175, v167, 5, s6
	s_waitcnt lgkmcnt(0)
	v_add_f32_e32 v173, v173, v174
	ds_write_b64 v175, v[172:173] offset:5120
.LBB0_1040:
	s_or_b64 exec, exec, s[4:5]
	v_mov_b32_e32 v172, v39
	v_mov_b32_e32 v173, v40
	s_waitcnt lgkmcnt(0)
	v_mov_b32_e32 v174, v38
	v_mov_b32_e32 v175, v41
	v_pk_add_f32 v[172:173], v[172:173], v[174:175]
	v_mov_b32_e32 v174, v35
	v_mov_b32_e32 v175, v36
	v_mov_b32_e32 v176, v34
	v_mov_b32_e32 v177, v37
	v_pk_add_f32 v[174:175], v[174:175], v[176:177]
	v_add_f32_e32 v172, v172, v173
	v_pk_add_f32 v[174:175], v[174:175], v[174:175] op_sel_hi:[0,1]
	v_add_f32_e32 v173, 0, v172
	v_add_f32_e32 v177, v22, v23
	v_add_f32_e32 v197, v24, v25
	v_mov_b32_e32 v176, v18
	v_mov_b32_e32 v196, v19
	v_mov_b32_e32 v174, v20
	v_mov_b32_e32 v172, v21
	v_pk_add_f32 v[176:177], v[176:177], v[196:197]
	v_pk_add_f32 v[172:173], v[174:175], v[172:173]
	s_nop 0
	v_pk_add_f32 v[172:173], v[176:177], v[172:173]
	s_nop 0
	v_add_f32_e32 v172, v172, v173
	v_mov_b32_e32 v173, v172
	s_nop 1
	v_permlane16_swap_b32_e32 v173, v172
	s_waitcnt lgkmcnt(0)
	v_add_f32_e32 v172, v172, v173
	v_mov_b32_e32 v173, v172
	s_nop 1
	v_permlane32_swap_b32_e32 v173, v172
	s_waitcnt lgkmcnt(0)
	v_add_f32_e32 v172, v172, v173
	v_fmamk_f32 v174, v172, 0xbc800000, v41
	v_fmamk_f32 v176, v172, 0xbc800000, v39
	v_fmamk_f32 v173, v172, 0xbc800000, v40
	v_fmamk_f32 v175, v172, 0xbc800000, v38
	v_mul_f32_e32 v176, v176, v176
	v_mul_f32_e32 v174, v174, v174
	v_fmac_f32_e32 v176, v175, v175
	v_fmac_f32_e32 v174, v173, v173
	v_fmamk_f32 v175, v172, 0xbc800000, v37
	v_fmamk_f32 v177, v172, 0xbc800000, v35
	v_add_f32_e32 v173, v176, v174
	v_fmamk_f32 v174, v172, 0xbc800000, v36
	v_fmamk_f32 v176, v172, 0xbc800000, v34
	v_mul_f32_e32 v177, v177, v177
	v_mul_f32_e32 v175, v175, v175
	v_fmac_f32_e32 v177, v176, v176
	v_fmac_f32_e32 v175, v174, v174
	v_add_f32_e32 v174, v177, v175
	v_fmamk_f32 v175, v172, 0xbc800000, v25
	v_fmamk_f32 v177, v172, 0xbc800000, v23
	v_add_f32_e32 v173, v173, v174
	v_fmamk_f32 v174, v172, 0xbc800000, v24
	v_fmamk_f32 v176, v172, 0xbc800000, v22
	v_mul_f32_e32 v177, v177, v177
	v_mul_f32_e32 v175, v175, v175
	v_fmac_f32_e32 v177, v176, v176
	v_fmac_f32_e32 v175, v174, v174
	v_add_f32_e32 v174, v177, v175
	v_fmamk_f32 v175, v172, 0xbc800000, v21
	v_fmamk_f32 v177, v172, 0xbc800000, v19
	v_add_f32_e32 v173, v174, v173
	v_fmamk_f32 v174, v172, 0xbc800000, v20
	v_fmamk_f32 v176, v172, 0xbc800000, v18
	v_mul_f32_e32 v177, v177, v177
	v_mul_f32_e32 v175, v175, v175
	v_fmac_f32_e32 v177, v176, v176
	v_fmac_f32_e32 v175, v174, v174
	v_add_f32_e32 v174, v177, v175
	v_add_f32_e32 v173, v174, v173
	v_mov_b32_e32 v170, v173
	s_nop 1
	v_permlane16_swap_b32_e32 v170, v173
	s_waitcnt lgkmcnt(0)
	v_add_f32_e32 v170, v173, v170
	v_mov_b32_e32 v171, v170
	s_nop 1
	v_permlane32_swap_b32_e32 v171, v170
	s_and_saveexec_b64 s[4:5], vcc
	s_cbranch_execz .LBB0_1042
	s_lshl_b32 s6, s12, 11
	s_add_i32 s1, s1, s6
	v_mul_f32_e32 v172, 0x3c800000, v172
	v_lshl_add_u32 v167, v167, 5, s1
	s_waitcnt lgkmcnt(0)
	v_add_f32_e32 v173, v170, v171
	ds_write_b64 v167, v[172:173] offset:5632

.LBB0_1231:
	s_lshl_b64 s[0:1], s[34:35], 2
	s_add_u32 s28, s72, s0
	s_addc_u32 s29, s73, s1
	s_add_u32 s0, s74, s88
	s_addc_u32 s1, s75, s89
	v_lshrrev_b32_e32 v130, 1, v166
	s_add_u32 s34, s0, 0x9c00000
	v_and_b32_e32 v130, 24, v130
	s_addc_u32 s35, s1, 0
	s_lshl_b32 s0, s24, 8
	v_lshl_or_b32 v130, s38, 5, v130
	v_lshl_or_b32 v131, s38, 6, v144
	s_lshl_b32 s88, s93, 8
	v_or_b32_e32 v130, s0, v130
	v_or_b32_e32 v162, s0, v131
	s_add_i32 s0, s88, s84
	v_or_b32_e32 v132, s0, v167
	v_ashrrev_i32_e32 v133, 31, v132
	v_lshlrev_b64 v[138:139], 11, v[132:133]
	v_ashrrev_i32_e32 v163, 31, v162
	v_lshl_add_u64 v[134:135], s[28:29], 0, v[138:139]
	v_lshl_add_u64 v[134:135], v[134:135], 0, v[162:163]
	s_barrier
	v_ashrrev_i32_e32 v131, 31, v130
	v_mov_b64_e32 v[248:249], v[134:135]
	v_lshl_add_u64 v[138:139], s[34:35], 0, v[138:139]
	v_lshlrev_b64 v[164:165], 1, v[130:131]
	v_lshl_add_u64 v[142:143], v[138:139], 0, v[164:165]
	v_mov_b64_e32 v[250:251], v[142:143]
	v_mov_b64_e32 v[212:213], v[248:249]
	global_load_dwordx4 v[212:215], v[212:213], off
	v_mov_b64_e32 v[216:217], v[250:251]
	global_load_dwordx4 v[216:219], v[216:217], off
	v_mov_b64_e32 v[220:221], v[250:251]
	global_load_dwordx4 v[220:223], v[220:221], off offset:256
	s_mov_b32 s98, 0x8000
	s_mov_b32 s99, 0
	v_lshl_add_u64 v[224:225], v[248:249], 0, s[98:99]
	global_load_dwordx4 v[224:227], v[224:225], off
	s_mov_b32 s98, 0x8000
	s_mov_b32 s99, 0
	v_lshl_add_u64 v[228:229], v[250:251], 0, s[98:99]
	global_load_dwordx4 v[228:231], v[228:229], off
	s_mov_b32 s98, 0x8000
	s_mov_b32 s99, 0
	v_lshl_add_u64 v[232:233], v[250:251], 0, s[98:99]
	global_load_dwordx4 v[232:235], v[232:233], off offset:256
	s_mov_b32 s98, 0x10000
	s_mov_b32 s99, 0
	v_lshl_add_u64 v[236:237], v[248:249], 0, s[98:99]
	global_load_dwordx4 v[236:239], v[236:237], off
	s_mov_b32 s98, 0x10000
	s_mov_b32 s99, 0
	v_lshl_add_u64 v[240:241], v[250:251], 0, s[98:99]
	global_load_dwordx4 v[240:243], v[240:241], off
	s_mov_b32 s98, 0x10000
	s_mov_b32 s99, 0
	v_lshl_add_u64 v[244:245], v[250:251], 0, s[98:99]
	global_load_dwordx4 v[244:247], v[244:245], off offset:256
	s_waitcnt vmcnt(0)
	v_mov_b64_e32 v[134:135], v[212:213]
	v_mov_b64_e32 v[136:137], v[214:215]
	v_mov_b64_e32 v[138:139], v[216:217]
	v_mov_b64_e32 v[140:141], v[218:219]
	s_mov_b32 s0, 0x3a000000
	v_readlane_b32 s4, v255, 27
	v_lshlrev_b64 v[130:131], 2, v[130:131]
	v_readlane_b32 s5, v255, 28
	v_and_b32_e32 v171, 64, v205
	v_xor_b32_e32 v170, 16, v205
	v_add_u32_e32 v171, 64, v171
	v_xor_b32_e32 v172, 32, v205
	v_and_b32_e32 v169, 63, v166
	s_waitcnt vmcnt(0)
	v_cvt_pk_f32_fp8_sdwa v[146:147], v134 src0_sel:WORD_1
	v_cvt_pk_f32_fp8_e32 v[144:145], v134
	v_cvt_pk_f32_fp8_e32 v[148:149], v135
	v_cvt_pk_f32_fp8_sdwa v[134:135], v135 src0_sel:WORD_1
	v_lshlrev_b32_e32 v150, 16, v138
	v_and_b32_e32 v151, 0xffff0000, v138
	v_lshlrev_b32_e32 v138, 16, v139
	v_and_b32_e32 v139, 0xffff0000, v139
	v_pk_fma_f32 v[138:139], v[146:147], s[0:1], v[138:139] op_sel_hi:[1,0,1]
	v_lshlrev_b32_e32 v146, 16, v140
	v_and_b32_e32 v147, 0xffff0000, v140
	v_lshlrev_b32_e32 v140, 16, v141
	v_and_b32_e32 v141, 0xffff0000, v141
	v_pk_fma_f32 v[134:135], v[134:135], s[0:1], v[140:141] op_sel_hi:[1,0,1]
	v_pk_fma_f32 v[8:9], v[138:139], s[86:87], v[8:9] op_sel_hi:[1,0,1]
	s_waitcnt vmcnt(0)
	v_mov_b64_e32 v[138:139], v[220:221]
	v_mov_b64_e32 v[140:141], v[222:223]
	v_pk_fma_f32 v[4:5], v[134:135], s[86:87], v[4:5] op_sel_hi:[1,0,1]
	v_cvt_pk_f32_fp8_e32 v[134:135], v136
	v_pk_fma_f32 v[146:147], v[148:149], s[0:1], v[146:147] op_sel_hi:[1,0,1]
	v_cvt_pk_f32_fp8_sdwa v[142:143], v136 src0_sel:WORD_1
	v_pk_fma_f32 v[144:145], v[144:145], s[0:1], v[150:151] op_sel_hi:[1,0,1]
	v_pk_fma_f32 v[2:3], v[146:147], s[86:87], v[2:3] op_sel_hi:[1,0,1]
	v_pk_fma_f32 v[6:7], v[144:145], s[86:87], v[6:7] op_sel_hi:[1,0,1]
	v_cvt_pk_f32_fp8_e32 v[144:145], v137
	v_cvt_pk_f32_fp8_sdwa v[136:137], v137 src0_sel:WORD_1
	s_waitcnt vmcnt(0)
	v_lshlrev_b32_e32 v146, 16, v138
	v_and_b32_e32 v147, 0xffff0000, v138
	v_pk_fma_f32 v[134:135], v[134:135], s[0:1], v[146:147] op_sel_hi:[1,0,1]
	v_lshlrev_b32_e32 v138, 16, v139
	v_and_b32_e32 v139, 0xffff0000, v139
	v_pk_fma_f32 v[18:19], v[134:135], s[86:87], v[18:19] op_sel_hi:[1,0,1]
	v_or_b32_e32 v134, 16, v132
	v_pk_fma_f32 v[138:139], v[142:143], s[0:1], v[138:139] op_sel_hi:[1,0,1]
	v_ashrrev_i32_e32 v135, 31, v134
	v_lshlrev_b32_e32 v142, 16, v140
	v_and_b32_e32 v143, 0xffff0000, v140
	v_lshlrev_b32_e32 v140, 16, v141
	v_and_b32_e32 v141, 0xffff0000, v141
	v_pk_fma_f32 v[20:21], v[138:139], s[86:87], v[20:21] op_sel_hi:[1,0,1]
	v_lshlrev_b64 v[138:139], 11, v[134:135]
	v_pk_fma_f32 v[142:143], v[144:145], s[0:1], v[142:143] op_sel_hi:[1,0,1]
	v_pk_fma_f32 v[136:137], v[136:137], s[0:1], v[140:141] op_sel_hi:[1,0,1]
	v_lshl_add_u64 v[134:135], s[28:29], 0, v[138:139]
	v_pk_fma_f32 v[16:17], v[136:137], s[86:87], v[16:17] op_sel_hi:[1,0,1]
	v_pk_fma_f32 v[14:15], v[142:143], s[86:87], v[14:15] op_sel_hi:[1,0,1]
	v_lshl_add_u64 v[134:135], v[134:135], 0, v[162:163]
	s_waitcnt vmcnt(0)
	v_mov_b64_e32 v[134:135], v[224:225]
	v_mov_b64_e32 v[136:137], v[226:227]
	v_lshl_add_u64 v[138:139], s[34:35], 0, v[138:139]
	v_lshl_add_u64 v[142:143], v[138:139], 0, v[164:165]
	s_waitcnt vmcnt(0)
	v_mov_b64_e32 v[138:139], v[228:229]
	v_mov_b64_e32 v[140:141], v[230:231]
	v_mov_b32_e32 v173, v8
	v_mov_b32_e32 v174, v6
	v_mov_b32_e32 v175, v9
	v_mov_b32_e32 v176, v2
	v_mov_b32_e32 v177, v5
	v_add_f32_e32 v197, v20, v21
	v_mov_b32_e32 v196, v15
	s_waitcnt vmcnt(1)
	v_cvt_pk_f32_fp8_sdwa v[146:147], v134 src0_sel:WORD_1
	v_cvt_pk_f32_fp8_e32 v[144:145], v134
	v_cvt_pk_f32_fp8_e32 v[148:149], v135
	v_cvt_pk_f32_fp8_sdwa v[134:135], v135 src0_sel:WORD_1
	s_waitcnt vmcnt(0)
	v_lshlrev_b32_e32 v150, 16, v138
	v_and_b32_e32 v151, 0xffff0000, v138
	v_lshlrev_b32_e32 v138, 16, v139
	v_and_b32_e32 v139, 0xffff0000, v139
	v_pk_fma_f32 v[138:139], v[146:147], s[0:1], v[138:139] op_sel_hi:[1,0,1]
	v_lshlrev_b32_e32 v146, 16, v140
	v_and_b32_e32 v147, 0xffff0000, v140
	v_lshlrev_b32_e32 v140, 16, v141
	v_and_b32_e32 v141, 0xffff0000, v141
	v_pk_fma_f32 v[134:135], v[134:135], s[0:1], v[140:141] op_sel_hi:[1,0,1]
	v_pk_fma_f32 v[40:41], v[138:139], s[86:87], v[40:41] op_sel_hi:[1,0,1]
	s_waitcnt vmcnt(0)
	v_mov_b64_e32 v[138:139], v[232:233]
	v_mov_b64_e32 v[140:141], v[234:235]
	v_pk_fma_f32 v[36:37], v[134:135], s[86:87], v[36:37] op_sel_hi:[1,0,1]
	v_cvt_pk_f32_fp8_e32 v[134:135], v136
	v_pk_fma_f32 v[146:147], v[148:149], s[0:1], v[146:147] op_sel_hi:[1,0,1]
	v_cvt_pk_f32_fp8_sdwa v[142:143], v136 src0_sel:WORD_1
	v_pk_fma_f32 v[144:145], v[144:145], s[0:1], v[150:151] op_sel_hi:[1,0,1]
	v_pk_fma_f32 v[34:35], v[146:147], s[86:87], v[34:35] op_sel_hi:[1,0,1]
	v_pk_fma_f32 v[38:39], v[144:145], s[86:87], v[38:39] op_sel_hi:[1,0,1]
	v_cvt_pk_f32_fp8_e32 v[144:145], v137
	v_cvt_pk_f32_fp8_sdwa v[136:137], v137 src0_sel:WORD_1
	s_waitcnt vmcnt(0)
	v_lshlrev_b32_e32 v146, 16, v138
	v_and_b32_e32 v147, 0xffff0000, v138
	v_pk_fma_f32 v[134:135], v[134:135], s[0:1], v[146:147] op_sel_hi:[1,0,1]
	v_lshlrev_b32_e32 v138, 16, v139
	v_and_b32_e32 v139, 0xffff0000, v139
	v_pk_fma_f32 v[46:47], v[134:135], s[86:87], v[46:47] op_sel_hi:[1,0,1]
	v_or_b32_e32 v134, 32, v132
	v_pk_fma_f32 v[138:139], v[142:143], s[0:1], v[138:139] op_sel_hi:[1,0,1]
	v_ashrrev_i32_e32 v135, 31, v134
	v_lshlrev_b32_e32 v142, 16, v140
	v_and_b32_e32 v143, 0xffff0000, v140
	v_lshlrev_b32_e32 v140, 16, v141
	v_and_b32_e32 v141, 0xffff0000, v141
	v_pk_fma_f32 v[48:49], v[138:139], s[86:87], v[48:49] op_sel_hi:[1,0,1]
	v_lshlrev_b64 v[138:139], 11, v[134:135]
	v_pk_fma_f32 v[142:143], v[144:145], s[0:1], v[142:143] op_sel_hi:[1,0,1]
	v_pk_fma_f32 v[136:137], v[136:137], s[0:1], v[140:141] op_sel_hi:[1,0,1]
	v_lshl_add_u64 v[134:135], s[28:29], 0, v[138:139]
	v_pk_fma_f32 v[44:45], v[136:137], s[86:87], v[44:45] op_sel_hi:[1,0,1]
	v_pk_fma_f32 v[42:43], v[142:143], s[86:87], v[42:43] op_sel_hi:[1,0,1]
	v_lshl_add_u64 v[134:135], v[134:135], 0, v[162:163]
	s_waitcnt vmcnt(0)
	v_mov_b64_e32 v[134:135], v[236:237]
	v_mov_b64_e32 v[136:137], v[238:239]
	v_lshl_add_u64 v[138:139], s[34:35], 0, v[138:139]
	v_lshl_add_u64 v[142:143], v[138:139], 0, v[164:165]
	s_waitcnt vmcnt(0)
	v_mov_b64_e32 v[138:139], v[240:241]
	v_mov_b64_e32 v[140:141], v[242:243]
	s_waitcnt vmcnt(1)
	v_cvt_pk_f32_fp8_sdwa v[146:147], v134 src0_sel:WORD_1
	v_cvt_pk_f32_fp8_e32 v[144:145], v134
	v_cvt_pk_f32_fp8_e32 v[148:149], v135
	v_cvt_pk_f32_fp8_sdwa v[134:135], v135 src0_sel:WORD_1
	s_waitcnt vmcnt(0)
	v_lshlrev_b32_e32 v150, 16, v138
	v_and_b32_e32 v151, 0xffff0000, v138
	v_lshlrev_b32_e32 v138, 16, v139
	v_and_b32_e32 v139, 0xffff0000, v139
	v_pk_fma_f32 v[138:139], v[146:147], s[0:1], v[138:139] op_sel_hi:[1,0,1]
	v_lshlrev_b32_e32 v146, 16, v140
	v_and_b32_e32 v147, 0xffff0000, v140
	v_lshlrev_b32_e32 v140, 16, v141
	v_and_b32_e32 v141, 0xffff0000, v141
	v_pk_fma_f32 v[134:135], v[134:135], s[0:1], v[140:141] op_sel_hi:[1,0,1]
	v_pk_fma_f32 v[64:65], v[138:139], s[86:87], v[64:65] op_sel_hi:[1,0,1]
	s_waitcnt vmcnt(0)
	v_mov_b64_e32 v[138:139], v[244:245]
	v_mov_b64_e32 v[140:141], v[246:247]
	s_mov_b32 s98, 0x18000
	s_mov_b32 s99, 0
	v_lshl_add_u64 v[212:213], v[248:249], 0, s[98:99]
	global_load_dwordx4 v[212:215], v[212:213], off
	s_mov_b32 s98, 0x18000
	s_mov_b32 s99, 0
	v_lshl_add_u64 v[216:217], v[250:251], 0, s[98:99]
	global_load_dwordx4 v[216:219], v[216:217], off
	s_mov_b32 s98, 0x18000
	s_mov_b32 s99, 0
	v_lshl_add_u64 v[220:221], v[250:251], 0, s[98:99]
	global_load_dwordx4 v[220:223], v[220:221], off offset:256
	s_mov_b32 s98, 0x40000
	s_mov_b32 s99, 0
	v_lshl_add_u64 v[224:225], v[248:249], 0, s[98:99]
	global_load_dwordx4 v[224:227], v[224:225], off
	s_mov_b32 s98, 0x40000
	s_mov_b32 s99, 0
	v_lshl_add_u64 v[228:229], v[250:251], 0, s[98:99]
	global_load_dwordx4 v[228:231], v[228:229], off
	s_mov_b32 s98, 0x40000
	s_mov_b32 s99, 0
	v_lshl_add_u64 v[232:233], v[250:251], 0, s[98:99]
	global_load_dwordx4 v[232:235], v[232:233], off offset:256
	s_mov_b32 s98, 0x48000
	s_mov_b32 s99, 0
	v_lshl_add_u64 v[236:237], v[248:249], 0, s[98:99]
	global_load_dwordx4 v[236:239], v[236:237], off
	s_mov_b32 s98, 0x48000
	s_mov_b32 s99, 0
	v_lshl_add_u64 v[240:241], v[250:251], 0, s[98:99]
	global_load_dwordx4 v[240:243], v[240:241], off
	s_mov_b32 s98, 0x48000
	s_mov_b32 s99, 0
	v_lshl_add_u64 v[244:245], v[250:251], 0, s[98:99]
	global_load_dwordx4 v[244:247], v[244:245], off offset:256
	v_pk_fma_f32 v[60:61], v[134:135], s[86:87], v[60:61] op_sel_hi:[1,0,1]
	v_cvt_pk_f32_fp8_e32 v[134:135], v136
	v_pk_fma_f32 v[146:147], v[148:149], s[0:1], v[146:147] op_sel_hi:[1,0,1]
	v_cvt_pk_f32_fp8_sdwa v[142:143], v136 src0_sel:WORD_1
	v_pk_fma_f32 v[144:145], v[144:145], s[0:1], v[150:151] op_sel_hi:[1,0,1]
	v_pk_fma_f32 v[58:59], v[146:147], s[86:87], v[58:59] op_sel_hi:[1,0,1]
	v_pk_fma_f32 v[62:63], v[144:145], s[86:87], v[62:63] op_sel_hi:[1,0,1]
	v_cvt_pk_f32_fp8_e32 v[144:145], v137
	v_cvt_pk_f32_fp8_sdwa v[136:137], v137 src0_sel:WORD_1
	s_waitcnt vmcnt(0)
	v_lshlrev_b32_e32 v146, 16, v138
	v_and_b32_e32 v147, 0xffff0000, v138
	v_pk_fma_f32 v[134:135], v[134:135], s[0:1], v[146:147] op_sel_hi:[1,0,1]
	v_lshlrev_b32_e32 v138, 16, v139
	v_and_b32_e32 v139, 0xffff0000, v139
	v_pk_fma_f32 v[70:71], v[134:135], s[86:87], v[70:71] op_sel_hi:[1,0,1]
	v_or_b32_e32 v134, 48, v132
	v_pk_fma_f32 v[138:139], v[142:143], s[0:1], v[138:139] op_sel_hi:[1,0,1]
	v_ashrrev_i32_e32 v135, 31, v134
	v_lshlrev_b32_e32 v142, 16, v140
	v_and_b32_e32 v143, 0xffff0000, v140
	v_lshlrev_b32_e32 v140, 16, v141
	v_and_b32_e32 v141, 0xffff0000, v141
	v_pk_fma_f32 v[72:73], v[138:139], s[86:87], v[72:73] op_sel_hi:[1,0,1]
	v_lshlrev_b64 v[138:139], 11, v[134:135]
	v_pk_fma_f32 v[142:143], v[144:145], s[0:1], v[142:143] op_sel_hi:[1,0,1]
	v_pk_fma_f32 v[136:137], v[136:137], s[0:1], v[140:141] op_sel_hi:[1,0,1]
	v_lshl_add_u64 v[134:135], s[28:29], 0, v[138:139]
	v_pk_fma_f32 v[68:69], v[136:137], s[86:87], v[68:69] op_sel_hi:[1,0,1]
	v_pk_fma_f32 v[66:67], v[142:143], s[86:87], v[66:67] op_sel_hi:[1,0,1]
	v_lshl_add_u64 v[134:135], v[134:135], 0, v[162:163]
	s_waitcnt vmcnt(0)
	v_mov_b64_e32 v[134:135], v[212:213]
	v_mov_b64_e32 v[136:137], v[214:215]
	v_lshl_add_u64 v[138:139], s[34:35], 0, v[138:139]
	v_lshl_add_u64 v[142:143], v[138:139], 0, v[164:165]
	s_waitcnt vmcnt(0)
	v_mov_b64_e32 v[138:139], v[216:217]
	v_mov_b64_e32 v[140:141], v[218:219]
	s_waitcnt vmcnt(1)
	v_cvt_pk_f32_fp8_sdwa v[146:147], v134 src0_sel:WORD_1
	v_cvt_pk_f32_fp8_e32 v[144:145], v134
	v_cvt_pk_f32_fp8_e32 v[148:149], v135
	v_cvt_pk_f32_fp8_sdwa v[134:135], v135 src0_sel:WORD_1
	s_waitcnt vmcnt(0)
	v_lshlrev_b32_e32 v150, 16, v138
	v_and_b32_e32 v151, 0xffff0000, v138
	v_lshlrev_b32_e32 v138, 16, v139
	v_and_b32_e32 v139, 0xffff0000, v139
	v_pk_fma_f32 v[138:139], v[146:147], s[0:1], v[138:139] op_sel_hi:[1,0,1]
	v_lshlrev_b32_e32 v146, 16, v140
	v_and_b32_e32 v147, 0xffff0000, v140
	v_lshlrev_b32_e32 v140, 16, v141
	v_and_b32_e32 v141, 0xffff0000, v141
	v_pk_fma_f32 v[134:135], v[134:135], s[0:1], v[140:141] op_sel_hi:[1,0,1]
	v_pk_fma_f32 v[88:89], v[138:139], s[86:87], v[88:89] op_sel_hi:[1,0,1]
	s_waitcnt vmcnt(0)
	v_mov_b64_e32 v[138:139], v[220:221]
	v_mov_b64_e32 v[140:141], v[222:223]
	v_pk_fma_f32 v[84:85], v[134:135], s[86:87], v[84:85] op_sel_hi:[1,0,1]
	v_cvt_pk_f32_fp8_e32 v[134:135], v136
	v_pk_fma_f32 v[146:147], v[148:149], s[0:1], v[146:147] op_sel_hi:[1,0,1]
	v_cvt_pk_f32_fp8_sdwa v[142:143], v136 src0_sel:WORD_1
	v_pk_fma_f32 v[144:145], v[144:145], s[0:1], v[150:151] op_sel_hi:[1,0,1]
	v_pk_fma_f32 v[82:83], v[146:147], s[86:87], v[82:83] op_sel_hi:[1,0,1]
	v_pk_fma_f32 v[86:87], v[144:145], s[86:87], v[86:87] op_sel_hi:[1,0,1]
	v_cvt_pk_f32_fp8_e32 v[144:145], v137
	v_cvt_pk_f32_fp8_sdwa v[136:137], v137 src0_sel:WORD_1
	s_waitcnt vmcnt(0)
	v_lshlrev_b32_e32 v146, 16, v138
	v_and_b32_e32 v147, 0xffff0000, v138
	v_pk_fma_f32 v[134:135], v[134:135], s[0:1], v[146:147] op_sel_hi:[1,0,1]
	v_lshlrev_b32_e32 v138, 16, v139
	v_and_b32_e32 v139, 0xffff0000, v139
	v_pk_fma_f32 v[94:95], v[134:135], s[86:87], v[94:95] op_sel_hi:[1,0,1]
	v_add_u32_e32 v134, 0x80, v132
	v_pk_fma_f32 v[138:139], v[142:143], s[0:1], v[138:139] op_sel_hi:[1,0,1]
	v_ashrrev_i32_e32 v135, 31, v134
	v_lshlrev_b32_e32 v142, 16, v140
	v_and_b32_e32 v143, 0xffff0000, v140
	v_lshlrev_b32_e32 v140, 16, v141
	v_and_b32_e32 v141, 0xffff0000, v141
	v_pk_fma_f32 v[96:97], v[138:139], s[86:87], v[96:97] op_sel_hi:[1,0,1]
	v_lshlrev_b64 v[138:139], 11, v[134:135]
	v_pk_fma_f32 v[142:143], v[144:145], s[0:1], v[142:143] op_sel_hi:[1,0,1]
	v_pk_fma_f32 v[136:137], v[136:137], s[0:1], v[140:141] op_sel_hi:[1,0,1]
	v_lshl_add_u64 v[134:135], s[28:29], 0, v[138:139]
	v_pk_fma_f32 v[92:93], v[136:137], s[86:87], v[92:93] op_sel_hi:[1,0,1]
	v_pk_fma_f32 v[90:91], v[142:143], s[86:87], v[90:91] op_sel_hi:[1,0,1]
	v_lshl_add_u64 v[134:135], v[134:135], 0, v[162:163]
	s_waitcnt vmcnt(0)
	v_mov_b64_e32 v[134:135], v[224:225]
	v_mov_b64_e32 v[136:137], v[226:227]
	v_lshl_add_u64 v[138:139], s[34:35], 0, v[138:139]
	v_lshl_add_u64 v[142:143], v[138:139], 0, v[164:165]
	s_waitcnt vmcnt(0)
	v_mov_b64_e32 v[138:139], v[228:229]
	v_mov_b64_e32 v[140:141], v[230:231]
	s_waitcnt vmcnt(1)
	v_cvt_pk_f32_fp8_sdwa v[146:147], v134 src0_sel:WORD_1
	v_cvt_pk_f32_fp8_e32 v[144:145], v134
	v_cvt_pk_f32_fp8_e32 v[148:149], v135
	v_cvt_pk_f32_fp8_sdwa v[134:135], v135 src0_sel:WORD_1
	s_waitcnt vmcnt(0)
	v_lshlrev_b32_e32 v150, 16, v138
	v_and_b32_e32 v151, 0xffff0000, v138
	v_lshlrev_b32_e32 v138, 16, v139
	v_and_b32_e32 v139, 0xffff0000, v139
	v_pk_fma_f32 v[138:139], v[146:147], s[0:1], v[138:139] op_sel_hi:[1,0,1]
	v_lshlrev_b32_e32 v146, 16, v140
	v_and_b32_e32 v147, 0xffff0000, v140
	v_lshlrev_b32_e32 v140, 16, v141
	v_and_b32_e32 v141, 0xffff0000, v141
	v_pk_fma_f32 v[134:135], v[134:135], s[0:1], v[140:141] op_sel_hi:[1,0,1]
	v_pk_fma_f32 v[112:113], v[138:139], s[86:87], v[112:113] op_sel_hi:[1,0,1]
	s_waitcnt vmcnt(0)
	v_mov_b64_e32 v[138:139], v[232:233]
	v_mov_b64_e32 v[140:141], v[234:235]
	v_pk_fma_f32 v[108:109], v[134:135], s[86:87], v[108:109] op_sel_hi:[1,0,1]
	v_cvt_pk_f32_fp8_e32 v[134:135], v136
	v_pk_fma_f32 v[146:147], v[148:149], s[0:1], v[146:147] op_sel_hi:[1,0,1]
	v_cvt_pk_f32_fp8_sdwa v[142:143], v136 src0_sel:WORD_1
	v_pk_fma_f32 v[144:145], v[144:145], s[0:1], v[150:151] op_sel_hi:[1,0,1]
	v_pk_fma_f32 v[106:107], v[146:147], s[86:87], v[106:107] op_sel_hi:[1,0,1]
	v_pk_fma_f32 v[110:111], v[144:145], s[86:87], v[110:111] op_sel_hi:[1,0,1]
	v_cvt_pk_f32_fp8_e32 v[144:145], v137
	v_cvt_pk_f32_fp8_sdwa v[136:137], v137 src0_sel:WORD_1
	s_waitcnt vmcnt(0)
	v_lshlrev_b32_e32 v146, 16, v138
	v_and_b32_e32 v147, 0xffff0000, v138
	v_pk_fma_f32 v[134:135], v[134:135], s[0:1], v[146:147] op_sel_hi:[1,0,1]
	v_lshlrev_b32_e32 v138, 16, v139
	v_and_b32_e32 v139, 0xffff0000, v139
	v_pk_fma_f32 v[122:123], v[134:135], s[86:87], v[122:123] op_sel_hi:[1,0,1]
	v_add_u32_e32 v134, 0x90, v132
	v_pk_fma_f32 v[138:139], v[142:143], s[0:1], v[138:139] op_sel_hi:[1,0,1]
	v_ashrrev_i32_e32 v135, 31, v134
	v_lshlrev_b32_e32 v142, 16, v140
	v_and_b32_e32 v143, 0xffff0000, v140
	v_lshlrev_b32_e32 v140, 16, v141
	v_and_b32_e32 v141, 0xffff0000, v141
	v_pk_fma_f32 v[124:125], v[138:139], s[86:87], v[124:125] op_sel_hi:[1,0,1]
	v_lshlrev_b64 v[138:139], 11, v[134:135]
	v_pk_fma_f32 v[142:143], v[144:145], s[0:1], v[142:143] op_sel_hi:[1,0,1]
	v_pk_fma_f32 v[136:137], v[136:137], s[0:1], v[140:141] op_sel_hi:[1,0,1]
	v_lshl_add_u64 v[134:135], s[28:29], 0, v[138:139]
	v_pk_fma_f32 v[116:117], v[136:137], s[86:87], v[116:117] op_sel_hi:[1,0,1]
	v_pk_fma_f32 v[114:115], v[142:143], s[86:87], v[114:115] op_sel_hi:[1,0,1]
	v_lshl_add_u64 v[134:135], v[134:135], 0, v[162:163]
	s_waitcnt vmcnt(0)
	v_mov_b64_e32 v[134:135], v[236:237]
	v_mov_b64_e32 v[136:137], v[238:239]
	v_lshl_add_u64 v[138:139], s[34:35], 0, v[138:139]
	v_lshl_add_u64 v[142:143], v[138:139], 0, v[164:165]
	s_waitcnt vmcnt(0)
	v_mov_b64_e32 v[138:139], v[240:241]
	v_mov_b64_e32 v[140:141], v[242:243]
	s_waitcnt vmcnt(1)
	v_cvt_pk_f32_fp8_sdwa v[146:147], v134 src0_sel:WORD_1
	v_cvt_pk_f32_fp8_e32 v[144:145], v134
	v_cvt_pk_f32_fp8_e32 v[148:149], v135
	v_cvt_pk_f32_fp8_sdwa v[134:135], v135 src0_sel:WORD_1
	s_waitcnt vmcnt(0)
	v_lshlrev_b32_e32 v150, 16, v138
	v_and_b32_e32 v151, 0xffff0000, v138
	v_lshlrev_b32_e32 v138, 16, v139
	v_and_b32_e32 v139, 0xffff0000, v139
	v_pk_fma_f32 v[138:139], v[146:147], s[0:1], v[138:139] op_sel_hi:[1,0,1]
	v_lshlrev_b32_e32 v146, 16, v140
	v_and_b32_e32 v147, 0xffff0000, v140
	v_lshlrev_b32_e32 v140, 16, v141
	v_and_b32_e32 v141, 0xffff0000, v141
	v_pk_fma_f32 v[134:135], v[134:135], s[0:1], v[140:141] op_sel_hi:[1,0,1]
	v_pk_fma_f32 v[128:129], v[138:139], s[86:87], v[128:129] op_sel_hi:[1,0,1]
	s_waitcnt vmcnt(0)
	v_mov_b64_e32 v[138:139], v[244:245]
	v_mov_b64_e32 v[140:141], v[246:247]
	s_mov_b32 s98, 0x50000
	s_mov_b32 s99, 0
	v_lshl_add_u64 v[212:213], v[248:249], 0, s[98:99]
	global_load_dwordx4 v[212:215], v[212:213], off
	s_mov_b32 s98, 0x50000
	s_mov_b32 s99, 0
	v_lshl_add_u64 v[216:217], v[250:251], 0, s[98:99]
	global_load_dwordx4 v[216:219], v[216:217], off
	s_mov_b32 s98, 0x50000
	s_mov_b32 s99, 0
	v_lshl_add_u64 v[220:221], v[250:251], 0, s[98:99]
	global_load_dwordx4 v[220:223], v[220:221], off offset:256
	s_mov_b32 s98, 0x58000
	s_mov_b32 s99, 0
	v_lshl_add_u64 v[224:225], v[248:249], 0, s[98:99]
	global_load_dwordx4 v[224:227], v[224:225], off
	s_mov_b32 s98, 0x58000
	s_mov_b32 s99, 0
	v_lshl_add_u64 v[228:229], v[250:251], 0, s[98:99]
	global_load_dwordx4 v[228:231], v[228:229], off
	s_mov_b32 s98, 0x58000
	s_mov_b32 s99, 0
	v_lshl_add_u64 v[232:233], v[250:251], 0, s[98:99]
	global_load_dwordx4 v[232:235], v[232:233], off offset:256
	v_pk_fma_f32 v[120:121], v[134:135], s[86:87], v[120:121] op_sel_hi:[1,0,1]
	v_cvt_pk_f32_fp8_e32 v[134:135], v136
	v_pk_fma_f32 v[146:147], v[148:149], s[0:1], v[146:147] op_sel_hi:[1,0,1]
	v_cvt_pk_f32_fp8_sdwa v[142:143], v136 src0_sel:WORD_1
	v_pk_fma_f32 v[144:145], v[144:145], s[0:1], v[150:151] op_sel_hi:[1,0,1]
	v_pk_fma_f32 v[118:119], v[146:147], s[86:87], v[118:119] op_sel_hi:[1,0,1]
	v_pk_fma_f32 v[126:127], v[144:145], s[86:87], v[126:127] op_sel_hi:[1,0,1]
	v_cvt_pk_f32_fp8_e32 v[144:145], v137
	v_cvt_pk_f32_fp8_sdwa v[136:137], v137 src0_sel:WORD_1
	s_waitcnt vmcnt(0)
	v_lshlrev_b32_e32 v146, 16, v138
	v_and_b32_e32 v147, 0xffff0000, v138
	v_pk_fma_f32 v[134:135], v[134:135], s[0:1], v[146:147] op_sel_hi:[1,0,1]
	v_lshlrev_b32_e32 v138, 16, v139
	v_and_b32_e32 v139, 0xffff0000, v139
	v_pk_fma_f32 v[102:103], v[134:135], s[86:87], v[102:103] op_sel_hi:[1,0,1]
	v_add_u32_e32 v134, 0xa0, v132
	v_pk_fma_f32 v[138:139], v[142:143], s[0:1], v[138:139] op_sel_hi:[1,0,1]
	v_ashrrev_i32_e32 v135, 31, v134
	v_lshlrev_b32_e32 v142, 16, v140
	v_and_b32_e32 v143, 0xffff0000, v140
	v_lshlrev_b32_e32 v140, 16, v141
	v_and_b32_e32 v141, 0xffff0000, v141
	v_pk_fma_f32 v[104:105], v[138:139], s[86:87], v[104:105] op_sel_hi:[1,0,1]
	v_lshlrev_b64 v[138:139], 11, v[134:135]
	v_pk_fma_f32 v[142:143], v[144:145], s[0:1], v[142:143] op_sel_hi:[1,0,1]
	v_pk_fma_f32 v[136:137], v[136:137], s[0:1], v[140:141] op_sel_hi:[1,0,1]
	v_lshl_add_u64 v[134:135], s[28:29], 0, v[138:139]
	v_pk_fma_f32 v[100:101], v[136:137], s[86:87], v[100:101] op_sel_hi:[1,0,1]
	v_pk_fma_f32 v[98:99], v[142:143], s[86:87], v[98:99] op_sel_hi:[1,0,1]
	v_lshl_add_u64 v[134:135], v[134:135], 0, v[162:163]
	s_waitcnt vmcnt(0)
	v_mov_b64_e32 v[134:135], v[212:213]
	v_mov_b64_e32 v[136:137], v[214:215]
	v_lshl_add_u64 v[138:139], s[34:35], 0, v[138:139]
	v_lshl_add_u64 v[142:143], v[138:139], 0, v[164:165]
	s_waitcnt vmcnt(0)
	v_mov_b64_e32 v[138:139], v[216:217]
	v_mov_b64_e32 v[140:141], v[218:219]
	v_add_u32_e32 v132, 0xb0, v132
	v_ashrrev_i32_e32 v133, 31, v132
	s_waitcnt vmcnt(1)
	v_cvt_pk_f32_fp8_sdwa v[146:147], v134 src0_sel:WORD_1
	v_cvt_pk_f32_fp8_e32 v[144:145], v134
	v_cvt_pk_f32_fp8_e32 v[148:149], v135
	v_cvt_pk_f32_fp8_sdwa v[134:135], v135 src0_sel:WORD_1
	s_waitcnt vmcnt(0)
	v_lshlrev_b32_e32 v150, 16, v138
	v_and_b32_e32 v151, 0xffff0000, v138
	v_lshlrev_b32_e32 v138, 16, v139
	v_and_b32_e32 v139, 0xffff0000, v139
	v_pk_fma_f32 v[138:139], v[146:147], s[0:1], v[138:139] op_sel_hi:[1,0,1]
	v_lshlrev_b32_e32 v146, 16, v140
	v_and_b32_e32 v147, 0xffff0000, v140
	v_lshlrev_b32_e32 v140, 16, v141
	v_and_b32_e32 v141, 0xffff0000, v141
	v_pk_fma_f32 v[134:135], v[134:135], s[0:1], v[140:141] op_sel_hi:[1,0,1]
	v_pk_fma_f32 v[80:81], v[138:139], s[86:87], v[80:81] op_sel_hi:[1,0,1]
	s_waitcnt vmcnt(0)
	v_mov_b64_e32 v[138:139], v[220:221]
	v_mov_b64_e32 v[140:141], v[222:223]
	v_pk_fma_f32 v[144:145], v[144:145], s[0:1], v[150:151] op_sel_hi:[1,0,1]
	v_cvt_pk_f32_fp8_sdwa v[142:143], v136 src0_sel:WORD_1
	v_pk_fma_f32 v[78:79], v[144:145], s[86:87], v[78:79] op_sel_hi:[1,0,1]
	v_pk_fma_f32 v[76:77], v[134:135], s[86:87], v[76:77] op_sel_hi:[1,0,1]
	v_cvt_pk_f32_fp8_e32 v[134:135], v136
	v_cvt_pk_f32_fp8_e32 v[144:145], v137
	v_cvt_pk_f32_fp8_sdwa v[136:137], v137 src0_sel:WORD_1
	v_pk_fma_f32 v[146:147], v[148:149], s[0:1], v[146:147] op_sel_hi:[1,0,1]
	s_nop 0
	v_pk_fma_f32 v[74:75], v[146:147], s[86:87], v[74:75] op_sel_hi:[1,0,1]
	s_waitcnt vmcnt(0)
	v_lshlrev_b32_e32 v146, 16, v138
	v_and_b32_e32 v147, 0xffff0000, v138
	v_lshlrev_b32_e32 v138, 16, v139
	v_and_b32_e32 v139, 0xffff0000, v139
	v_pk_fma_f32 v[138:139], v[142:143], s[0:1], v[138:139] op_sel_hi:[1,0,1]
	v_lshlrev_b32_e32 v142, 16, v140
	v_and_b32_e32 v143, 0xffff0000, v140
	v_lshlrev_b32_e32 v140, 16, v141
	v_and_b32_e32 v141, 0xffff0000, v141
	v_pk_fma_f32 v[136:137], v[136:137], s[0:1], v[140:141] op_sel_hi:[1,0,1]
	v_pk_fma_f32 v[134:135], v[134:135], s[0:1], v[146:147] op_sel_hi:[1,0,1]
	v_pk_fma_f32 v[52:53], v[136:137], s[86:87], v[52:53] op_sel_hi:[1,0,1]
	v_lshlrev_b64 v[136:137], 11, v[132:133]
	v_pk_fma_f32 v[142:143], v[144:145], s[0:1], v[142:143] op_sel_hi:[1,0,1]
	v_lshl_add_u64 v[132:133], s[28:29], 0, v[136:137]
	v_pk_fma_f32 v[56:57], v[138:139], s[86:87], v[56:57] op_sel_hi:[1,0,1]
	v_pk_fma_f32 v[54:55], v[134:135], s[86:87], v[54:55] op_sel_hi:[1,0,1]
	v_pk_fma_f32 v[50:51], v[142:143], s[86:87], v[50:51] op_sel_hi:[1,0,1]
	v_lshl_add_u64 v[132:133], v[132:133], 0, v[162:163]
	s_waitcnt vmcnt(0)
	v_mov_b64_e32 v[132:133], v[224:225]
	v_mov_b64_e32 v[134:135], v[226:227]
	v_lshl_add_u64 v[136:137], s[34:35], 0, v[136:137]
	v_lshl_add_u64 v[140:141], v[136:137], 0, v[164:165]
	s_waitcnt vmcnt(0)
	v_mov_b64_e32 v[136:137], v[228:229]
	v_mov_b64_e32 v[138:139], v[230:231]
	s_waitcnt vmcnt(1)
	v_cvt_pk_f32_fp8_sdwa v[144:145], v132 src0_sel:WORD_1
	v_cvt_pk_f32_fp8_e32 v[142:143], v132
	v_cvt_pk_f32_fp8_e32 v[146:147], v133
	v_cvt_pk_f32_fp8_sdwa v[132:133], v133 src0_sel:WORD_1
	s_waitcnt vmcnt(0)
	v_lshlrev_b32_e32 v148, 16, v136
	v_and_b32_e32 v149, 0xffff0000, v136
	v_lshlrev_b32_e32 v136, 16, v137
	v_and_b32_e32 v137, 0xffff0000, v137
	v_pk_fma_f32 v[136:137], v[144:145], s[0:1], v[136:137] op_sel_hi:[1,0,1]
	v_lshlrev_b32_e32 v144, 16, v138
	v_and_b32_e32 v145, 0xffff0000, v138
	v_lshlrev_b32_e32 v138, 16, v139
	v_and_b32_e32 v139, 0xffff0000, v139
	v_pk_fma_f32 v[132:133], v[132:133], s[0:1], v[138:139] op_sel_hi:[1,0,1]
	v_pk_fma_f32 v[32:33], v[136:137], s[86:87], v[32:33] op_sel_hi:[1,0,1]
	s_waitcnt vmcnt(0)
	v_mov_b64_e32 v[136:137], v[232:233]
	v_mov_b64_e32 v[138:139], v[234:235]
	v_pk_fma_f32 v[142:143], v[142:143], s[0:1], v[148:149] op_sel_hi:[1,0,1]
	v_cvt_pk_f32_fp8_sdwa v[140:141], v134 src0_sel:WORD_1
	v_pk_fma_f32 v[30:31], v[142:143], s[86:87], v[30:31] op_sel_hi:[1,0,1]
	v_pk_fma_f32 v[28:29], v[132:133], s[86:87], v[28:29] op_sel_hi:[1,0,1]
	v_cvt_pk_f32_fp8_e32 v[132:133], v134
	v_cvt_pk_f32_fp8_e32 v[142:143], v135
	v_cvt_pk_f32_fp8_sdwa v[134:135], v135 src0_sel:WORD_1
	v_pk_fma_f32 v[144:145], v[146:147], s[0:1], v[144:145] op_sel_hi:[1,0,1]
	s_nop 0
	v_pk_fma_f32 v[26:27], v[144:145], s[86:87], v[26:27] op_sel_hi:[1,0,1]
	s_waitcnt vmcnt(0)
	v_lshlrev_b32_e32 v144, 16, v136
	v_and_b32_e32 v145, 0xffff0000, v136
	v_lshlrev_b32_e32 v136, 16, v137
	v_and_b32_e32 v137, 0xffff0000, v137
	v_pk_fma_f32 v[136:137], v[140:141], s[0:1], v[136:137] op_sel_hi:[1,0,1]
	v_lshlrev_b32_e32 v140, 16, v138
	v_and_b32_e32 v141, 0xffff0000, v138
	v_lshlrev_b32_e32 v138, 16, v139
	v_and_b32_e32 v139, 0xffff0000, v139
	v_pk_fma_f32 v[132:133], v[132:133], s[0:1], v[144:145] op_sel_hi:[1,0,1]
	v_pk_fma_f32 v[140:141], v[142:143], s[0:1], v[140:141] op_sel_hi:[1,0,1]
	v_pk_fma_f32 v[134:135], v[134:135], s[0:1], v[138:139] op_sel_hi:[1,0,1]
	v_readlane_b32 s0, v255, 18
	v_readlane_b32 s1, v255, 19
	v_pk_fma_f32 v[22:23], v[132:133], s[86:87], v[22:23] op_sel_hi:[1,0,1]
	v_pk_fma_f32 v[12:13], v[134:135], s[86:87], v[12:13] op_sel_hi:[1,0,1]
	v_lshl_add_u64 v[132:133], s[0:1], 0, v[130:131]
	s_mov_b64 s[0:1], 0x2000
	v_lshl_add_u64 v[130:131], s[4:5], 0, v[130:131]
	v_lshl_add_u64 v[134:135], v[132:133], 0, s[0:1]
	v_lshl_add_u64 v[142:143], v[130:131], 0, s[0:1]
	s_movk_i32 s0, 0x2000
	v_add_co_u32_e32 v132, vcc, s0, v132
	v_pk_fma_f32 v[24:25], v[136:137], s[86:87], v[24:25] op_sel_hi:[1,0,1]
	s_nop 0
	v_addc_co_u32_e32 v133, vcc, 0, v133, vcc
	v_add_co_u32_e32 v130, vcc, s0, v130
	v_pk_fma_f32 v[10:11], v[140:141], s[86:87], v[10:11] op_sel_hi:[1,0,1]
	s_nop 0
	v_addc_co_u32_e32 v131, vcc, 0, v131, vcc
	global_load_dwordx4 v[154:157], v[132:133], off
	global_load_dwordx4 v[146:149], v[134:135], off offset:16
	global_load_dwordx4 v[158:161], v[130:131], off
	global_load_dwordx4 v[150:153], v[142:143], off offset:16
	s_nop 0
	global_load_dwordx4 v[130:133], v[134:135], off offset:528
	global_load_dwordx4 v[138:141], v[134:135], off offset:512
	s_nop 0
	global_load_dwordx4 v[134:137], v[142:143], off offset:528
	s_nop 0
	global_load_dwordx4 v[142:145], v[142:143], off offset:512
	v_cmp_lt_i32_e32 vcc, v170, v171
	s_lshl_b32 s0, s38, 3
	s_add_i32 s4, s0, 0
	v_cndmask_b32_e32 v170, v205, v170, vcc
	v_cmp_lt_i32_e32 vcc, v172, v171
	v_lshlrev_b32_e32 v170, 2, v170
	s_nop 0
	v_cndmask_b32_e32 v171, v205, v172, vcc
	v_mov_b32_e32 v172, v7
	v_pk_add_f32 v[172:173], v[172:173], v[174:175]
	v_mov_b32_e32 v174, v3
	v_mov_b32_e32 v175, v4
	v_pk_add_f32 v[174:175], v[174:175], v[176:177]
	v_add_f32_e32 v172, v172, v173
	v_pk_add_f32 v[174:175], v[174:175], v[174:175] op_sel_hi:[0,1]
	v_add_f32_e32 v173, 0, v172
	v_add_f32_e32 v177, v18, v19
	v_mov_b32_e32 v176, v14
	v_mov_b32_e32 v174, v16
	v_mov_b32_e32 v172, v17
	v_pk_add_f32 v[176:177], v[176:177], v[196:197]
	v_pk_add_f32 v[172:173], v[174:175], v[172:173]
	v_lshlrev_b32_e32 v171, 2, v171
	v_pk_add_f32 v[172:173], v[176:177], v[172:173]
	v_cmp_gt_u32_e32 vcc, 16, v169
	v_add_f32_e32 v172, v172, v173
	v_mov_b32_e32 v173, v172
	s_nop 1
	v_permlane16_swap_b32_e32 v173, v172
	s_waitcnt lgkmcnt(0)
	v_add_f32_e32 v172, v172, v173
	v_mov_b32_e32 v173, v172
	s_nop 1
	v_permlane32_swap_b32_e32 v173, v172
	s_waitcnt lgkmcnt(0)
	v_add_f32_e32 v172, v172, v173
	v_fmamk_f32 v174, v172, 0xbc800000, v9
	v_fmamk_f32 v176, v172, 0xbc800000, v7
	v_fmamk_f32 v173, v172, 0xbc800000, v8
	v_fmamk_f32 v175, v172, 0xbc800000, v6
	v_mul_f32_e32 v176, v176, v176
	v_mul_f32_e32 v174, v174, v174
	v_fmac_f32_e32 v176, v175, v175
	v_fmac_f32_e32 v174, v173, v173
	v_fmamk_f32 v175, v172, 0xbc800000, v5
	v_fmamk_f32 v177, v172, 0xbc800000, v3
	v_add_f32_e32 v173, v176, v174
	v_fmamk_f32 v174, v172, 0xbc800000, v4
	v_fmamk_f32 v176, v172, 0xbc800000, v2
	v_mul_f32_e32 v177, v177, v177
	v_mul_f32_e32 v175, v175, v175
	v_fmac_f32_e32 v177, v176, v176
	v_fmac_f32_e32 v175, v174, v174
	v_add_f32_e32 v174, v177, v175
	v_fmamk_f32 v175, v172, 0xbc800000, v21
	v_fmamk_f32 v177, v172, 0xbc800000, v19
	v_add_f32_e32 v173, v173, v174
	v_fmamk_f32 v174, v172, 0xbc800000, v20
	v_fmamk_f32 v176, v172, 0xbc800000, v18
	v_mul_f32_e32 v177, v177, v177
	v_mul_f32_e32 v175, v175, v175
	v_fmac_f32_e32 v177, v176, v176
	v_fmac_f32_e32 v175, v174, v174
	v_add_f32_e32 v174, v177, v175
	v_fmamk_f32 v175, v172, 0xbc800000, v17
	v_fmamk_f32 v177, v172, 0xbc800000, v15
	v_add_f32_e32 v173, v174, v173
	v_fmamk_f32 v174, v172, 0xbc800000, v16
	v_fmamk_f32 v176, v172, 0xbc800000, v14
	v_mul_f32_e32 v177, v177, v177
	v_mul_f32_e32 v175, v175, v175
	v_fmac_f32_e32 v177, v176, v176
	v_fmac_f32_e32 v175, v174, v174
	v_add_f32_e32 v174, v177, v175
	v_add_f32_e32 v173, v174, v173
	v_mov_b32_e32 v174, v173
	s_nop 1
	v_permlane16_swap_b32_e32 v174, v173
	s_waitcnt lgkmcnt(0)
	v_add_f32_e32 v173, v173, v174
	v_mov_b32_e32 v174, v173
	s_nop 1
	v_permlane32_swap_b32_e32 v174, v173
	s_and_saveexec_b64 s[0:1], vcc
	s_mov_b64 s[38:39], s[62:63]
	s_cbranch_execz .LBB0_1233
	s_lshl_b32 s5, s82, 11
	s_add_i32 s5, s4, s5
	v_mul_f32_e32 v172, 0x3c800000, v172
	v_lshl_add_u32 v175, v167, 5, s5
	s_waitcnt lgkmcnt(0)
	v_add_f32_e32 v173, v173, v174
	ds_write_b64 v175, v[172:173]
.LBB0_1233:
	s_or_b64 exec, exec, s[0:1]
	v_mov_b32_e32 v172, v39
	v_mov_b32_e32 v173, v40
	s_waitcnt lgkmcnt(0)
	v_mov_b32_e32 v174, v38
	v_mov_b32_e32 v175, v41
	v_pk_add_f32 v[172:173], v[172:173], v[174:175]
	v_mov_b32_e32 v174, v35
	v_mov_b32_e32 v175, v36
	v_mov_b32_e32 v176, v34
	v_mov_b32_e32 v177, v37
	v_pk_add_f32 v[174:175], v[174:175], v[176:177]
	v_add_f32_e32 v172, v172, v173
	v_pk_add_f32 v[174:175], v[174:175], v[174:175] op_sel_hi:[0,1]
	v_add_f32_e32 v173, 0, v172
	v_add_f32_e32 v177, v46, v47
	v_add_f32_e32 v197, v48, v49
	v_mov_b32_e32 v176, v42
	v_mov_b32_e32 v196, v43
	v_mov_b32_e32 v174, v44
	v_mov_b32_e32 v172, v45
	v_pk_add_f32 v[176:177], v[176:177], v[196:197]
	v_pk_add_f32 v[172:173], v[174:175], v[172:173]
	s_nop 0
	v_pk_add_f32 v[172:173], v[176:177], v[172:173]
	s_nop 0
	v_add_f32_e32 v172, v172, v173
	v_mov_b32_e32 v173, v172
	s_nop 1
	v_permlane16_swap_b32_e32 v173, v172
	s_waitcnt lgkmcnt(0)
	v_add_f32_e32 v172, v172, v173
	v_mov_b32_e32 v173, v172
	s_nop 1
	v_permlane32_swap_b32_e32 v173, v172
	s_waitcnt lgkmcnt(0)
	v_add_f32_e32 v172, v172, v173
	v_fmamk_f32 v174, v172, 0xbc800000, v41
	v_fmamk_f32 v176, v172, 0xbc800000, v39
	v_fmamk_f32 v173, v172, 0xbc800000, v40
	v_fmamk_f32 v175, v172, 0xbc800000, v38
	v_mul_f32_e32 v176, v176, v176
	v_mul_f32_e32 v174, v174, v174
	v_fmac_f32_e32 v176, v175, v175
	v_fmac_f32_e32 v174, v173, v173
	v_fmamk_f32 v175, v172, 0xbc800000, v37
	v_fmamk_f32 v177, v172, 0xbc800000, v35
	v_add_f32_e32 v173, v176, v174
	v_fmamk_f32 v174, v172, 0xbc800000, v36
	v_fmamk_f32 v176, v172, 0xbc800000, v34
	v_mul_f32_e32 v177, v177, v177
	v_mul_f32_e32 v175, v175, v175
	v_fmac_f32_e32 v177, v176, v176
	v_fmac_f32_e32 v175, v174, v174
	v_add_f32_e32 v174, v177, v175
	v_fmamk_f32 v175, v172, 0xbc800000, v49
	v_fmamk_f32 v177, v172, 0xbc800000, v47
	v_add_f32_e32 v173, v173, v174
	v_fmamk_f32 v174, v172, 0xbc800000, v48
	v_fmamk_f32 v176, v172, 0xbc800000, v46
	v_mul_f32_e32 v177, v177, v177
	v_mul_f32_e32 v175, v175, v175
	v_fmac_f32_e32 v177, v176, v176
	v_fmac_f32_e32 v175, v174, v174
	v_add_f32_e32 v174, v177, v175
	v_fmamk_f32 v175, v172, 0xbc800000, v45
	v_fmamk_f32 v177, v172, 0xbc800000, v43
	v_add_f32_e32 v173, v174, v173
	v_fmamk_f32 v174, v172, 0xbc800000, v44
	v_fmamk_f32 v176, v172, 0xbc800000, v42
	v_mul_f32_e32 v177, v177, v177
	v_mul_f32_e32 v175, v175, v175
	v_fmac_f32_e32 v177, v176, v176
	v_fmac_f32_e32 v175, v174, v174
	v_add_f32_e32 v174, v177, v175
	v_add_f32_e32 v173, v174, v173
	v_mov_b32_e32 v174, v173
	s_nop 1
	v_permlane16_swap_b32_e32 v174, v173
	s_waitcnt lgkmcnt(0)
	v_add_f32_e32 v173, v173, v174
	v_mov_b32_e32 v174, v173
	s_nop 1
	v_permlane32_swap_b32_e32 v174, v173
	s_and_saveexec_b64 s[0:1], vcc
	v_readlane_b32 s62, v255, 10
	v_readlane_b32 s84, v255, 12
	v_readlane_b32 s63, v255, 11
	v_readlane_b32 s85, v255, 13
	s_cbranch_execz .LBB0_1235
	s_lshl_b32 s5, s82, 11
	s_add_i32 s5, s4, s5
	v_mul_f32_e32 v172, 0x3c800000, v172
	v_lshl_add_u32 v175, v167, 5, s5
	s_waitcnt lgkmcnt(0)
	v_add_f32_e32 v173, v173, v174
	ds_write_b64 v175, v[172:173] offset:512
.LBB0_1235:
	s_or_b64 exec, exec, s[0:1]
	v_mov_b32_e32 v172, v63
	v_mov_b32_e32 v173, v64
	s_waitcnt lgkmcnt(0)
	v_mov_b32_e32 v174, v62
	v_mov_b32_e32 v175, v65
	v_pk_add_f32 v[172:173], v[172:173], v[174:175]
	v_mov_b32_e32 v174, v59
	v_mov_b32_e32 v175, v60
	v_mov_b32_e32 v176, v58
	v_mov_b32_e32 v177, v61
	v_pk_add_f32 v[174:175], v[174:175], v[176:177]
	v_add_f32_e32 v172, v172, v173
	v_pk_add_f32 v[174:175], v[174:175], v[174:175] op_sel_hi:[0,1]
	v_add_f32_e32 v173, 0, v172
	v_add_f32_e32 v177, v70, v71
	v_add_f32_e32 v197, v72, v73
	v_mov_b32_e32 v176, v66
	v_mov_b32_e32 v196, v67
	v_mov_b32_e32 v174, v68
	v_mov_b32_e32 v172, v69
	v_pk_add_f32 v[176:177], v[176:177], v[196:197]
	v_pk_add_f32 v[172:173], v[174:175], v[172:173]
	s_nop 0
	v_pk_add_f32 v[172:173], v[176:177], v[172:173]
	s_nop 0
	v_add_f32_e32 v172, v172, v173
	v_mov_b32_e32 v173, v172
	s_nop 1
	v_permlane16_swap_b32_e32 v173, v172
	s_waitcnt lgkmcnt(0)
	v_add_f32_e32 v172, v172, v173
	v_mov_b32_e32 v173, v172
	s_nop 1
	v_permlane32_swap_b32_e32 v173, v172
	s_waitcnt lgkmcnt(0)
	v_add_f32_e32 v172, v172, v173
	v_fmamk_f32 v174, v172, 0xbc800000, v65
	v_fmamk_f32 v176, v172, 0xbc800000, v63
	v_fmamk_f32 v173, v172, 0xbc800000, v64
	v_fmamk_f32 v175, v172, 0xbc800000, v62
	v_mul_f32_e32 v176, v176, v176
	v_mul_f32_e32 v174, v174, v174
	v_fmac_f32_e32 v176, v175, v175
	v_fmac_f32_e32 v174, v173, v173
	v_fmamk_f32 v175, v172, 0xbc800000, v61
	v_fmamk_f32 v177, v172, 0xbc800000, v59
	v_add_f32_e32 v173, v176, v174
	v_fmamk_f32 v174, v172, 0xbc800000, v60
	v_fmamk_f32 v176, v172, 0xbc800000, v58
	v_mul_f32_e32 v177, v177, v177
	v_mul_f32_e32 v175, v175, v175
	v_fmac_f32_e32 v177, v176, v176
	v_fmac_f32_e32 v175, v174, v174
	v_add_f32_e32 v174, v177, v175
	v_fmamk_f32 v175, v172, 0xbc800000, v73
	v_fmamk_f32 v177, v172, 0xbc800000, v71
	v_add_f32_e32 v173, v173, v174
	v_fmamk_f32 v174, v172, 0xbc800000, v72
	v_fmamk_f32 v176, v172, 0xbc800000, v70
	v_mul_f32_e32 v177, v177, v177
	v_mul_f32_e32 v175, v175, v175
	v_fmac_f32_e32 v177, v176, v176
	v_fmac_f32_e32 v175, v174, v174
	v_add_f32_e32 v174, v177, v175
	v_fmamk_f32 v175, v172, 0xbc800000, v69
	v_fmamk_f32 v177, v172, 0xbc800000, v67
	v_add_f32_e32 v173, v174, v173
	v_fmamk_f32 v174, v172, 0xbc800000, v68
	v_fmamk_f32 v176, v172, 0xbc800000, v66
	v_mul_f32_e32 v177, v177, v177
	v_mul_f32_e32 v175, v175, v175
	v_fmac_f32_e32 v177, v176, v176
	v_fmac_f32_e32 v175, v174, v174
	v_add_f32_e32 v174, v177, v175
	v_add_f32_e32 v173, v174, v173
	v_mov_b32_e32 v174, v173
	s_nop 1
	v_permlane16_swap_b32_e32 v174, v173
	s_waitcnt lgkmcnt(0)
	v_add_f32_e32 v173, v173, v174
	v_mov_b32_e32 v174, v173
	s_nop 1
	v_permlane32_swap_b32_e32 v174, v173
	s_and_saveexec_b64 s[0:1], vcc
	s_cbranch_execz .LBB0_1237
	s_lshl_b32 s5, s82, 11
	s_add_i32 s5, s4, s5
	v_mul_f32_e32 v172, 0x3c800000, v172
	v_lshl_add_u32 v175, v167, 5, s5
	s_waitcnt lgkmcnt(0)
	v_add_f32_e32 v173, v173, v174
	ds_write_b64 v175, v[172:173] offset:1024
.LBB0_1237:
	s_or_b64 exec, exec, s[0:1]
	v_mov_b32_e32 v172, v87
	v_mov_b32_e32 v173, v88
	s_waitcnt lgkmcnt(0)
	v_mov_b32_e32 v174, v86
	v_mov_b32_e32 v175, v89
	v_pk_add_f32 v[172:173], v[172:173], v[174:175]
	v_mov_b32_e32 v174, v83
	v_mov_b32_e32 v175, v84
	v_mov_b32_e32 v176, v82
	v_mov_b32_e32 v177, v85
	v_pk_add_f32 v[174:175], v[174:175], v[176:177]
	v_add_f32_e32 v172, v172, v173
	v_pk_add_f32 v[174:175], v[174:175], v[174:175] op_sel_hi:[0,1]
	v_add_f32_e32 v173, 0, v172
	v_add_f32_e32 v177, v94, v95
	v_add_f32_e32 v197, v96, v97
	v_mov_b32_e32 v176, v90
	v_mov_b32_e32 v196, v91
	v_mov_b32_e32 v174, v92
	v_mov_b32_e32 v172, v93
	v_pk_add_f32 v[176:177], v[176:177], v[196:197]
	v_pk_add_f32 v[172:173], v[174:175], v[172:173]
	s_nop 0
	v_pk_add_f32 v[172:173], v[176:177], v[172:173]
	s_nop 0
	v_add_f32_e32 v172, v172, v173
	v_mov_b32_e32 v173, v172
	s_nop 1
	v_permlane16_swap_b32_e32 v173, v172
	s_waitcnt lgkmcnt(0)
	v_add_f32_e32 v172, v172, v173
	v_mov_b32_e32 v173, v172
	s_nop 1
	v_permlane32_swap_b32_e32 v173, v172
	s_waitcnt lgkmcnt(0)
	v_add_f32_e32 v172, v172, v173
	v_fmamk_f32 v174, v172, 0xbc800000, v89
	v_fmamk_f32 v176, v172, 0xbc800000, v87
	v_fmamk_f32 v173, v172, 0xbc800000, v88
	v_fmamk_f32 v175, v172, 0xbc800000, v86
	v_mul_f32_e32 v176, v176, v176
	v_mul_f32_e32 v174, v174, v174
	v_fmac_f32_e32 v176, v175, v175
	v_fmac_f32_e32 v174, v173, v173
	v_fmamk_f32 v175, v172, 0xbc800000, v85
	v_fmamk_f32 v177, v172, 0xbc800000, v83
	v_add_f32_e32 v173, v176, v174
	v_fmamk_f32 v174, v172, 0xbc800000, v84
	v_fmamk_f32 v176, v172, 0xbc800000, v82
	v_mul_f32_e32 v177, v177, v177
	v_mul_f32_e32 v175, v175, v175
	v_fmac_f32_e32 v177, v176, v176
	v_fmac_f32_e32 v175, v174, v174
	v_add_f32_e32 v174, v177, v175
	v_fmamk_f32 v175, v172, 0xbc800000, v97
	v_fmamk_f32 v177, v172, 0xbc800000, v95
	v_add_f32_e32 v173, v173, v174
	v_fmamk_f32 v174, v172, 0xbc800000, v96
	v_fmamk_f32 v176, v172, 0xbc800000, v94
	v_mul_f32_e32 v177, v177, v177
	v_mul_f32_e32 v175, v175, v175
	v_fmac_f32_e32 v177, v176, v176
	v_fmac_f32_e32 v175, v174, v174
	v_add_f32_e32 v174, v177, v175
	v_fmamk_f32 v175, v172, 0xbc800000, v93
	v_fmamk_f32 v177, v172, 0xbc800000, v91
	v_add_f32_e32 v173, v174, v173
	v_fmamk_f32 v174, v172, 0xbc800000, v92
	v_fmamk_f32 v176, v172, 0xbc800000, v90
	v_mul_f32_e32 v177, v177, v177
	v_mul_f32_e32 v175, v175, v175
	v_fmac_f32_e32 v177, v176, v176
	v_fmac_f32_e32 v175, v174, v174
	v_add_f32_e32 v174, v177, v175
	v_add_f32_e32 v173, v174, v173
	v_mov_b32_e32 v174, v173
	s_nop 1
	v_permlane16_swap_b32_e32 v174, v173
	s_waitcnt lgkmcnt(0)
	v_add_f32_e32 v173, v173, v174
	v_mov_b32_e32 v174, v173
	s_nop 1
	v_permlane32_swap_b32_e32 v174, v173
	s_and_saveexec_b64 s[0:1], vcc
	s_cbranch_execz .LBB0_1239
	s_lshl_b32 s5, s82, 11
	s_add_i32 s5, s4, s5
	v_mul_f32_e32 v172, 0x3c800000, v172
	v_lshl_add_u32 v175, v167, 5, s5
	s_waitcnt lgkmcnt(0)
	v_add_f32_e32 v173, v173, v174
	ds_write_b64 v175, v[172:173] offset:1536
.LBB0_1239:
	s_or_b64 exec, exec, s[0:1]
	v_mov_b32_e32 v172, v111
	v_mov_b32_e32 v173, v112
	s_waitcnt lgkmcnt(0)
	v_mov_b32_e32 v174, v110
	v_mov_b32_e32 v175, v113
	v_pk_add_f32 v[172:173], v[172:173], v[174:175]
	v_mov_b32_e32 v174, v107
	v_mov_b32_e32 v175, v108
	v_mov_b32_e32 v176, v106
	v_mov_b32_e32 v177, v109
	v_pk_add_f32 v[174:175], v[174:175], v[176:177]
	v_add_f32_e32 v172, v172, v173
	v_pk_add_f32 v[174:175], v[174:175], v[174:175] op_sel_hi:[0,1]
	v_add_f32_e32 v173, 0, v172
	v_add_f32_e32 v177, v122, v123
	v_add_f32_e32 v197, v124, v125
	v_mov_b32_e32 v176, v114
	v_mov_b32_e32 v196, v115
	v_mov_b32_e32 v174, v116
	v_mov_b32_e32 v172, v117
	v_pk_add_f32 v[176:177], v[176:177], v[196:197]
	v_pk_add_f32 v[172:173], v[174:175], v[172:173]
	s_nop 0
	v_pk_add_f32 v[172:173], v[176:177], v[172:173]
	s_nop 0
	v_add_f32_e32 v172, v172, v173
	v_mov_b32_e32 v173, v172
	s_nop 1
	v_permlane16_swap_b32_e32 v173, v172
	s_waitcnt lgkmcnt(0)
	v_add_f32_e32 v172, v172, v173
	v_mov_b32_e32 v173, v172
	s_nop 1
	v_permlane32_swap_b32_e32 v173, v172
	s_waitcnt lgkmcnt(0)
	v_add_f32_e32 v172, v172, v173
	v_fmamk_f32 v174, v172, 0xbc800000, v113
	v_fmamk_f32 v176, v172, 0xbc800000, v111
	v_fmamk_f32 v173, v172, 0xbc800000, v112
	v_fmamk_f32 v175, v172, 0xbc800000, v110
	v_mul_f32_e32 v176, v176, v176
	v_mul_f32_e32 v174, v174, v174
	v_fmac_f32_e32 v176, v175, v175
	v_fmac_f32_e32 v174, v173, v173
	v_fmamk_f32 v175, v172, 0xbc800000, v109
	v_fmamk_f32 v177, v172, 0xbc800000, v107
	v_add_f32_e32 v173, v176, v174
	v_fmamk_f32 v174, v172, 0xbc800000, v108
	v_fmamk_f32 v176, v172, 0xbc800000, v106
	v_mul_f32_e32 v177, v177, v177
	v_mul_f32_e32 v175, v175, v175
	v_fmac_f32_e32 v177, v176, v176
	v_fmac_f32_e32 v175, v174, v174
	v_add_f32_e32 v174, v177, v175
	v_fmamk_f32 v175, v172, 0xbc800000, v125
	v_fmamk_f32 v177, v172, 0xbc800000, v123
	v_add_f32_e32 v173, v173, v174
	v_fmamk_f32 v174, v172, 0xbc800000, v124
	v_fmamk_f32 v176, v172, 0xbc800000, v122
	v_mul_f32_e32 v177, v177, v177
	v_mul_f32_e32 v175, v175, v175
	v_fmac_f32_e32 v177, v176, v176
	v_fmac_f32_e32 v175, v174, v174
	v_add_f32_e32 v174, v177, v175
	v_fmamk_f32 v175, v172, 0xbc800000, v117
	v_fmamk_f32 v177, v172, 0xbc800000, v115
	v_add_f32_e32 v173, v174, v173
	v_fmamk_f32 v174, v172, 0xbc800000, v116
	v_fmamk_f32 v176, v172, 0xbc800000, v114
	v_mul_f32_e32 v177, v177, v177
	v_mul_f32_e32 v175, v175, v175
	v_fmac_f32_e32 v177, v176, v176
	v_fmac_f32_e32 v175, v174, v174
	v_add_f32_e32 v174, v177, v175
	v_add_f32_e32 v173, v174, v173
	v_mov_b32_e32 v174, v173
	s_nop 1
	v_permlane16_swap_b32_e32 v174, v173
	s_waitcnt lgkmcnt(0)
	v_add_f32_e32 v173, v173, v174
	v_mov_b32_e32 v174, v173
	s_nop 1
	v_permlane32_swap_b32_e32 v174, v173
	s_and_saveexec_b64 s[0:1], vcc
	s_cbranch_execz .LBB0_1241
	s_lshl_b32 s5, s82, 11
	s_add_i32 s5, s4, s5
	v_mul_f32_e32 v172, 0x3c800000, v172
	v_lshl_add_u32 v175, v167, 5, s5
	s_waitcnt lgkmcnt(0)
	v_add_f32_e32 v173, v173, v174
	ds_write_b64 v175, v[172:173] offset:4096
.LBB0_1241:
	s_or_b64 exec, exec, s[0:1]
	v_mov_b32_e32 v172, v127
	v_mov_b32_e32 v173, v128
	s_waitcnt lgkmcnt(0)
	v_mov_b32_e32 v174, v126
	v_mov_b32_e32 v175, v129
	v_pk_add_f32 v[172:173], v[172:173], v[174:175]
	v_mov_b32_e32 v174, v119
	v_mov_b32_e32 v175, v120
	v_mov_b32_e32 v176, v118
	v_mov_b32_e32 v177, v121
	v_pk_add_f32 v[174:175], v[174:175], v[176:177]
	v_add_f32_e32 v172, v172, v173
	v_pk_add_f32 v[174:175], v[174:175], v[174:175] op_sel_hi:[0,1]
	v_add_f32_e32 v173, 0, v172
	v_add_f32_e32 v177, v102, v103
	v_add_f32_e32 v197, v104, v105
	v_mov_b32_e32 v176, v98
	v_mov_b32_e32 v196, v99
	v_mov_b32_e32 v174, v100
	v_mov_b32_e32 v172, v101
	v_pk_add_f32 v[176:177], v[176:177], v[196:197]
	v_pk_add_f32 v[172:173], v[174:175], v[172:173]
	s_nop 0
	v_pk_add_f32 v[172:173], v[176:177], v[172:173]
	s_nop 0
	v_add_f32_e32 v172, v172, v173
	v_mov_b32_e32 v173, v172
	s_nop 1
	v_permlane16_swap_b32_e32 v173, v172
	s_waitcnt lgkmcnt(0)
	v_add_f32_e32 v172, v172, v173
	v_mov_b32_e32 v173, v172
	s_nop 1
	v_permlane32_swap_b32_e32 v173, v172
	s_waitcnt lgkmcnt(0)
	v_add_f32_e32 v172, v172, v173
	v_fmamk_f32 v174, v172, 0xbc800000, v129
	v_fmamk_f32 v176, v172, 0xbc800000, v127
	v_fmamk_f32 v173, v172, 0xbc800000, v128
	v_fmamk_f32 v175, v172, 0xbc800000, v126
	v_mul_f32_e32 v176, v176, v176
	v_mul_f32_e32 v174, v174, v174
	v_fmac_f32_e32 v176, v175, v175
	v_fmac_f32_e32 v174, v173, v173
	v_fmamk_f32 v175, v172, 0xbc800000, v121
	v_fmamk_f32 v177, v172, 0xbc800000, v119
	v_add_f32_e32 v173, v176, v174
	v_fmamk_f32 v174, v172, 0xbc800000, v120
	v_fmamk_f32 v176, v172, 0xbc800000, v118
	v_mul_f32_e32 v177, v177, v177
	v_mul_f32_e32 v175, v175, v175
	v_fmac_f32_e32 v177, v176, v176
	v_fmac_f32_e32 v175, v174, v174
	v_add_f32_e32 v174, v177, v175
	v_fmamk_f32 v175, v172, 0xbc800000, v105
	v_fmamk_f32 v177, v172, 0xbc800000, v103
	v_add_f32_e32 v173, v173, v174
	v_fmamk_f32 v174, v172, 0xbc800000, v104
	v_fmamk_f32 v176, v172, 0xbc800000, v102
	v_mul_f32_e32 v177, v177, v177
	v_mul_f32_e32 v175, v175, v175
	v_fmac_f32_e32 v177, v176, v176
	v_fmac_f32_e32 v175, v174, v174
	v_add_f32_e32 v174, v177, v175
	v_fmamk_f32 v175, v172, 0xbc800000, v101
	v_fmamk_f32 v177, v172, 0xbc800000, v99
	v_add_f32_e32 v173, v174, v173
	v_fmamk_f32 v174, v172, 0xbc800000, v100
	v_fmamk_f32 v176, v172, 0xbc800000, v98
	v_mul_f32_e32 v177, v177, v177
	v_mul_f32_e32 v175, v175, v175
	v_fmac_f32_e32 v177, v176, v176
	v_fmac_f32_e32 v175, v174, v174
	v_add_f32_e32 v174, v177, v175
	v_add_f32_e32 v173, v174, v173
	v_mov_b32_e32 v174, v173
	s_nop 1
	v_permlane16_swap_b32_e32 v174, v173
	s_waitcnt lgkmcnt(0)
	v_add_f32_e32 v173, v173, v174
	v_mov_b32_e32 v174, v173
	s_nop 1
	v_permlane32_swap_b32_e32 v174, v173
	s_and_saveexec_b64 s[0:1], vcc
	s_cbranch_execz .LBB0_1243
	s_lshl_b32 s5, s82, 11
	s_add_i32 s5, s4, s5
	v_mul_f32_e32 v172, 0x3c800000, v172
	v_lshl_add_u32 v175, v167, 5, s5
	s_waitcnt lgkmcnt(0)
	v_add_f32_e32 v173, v173, v174
	ds_write_b64 v175, v[172:173] offset:4608
.LBB0_1243:
	s_or_b64 exec, exec, s[0:1]
	v_mov_b32_e32 v172, v79
	v_mov_b32_e32 v173, v80
	s_waitcnt lgkmcnt(0)
	v_mov_b32_e32 v174, v78
	v_mov_b32_e32 v175, v81
	v_pk_add_f32 v[172:173], v[172:173], v[174:175]
	v_mov_b32_e32 v174, v75
	v_mov_b32_e32 v175, v76
	v_mov_b32_e32 v176, v74
	v_mov_b32_e32 v177, v77
	v_pk_add_f32 v[174:175], v[174:175], v[176:177]
	v_add_f32_e32 v172, v172, v173
	v_pk_add_f32 v[174:175], v[174:175], v[174:175] op_sel_hi:[0,1]
	v_add_f32_e32 v173, 0, v172
	v_add_f32_e32 v177, v54, v55
	v_add_f32_e32 v197, v56, v57
	v_mov_b32_e32 v176, v50
	v_mov_b32_e32 v196, v51
	v_mov_b32_e32 v174, v52
	v_mov_b32_e32 v172, v53
	v_pk_add_f32 v[176:177], v[176:177], v[196:197]
	v_pk_add_f32 v[172:173], v[174:175], v[172:173]
	s_nop 0
	v_pk_add_f32 v[172:173], v[176:177], v[172:173]
	s_nop 0
	v_add_f32_e32 v172, v172, v173
	v_mov_b32_e32 v173, v172
	s_nop 1
	v_permlane16_swap_b32_e32 v173, v172
	s_waitcnt lgkmcnt(0)
	v_add_f32_e32 v172, v172, v173
	v_mov_b32_e32 v173, v172
	s_nop 1
	v_permlane32_swap_b32_e32 v173, v172
	s_waitcnt lgkmcnt(0)
	v_add_f32_e32 v172, v172, v173
	v_fmamk_f32 v174, v172, 0xbc800000, v81
	v_fmamk_f32 v176, v172, 0xbc800000, v79
	v_fmamk_f32 v173, v172, 0xbc800000, v80
	v_fmamk_f32 v175, v172, 0xbc800000, v78
	v_mul_f32_e32 v176, v176, v176
	v_mul_f32_e32 v174, v174, v174
	v_fmac_f32_e32 v176, v175, v175
	v_fmac_f32_e32 v174, v173, v173
	v_fmamk_f32 v175, v172, 0xbc800000, v77
	v_fmamk_f32 v177, v172, 0xbc800000, v75
	v_add_f32_e32 v173, v176, v174
	v_fmamk_f32 v174, v172, 0xbc800000, v76
	v_fmamk_f32 v176, v172, 0xbc800000, v74
	v_mul_f32_e32 v177, v177, v177
	v_mul_f32_e32 v175, v175, v175
	v_fmac_f32_e32 v177, v176, v176
	v_fmac_f32_e32 v175, v174, v174
	v_add_f32_e32 v174, v177, v175
	v_fmamk_f32 v175, v172, 0xbc800000, v57
	v_fmamk_f32 v177, v172, 0xbc800000, v55
	v_add_f32_e32 v173, v173, v174
	v_fmamk_f32 v174, v172, 0xbc800000, v56
	v_fmamk_f32 v176, v172, 0xbc800000, v54
	v_mul_f32_e32 v177, v177, v177
	v_mul_f32_e32 v175, v175, v175
	v_fmac_f32_e32 v177, v176, v176
	v_fmac_f32_e32 v175, v174, v174
	v_add_f32_e32 v174, v177, v175
	v_fmamk_f32 v175, v172, 0xbc800000, v53
	v_fmamk_f32 v177, v172, 0xbc800000, v51
	v_add_f32_e32 v173, v174, v173
	v_fmamk_f32 v174, v172, 0xbc800000, v52
	v_fmamk_f32 v176, v172, 0xbc800000, v50
	v_mul_f32_e32 v177, v177, v177
	v_mul_f32_e32 v175, v175, v175
	v_fmac_f32_e32 v177, v176, v176
	v_fmac_f32_e32 v175, v174, v174
	v_add_f32_e32 v174, v177, v175
	v_add_f32_e32 v173, v174, v173
	v_mov_b32_e32 v174, v173
	s_nop 1
	v_permlane16_swap_b32_e32 v174, v173
	s_waitcnt lgkmcnt(0)
	v_add_f32_e32 v173, v173, v174
	v_mov_b32_e32 v174, v173
	s_nop 1
	v_permlane32_swap_b32_e32 v174, v173
	s_and_saveexec_b64 s[0:1], vcc
	s_cbranch_execz .LBB0_1245
	s_lshl_b32 s5, s82, 11
	s_add_i32 s5, s4, s5
	v_mul_f32_e32 v172, 0x3c800000, v172
	v_lshl_add_u32 v175, v167, 5, s5
	s_waitcnt lgkmcnt(0)
	v_add_f32_e32 v173, v173, v174
	ds_write_b64 v175, v[172:173] offset:5120
.LBB0_1245:
	s_or_b64 exec, exec, s[0:1]
	v_mov_b32_e32 v172, v31
	v_mov_b32_e32 v173, v32
	s_waitcnt lgkmcnt(0)
	v_mov_b32_e32 v174, v30
	v_mov_b32_e32 v175, v33
	v_pk_add_f32 v[172:173], v[172:173], v[174:175]
	v_mov_b32_e32 v174, v27
	v_mov_b32_e32 v175, v28
	v_mov_b32_e32 v176, v26
	v_mov_b32_e32 v177, v29
	v_pk_add_f32 v[174:175], v[174:175], v[176:177]
	v_add_f32_e32 v172, v172, v173
	v_pk_add_f32 v[174:175], v[174:175], v[174:175] op_sel_hi:[0,1]
	v_add_f32_e32 v173, 0, v172
	v_add_f32_e32 v177, v22, v23
	v_add_f32_e32 v197, v24, v25
	v_mov_b32_e32 v176, v10
	v_mov_b32_e32 v196, v11
	v_mov_b32_e32 v174, v12
	v_mov_b32_e32 v172, v13
	v_pk_add_f32 v[176:177], v[176:177], v[196:197]
	v_pk_add_f32 v[172:173], v[174:175], v[172:173]
	s_nop 0
	v_pk_add_f32 v[172:173], v[176:177], v[172:173]
	s_nop 0
	v_add_f32_e32 v172, v172, v173
	v_mov_b32_e32 v173, v172
	s_nop 1
	v_permlane16_swap_b32_e32 v173, v172
	s_waitcnt lgkmcnt(0)
	v_add_f32_e32 v172, v172, v173
	v_mov_b32_e32 v173, v172
	s_nop 1
	v_permlane32_swap_b32_e32 v173, v172
	s_waitcnt lgkmcnt(0)
	v_add_f32_e32 v172, v172, v173
	v_fmamk_f32 v174, v172, 0xbc800000, v33
	v_fmamk_f32 v176, v172, 0xbc800000, v31
	v_fmamk_f32 v173, v172, 0xbc800000, v32
	v_fmamk_f32 v175, v172, 0xbc800000, v30
	v_mul_f32_e32 v176, v176, v176
	v_mul_f32_e32 v174, v174, v174
	v_fmac_f32_e32 v176, v175, v175
	v_fmac_f32_e32 v174, v173, v173
	v_fmamk_f32 v175, v172, 0xbc800000, v29
	v_fmamk_f32 v177, v172, 0xbc800000, v27
	v_add_f32_e32 v173, v176, v174
	v_fmamk_f32 v174, v172, 0xbc800000, v28
	v_fmamk_f32 v176, v172, 0xbc800000, v26
	v_mul_f32_e32 v177, v177, v177
	v_mul_f32_e32 v175, v175, v175
	v_fmac_f32_e32 v177, v176, v176
	v_fmac_f32_e32 v175, v174, v174
	v_add_f32_e32 v174, v177, v175
	v_fmamk_f32 v175, v172, 0xbc800000, v25
	v_fmamk_f32 v177, v172, 0xbc800000, v23
	v_add_f32_e32 v173, v173, v174
	v_fmamk_f32 v174, v172, 0xbc800000, v24
	v_fmamk_f32 v176, v172, 0xbc800000, v22
	v_mul_f32_e32 v177, v177, v177
	v_mul_f32_e32 v175, v175, v175
	v_fmac_f32_e32 v177, v176, v176
	v_fmac_f32_e32 v175, v174, v174
	v_add_f32_e32 v174, v177, v175
	v_fmamk_f32 v175, v172, 0xbc800000, v13
	v_fmamk_f32 v177, v172, 0xbc800000, v11
	v_add_f32_e32 v173, v174, v173
	v_fmamk_f32 v174, v172, 0xbc800000, v12
	v_fmamk_f32 v176, v172, 0xbc800000, v10
	v_mul_f32_e32 v177, v177, v177
	v_mul_f32_e32 v175, v175, v175
	v_fmac_f32_e32 v177, v176, v176
	v_fmac_f32_e32 v175, v174, v174
	v_add_f32_e32 v174, v177, v175
	v_add_f32_e32 v173, v174, v173
	v_mov_b32_e32 v170, v173
	s_nop 1
	v_permlane16_swap_b32_e32 v170, v173
	s_waitcnt lgkmcnt(0)
	v_add_f32_e32 v170, v173, v170
	v_mov_b32_e32 v171, v170
	s_nop 1
	v_permlane32_swap_b32_e32 v171, v170
	s_and_saveexec_b64 s[0:1], vcc
	s_cbranch_execz .LBB0_1247
	s_lshl_b32 s5, s82, 11
	s_add_i32 s4, s4, s5
	v_mul_f32_e32 v172, 0x3c800000, v172
	v_lshl_add_u32 v167, v167, 5, s4
	s_waitcnt lgkmcnt(0)
	v_add_f32_e32 v173, v170, v171
	ds_write_b64 v167, v[172:173] offset:5632

.LBB0_1296:
	s_add_u32 s0, s74, s34
	s_addc_u32 s1, s75, s35
	s_add_u32 s8, s0, 0x12c00000
	s_addc_u32 s9, s1, 0
	s_add_u32 s0, s74, s28
	s_addc_u32 s1, s75, s29
	v_lshrrev_b32_e32 v130, 1, v164
	s_add_u32 s6, s0, 0x9c00000
	v_and_b32_e32 v130, 24, v130
	s_addc_u32 s7, s1, 0
	s_lshl_b32 s0, s12, 8
	v_lshl_or_b32 v130, s38, 5, v130
	v_lshl_or_b32 v131, s38, 6, v144
	s_lshl_b32 s20, s95, 8
	v_or_b32_e32 v130, s0, v130
	v_or_b32_e32 v134, s0, v131
	s_add_i32 s0, s20, s84
	v_or_b32_e32 v136, s0, v165
	v_ashrrev_i32_e32 v137, 31, v136
	v_lshlrev_b64 v[132:133], 11, v[136:137]
	v_ashrrev_i32_e32 v135, 31, v134
	v_lshl_add_u64 v[138:139], s[8:9], 0, v[132:133]
	v_lshl_add_u64 v[138:139], v[138:139], 0, v[134:135]
	s_barrier
	v_ashrrev_i32_e32 v131, 31, v130
	v_mov_b64_e32 v[248:249], v[138:139]
	v_lshl_add_u64 v[142:143], s[6:7], 0, v[132:133]
	v_lshlrev_b64 v[132:133], 1, v[130:131]
	v_lshl_add_u64 v[146:147], v[142:143], 0, v[132:133]
	v_mov_b64_e32 v[250:251], v[146:147]
	v_mov_b64_e32 v[212:213], v[248:249]
	global_load_dwordx4 v[212:215], v[212:213], off
	v_mov_b64_e32 v[216:217], v[250:251]
	global_load_dwordx4 v[216:219], v[216:217], off
	v_mov_b64_e32 v[220:221], v[250:251]
	global_load_dwordx4 v[220:223], v[220:221], off offset:256
	s_mov_b32 s98, 0x8000
	s_mov_b32 s99, 0
	v_lshl_add_u64 v[224:225], v[248:249], 0, s[98:99]
	global_load_dwordx4 v[224:227], v[224:225], off
	s_mov_b32 s98, 0x8000
	s_mov_b32 s99, 0
	v_lshl_add_u64 v[228:229], v[250:251], 0, s[98:99]
	global_load_dwordx4 v[228:231], v[228:229], off
	s_mov_b32 s98, 0x8000
	s_mov_b32 s99, 0
	v_lshl_add_u64 v[232:233], v[250:251], 0, s[98:99]
	global_load_dwordx4 v[232:235], v[232:233], off offset:256
	s_mov_b32 s98, 0x10000
	s_mov_b32 s99, 0
	v_lshl_add_u64 v[236:237], v[248:249], 0, s[98:99]
	global_load_dwordx4 v[236:239], v[236:237], off
	s_mov_b32 s98, 0x10000
	s_mov_b32 s99, 0
	v_lshl_add_u64 v[240:241], v[250:251], 0, s[98:99]
	global_load_dwordx4 v[240:243], v[240:241], off
	s_mov_b32 s98, 0x10000
	s_mov_b32 s99, 0
	v_lshl_add_u64 v[244:245], v[250:251], 0, s[98:99]
	global_load_dwordx4 v[244:247], v[244:245], off offset:256
	s_waitcnt vmcnt(0)
	v_mov_b64_e32 v[138:139], v[212:213]
	v_mov_b64_e32 v[140:141], v[214:215]
	v_mov_b64_e32 v[142:143], v[216:217]
	v_mov_b64_e32 v[144:145], v[218:219]
	s_mov_b32 s0, 0x3a000000
	v_readlane_b32 s4, v255, 27
	v_lshlrev_b64 v[162:163], 2, v[130:131]
	v_readlane_b32 s5, v255, 28
	v_and_b32_e32 v169, 64, v205
	v_xor_b32_e32 v168, 16, v205
	v_add_u32_e32 v169, 64, v169
	v_xor_b32_e32 v170, 32, v205
	v_and_b32_e32 v167, 63, v164
	s_waitcnt vmcnt(0)
	v_cvt_pk_f32_fp8_sdwa v[150:151], v138 src0_sel:WORD_1
	v_cvt_pk_f32_fp8_e32 v[148:149], v138
	v_cvt_pk_f32_fp8_e32 v[152:153], v139
	v_cvt_pk_f32_fp8_sdwa v[138:139], v139 src0_sel:WORD_1
	v_lshlrev_b32_e32 v154, 16, v142
	v_and_b32_e32 v155, 0xffff0000, v142
	v_lshlrev_b32_e32 v142, 16, v143
	v_and_b32_e32 v143, 0xffff0000, v143
	v_pk_fma_f32 v[142:143], v[150:151], s[0:1], v[142:143] op_sel_hi:[1,0,1]
	v_lshlrev_b32_e32 v150, 16, v144
	v_and_b32_e32 v151, 0xffff0000, v144
	v_lshlrev_b32_e32 v144, 16, v145
	v_and_b32_e32 v145, 0xffff0000, v145
	v_pk_fma_f32 v[138:139], v[138:139], s[0:1], v[144:145] op_sel_hi:[1,0,1]
	v_pk_fma_f32 v[8:9], v[142:143], s[86:87], v[8:9] op_sel_hi:[1,0,1]
	s_waitcnt vmcnt(0)
	v_mov_b64_e32 v[142:143], v[220:221]
	v_mov_b64_e32 v[144:145], v[222:223]
	v_pk_fma_f32 v[4:5], v[138:139], s[86:87], v[4:5] op_sel_hi:[1,0,1]
	v_cvt_pk_f32_fp8_e32 v[138:139], v140
	v_pk_fma_f32 v[150:151], v[152:153], s[0:1], v[150:151] op_sel_hi:[1,0,1]
	v_cvt_pk_f32_fp8_sdwa v[146:147], v140 src0_sel:WORD_1
	v_pk_fma_f32 v[148:149], v[148:149], s[0:1], v[154:155] op_sel_hi:[1,0,1]
	v_pk_fma_f32 v[2:3], v[150:151], s[86:87], v[2:3] op_sel_hi:[1,0,1]
	v_pk_fma_f32 v[6:7], v[148:149], s[86:87], v[6:7] op_sel_hi:[1,0,1]
	v_cvt_pk_f32_fp8_e32 v[148:149], v141
	v_cvt_pk_f32_fp8_sdwa v[140:141], v141 src0_sel:WORD_1
	s_waitcnt vmcnt(0)
	v_lshlrev_b32_e32 v150, 16, v142
	v_and_b32_e32 v151, 0xffff0000, v142
	v_pk_fma_f32 v[138:139], v[138:139], s[0:1], v[150:151] op_sel_hi:[1,0,1]
	v_lshlrev_b32_e32 v142, 16, v143
	v_and_b32_e32 v143, 0xffff0000, v143
	v_pk_fma_f32 v[22:23], v[138:139], s[86:87], v[22:23] op_sel_hi:[1,0,1]
	v_or_b32_e32 v138, 16, v136
	v_pk_fma_f32 v[142:143], v[146:147], s[0:1], v[142:143] op_sel_hi:[1,0,1]
	v_ashrrev_i32_e32 v139, 31, v138
	v_lshlrev_b32_e32 v146, 16, v144
	v_and_b32_e32 v147, 0xffff0000, v144
	v_lshlrev_b32_e32 v144, 16, v145
	v_and_b32_e32 v145, 0xffff0000, v145
	v_pk_fma_f32 v[24:25], v[142:143], s[86:87], v[24:25] op_sel_hi:[1,0,1]
	v_lshlrev_b64 v[142:143], 11, v[138:139]
	v_pk_fma_f32 v[146:147], v[148:149], s[0:1], v[146:147] op_sel_hi:[1,0,1]
	v_pk_fma_f32 v[140:141], v[140:141], s[0:1], v[144:145] op_sel_hi:[1,0,1]
	v_lshl_add_u64 v[138:139], s[8:9], 0, v[142:143]
	v_pk_fma_f32 v[20:21], v[140:141], s[86:87], v[20:21] op_sel_hi:[1,0,1]
	v_pk_fma_f32 v[18:19], v[146:147], s[86:87], v[18:19] op_sel_hi:[1,0,1]
	v_lshl_add_u64 v[138:139], v[138:139], 0, v[134:135]
	s_waitcnt vmcnt(0)
	v_mov_b64_e32 v[138:139], v[224:225]
	v_mov_b64_e32 v[140:141], v[226:227]
	v_lshl_add_u64 v[142:143], s[6:7], 0, v[142:143]
	v_lshl_add_u64 v[146:147], v[142:143], 0, v[132:133]
	s_waitcnt vmcnt(0)
	v_mov_b64_e32 v[142:143], v[228:229]
	v_mov_b64_e32 v[144:145], v[230:231]
	v_mov_b32_e32 v171, v8
	v_mov_b32_e32 v172, v6
	v_mov_b32_e32 v173, v9
	v_mov_b32_e32 v174, v2
	v_mov_b32_e32 v175, v5
	v_add_f32_e32 v177, v24, v25
	v_mov_b32_e32 v176, v19
	s_waitcnt vmcnt(1)
	v_cvt_pk_f32_fp8_sdwa v[150:151], v138 src0_sel:WORD_1
	v_cvt_pk_f32_fp8_e32 v[148:149], v138
	v_cvt_pk_f32_fp8_e32 v[152:153], v139
	v_cvt_pk_f32_fp8_sdwa v[138:139], v139 src0_sel:WORD_1
	s_waitcnt vmcnt(0)
	v_lshlrev_b32_e32 v154, 16, v142
	v_and_b32_e32 v155, 0xffff0000, v142
	v_lshlrev_b32_e32 v142, 16, v143
	v_and_b32_e32 v143, 0xffff0000, v143
	v_pk_fma_f32 v[142:143], v[150:151], s[0:1], v[142:143] op_sel_hi:[1,0,1]
	v_lshlrev_b32_e32 v150, 16, v144
	v_and_b32_e32 v151, 0xffff0000, v144
	v_lshlrev_b32_e32 v144, 16, v145
	v_and_b32_e32 v145, 0xffff0000, v145
	v_pk_fma_f32 v[138:139], v[138:139], s[0:1], v[144:145] op_sel_hi:[1,0,1]
	v_pk_fma_f32 v[40:41], v[142:143], s[86:87], v[40:41] op_sel_hi:[1,0,1]
	s_waitcnt vmcnt(0)
	v_mov_b64_e32 v[142:143], v[232:233]
	v_mov_b64_e32 v[144:145], v[234:235]
	v_pk_fma_f32 v[36:37], v[138:139], s[86:87], v[36:37] op_sel_hi:[1,0,1]
	v_cvt_pk_f32_fp8_e32 v[138:139], v140
	v_pk_fma_f32 v[150:151], v[152:153], s[0:1], v[150:151] op_sel_hi:[1,0,1]
	v_cvt_pk_f32_fp8_sdwa v[146:147], v140 src0_sel:WORD_1
	v_pk_fma_f32 v[148:149], v[148:149], s[0:1], v[154:155] op_sel_hi:[1,0,1]
	v_pk_fma_f32 v[34:35], v[150:151], s[86:87], v[34:35] op_sel_hi:[1,0,1]
	v_pk_fma_f32 v[38:39], v[148:149], s[86:87], v[38:39] op_sel_hi:[1,0,1]
	v_cvt_pk_f32_fp8_e32 v[148:149], v141
	v_cvt_pk_f32_fp8_sdwa v[140:141], v141 src0_sel:WORD_1
	s_waitcnt vmcnt(0)
	v_lshlrev_b32_e32 v150, 16, v142
	v_and_b32_e32 v151, 0xffff0000, v142
	v_pk_fma_f32 v[138:139], v[138:139], s[0:1], v[150:151] op_sel_hi:[1,0,1]
	v_lshlrev_b32_e32 v142, 16, v143
	v_and_b32_e32 v143, 0xffff0000, v143
	v_pk_fma_f32 v[46:47], v[138:139], s[86:87], v[46:47] op_sel_hi:[1,0,1]
	v_or_b32_e32 v138, 32, v136
	v_pk_fma_f32 v[142:143], v[146:147], s[0:1], v[142:143] op_sel_hi:[1,0,1]
	v_ashrrev_i32_e32 v139, 31, v138
	v_lshlrev_b32_e32 v146, 16, v144
	v_and_b32_e32 v147, 0xffff0000, v144
	v_lshlrev_b32_e32 v144, 16, v145
	v_and_b32_e32 v145, 0xffff0000, v145
	v_pk_fma_f32 v[48:49], v[142:143], s[86:87], v[48:49] op_sel_hi:[1,0,1]
	v_lshlrev_b64 v[142:143], 11, v[138:139]
	v_pk_fma_f32 v[146:147], v[148:149], s[0:1], v[146:147] op_sel_hi:[1,0,1]
	v_pk_fma_f32 v[140:141], v[140:141], s[0:1], v[144:145] op_sel_hi:[1,0,1]
	v_lshl_add_u64 v[138:139], s[8:9], 0, v[142:143]
	v_pk_fma_f32 v[44:45], v[140:141], s[86:87], v[44:45] op_sel_hi:[1,0,1]
	v_pk_fma_f32 v[42:43], v[146:147], s[86:87], v[42:43] op_sel_hi:[1,0,1]
	v_lshl_add_u64 v[138:139], v[138:139], 0, v[134:135]
	s_waitcnt vmcnt(0)
	v_mov_b64_e32 v[138:139], v[236:237]
	v_mov_b64_e32 v[140:141], v[238:239]
	v_lshl_add_u64 v[142:143], s[6:7], 0, v[142:143]
	v_lshl_add_u64 v[146:147], v[142:143], 0, v[132:133]
	s_waitcnt vmcnt(0)
	v_mov_b64_e32 v[142:143], v[240:241]
	v_mov_b64_e32 v[144:145], v[242:243]
	s_waitcnt vmcnt(1)
	v_cvt_pk_f32_fp8_sdwa v[150:151], v138 src0_sel:WORD_1
	v_cvt_pk_f32_fp8_e32 v[148:149], v138
	v_cvt_pk_f32_fp8_e32 v[152:153], v139
	v_cvt_pk_f32_fp8_sdwa v[138:139], v139 src0_sel:WORD_1
	s_waitcnt vmcnt(0)
	v_lshlrev_b32_e32 v154, 16, v142
	v_and_b32_e32 v155, 0xffff0000, v142
	v_lshlrev_b32_e32 v142, 16, v143
	v_and_b32_e32 v143, 0xffff0000, v143
	v_pk_fma_f32 v[142:143], v[150:151], s[0:1], v[142:143] op_sel_hi:[1,0,1]
	v_lshlrev_b32_e32 v150, 16, v144
	v_and_b32_e32 v151, 0xffff0000, v144
	v_lshlrev_b32_e32 v144, 16, v145
	v_and_b32_e32 v145, 0xffff0000, v145
	v_pk_fma_f32 v[138:139], v[138:139], s[0:1], v[144:145] op_sel_hi:[1,0,1]
	v_pk_fma_f32 v[64:65], v[142:143], s[86:87], v[64:65] op_sel_hi:[1,0,1]
	s_waitcnt vmcnt(0)
	v_mov_b64_e32 v[142:143], v[244:245]
	v_mov_b64_e32 v[144:145], v[246:247]
	s_mov_b32 s98, 0x18000
	s_mov_b32 s99, 0
	v_lshl_add_u64 v[212:213], v[248:249], 0, s[98:99]
	global_load_dwordx4 v[212:215], v[212:213], off
	s_mov_b32 s98, 0x18000
	s_mov_b32 s99, 0
	v_lshl_add_u64 v[216:217], v[250:251], 0, s[98:99]
	global_load_dwordx4 v[216:219], v[216:217], off
	s_mov_b32 s98, 0x18000
	s_mov_b32 s99, 0
	v_lshl_add_u64 v[220:221], v[250:251], 0, s[98:99]
	global_load_dwordx4 v[220:223], v[220:221], off offset:256
	s_mov_b32 s98, 0x40000
	s_mov_b32 s99, 0
	v_lshl_add_u64 v[224:225], v[248:249], 0, s[98:99]
	global_load_dwordx4 v[224:227], v[224:225], off
	s_mov_b32 s98, 0x40000
	s_mov_b32 s99, 0
	v_lshl_add_u64 v[228:229], v[250:251], 0, s[98:99]
	global_load_dwordx4 v[228:231], v[228:229], off
	s_mov_b32 s98, 0x40000
	s_mov_b32 s99, 0
	v_lshl_add_u64 v[232:233], v[250:251], 0, s[98:99]
	global_load_dwordx4 v[232:235], v[232:233], off offset:256
	s_mov_b32 s98, 0x48000
	s_mov_b32 s99, 0
	v_lshl_add_u64 v[236:237], v[248:249], 0, s[98:99]
	global_load_dwordx4 v[236:239], v[236:237], off
	s_mov_b32 s98, 0x48000
	s_mov_b32 s99, 0
	v_lshl_add_u64 v[240:241], v[250:251], 0, s[98:99]
	global_load_dwordx4 v[240:243], v[240:241], off
	s_mov_b32 s98, 0x48000
	s_mov_b32 s99, 0
	v_lshl_add_u64 v[244:245], v[250:251], 0, s[98:99]
	global_load_dwordx4 v[244:247], v[244:245], off offset:256
	v_pk_fma_f32 v[60:61], v[138:139], s[86:87], v[60:61] op_sel_hi:[1,0,1]
	v_cvt_pk_f32_fp8_e32 v[138:139], v140
	v_pk_fma_f32 v[150:151], v[152:153], s[0:1], v[150:151] op_sel_hi:[1,0,1]
	v_cvt_pk_f32_fp8_sdwa v[146:147], v140 src0_sel:WORD_1
	v_pk_fma_f32 v[148:149], v[148:149], s[0:1], v[154:155] op_sel_hi:[1,0,1]
	v_pk_fma_f32 v[58:59], v[150:151], s[86:87], v[58:59] op_sel_hi:[1,0,1]
	v_pk_fma_f32 v[62:63], v[148:149], s[86:87], v[62:63] op_sel_hi:[1,0,1]
	v_cvt_pk_f32_fp8_e32 v[148:149], v141
	v_cvt_pk_f32_fp8_sdwa v[140:141], v141 src0_sel:WORD_1
	s_waitcnt vmcnt(0)
	v_lshlrev_b32_e32 v150, 16, v142
	v_and_b32_e32 v151, 0xffff0000, v142
	v_pk_fma_f32 v[138:139], v[138:139], s[0:1], v[150:151] op_sel_hi:[1,0,1]
	v_lshlrev_b32_e32 v142, 16, v143
	v_and_b32_e32 v143, 0xffff0000, v143
	v_pk_fma_f32 v[78:79], v[138:139], s[86:87], v[78:79] op_sel_hi:[1,0,1]
	v_or_b32_e32 v138, 48, v136
	v_pk_fma_f32 v[142:143], v[146:147], s[0:1], v[142:143] op_sel_hi:[1,0,1]
	v_ashrrev_i32_e32 v139, 31, v138
	v_lshlrev_b32_e32 v146, 16, v144
	v_and_b32_e32 v147, 0xffff0000, v144
	v_lshlrev_b32_e32 v144, 16, v145
	v_and_b32_e32 v145, 0xffff0000, v145
	v_pk_fma_f32 v[80:81], v[142:143], s[86:87], v[80:81] op_sel_hi:[1,0,1]
	v_lshlrev_b64 v[142:143], 11, v[138:139]
	v_pk_fma_f32 v[146:147], v[148:149], s[0:1], v[146:147] op_sel_hi:[1,0,1]
	v_pk_fma_f32 v[140:141], v[140:141], s[0:1], v[144:145] op_sel_hi:[1,0,1]
	v_lshl_add_u64 v[138:139], s[8:9], 0, v[142:143]
	v_pk_fma_f32 v[76:77], v[140:141], s[86:87], v[76:77] op_sel_hi:[1,0,1]
	v_pk_fma_f32 v[74:75], v[146:147], s[86:87], v[74:75] op_sel_hi:[1,0,1]
	v_lshl_add_u64 v[138:139], v[138:139], 0, v[134:135]
	s_waitcnt vmcnt(0)
	v_mov_b64_e32 v[138:139], v[212:213]
	v_mov_b64_e32 v[140:141], v[214:215]
	v_lshl_add_u64 v[142:143], s[6:7], 0, v[142:143]
	v_lshl_add_u64 v[146:147], v[142:143], 0, v[132:133]
	s_waitcnt vmcnt(0)
	v_mov_b64_e32 v[142:143], v[216:217]
	v_mov_b64_e32 v[144:145], v[218:219]
	s_waitcnt vmcnt(1)
	v_cvt_pk_f32_fp8_sdwa v[150:151], v138 src0_sel:WORD_1
	v_cvt_pk_f32_fp8_e32 v[148:149], v138
	v_cvt_pk_f32_fp8_e32 v[152:153], v139
	v_cvt_pk_f32_fp8_sdwa v[138:139], v139 src0_sel:WORD_1
	s_waitcnt vmcnt(0)
	v_lshlrev_b32_e32 v154, 16, v142
	v_and_b32_e32 v155, 0xffff0000, v142
	v_lshlrev_b32_e32 v142, 16, v143
	v_and_b32_e32 v143, 0xffff0000, v143
	v_pk_fma_f32 v[142:143], v[150:151], s[0:1], v[142:143] op_sel_hi:[1,0,1]
	v_lshlrev_b32_e32 v150, 16, v144
	v_and_b32_e32 v151, 0xffff0000, v144
	v_lshlrev_b32_e32 v144, 16, v145
	v_and_b32_e32 v145, 0xffff0000, v145
	v_pk_fma_f32 v[138:139], v[138:139], s[0:1], v[144:145] op_sel_hi:[1,0,1]
	v_pk_fma_f32 v[96:97], v[142:143], s[86:87], v[96:97] op_sel_hi:[1,0,1]
	s_waitcnt vmcnt(0)
	v_mov_b64_e32 v[142:143], v[220:221]
	v_mov_b64_e32 v[144:145], v[222:223]
	v_pk_fma_f32 v[92:93], v[138:139], s[86:87], v[92:93] op_sel_hi:[1,0,1]
	v_cvt_pk_f32_fp8_e32 v[138:139], v140
	v_pk_fma_f32 v[150:151], v[152:153], s[0:1], v[150:151] op_sel_hi:[1,0,1]
	v_cvt_pk_f32_fp8_sdwa v[146:147], v140 src0_sel:WORD_1
	v_pk_fma_f32 v[148:149], v[148:149], s[0:1], v[154:155] op_sel_hi:[1,0,1]
	v_pk_fma_f32 v[90:91], v[150:151], s[86:87], v[90:91] op_sel_hi:[1,0,1]
	v_pk_fma_f32 v[94:95], v[148:149], s[86:87], v[94:95] op_sel_hi:[1,0,1]
	v_cvt_pk_f32_fp8_e32 v[148:149], v141
	v_cvt_pk_f32_fp8_sdwa v[140:141], v141 src0_sel:WORD_1
	s_waitcnt vmcnt(0)
	v_lshlrev_b32_e32 v150, 16, v142
	v_and_b32_e32 v151, 0xffff0000, v142
	v_pk_fma_f32 v[138:139], v[138:139], s[0:1], v[150:151] op_sel_hi:[1,0,1]
	v_lshlrev_b32_e32 v142, 16, v143
	v_and_b32_e32 v143, 0xffff0000, v143
	v_pk_fma_f32 v[102:103], v[138:139], s[86:87], v[102:103] op_sel_hi:[1,0,1]
	v_add_u32_e32 v138, 0x80, v136
	v_pk_fma_f32 v[142:143], v[146:147], s[0:1], v[142:143] op_sel_hi:[1,0,1]
	v_ashrrev_i32_e32 v139, 31, v138
	v_lshlrev_b32_e32 v146, 16, v144
	v_and_b32_e32 v147, 0xffff0000, v144
	v_lshlrev_b32_e32 v144, 16, v145
	v_and_b32_e32 v145, 0xffff0000, v145
	v_pk_fma_f32 v[104:105], v[142:143], s[86:87], v[104:105] op_sel_hi:[1,0,1]
	v_lshlrev_b64 v[142:143], 11, v[138:139]
	v_pk_fma_f32 v[146:147], v[148:149], s[0:1], v[146:147] op_sel_hi:[1,0,1]
	v_pk_fma_f32 v[140:141], v[140:141], s[0:1], v[144:145] op_sel_hi:[1,0,1]
	v_lshl_add_u64 v[138:139], s[8:9], 0, v[142:143]
	v_pk_fma_f32 v[100:101], v[140:141], s[86:87], v[100:101] op_sel_hi:[1,0,1]
	v_pk_fma_f32 v[98:99], v[146:147], s[86:87], v[98:99] op_sel_hi:[1,0,1]
	v_lshl_add_u64 v[138:139], v[138:139], 0, v[134:135]
	s_waitcnt vmcnt(0)
	v_mov_b64_e32 v[138:139], v[224:225]
	v_mov_b64_e32 v[140:141], v[226:227]
	v_lshl_add_u64 v[142:143], s[6:7], 0, v[142:143]
	v_lshl_add_u64 v[146:147], v[142:143], 0, v[132:133]
	s_waitcnt vmcnt(0)
	v_mov_b64_e32 v[142:143], v[228:229]
	v_mov_b64_e32 v[144:145], v[230:231]
	s_waitcnt vmcnt(1)
	v_cvt_pk_f32_fp8_sdwa v[150:151], v138 src0_sel:WORD_1
	v_cvt_pk_f32_fp8_e32 v[148:149], v138
	v_cvt_pk_f32_fp8_e32 v[152:153], v139
	v_cvt_pk_f32_fp8_sdwa v[138:139], v139 src0_sel:WORD_1
	s_waitcnt vmcnt(0)
	v_lshlrev_b32_e32 v154, 16, v142
	v_and_b32_e32 v155, 0xffff0000, v142
	v_lshlrev_b32_e32 v142, 16, v143
	v_and_b32_e32 v143, 0xffff0000, v143
	v_pk_fma_f32 v[142:143], v[150:151], s[0:1], v[142:143] op_sel_hi:[1,0,1]
	v_lshlrev_b32_e32 v150, 16, v144
	v_and_b32_e32 v151, 0xffff0000, v144
	v_lshlrev_b32_e32 v144, 16, v145
	v_and_b32_e32 v145, 0xffff0000, v145
	v_pk_fma_f32 v[138:139], v[138:139], s[0:1], v[144:145] op_sel_hi:[1,0,1]
	v_pk_fma_f32 v[120:121], v[142:143], s[86:87], v[120:121] op_sel_hi:[1,0,1]
	s_waitcnt vmcnt(0)
	v_mov_b64_e32 v[142:143], v[232:233]
	v_mov_b64_e32 v[144:145], v[234:235]
	v_pk_fma_f32 v[116:117], v[138:139], s[86:87], v[116:117] op_sel_hi:[1,0,1]
	v_cvt_pk_f32_fp8_e32 v[138:139], v140
	v_pk_fma_f32 v[150:151], v[152:153], s[0:1], v[150:151] op_sel_hi:[1,0,1]
	v_cvt_pk_f32_fp8_sdwa v[146:147], v140 src0_sel:WORD_1
	v_pk_fma_f32 v[148:149], v[148:149], s[0:1], v[154:155] op_sel_hi:[1,0,1]
	v_pk_fma_f32 v[114:115], v[150:151], s[86:87], v[114:115] op_sel_hi:[1,0,1]
	v_pk_fma_f32 v[118:119], v[148:149], s[86:87], v[118:119] op_sel_hi:[1,0,1]
	v_cvt_pk_f32_fp8_e32 v[148:149], v141
	v_cvt_pk_f32_fp8_sdwa v[140:141], v141 src0_sel:WORD_1
	s_waitcnt vmcnt(0)
	v_lshlrev_b32_e32 v150, 16, v142
	v_and_b32_e32 v151, 0xffff0000, v142
	v_pk_fma_f32 v[138:139], v[138:139], s[0:1], v[150:151] op_sel_hi:[1,0,1]
	v_lshlrev_b32_e32 v142, 16, v143
	v_and_b32_e32 v143, 0xffff0000, v143
	v_pk_fma_f32 v[126:127], v[138:139], s[86:87], v[126:127] op_sel_hi:[1,0,1]
	v_add_u32_e32 v138, 0x90, v136
	v_pk_fma_f32 v[142:143], v[146:147], s[0:1], v[142:143] op_sel_hi:[1,0,1]
	v_ashrrev_i32_e32 v139, 31, v138
	v_lshlrev_b32_e32 v146, 16, v144
	v_and_b32_e32 v147, 0xffff0000, v144
	v_lshlrev_b32_e32 v144, 16, v145
	v_and_b32_e32 v145, 0xffff0000, v145
	v_pk_fma_f32 v[128:129], v[142:143], s[86:87], v[128:129] op_sel_hi:[1,0,1]
	v_lshlrev_b64 v[142:143], 11, v[138:139]
	v_pk_fma_f32 v[146:147], v[148:149], s[0:1], v[146:147] op_sel_hi:[1,0,1]
	v_pk_fma_f32 v[140:141], v[140:141], s[0:1], v[144:145] op_sel_hi:[1,0,1]
	v_lshl_add_u64 v[138:139], s[8:9], 0, v[142:143]
	v_pk_fma_f32 v[124:125], v[140:141], s[86:87], v[124:125] op_sel_hi:[1,0,1]
	v_pk_fma_f32 v[122:123], v[146:147], s[86:87], v[122:123] op_sel_hi:[1,0,1]
	v_lshl_add_u64 v[138:139], v[138:139], 0, v[134:135]
	s_waitcnt vmcnt(0)
	v_mov_b64_e32 v[138:139], v[236:237]
	v_mov_b64_e32 v[140:141], v[238:239]
	v_lshl_add_u64 v[142:143], s[6:7], 0, v[142:143]
	v_lshl_add_u64 v[146:147], v[142:143], 0, v[132:133]
	s_waitcnt vmcnt(0)
	v_mov_b64_e32 v[142:143], v[240:241]
	v_mov_b64_e32 v[144:145], v[242:243]
	s_waitcnt vmcnt(1)
	v_cvt_pk_f32_fp8_sdwa v[150:151], v138 src0_sel:WORD_1
	v_cvt_pk_f32_fp8_e32 v[148:149], v138
	v_cvt_pk_f32_fp8_e32 v[152:153], v139
	v_cvt_pk_f32_fp8_sdwa v[138:139], v139 src0_sel:WORD_1
	s_waitcnt vmcnt(0)
	v_lshlrev_b32_e32 v154, 16, v142
	v_and_b32_e32 v155, 0xffff0000, v142
	v_lshlrev_b32_e32 v142, 16, v143
	v_and_b32_e32 v143, 0xffff0000, v143
	v_pk_fma_f32 v[142:143], v[150:151], s[0:1], v[142:143] op_sel_hi:[1,0,1]
	v_lshlrev_b32_e32 v150, 16, v144
	v_and_b32_e32 v151, 0xffff0000, v144
	v_lshlrev_b32_e32 v144, 16, v145
	v_and_b32_e32 v145, 0xffff0000, v145
	v_pk_fma_f32 v[138:139], v[138:139], s[0:1], v[144:145] op_sel_hi:[1,0,1]
	v_pk_fma_f32 v[112:113], v[142:143], s[86:87], v[112:113] op_sel_hi:[1,0,1]
	s_waitcnt vmcnt(0)
	v_mov_b64_e32 v[142:143], v[244:245]
	v_mov_b64_e32 v[144:145], v[246:247]
	s_mov_b32 s98, 0x50000
	s_mov_b32 s99, 0
	v_lshl_add_u64 v[212:213], v[248:249], 0, s[98:99]
	global_load_dwordx4 v[212:215], v[212:213], off
	s_mov_b32 s98, 0x50000
	s_mov_b32 s99, 0
	v_lshl_add_u64 v[216:217], v[250:251], 0, s[98:99]
	global_load_dwordx4 v[216:219], v[216:217], off
	s_mov_b32 s98, 0x50000
	s_mov_b32 s99, 0
	v_lshl_add_u64 v[220:221], v[250:251], 0, s[98:99]
	global_load_dwordx4 v[220:223], v[220:221], off offset:256
	s_mov_b32 s98, 0x58000
	s_mov_b32 s99, 0
	v_lshl_add_u64 v[224:225], v[248:249], 0, s[98:99]
	global_load_dwordx4 v[224:227], v[224:225], off
	s_mov_b32 s98, 0x58000
	s_mov_b32 s99, 0
	v_lshl_add_u64 v[228:229], v[250:251], 0, s[98:99]
	global_load_dwordx4 v[228:231], v[228:229], off
	s_mov_b32 s98, 0x58000
	s_mov_b32 s99, 0
	v_lshl_add_u64 v[232:233], v[250:251], 0, s[98:99]
	global_load_dwordx4 v[232:235], v[232:233], off offset:256
	v_pk_fma_f32 v[108:109], v[138:139], s[86:87], v[108:109] op_sel_hi:[1,0,1]
	v_cvt_pk_f32_fp8_e32 v[138:139], v140
	v_pk_fma_f32 v[150:151], v[152:153], s[0:1], v[150:151] op_sel_hi:[1,0,1]
	v_cvt_pk_f32_fp8_sdwa v[146:147], v140 src0_sel:WORD_1
	v_pk_fma_f32 v[148:149], v[148:149], s[0:1], v[154:155] op_sel_hi:[1,0,1]
	v_pk_fma_f32 v[106:107], v[150:151], s[86:87], v[106:107] op_sel_hi:[1,0,1]
	v_pk_fma_f32 v[110:111], v[148:149], s[86:87], v[110:111] op_sel_hi:[1,0,1]
	v_cvt_pk_f32_fp8_e32 v[148:149], v141
	v_cvt_pk_f32_fp8_sdwa v[140:141], v141 src0_sel:WORD_1
	s_waitcnt vmcnt(0)
	v_lshlrev_b32_e32 v150, 16, v142
	v_and_b32_e32 v151, 0xffff0000, v142
	v_pk_fma_f32 v[138:139], v[138:139], s[0:1], v[150:151] op_sel_hi:[1,0,1]
	v_lshlrev_b32_e32 v142, 16, v143
	v_and_b32_e32 v143, 0xffff0000, v143
	v_pk_fma_f32 v[86:87], v[138:139], s[86:87], v[86:87] op_sel_hi:[1,0,1]
	v_add_u32_e32 v138, 0xa0, v136
	v_pk_fma_f32 v[142:143], v[146:147], s[0:1], v[142:143] op_sel_hi:[1,0,1]
	v_ashrrev_i32_e32 v139, 31, v138
	v_lshlrev_b32_e32 v146, 16, v144
	v_and_b32_e32 v147, 0xffff0000, v144
	v_lshlrev_b32_e32 v144, 16, v145
	v_and_b32_e32 v145, 0xffff0000, v145
	v_pk_fma_f32 v[88:89], v[142:143], s[86:87], v[88:89] op_sel_hi:[1,0,1]
	v_lshlrev_b64 v[142:143], 11, v[138:139]
	v_pk_fma_f32 v[146:147], v[148:149], s[0:1], v[146:147] op_sel_hi:[1,0,1]
	v_pk_fma_f32 v[140:141], v[140:141], s[0:1], v[144:145] op_sel_hi:[1,0,1]
	v_lshl_add_u64 v[138:139], s[8:9], 0, v[142:143]
	v_pk_fma_f32 v[84:85], v[140:141], s[86:87], v[84:85] op_sel_hi:[1,0,1]
	v_pk_fma_f32 v[82:83], v[146:147], s[86:87], v[82:83] op_sel_hi:[1,0,1]
	v_lshl_add_u64 v[138:139], v[138:139], 0, v[134:135]
	s_waitcnt vmcnt(0)
	v_mov_b64_e32 v[138:139], v[212:213]
	v_mov_b64_e32 v[140:141], v[214:215]
	v_lshl_add_u64 v[142:143], s[6:7], 0, v[142:143]
	v_lshl_add_u64 v[146:147], v[142:143], 0, v[132:133]
	s_waitcnt vmcnt(0)
	v_mov_b64_e32 v[142:143], v[216:217]
	v_mov_b64_e32 v[144:145], v[218:219]
	v_add_u32_e32 v136, 0xb0, v136
	v_ashrrev_i32_e32 v137, 31, v136
	s_waitcnt vmcnt(1)
	v_cvt_pk_f32_fp8_sdwa v[150:151], v138 src0_sel:WORD_1
	v_cvt_pk_f32_fp8_e32 v[148:149], v138
	v_cvt_pk_f32_fp8_e32 v[152:153], v139
	v_cvt_pk_f32_fp8_sdwa v[138:139], v139 src0_sel:WORD_1
	s_waitcnt vmcnt(0)
	v_lshlrev_b32_e32 v154, 16, v142
	v_and_b32_e32 v155, 0xffff0000, v142
	v_lshlrev_b32_e32 v142, 16, v143
	v_and_b32_e32 v143, 0xffff0000, v143
	v_pk_fma_f32 v[142:143], v[150:151], s[0:1], v[142:143] op_sel_hi:[1,0,1]
	v_lshlrev_b32_e32 v150, 16, v144
	v_and_b32_e32 v151, 0xffff0000, v144
	v_lshlrev_b32_e32 v144, 16, v145
	v_and_b32_e32 v145, 0xffff0000, v145
	v_pk_fma_f32 v[138:139], v[138:139], s[0:1], v[144:145] op_sel_hi:[1,0,1]
	v_pk_fma_f32 v[72:73], v[142:143], s[86:87], v[72:73] op_sel_hi:[1,0,1]
	s_waitcnt vmcnt(0)
	v_mov_b64_e32 v[142:143], v[220:221]
	v_mov_b64_e32 v[144:145], v[222:223]
	v_pk_fma_f32 v[68:69], v[138:139], s[86:87], v[68:69] op_sel_hi:[1,0,1]
	v_cvt_pk_f32_fp8_e32 v[138:139], v140
	v_pk_fma_f32 v[148:149], v[148:149], s[0:1], v[154:155] op_sel_hi:[1,0,1]
	v_cvt_pk_f32_fp8_sdwa v[146:147], v140 src0_sel:WORD_1
	v_pk_fma_f32 v[150:151], v[152:153], s[0:1], v[150:151] op_sel_hi:[1,0,1]
	v_pk_fma_f32 v[70:71], v[148:149], s[86:87], v[70:71] op_sel_hi:[1,0,1]
	v_cvt_pk_f32_fp8_e32 v[148:149], v141
	v_cvt_pk_f32_fp8_sdwa v[140:141], v141 src0_sel:WORD_1
	v_pk_fma_f32 v[66:67], v[150:151], s[86:87], v[66:67] op_sel_hi:[1,0,1]
	s_waitcnt vmcnt(0)
	v_lshlrev_b32_e32 v150, 16, v142
	v_and_b32_e32 v151, 0xffff0000, v142
	v_pk_fma_f32 v[138:139], v[138:139], s[0:1], v[150:151] op_sel_hi:[1,0,1]
	v_lshlrev_b32_e32 v142, 16, v143
	v_and_b32_e32 v143, 0xffff0000, v143
	v_pk_fma_f32 v[142:143], v[146:147], s[0:1], v[142:143] op_sel_hi:[1,0,1]
	v_lshlrev_b32_e32 v146, 16, v144
	v_and_b32_e32 v147, 0xffff0000, v144
	v_lshlrev_b32_e32 v144, 16, v145
	v_and_b32_e32 v145, 0xffff0000, v145
	v_pk_fma_f32 v[54:55], v[138:139], s[86:87], v[54:55] op_sel_hi:[1,0,1]
	v_lshlrev_b64 v[138:139], 11, v[136:137]
	v_pk_fma_f32 v[146:147], v[148:149], s[0:1], v[146:147] op_sel_hi:[1,0,1]
	v_pk_fma_f32 v[140:141], v[140:141], s[0:1], v[144:145] op_sel_hi:[1,0,1]
	v_lshl_add_u64 v[136:137], s[8:9], 0, v[138:139]
	v_pk_fma_f32 v[56:57], v[142:143], s[86:87], v[56:57] op_sel_hi:[1,0,1]
	v_pk_fma_f32 v[52:53], v[140:141], s[86:87], v[52:53] op_sel_hi:[1,0,1]
	v_pk_fma_f32 v[50:51], v[146:147], s[86:87], v[50:51] op_sel_hi:[1,0,1]
	v_lshl_add_u64 v[134:135], v[136:137], 0, v[134:135]
	s_waitcnt vmcnt(0)
	v_mov_b64_e32 v[134:135], v[224:225]
	v_mov_b64_e32 v[136:137], v[226:227]
	v_lshl_add_u64 v[138:139], s[6:7], 0, v[138:139]
	v_lshl_add_u64 v[132:133], v[138:139], 0, v[132:133]
	s_waitcnt vmcnt(0)
	v_mov_b64_e32 v[138:139], v[228:229]
	v_mov_b64_e32 v[140:141], v[230:231]
	s_waitcnt vmcnt(1)
	v_cvt_pk_f32_fp8_sdwa v[144:145], v134 src0_sel:WORD_1
	v_cvt_pk_f32_fp8_e32 v[142:143], v134
	v_cvt_pk_f32_fp8_e32 v[146:147], v135
	v_cvt_pk_f32_fp8_sdwa v[134:135], v135 src0_sel:WORD_1
	s_waitcnt vmcnt(0)
	v_lshlrev_b32_e32 v148, 16, v138
	v_and_b32_e32 v149, 0xffff0000, v138
	v_lshlrev_b32_e32 v138, 16, v139
	v_and_b32_e32 v139, 0xffff0000, v139
	v_pk_fma_f32 v[138:139], v[144:145], s[0:1], v[138:139] op_sel_hi:[1,0,1]
	v_lshlrev_b32_e32 v144, 16, v140
	v_and_b32_e32 v145, 0xffff0000, v140
	v_lshlrev_b32_e32 v140, 16, v141
	v_and_b32_e32 v141, 0xffff0000, v141
	v_pk_fma_f32 v[134:135], v[134:135], s[0:1], v[140:141] op_sel_hi:[1,0,1]
	v_pk_fma_f32 v[142:143], v[142:143], s[0:1], v[148:149] op_sel_hi:[1,0,1]
	v_pk_fma_f32 v[28:29], v[134:135], s[86:87], v[28:29] op_sel_hi:[1,0,1]
	s_waitcnt vmcnt(0)
	v_mov_b64_e32 v[132:133], v[232:233]
	v_mov_b64_e32 v[134:135], v[234:235]
	v_cvt_pk_f32_fp8_sdwa v[140:141], v136 src0_sel:WORD_1
	v_pk_fma_f32 v[32:33], v[138:139], s[86:87], v[32:33] op_sel_hi:[1,0,1]
	v_pk_fma_f32 v[30:31], v[142:143], s[86:87], v[30:31] op_sel_hi:[1,0,1]
	v_cvt_pk_f32_fp8_e32 v[138:139], v136
	v_cvt_pk_f32_fp8_e32 v[142:143], v137
	v_cvt_pk_f32_fp8_sdwa v[136:137], v137 src0_sel:WORD_1
	v_pk_fma_f32 v[144:145], v[146:147], s[0:1], v[144:145] op_sel_hi:[1,0,1]
	s_nop 0
	v_pk_fma_f32 v[26:27], v[144:145], s[86:87], v[26:27] op_sel_hi:[1,0,1]
	s_waitcnt vmcnt(0)
	v_lshlrev_b32_e32 v144, 16, v132
	v_and_b32_e32 v145, 0xffff0000, v132
	v_lshlrev_b32_e32 v132, 16, v133
	v_and_b32_e32 v133, 0xffff0000, v133
	v_pk_fma_f32 v[132:133], v[140:141], s[0:1], v[132:133] op_sel_hi:[1,0,1]
	v_lshlrev_b32_e32 v140, 16, v134
	v_and_b32_e32 v141, 0xffff0000, v134
	v_lshlrev_b32_e32 v134, 16, v135
	v_and_b32_e32 v135, 0xffff0000, v135
	v_pk_fma_f32 v[138:139], v[138:139], s[0:1], v[144:145] op_sel_hi:[1,0,1]
	v_pk_fma_f32 v[140:141], v[142:143], s[0:1], v[140:141] op_sel_hi:[1,0,1]
	v_pk_fma_f32 v[134:135], v[136:137], s[0:1], v[134:135] op_sel_hi:[1,0,1]
	v_readlane_b32 s0, v255, 18
	v_readlane_b32 s1, v255, 19
	v_pk_fma_f32 v[16:17], v[132:133], s[86:87], v[16:17] op_sel_hi:[1,0,1]
	v_lshl_add_u64 v[132:133], s[4:5], 0, v[162:163]
	v_lshl_add_u64 v[130:131], s[0:1], 0, v[162:163]
	s_mov_b64 s[0:1], 0x2000
	v_pk_fma_f32 v[12:13], v[134:135], s[86:87], v[12:13] op_sel_hi:[1,0,1]
	v_lshl_add_u64 v[134:135], v[130:131], 0, s[0:1]
	v_lshl_add_u64 v[142:143], v[132:133], 0, s[0:1]
	s_movk_i32 s0, 0x2000
	v_add_co_u32_e32 v130, vcc, s0, v130
	v_pk_fma_f32 v[14:15], v[138:139], s[86:87], v[14:15] op_sel_hi:[1,0,1]
	v_pk_fma_f32 v[10:11], v[140:141], s[86:87], v[10:11] op_sel_hi:[1,0,1]
	v_addc_co_u32_e32 v131, vcc, 0, v131, vcc
	global_load_dwordx4 v[154:157], v[130:131], off
	global_load_dwordx4 v[146:149], v[134:135], off offset:16
	v_add_co_u32_e32 v130, vcc, s0, v132
	s_lshl_b32 s0, s38, 3
	s_nop 0
	v_addc_co_u32_e32 v131, vcc, 0, v133, vcc
	global_load_dwordx4 v[158:161], v[130:131], off
	global_load_dwordx4 v[150:153], v[142:143], off offset:16
	s_nop 0
	global_load_dwordx4 v[130:133], v[134:135], off offset:528
	global_load_dwordx4 v[138:141], v[134:135], off offset:512
	s_nop 0
	global_load_dwordx4 v[134:137], v[142:143], off offset:528
	s_nop 0
	global_load_dwordx4 v[142:145], v[142:143], off offset:512
	v_cmp_lt_i32_e32 vcc, v168, v169
	s_add_i32 s4, s0, 0
	s_nop 0
	v_cndmask_b32_e32 v168, v205, v168, vcc
	v_cmp_lt_i32_e32 vcc, v170, v169
	v_lshlrev_b32_e32 v168, 2, v168
	s_nop 0
	v_cndmask_b32_e32 v169, v205, v170, vcc
	v_mov_b32_e32 v170, v7
	v_pk_add_f32 v[170:171], v[170:171], v[172:173]
	v_mov_b32_e32 v172, v3
	v_mov_b32_e32 v173, v4
	v_pk_add_f32 v[172:173], v[172:173], v[174:175]
	v_add_f32_e32 v170, v170, v171
	v_pk_add_f32 v[172:173], v[172:173], v[172:173] op_sel_hi:[0,1]
	v_add_f32_e32 v171, 0, v170
	v_add_f32_e32 v175, v22, v23
	v_mov_b32_e32 v174, v18
	v_mov_b32_e32 v172, v20
	v_mov_b32_e32 v170, v21
	v_pk_add_f32 v[174:175], v[174:175], v[176:177]
	v_pk_add_f32 v[170:171], v[172:173], v[170:171]
	v_lshlrev_b32_e32 v169, 2, v169
	v_pk_add_f32 v[170:171], v[174:175], v[170:171]
	v_cmp_gt_u32_e32 vcc, 16, v167
	v_add_f32_e32 v170, v170, v171
	v_mov_b32_e32 v171, v170
	s_nop 1
	v_permlane16_swap_b32_e32 v171, v170
	s_waitcnt lgkmcnt(0)
	v_add_f32_e32 v170, v170, v171
	v_mov_b32_e32 v171, v170
	s_nop 1
	v_permlane32_swap_b32_e32 v171, v170
	s_waitcnt lgkmcnt(0)
	v_add_f32_e32 v170, v170, v171
	v_fmamk_f32 v172, v170, 0xbc800000, v9
	v_fmamk_f32 v174, v170, 0xbc800000, v7
	v_fmamk_f32 v171, v170, 0xbc800000, v8
	v_fmamk_f32 v173, v170, 0xbc800000, v6
	v_mul_f32_e32 v174, v174, v174
	v_mul_f32_e32 v172, v172, v172
	v_fmac_f32_e32 v174, v173, v173
	v_fmac_f32_e32 v172, v171, v171
	v_fmamk_f32 v173, v170, 0xbc800000, v5
	v_fmamk_f32 v175, v170, 0xbc800000, v3
	v_add_f32_e32 v171, v174, v172
	v_fmamk_f32 v172, v170, 0xbc800000, v4
	v_fmamk_f32 v174, v170, 0xbc800000, v2
	v_mul_f32_e32 v175, v175, v175
	v_mul_f32_e32 v173, v173, v173
	v_fmac_f32_e32 v175, v174, v174
	v_fmac_f32_e32 v173, v172, v172
	v_add_f32_e32 v172, v175, v173
	v_fmamk_f32 v173, v170, 0xbc800000, v25
	v_fmamk_f32 v175, v170, 0xbc800000, v23
	v_add_f32_e32 v171, v171, v172
	v_fmamk_f32 v172, v170, 0xbc800000, v24
	v_fmamk_f32 v174, v170, 0xbc800000, v22
	v_mul_f32_e32 v175, v175, v175
	v_mul_f32_e32 v173, v173, v173
	v_fmac_f32_e32 v175, v174, v174
	v_fmac_f32_e32 v173, v172, v172
	v_add_f32_e32 v172, v175, v173
	v_fmamk_f32 v173, v170, 0xbc800000, v21
	v_fmamk_f32 v175, v170, 0xbc800000, v19
	v_add_f32_e32 v171, v172, v171
	v_fmamk_f32 v172, v170, 0xbc800000, v20
	v_fmamk_f32 v174, v170, 0xbc800000, v18
	v_mul_f32_e32 v175, v175, v175
	v_mul_f32_e32 v173, v173, v173
	v_fmac_f32_e32 v175, v174, v174
	v_fmac_f32_e32 v173, v172, v172
	v_add_f32_e32 v172, v175, v173
	v_add_f32_e32 v171, v172, v171
	v_mov_b32_e32 v172, v171
	s_nop 1
	v_permlane16_swap_b32_e32 v172, v171
	s_waitcnt lgkmcnt(0)
	v_add_f32_e32 v171, v171, v172
	v_mov_b32_e32 v172, v171
	s_nop 1
	v_permlane32_swap_b32_e32 v172, v171
	s_and_saveexec_b64 s[0:1], vcc
	s_movk_i32 s89, 0x60
	s_mov_b64 s[38:39], s[62:63]
	s_cbranch_execz .LBB0_1298
	s_lshl_b32 s5, s94, 11
	s_add_i32 s5, s4, s5
	v_mul_f32_e32 v170, 0x3c800000, v170
	v_lshl_add_u32 v173, v165, 5, s5
	s_waitcnt lgkmcnt(0)
	v_add_f32_e32 v171, v171, v172
	ds_write_b64 v173, v[170:171]
.LBB0_1298:
	s_or_b64 exec, exec, s[0:1]
	v_mov_b32_e32 v170, v39
	v_mov_b32_e32 v171, v40
	s_waitcnt lgkmcnt(0)
	v_mov_b32_e32 v172, v38
	v_mov_b32_e32 v173, v41
	v_pk_add_f32 v[170:171], v[170:171], v[172:173]
	v_mov_b32_e32 v172, v35
	v_mov_b32_e32 v173, v36
	v_mov_b32_e32 v174, v34
	v_mov_b32_e32 v175, v37
	v_pk_add_f32 v[172:173], v[172:173], v[174:175]
	v_add_f32_e32 v170, v170, v171
	v_pk_add_f32 v[172:173], v[172:173], v[172:173] op_sel_hi:[0,1]
	v_add_f32_e32 v171, 0, v170
	v_add_f32_e32 v175, v46, v47
	v_add_f32_e32 v177, v48, v49
	v_mov_b32_e32 v174, v42
	v_mov_b32_e32 v176, v43
	v_mov_b32_e32 v172, v44
	v_mov_b32_e32 v170, v45
	v_pk_add_f32 v[174:175], v[174:175], v[176:177]
	v_pk_add_f32 v[170:171], v[172:173], v[170:171]
	s_nop 0
	v_pk_add_f32 v[170:171], v[174:175], v[170:171]
	s_nop 0
	v_add_f32_e32 v170, v170, v171
	v_mov_b32_e32 v171, v170
	s_nop 1
	v_permlane16_swap_b32_e32 v171, v170
	s_waitcnt lgkmcnt(0)
	v_add_f32_e32 v170, v170, v171
	v_mov_b32_e32 v171, v170
	s_nop 1
	v_permlane32_swap_b32_e32 v171, v170
	s_waitcnt lgkmcnt(0)
	v_add_f32_e32 v170, v170, v171
	v_fmamk_f32 v172, v170, 0xbc800000, v41
	v_fmamk_f32 v174, v170, 0xbc800000, v39
	v_fmamk_f32 v171, v170, 0xbc800000, v40
	v_fmamk_f32 v173, v170, 0xbc800000, v38
	v_mul_f32_e32 v174, v174, v174
	v_mul_f32_e32 v172, v172, v172
	v_fmac_f32_e32 v174, v173, v173
	v_fmac_f32_e32 v172, v171, v171
	v_fmamk_f32 v173, v170, 0xbc800000, v37
	v_fmamk_f32 v175, v170, 0xbc800000, v35
	v_add_f32_e32 v171, v174, v172
	v_fmamk_f32 v172, v170, 0xbc800000, v36
	v_fmamk_f32 v174, v170, 0xbc800000, v34
	v_mul_f32_e32 v175, v175, v175
	v_mul_f32_e32 v173, v173, v173
	v_fmac_f32_e32 v175, v174, v174
	v_fmac_f32_e32 v173, v172, v172
	v_add_f32_e32 v172, v175, v173
	v_fmamk_f32 v173, v170, 0xbc800000, v49
	v_fmamk_f32 v175, v170, 0xbc800000, v47
	v_add_f32_e32 v171, v171, v172
	v_fmamk_f32 v172, v170, 0xbc800000, v48
	v_fmamk_f32 v174, v170, 0xbc800000, v46
	v_mul_f32_e32 v175, v175, v175
	v_mul_f32_e32 v173, v173, v173
	v_fmac_f32_e32 v175, v174, v174
	v_fmac_f32_e32 v173, v172, v172
	v_add_f32_e32 v172, v175, v173
	v_fmamk_f32 v173, v170, 0xbc800000, v45
	v_fmamk_f32 v175, v170, 0xbc800000, v43
	v_add_f32_e32 v171, v172, v171
	v_fmamk_f32 v172, v170, 0xbc800000, v44
	v_fmamk_f32 v174, v170, 0xbc800000, v42
	v_mul_f32_e32 v175, v175, v175
	v_mul_f32_e32 v173, v173, v173
	v_fmac_f32_e32 v175, v174, v174
	v_fmac_f32_e32 v173, v172, v172
	v_add_f32_e32 v172, v175, v173
	v_add_f32_e32 v171, v172, v171
	v_mov_b32_e32 v172, v171
	s_nop 1
	v_permlane16_swap_b32_e32 v172, v171
	s_waitcnt lgkmcnt(0)
	v_add_f32_e32 v171, v171, v172
	v_mov_b32_e32 v172, v171
	s_nop 1
	v_permlane32_swap_b32_e32 v172, v171
	s_and_saveexec_b64 s[0:1], vcc
	v_readlane_b32 s62, v255, 10
	v_readlane_b32 s84, v255, 12
	v_readlane_b32 s63, v255, 11
	v_readlane_b32 s85, v255, 13
	s_cbranch_execz .LBB0_1300
	s_lshl_b32 s5, s94, 11
	s_add_i32 s5, s4, s5
	v_mul_f32_e32 v170, 0x3c800000, v170
	v_lshl_add_u32 v173, v165, 5, s5
	s_waitcnt lgkmcnt(0)
	v_add_f32_e32 v171, v171, v172
	ds_write_b64 v173, v[170:171] offset:512
.LBB0_1300:
	s_or_b64 exec, exec, s[0:1]
	v_mov_b32_e32 v170, v63
	v_mov_b32_e32 v171, v64
	s_waitcnt lgkmcnt(0)
	v_mov_b32_e32 v172, v62
	v_mov_b32_e32 v173, v65
	v_pk_add_f32 v[170:171], v[170:171], v[172:173]
	v_mov_b32_e32 v172, v59
	v_mov_b32_e32 v173, v60
	v_mov_b32_e32 v174, v58
	v_mov_b32_e32 v175, v61
	v_pk_add_f32 v[172:173], v[172:173], v[174:175]
	v_add_f32_e32 v170, v170, v171
	v_pk_add_f32 v[172:173], v[172:173], v[172:173] op_sel_hi:[0,1]
	v_add_f32_e32 v171, 0, v170
	v_add_f32_e32 v175, v78, v79
	v_add_f32_e32 v177, v80, v81
	v_mov_b32_e32 v174, v74
	v_mov_b32_e32 v176, v75
	v_mov_b32_e32 v172, v76
	v_mov_b32_e32 v170, v77
	v_pk_add_f32 v[174:175], v[174:175], v[176:177]
	v_pk_add_f32 v[170:171], v[172:173], v[170:171]
	s_nop 0
	v_pk_add_f32 v[170:171], v[174:175], v[170:171]
	s_nop 0
	v_add_f32_e32 v170, v170, v171
	v_mov_b32_e32 v171, v170
	s_nop 1
	v_permlane16_swap_b32_e32 v171, v170
	s_waitcnt lgkmcnt(0)
	v_add_f32_e32 v170, v170, v171
	v_mov_b32_e32 v171, v170
	s_nop 1
	v_permlane32_swap_b32_e32 v171, v170
	s_waitcnt lgkmcnt(0)
	v_add_f32_e32 v170, v170, v171
	v_fmamk_f32 v172, v170, 0xbc800000, v65
	v_fmamk_f32 v174, v170, 0xbc800000, v63
	v_fmamk_f32 v171, v170, 0xbc800000, v64
	v_fmamk_f32 v173, v170, 0xbc800000, v62
	v_mul_f32_e32 v174, v174, v174
	v_mul_f32_e32 v172, v172, v172
	v_fmac_f32_e32 v174, v173, v173
	v_fmac_f32_e32 v172, v171, v171
	v_fmamk_f32 v173, v170, 0xbc800000, v61
	v_fmamk_f32 v175, v170, 0xbc800000, v59
	v_add_f32_e32 v171, v174, v172
	v_fmamk_f32 v172, v170, 0xbc800000, v60
	v_fmamk_f32 v174, v170, 0xbc800000, v58
	v_mul_f32_e32 v175, v175, v175
	v_mul_f32_e32 v173, v173, v173
	v_fmac_f32_e32 v175, v174, v174
	v_fmac_f32_e32 v173, v172, v172
	v_add_f32_e32 v172, v175, v173
	v_fmamk_f32 v173, v170, 0xbc800000, v81
	v_fmamk_f32 v175, v170, 0xbc800000, v79
	v_add_f32_e32 v171, v171, v172
	v_fmamk_f32 v172, v170, 0xbc800000, v80
	v_fmamk_f32 v174, v170, 0xbc800000, v78
	v_mul_f32_e32 v175, v175, v175
	v_mul_f32_e32 v173, v173, v173
	v_fmac_f32_e32 v175, v174, v174
	v_fmac_f32_e32 v173, v172, v172
	v_add_f32_e32 v172, v175, v173
	v_fmamk_f32 v173, v170, 0xbc800000, v77
	v_fmamk_f32 v175, v170, 0xbc800000, v75
	v_add_f32_e32 v171, v172, v171
	v_fmamk_f32 v172, v170, 0xbc800000, v76
	v_fmamk_f32 v174, v170, 0xbc800000, v74
	v_mul_f32_e32 v175, v175, v175
	v_mul_f32_e32 v173, v173, v173
	v_fmac_f32_e32 v175, v174, v174
	v_fmac_f32_e32 v173, v172, v172
	v_add_f32_e32 v172, v175, v173
	v_add_f32_e32 v171, v172, v171
	v_mov_b32_e32 v172, v171
	s_nop 1
	v_permlane16_swap_b32_e32 v172, v171
	s_waitcnt lgkmcnt(0)
	v_add_f32_e32 v171, v171, v172
	v_mov_b32_e32 v172, v171
	s_nop 1
	v_permlane32_swap_b32_e32 v172, v171
	s_and_saveexec_b64 s[0:1], vcc
	s_cbranch_execz .LBB0_1302
	s_lshl_b32 s5, s94, 11
	s_add_i32 s5, s4, s5
	v_mul_f32_e32 v170, 0x3c800000, v170
	v_lshl_add_u32 v173, v165, 5, s5
	s_waitcnt lgkmcnt(0)
	v_add_f32_e32 v171, v171, v172
	ds_write_b64 v173, v[170:171] offset:1024
.LBB0_1302:
	s_or_b64 exec, exec, s[0:1]
	v_mov_b32_e32 v170, v95
	v_mov_b32_e32 v171, v96
	s_waitcnt lgkmcnt(0)
	v_mov_b32_e32 v172, v94
	v_mov_b32_e32 v173, v97
	v_pk_add_f32 v[170:171], v[170:171], v[172:173]
	v_mov_b32_e32 v172, v91
	v_mov_b32_e32 v173, v92
	v_mov_b32_e32 v174, v90
	v_mov_b32_e32 v175, v93
	v_pk_add_f32 v[172:173], v[172:173], v[174:175]
	v_add_f32_e32 v170, v170, v171
	v_pk_add_f32 v[172:173], v[172:173], v[172:173] op_sel_hi:[0,1]
	v_add_f32_e32 v171, 0, v170
	v_add_f32_e32 v175, v102, v103
	v_add_f32_e32 v177, v104, v105
	v_mov_b32_e32 v174, v98
	v_mov_b32_e32 v176, v99
	v_mov_b32_e32 v172, v100
	v_mov_b32_e32 v170, v101
	v_pk_add_f32 v[174:175], v[174:175], v[176:177]
	v_pk_add_f32 v[170:171], v[172:173], v[170:171]
	s_nop 0
	v_pk_add_f32 v[170:171], v[174:175], v[170:171]
	s_nop 0
	v_add_f32_e32 v170, v170, v171
	v_mov_b32_e32 v171, v170
	s_nop 1
	v_permlane16_swap_b32_e32 v171, v170
	s_waitcnt lgkmcnt(0)
	v_add_f32_e32 v170, v170, v171
	v_mov_b32_e32 v171, v170
	s_nop 1
	v_permlane32_swap_b32_e32 v171, v170
	s_waitcnt lgkmcnt(0)
	v_add_f32_e32 v170, v170, v171
	v_fmamk_f32 v172, v170, 0xbc800000, v97
	v_fmamk_f32 v174, v170, 0xbc800000, v95
	v_fmamk_f32 v171, v170, 0xbc800000, v96
	v_fmamk_f32 v173, v170, 0xbc800000, v94
	v_mul_f32_e32 v174, v174, v174
	v_mul_f32_e32 v172, v172, v172
	v_fmac_f32_e32 v174, v173, v173
	v_fmac_f32_e32 v172, v171, v171
	v_fmamk_f32 v173, v170, 0xbc800000, v93
	v_fmamk_f32 v175, v170, 0xbc800000, v91
	v_add_f32_e32 v171, v174, v172
	v_fmamk_f32 v172, v170, 0xbc800000, v92
	v_fmamk_f32 v174, v170, 0xbc800000, v90
	v_mul_f32_e32 v175, v175, v175
	v_mul_f32_e32 v173, v173, v173
	v_fmac_f32_e32 v175, v174, v174
	v_fmac_f32_e32 v173, v172, v172
	v_add_f32_e32 v172, v175, v173
	v_fmamk_f32 v173, v170, 0xbc800000, v105
	v_fmamk_f32 v175, v170, 0xbc800000, v103
	v_add_f32_e32 v171, v171, v172
	v_fmamk_f32 v172, v170, 0xbc800000, v104
	v_fmamk_f32 v174, v170, 0xbc800000, v102
	v_mul_f32_e32 v175, v175, v175
	v_mul_f32_e32 v173, v173, v173
	v_fmac_f32_e32 v175, v174, v174
	v_fmac_f32_e32 v173, v172, v172
	v_add_f32_e32 v172, v175, v173
	v_fmamk_f32 v173, v170, 0xbc800000, v101
	v_fmamk_f32 v175, v170, 0xbc800000, v99
	v_add_f32_e32 v171, v172, v171
	v_fmamk_f32 v172, v170, 0xbc800000, v100
	v_fmamk_f32 v174, v170, 0xbc800000, v98
	v_mul_f32_e32 v175, v175, v175
	v_mul_f32_e32 v173, v173, v173
	v_fmac_f32_e32 v175, v174, v174
	v_fmac_f32_e32 v173, v172, v172
	v_add_f32_e32 v172, v175, v173
	v_add_f32_e32 v171, v172, v171
	v_mov_b32_e32 v172, v171
	s_nop 1
	v_permlane16_swap_b32_e32 v172, v171
	s_waitcnt lgkmcnt(0)
	v_add_f32_e32 v171, v171, v172
	v_mov_b32_e32 v172, v171
	s_nop 1
	v_permlane32_swap_b32_e32 v172, v171
	s_and_saveexec_b64 s[0:1], vcc
	s_cbranch_execz .LBB0_1304
	s_lshl_b32 s5, s94, 11
	s_add_i32 s5, s4, s5
	v_mul_f32_e32 v170, 0x3c800000, v170
	v_lshl_add_u32 v173, v165, 5, s5
	s_waitcnt lgkmcnt(0)
	v_add_f32_e32 v171, v171, v172
	ds_write_b64 v173, v[170:171] offset:1536
.LBB0_1304:
	s_or_b64 exec, exec, s[0:1]
	v_mov_b32_e32 v170, v119
	v_mov_b32_e32 v171, v120
	s_waitcnt lgkmcnt(0)
	v_mov_b32_e32 v172, v118
	v_mov_b32_e32 v173, v121
	v_pk_add_f32 v[170:171], v[170:171], v[172:173]
	v_mov_b32_e32 v172, v115
	v_mov_b32_e32 v173, v116
	v_mov_b32_e32 v174, v114
	v_mov_b32_e32 v175, v117
	v_pk_add_f32 v[172:173], v[172:173], v[174:175]
	v_add_f32_e32 v170, v170, v171
	v_pk_add_f32 v[172:173], v[172:173], v[172:173] op_sel_hi:[0,1]
	v_add_f32_e32 v171, 0, v170
	v_add_f32_e32 v175, v126, v127
	v_add_f32_e32 v177, v128, v129
	v_mov_b32_e32 v174, v122
	v_mov_b32_e32 v176, v123
	v_mov_b32_e32 v172, v124
	v_mov_b32_e32 v170, v125
	v_pk_add_f32 v[174:175], v[174:175], v[176:177]
	v_pk_add_f32 v[170:171], v[172:173], v[170:171]
	s_nop 0
	v_pk_add_f32 v[170:171], v[174:175], v[170:171]
	s_nop 0
	v_add_f32_e32 v170, v170, v171
	v_mov_b32_e32 v171, v170
	s_nop 1
	v_permlane16_swap_b32_e32 v171, v170
	s_waitcnt lgkmcnt(0)
	v_add_f32_e32 v170, v170, v171
	v_mov_b32_e32 v171, v170
	s_nop 1
	v_permlane32_swap_b32_e32 v171, v170
	s_waitcnt lgkmcnt(0)
	v_add_f32_e32 v170, v170, v171
	v_fmamk_f32 v172, v170, 0xbc800000, v121
	v_fmamk_f32 v174, v170, 0xbc800000, v119
	v_fmamk_f32 v171, v170, 0xbc800000, v120
	v_fmamk_f32 v173, v170, 0xbc800000, v118
	v_mul_f32_e32 v174, v174, v174
	v_mul_f32_e32 v172, v172, v172
	v_fmac_f32_e32 v174, v173, v173
	v_fmac_f32_e32 v172, v171, v171
	v_fmamk_f32 v173, v170, 0xbc800000, v117
	v_fmamk_f32 v175, v170, 0xbc800000, v115
	v_add_f32_e32 v171, v174, v172
	v_fmamk_f32 v172, v170, 0xbc800000, v116
	v_fmamk_f32 v174, v170, 0xbc800000, v114
	v_mul_f32_e32 v175, v175, v175
	v_mul_f32_e32 v173, v173, v173
	v_fmac_f32_e32 v175, v174, v174
	v_fmac_f32_e32 v173, v172, v172
	v_add_f32_e32 v172, v175, v173
	v_fmamk_f32 v173, v170, 0xbc800000, v129
	v_fmamk_f32 v175, v170, 0xbc800000, v127
	v_add_f32_e32 v171, v171, v172
	v_fmamk_f32 v172, v170, 0xbc800000, v128
	v_fmamk_f32 v174, v170, 0xbc800000, v126
	v_mul_f32_e32 v175, v175, v175
	v_mul_f32_e32 v173, v173, v173
	v_fmac_f32_e32 v175, v174, v174
	v_fmac_f32_e32 v173, v172, v172
	v_add_f32_e32 v172, v175, v173
	v_fmamk_f32 v173, v170, 0xbc800000, v125
	v_fmamk_f32 v175, v170, 0xbc800000, v123
	v_add_f32_e32 v171, v172, v171
	v_fmamk_f32 v172, v170, 0xbc800000, v124
	v_fmamk_f32 v174, v170, 0xbc800000, v122
	v_mul_f32_e32 v175, v175, v175
	v_mul_f32_e32 v173, v173, v173
	v_fmac_f32_e32 v175, v174, v174
	v_fmac_f32_e32 v173, v172, v172
	v_add_f32_e32 v172, v175, v173
	v_add_f32_e32 v171, v172, v171
	v_mov_b32_e32 v172, v171
	s_nop 1
	v_permlane16_swap_b32_e32 v172, v171
	s_waitcnt lgkmcnt(0)
	v_add_f32_e32 v171, v171, v172
	v_mov_b32_e32 v172, v171
	s_nop 1
	v_permlane32_swap_b32_e32 v172, v171
	s_and_saveexec_b64 s[0:1], vcc
	s_cbranch_execz .LBB0_1306
	s_lshl_b32 s5, s94, 11
	s_add_i32 s5, s4, s5
	v_mul_f32_e32 v170, 0x3c800000, v170
	v_lshl_add_u32 v173, v165, 5, s5
	s_waitcnt lgkmcnt(0)
	v_add_f32_e32 v171, v171, v172
	ds_write_b64 v173, v[170:171] offset:4096
.LBB0_1306:
	s_or_b64 exec, exec, s[0:1]
	v_mov_b32_e32 v170, v111
	v_mov_b32_e32 v171, v112
	s_waitcnt lgkmcnt(0)
	v_mov_b32_e32 v172, v110
	v_mov_b32_e32 v173, v113
	v_pk_add_f32 v[170:171], v[170:171], v[172:173]
	v_mov_b32_e32 v172, v107
	v_mov_b32_e32 v173, v108
	v_mov_b32_e32 v174, v106
	v_mov_b32_e32 v175, v109
	v_pk_add_f32 v[172:173], v[172:173], v[174:175]
	v_add_f32_e32 v170, v170, v171
	v_pk_add_f32 v[172:173], v[172:173], v[172:173] op_sel_hi:[0,1]
	v_add_f32_e32 v171, 0, v170
	v_add_f32_e32 v175, v86, v87
	v_add_f32_e32 v177, v88, v89
	v_mov_b32_e32 v174, v82
	v_mov_b32_e32 v176, v83
	v_mov_b32_e32 v172, v84
	v_mov_b32_e32 v170, v85
	v_pk_add_f32 v[174:175], v[174:175], v[176:177]
	v_pk_add_f32 v[170:171], v[172:173], v[170:171]
	s_nop 0
	v_pk_add_f32 v[170:171], v[174:175], v[170:171]
	s_nop 0
	v_add_f32_e32 v170, v170, v171
	v_mov_b32_e32 v171, v170
	s_nop 1
	v_permlane16_swap_b32_e32 v171, v170
	s_waitcnt lgkmcnt(0)
	v_add_f32_e32 v170, v170, v171
	v_mov_b32_e32 v171, v170
	s_nop 1
	v_permlane32_swap_b32_e32 v171, v170
	s_waitcnt lgkmcnt(0)
	v_add_f32_e32 v170, v170, v171
	v_fmamk_f32 v172, v170, 0xbc800000, v113
	v_fmamk_f32 v174, v170, 0xbc800000, v111
	v_fmamk_f32 v171, v170, 0xbc800000, v112
	v_fmamk_f32 v173, v170, 0xbc800000, v110
	v_mul_f32_e32 v174, v174, v174
	v_mul_f32_e32 v172, v172, v172
	v_fmac_f32_e32 v174, v173, v173
	v_fmac_f32_e32 v172, v171, v171
	v_fmamk_f32 v173, v170, 0xbc800000, v109
	v_fmamk_f32 v175, v170, 0xbc800000, v107
	v_add_f32_e32 v171, v174, v172
	v_fmamk_f32 v172, v170, 0xbc800000, v108
	v_fmamk_f32 v174, v170, 0xbc800000, v106
	v_mul_f32_e32 v175, v175, v175
	v_mul_f32_e32 v173, v173, v173
	v_fmac_f32_e32 v175, v174, v174
	v_fmac_f32_e32 v173, v172, v172
	v_add_f32_e32 v172, v175, v173
	v_fmamk_f32 v173, v170, 0xbc800000, v89
	v_fmamk_f32 v175, v170, 0xbc800000, v87
	v_add_f32_e32 v171, v171, v172
	v_fmamk_f32 v172, v170, 0xbc800000, v88
	v_fmamk_f32 v174, v170, 0xbc800000, v86
	v_mul_f32_e32 v175, v175, v175
	v_mul_f32_e32 v173, v173, v173
	v_fmac_f32_e32 v175, v174, v174
	v_fmac_f32_e32 v173, v172, v172
	v_add_f32_e32 v172, v175, v173
	v_fmamk_f32 v173, v170, 0xbc800000, v85
	v_fmamk_f32 v175, v170, 0xbc800000, v83
	v_add_f32_e32 v171, v172, v171
	v_fmamk_f32 v172, v170, 0xbc800000, v84
	v_fmamk_f32 v174, v170, 0xbc800000, v82
	v_mul_f32_e32 v175, v175, v175
	v_mul_f32_e32 v173, v173, v173
	v_fmac_f32_e32 v175, v174, v174
	v_fmac_f32_e32 v173, v172, v172
	v_add_f32_e32 v172, v175, v173
	v_add_f32_e32 v171, v172, v171
	v_mov_b32_e32 v172, v171
	s_nop 1
	v_permlane16_swap_b32_e32 v172, v171
	s_waitcnt lgkmcnt(0)
	v_add_f32_e32 v171, v171, v172
	v_mov_b32_e32 v172, v171
	s_nop 1
	v_permlane32_swap_b32_e32 v172, v171
	s_and_saveexec_b64 s[0:1], vcc
	s_cbranch_execz .LBB0_1308
	s_lshl_b32 s5, s94, 11
	s_add_i32 s5, s4, s5
	v_mul_f32_e32 v170, 0x3c800000, v170
	v_lshl_add_u32 v173, v165, 5, s5
	s_waitcnt lgkmcnt(0)
	v_add_f32_e32 v171, v171, v172
	ds_write_b64 v173, v[170:171] offset:4608
.LBB0_1308:
	s_or_b64 exec, exec, s[0:1]
	v_mov_b32_e32 v170, v71
	v_mov_b32_e32 v171, v72
	s_waitcnt lgkmcnt(0)
	v_mov_b32_e32 v172, v70
	v_mov_b32_e32 v173, v73
	v_pk_add_f32 v[170:171], v[170:171], v[172:173]
	v_mov_b32_e32 v172, v67
	v_mov_b32_e32 v173, v68
	v_mov_b32_e32 v174, v66
	v_mov_b32_e32 v175, v69
	v_pk_add_f32 v[172:173], v[172:173], v[174:175]
	v_add_f32_e32 v170, v170, v171
	v_pk_add_f32 v[172:173], v[172:173], v[172:173] op_sel_hi:[0,1]
	v_add_f32_e32 v171, 0, v170
	v_add_f32_e32 v175, v54, v55
	v_add_f32_e32 v177, v56, v57
	v_mov_b32_e32 v174, v50
	v_mov_b32_e32 v176, v51
	v_mov_b32_e32 v172, v52
	v_mov_b32_e32 v170, v53
	v_pk_add_f32 v[174:175], v[174:175], v[176:177]
	v_pk_add_f32 v[170:171], v[172:173], v[170:171]
	s_nop 0
	v_pk_add_f32 v[170:171], v[174:175], v[170:171]
	s_nop 0
	v_add_f32_e32 v170, v170, v171
	v_mov_b32_e32 v171, v170
	s_nop 1
	v_permlane16_swap_b32_e32 v171, v170
	s_waitcnt lgkmcnt(0)
	v_add_f32_e32 v170, v170, v171
	v_mov_b32_e32 v171, v170
	s_nop 1
	v_permlane32_swap_b32_e32 v171, v170
	s_waitcnt lgkmcnt(0)
	v_add_f32_e32 v170, v170, v171
	v_fmamk_f32 v172, v170, 0xbc800000, v73
	v_fmamk_f32 v174, v170, 0xbc800000, v71
	v_fmamk_f32 v171, v170, 0xbc800000, v72
	v_fmamk_f32 v173, v170, 0xbc800000, v70
	v_mul_f32_e32 v174, v174, v174
	v_mul_f32_e32 v172, v172, v172
	v_fmac_f32_e32 v174, v173, v173
	v_fmac_f32_e32 v172, v171, v171
	v_fmamk_f32 v173, v170, 0xbc800000, v69
	v_fmamk_f32 v175, v170, 0xbc800000, v67
	v_add_f32_e32 v171, v174, v172
	v_fmamk_f32 v172, v170, 0xbc800000, v68
	v_fmamk_f32 v174, v170, 0xbc800000, v66
	v_mul_f32_e32 v175, v175, v175
	v_mul_f32_e32 v173, v173, v173
	v_fmac_f32_e32 v175, v174, v174
	v_fmac_f32_e32 v173, v172, v172
	v_add_f32_e32 v172, v175, v173
	v_fmamk_f32 v173, v170, 0xbc800000, v57
	v_fmamk_f32 v175, v170, 0xbc800000, v55
	v_add_f32_e32 v171, v171, v172
	v_fmamk_f32 v172, v170, 0xbc800000, v56
	v_fmamk_f32 v174, v170, 0xbc800000, v54
	v_mul_f32_e32 v175, v175, v175
	v_mul_f32_e32 v173, v173, v173
	v_fmac_f32_e32 v175, v174, v174
	v_fmac_f32_e32 v173, v172, v172
	v_add_f32_e32 v172, v175, v173
	v_fmamk_f32 v173, v170, 0xbc800000, v53
	v_fmamk_f32 v175, v170, 0xbc800000, v51
	v_add_f32_e32 v171, v172, v171
	v_fmamk_f32 v172, v170, 0xbc800000, v52
	v_fmamk_f32 v174, v170, 0xbc800000, v50
	v_mul_f32_e32 v175, v175, v175
	v_mul_f32_e32 v173, v173, v173
	v_fmac_f32_e32 v175, v174, v174
	v_fmac_f32_e32 v173, v172, v172
	v_add_f32_e32 v172, v175, v173
	v_add_f32_e32 v171, v172, v171
	v_mov_b32_e32 v172, v171
	s_nop 1
	v_permlane16_swap_b32_e32 v172, v171
	s_waitcnt lgkmcnt(0)
	v_add_f32_e32 v171, v171, v172
	v_mov_b32_e32 v172, v171
	s_nop 1
	v_permlane32_swap_b32_e32 v172, v171
	s_and_saveexec_b64 s[0:1], vcc
	s_cbranch_execz .LBB0_1310
	s_lshl_b32 s5, s94, 11
	s_add_i32 s5, s4, s5
	v_mul_f32_e32 v170, 0x3c800000, v170
	v_lshl_add_u32 v173, v165, 5, s5
	s_waitcnt lgkmcnt(0)
	v_add_f32_e32 v171, v171, v172
	ds_write_b64 v173, v[170:171] offset:5120
.LBB0_1310:
	s_or_b64 exec, exec, s[0:1]
	v_mov_b32_e32 v170, v31
	v_mov_b32_e32 v171, v32
	s_waitcnt lgkmcnt(0)
	v_mov_b32_e32 v172, v30
	v_mov_b32_e32 v173, v33
	v_pk_add_f32 v[170:171], v[170:171], v[172:173]
	v_mov_b32_e32 v172, v27
	v_mov_b32_e32 v173, v28
	v_mov_b32_e32 v174, v26
	v_mov_b32_e32 v175, v29
	v_pk_add_f32 v[172:173], v[172:173], v[174:175]
	v_add_f32_e32 v170, v170, v171
	v_pk_add_f32 v[172:173], v[172:173], v[172:173] op_sel_hi:[0,1]
	v_add_f32_e32 v171, 0, v170
	v_add_f32_e32 v175, v14, v15
	v_add_f32_e32 v177, v16, v17
	v_mov_b32_e32 v174, v10
	v_mov_b32_e32 v176, v11
	v_mov_b32_e32 v172, v12
	v_mov_b32_e32 v170, v13
	v_pk_add_f32 v[174:175], v[174:175], v[176:177]
	v_pk_add_f32 v[170:171], v[172:173], v[170:171]
	s_nop 0
	v_pk_add_f32 v[170:171], v[174:175], v[170:171]
	s_nop 0
	v_add_f32_e32 v170, v170, v171
	v_mov_b32_e32 v171, v170
	s_nop 1
	v_permlane16_swap_b32_e32 v171, v170
	s_waitcnt lgkmcnt(0)
	v_add_f32_e32 v170, v170, v171
	v_mov_b32_e32 v171, v170
	s_nop 1
	v_permlane32_swap_b32_e32 v171, v170
	s_waitcnt lgkmcnt(0)
	v_add_f32_e32 v170, v170, v171
	v_fmamk_f32 v172, v170, 0xbc800000, v33
	v_fmamk_f32 v174, v170, 0xbc800000, v31
	v_fmamk_f32 v171, v170, 0xbc800000, v32
	v_fmamk_f32 v173, v170, 0xbc800000, v30
	v_mul_f32_e32 v174, v174, v174
	v_mul_f32_e32 v172, v172, v172
	v_fmac_f32_e32 v174, v173, v173
	v_fmac_f32_e32 v172, v171, v171
	v_fmamk_f32 v173, v170, 0xbc800000, v29
	v_fmamk_f32 v175, v170, 0xbc800000, v27
	v_add_f32_e32 v171, v174, v172
	v_fmamk_f32 v172, v170, 0xbc800000, v28
	v_fmamk_f32 v174, v170, 0xbc800000, v26
	v_mul_f32_e32 v175, v175, v175
	v_mul_f32_e32 v173, v173, v173
	v_fmac_f32_e32 v175, v174, v174
	v_fmac_f32_e32 v173, v172, v172
	v_add_f32_e32 v172, v175, v173
	v_fmamk_f32 v173, v170, 0xbc800000, v17
	v_fmamk_f32 v175, v170, 0xbc800000, v15
	v_add_f32_e32 v171, v171, v172
	v_fmamk_f32 v172, v170, 0xbc800000, v16
	v_fmamk_f32 v174, v170, 0xbc800000, v14
	v_mul_f32_e32 v175, v175, v175
	v_mul_f32_e32 v173, v173, v173
	v_fmac_f32_e32 v175, v174, v174
	v_fmac_f32_e32 v173, v172, v172
	v_add_f32_e32 v172, v175, v173
	v_fmamk_f32 v173, v170, 0xbc800000, v13
	v_fmamk_f32 v175, v170, 0xbc800000, v11
	v_add_f32_e32 v171, v172, v171
	v_fmamk_f32 v172, v170, 0xbc800000, v12
	v_fmamk_f32 v174, v170, 0xbc800000, v10
	v_mul_f32_e32 v175, v175, v175
	v_mul_f32_e32 v173, v173, v173
	v_fmac_f32_e32 v175, v174, v174
	v_fmac_f32_e32 v173, v172, v172
	v_add_f32_e32 v172, v175, v173
	v_add_f32_e32 v171, v172, v171
	v_mov_b32_e32 v168, v171
	s_nop 1
	v_permlane16_swap_b32_e32 v168, v171
	s_waitcnt lgkmcnt(0)
	v_add_f32_e32 v168, v171, v168
	v_mov_b32_e32 v169, v168
	s_nop 1
	v_permlane32_swap_b32_e32 v169, v168
	s_and_saveexec_b64 s[0:1], vcc
	s_cbranch_execz .LBB0_1312
	s_lshl_b32 s5, s94, 11
	s_add_i32 s4, s4, s5
	v_mul_f32_e32 v170, 0x3c800000, v170
	v_lshl_add_u32 v165, v165, 5, s4
	s_waitcnt lgkmcnt(0)
	v_add_f32_e32 v171, v168, v169
	ds_write_b64 v165, v[170:171] offset:5632
